# v078 + GEMM staging loads take scalar base + 32-bit lane offset (120 64-bit VALU address adds removed)
# baseline (speedup 1.0000x reference)
; #define PG8_STAGE(bufoff, gbase, voff) do { _Pragma("unroll") for (int _i = 0; _i < 2; ++_i) \
;         __builtin_amdgcn_global_load_lds((const unsigned*)((const char*)(gbase) + (voff)[_i]), (PG8_LAS unsigned*)(lds + (bufoff) + ldsw + _i * 8192), 16, 0, 0); } while (0)
; #define PG8_WAIT_V(n) asm volatile("s_waitcnt vmcnt(" #n ")" ::: "memory")
; #define PG8_BAR __builtin_amdgcn_s_barrier()
; template <class Epi, class Sched, bool ALIGN_EPI = false, bool SP2 = false>
; __device__ __forceinline__ void gemm_phase(PG8_LAS unsigned char* lds, const Gemm g, const Sched& S, const Epi& E) {
;     const int tid = threadIdx.x, wid = __builtin_amdgcn_readfirstlane(tid >> 6), lane = tid & 63, wr = wid >> 2, wc = wid & 3, fr = lane & 15, fq = lane >> 4;
;     const int K = g.K, nt = K / BK;
;     unsigned voffA[2], voffB[2];
; #pragma unroll
;     for (int i = 0; i < 2; ++i) { int R, C; stage_rc(tid * 16 + i * 8192, R, C); const int Rb = Epi::PERM ? ((R & ~31) + perm32(R & 31)) : R;
;         voffA[i] = (unsigned)(R * K + C) * 2u; voffB[i] = (unsigned)(Rb * K + C) * 2u; }
;     const size_t kstep = (size_t)(BK * 2);
;     const size_t hstep = (size_t)HALF * K * 2;
;     const size_t tstep = 2 * hstep;
;     const unsigned ldsw = (unsigned)wid * 1024u;
;     const int aoff = lds_byte(wr * 64 + fr, fq * 8), boff = lds_byte(wc * 32 + fr, fq * 8);
;     ...
;     if constexpr (SP2) {
;         PG8_STAGE(PG8_SB(0, 0), cB, voffB); PG8_STAGE(PG8_SB(0, 1), cB + hstep, voffB); PG8_STAGE(PG8_SA(0, 0), cA, voffA); PG8_STAGE(PG8_SA(0, 1), cA + hstep, voffA);
;         if (wr == 1) PG8_BAR;
;         PG8_WAIT_V(2); PG8_BAR;
;         PG8_STAGE(PG8_SB(1, 0), cB + kstep, voffB); PG8_STAGE(PG8_SA(1, 0), cA + kstep, voffA); PG8_STAGE(PG8_SB(1, 1), cB + hstep + kstep, voffB);
;         PG8_WAIT_V(6); PG8_BAR;
.LBB0_84:
	s_mov_b64 s[18:19], 0x80
	s_and_b32 s17, s17, 3
	s_add_i32 m0, s87, 0x18000
	v_lshl_add_u64 v[6:7], v[6:7], 0, s[18:19]
	s_lshl_b32 s92, s85, 6
	s_lshl_b32 s22, s85, 13
	s_lshl_b32 s24, s17, 12
	s_waitcnt vmcnt(2)
	s_barrier
	global_load_lds_dwordx4 v[6:7], off
	v_lshl_add_u64 v[4:5], v[4:5], 0, s[18:19]
	s_add_i32 m0, s87, 0x1a000
	s_add_i32 s93, s87, 0x8000
	s_add_i32 s94, s87, 0xa000
	global_load_lds_dwordx4 v[4:5], off
	v_lshl_add_u64 v[0:1], v[0:1], 0, s[18:19]
	s_mov_b32 m0, s93
	s_add_u32 s20, s78, 0x40080
	global_load_lds_dwordx4 v[0:1], off
	v_lshl_add_u64 v[0:1], v[2:3], 0, s[18:19]
	s_mov_b32 m0, s94
	s_addc_u32 s21, s79, 0
	global_load_lds_dwordx4 v[0:1], off
	s_add_i32 m0, s87, 0x1c000
	global_load_lds_dwordx4 v146, s[20:21]
	v_lshl_add_u64 v[0:1], s[20:21], 0, v[150:151]
	s_add_i32 m0, s87, 0x1e000
	v_and_b32_e32 v171, 15, v230
	global_load_lds_dwordx4 v[0:1], off
	v_bfe_u32 v1, v230, 4, 2
	v_lshlrev_b32_e32 v152, 4, v1
	v_lshlrev_b32_e32 v0, 6, v171
	v_lshlrev_b32_e32 v3, 2, v230
	v_or_b32_e32 v2, v0, v152
	v_and_b32_e32 v3, 32, v3
	v_bitop3_b32 v5, v2, s22, v3 bitop3:0xde
	v_lshlrev_b32_e32 v2, 6, v230
	s_movk_i32 s20, 0x3c0
	s_cmpk_lt_u32 s16, 0x100
	v_and_or_b32 v2, v2, s20, v152
	s_cselect_b64 s[20:21], -1, 0
	s_lshl_b32 s95, s17, 6
	s_lshl_b32 s16, s17, 11
	s_add_i32 s17, s22, 0
	s_add_i32 s16, s17, s16
	v_lshlrev_b32_e32 v154, 3, v1
	v_bitop3_b32 v177, s24, v2, v3 bitop3:0xf6
	v_lshlrev_b32_e32 v1, 9, v1
	v_lshlrev_b32_e32 v3, 1, v171
	v_lshlrev_b32_e32 v4, 7, v13
	s_add_i32 s16, s16, 0x20000
	v_and_b32_e32 v7, 0x780, v4
	v_add3_u32 v181, s16, v1, v3
	v_lshlrev_b32_e32 v3, 8, v230
	v_add_u32_e32 v1, s16, v7
	v_and_b32_e32 v3, 0x38000, v3
	v_lshlrev_b32_e32 v7, 11, v10
	v_or3_b32 v3, v8, v3, v7
	v_add_u32_e32 v158, v3, v9
	v_lshlrev_b32_e32 v3, 4, v11
	s_waitcnt vmcnt(6)
	v_and_b32_e32 v2, 3, v230
	v_and_b32_e32 v3, 0x78000, v3
	v_lshlrev_b32_e32 v13, 5, v2
	v_lshlrev_b32_e32 v2, 4, v2
	v_or_b32_e32 v4, 0x800, v0
	v_or_b32_e32 v6, 0xc00, v0
	v_lshl_add_u64 v[156:157], s[34:35], 0, v[152:153]
	v_or3_b32 v3, v8, v3, v7
	s_add_i32 s33, 0, 0x10000
	s_add_i32 s16, 0, 0x14000
	v_lshlrev_b32_e32 v152, 1, v0
	v_mbcnt_lo_u32_b32 v0, -1, 0
	v_or_b32_e32 v175, s92, v171
	v_or_b32_e32 v179, v154, v12
	s_add_i32 s96, s82, -2
	s_ashr_i32 s97, s2, 31
	v_mov_b32_e32 v159, v153
	v_add_u32_e32 v160, v3, v9
	v_mov_b32_e32 v161, v153
	v_add_u32_e32 v183, s33, v177
	v_add_u32_e32 v185, s16, v177
	v_add_u32_e32 v186, 0, v5
	v_mov_b32_e32 v187, 0x358637bd
	v_add_u32_e32 v188, v1, v13
	v_lshlrev_b32_e32 v162, 1, v2
	s_mov_b64 s[36:37], 0x1000
	s_movk_i32 s17, 0x1000
	s_mov_b64 s[38:39], 0x1200
	v_lshlrev_b32_e32 v164, 1, v4
	v_lshlrev_b32_e32 v166, 1, v6
	v_mov_b64_e32 v[168:169], 0x11ff
	v_mbcnt_hi_u32_b32 v189, -1, v0
	v_mov_b32_e32 v190, 0x280
	s_barrier
	s_branch .LBB0_87

; #define PG8_STAGE(bufoff, gbase, voff) do { _Pragma("unroll") for (int _i = 0; _i < 2; ++_i) \
;         __builtin_amdgcn_global_load_lds((const unsigned*)((const char*)(gbase) + (voff)[_i]), (PG8_LAS unsigned*)(lds + (bufoff) + ldsw + _i * 8192), 16, 0, 0); } while (0)
; #define PG8_LDA(dst, b, h) do { _Pragma("unroll") for (int m = 0; m < 4; ++m) _Pragma("unroll") for (int k = 0; k < 2; ++k) dst[m][k] = *(const PG8_LAS bf16x8*)(lds + PG8_SA(b, h) + aoff + m * 2048 + k * 1024); } while (0)
; #define PG8_LDB(dst, b, h) do { _Pragma("unroll") for (int n = 0; n < 2; ++n) _Pragma("unroll") for (int k = 0; k < 2; ++k) dst[n][k] = *(const PG8_LAS bf16x8*)(lds + PG8_SB(b, h) + boff + n * 2048 + k * 1024); } while (0)
; #define PG8_MMA(ai, bj, At, Bt) do { __builtin_amdgcn_s_setprio(1); _Pragma("unroll") for (int m = 0; m < 4; ++m) _Pragma("unroll") for (int n = 0; n < 2; ++n) _Pragma("unroll") for (int k = 0; k < 2; ++k) \
;         acc[ai][bj][m][n] = __builtin_amdgcn_mfma_f32_16x16x32_bf16(Bt[n][k], At[m][k], acc[ai][bj][m][n], 0, 0, 0); __builtin_amdgcn_s_setprio(0); } while (0)
; #define PG8_BAR __builtin_amdgcn_s_barrier()
; template <class Epi, class Sched, bool ALIGN_EPI = false, bool SP2 = false>
; __device__ __forceinline__ void gemm_phase(PG8_LAS unsigned char* lds, const Gemm g, const Sched& S, const Epi& E) {
;     ...
;         const bool has_next = S.next(ui + 1, nxt);
;         const char* nA = has_next ? (const char*)g.A + (size_t)nxt.pm * tstep : cA; const char* nB = has_next ? (const char*)g.Bt + (size_t)nxt.pn * tstep : cB;
;         for (int t = 0; t < nt; t += 2) {
;             const bool last = (t == nt - 2);
;             const char* a1 = cA + (size_t)(t + 1) * kstep;
;             const char* a2 = last ? nA : cA + (size_t)(t + 2) * kstep; const char* b2 = last ? nB : cB + (size_t)(t + 2) * kstep;
;             const char* a3 = a2 + kstep; const char* b3 = b2 + kstep;
;             if (last && has_next) S.a_ready(nxt);
;             if constexpr (SP2) {
;             PG8_LDB(B0, 0, 0); PG8_LDB(B1, 0, 1); PG8_SCHED; PG8_LDA(At, 0, 0); PG8_STAGE(PG8_SA(1, 1), a1 + hstep, voffA);
;             PG8_WAIT_V(8); PG8_WAIT_L(0); PG8_BAR; PG8_MMA(0, 0, At, B0); PG8_MMA(0, 1, At, B1); PG8_BAR; PG8_SCHED;
;             PG8_LDA(At, 0, 1); PG8_STAGE(PG8_SB(0, 0), b2, voffB); PG8_STAGE(PG8_SB(0, 1), b2 + hstep, voffB); PG8_STAGE(PG8_SA(0, 0), a2, voffA);
.LBB0_90:
	s_ashr_i32 s55, s54, 31
	s_lshl_b64 s[24:25], s[54:55], 19
	s_add_u32 s60, s70, s24
	s_addc_u32 s61, s71, s25
	s_and_b64 s[24:25], s[58:59], exec
	s_cselect_b32 s23, s61, s77
	s_cselect_b32 s24, s60, s76
	s_ashr_i32 s53, s52, 31
	s_lshl_b64 s[26:27], s[52:53], 19
	s_add_u32 s62, s83, s26
	s_addc_u32 s63, s84, s27
	s_and_b64 s[26:27], s[58:59], exec
	s_cselect_b32 s25, s63, s79
	s_cselect_b32 s26, s62, s78
	s_add_u32 s76, s76, 0x40080
	s_addc_u32 s77, s77, 0
	s_add_u32 s27, s78, 0x100
	s_addc_u32 s28, s79, 0
	s_mov_b32 s29, -2
	ds_read_b128 v[128:131], v183
	ds_read_b128 v[132:135], v183 offset:1024
	ds_read_b128 v[136:139], v183 offset:2048
	ds_read_b128 v[140:143], v183 offset:3072
	ds_read_b128 v[192:195], v185
	ds_read_b128 v[196:199], v185 offset:1024
	ds_read_b128 v[200:203], v185 offset:2048
	ds_read_b128 v[204:207], v185 offset:3072
	s_add_u32 s30, s76, 0xfffc0080
	s_addc_u32 s31, s77, -1
	s_cmp_eq_u32 s29, 12
	s_cselect_b32 s81, s23, s31
	s_cselect_b32 s80, s24, s30
	s_cselect_b32 s79, s25, s28
	s_cselect_b32 s78, s26, s27
	s_add_i32 m0, s87, 0xc000
	ds_read_b128 v[208:211], v186
	ds_read_b128 v[212:215], v186 offset:1024
	ds_read_b128 v[216:219], v186 offset:2048
	ds_read_b128 v[220:223], v186 offset:3072
	ds_read_b128 v[224:227], v186 offset:4096
	ds_read_b128 v[232:235], v186 offset:5120
	ds_read_b128 v[236:239], v186 offset:6144
	ds_read_b128 v[240:243], v186 offset:7168
	global_load_lds_dwordx4 v158, s[76:77]
	s_add_i32 m0, s87, 0xe000
	s_nop 0
	global_load_lds_dwordx4 v160, s[76:77]
	s_waitcnt vmcnt(8)
	s_waitcnt lgkmcnt(0)
	s_barrier
	s_setprio 1
	s_waitcnt lgkmcnt(0)
	v_mfma_f32_16x16x32_bf16 v[124:127], v[128:131], v[208:211], 0
	v_mfma_f32_16x16x32_bf16 v[120:123], v[136:139], v[208:211], 0
	v_mfma_f32_16x16x32_bf16 v[112:115], v[128:131], v[216:219], 0
	v_mfma_f32_16x16x32_bf16 v[108:111], v[136:139], v[216:219], 0
	v_mfma_f32_16x16x32_bf16 v[96:99], v[128:131], v[224:227], 0
	v_mfma_f32_16x16x32_bf16 v[88:91], v[136:139], v[224:227], 0
	v_mfma_f32_16x16x32_bf16 v[80:83], v[128:131], v[236:239], 0
	v_mfma_f32_16x16x32_bf16 v[72:75], v[136:139], v[236:239], 0
	v_mfma_f32_16x16x32_bf16 v[124:127], v[132:135], v[212:215], v[124:127]
	v_mfma_f32_16x16x32_bf16 v[120:123], v[140:143], v[212:215], v[120:123]
	v_mfma_f32_16x16x32_bf16 v[112:115], v[132:135], v[220:223], v[112:115]
	v_mfma_f32_16x16x32_bf16 v[108:111], v[140:143], v[220:223], v[108:111]
	v_mfma_f32_16x16x32_bf16 v[96:99], v[132:135], v[232:235], v[96:99]
	v_mfma_f32_16x16x32_bf16 v[88:91], v[140:143], v[232:235], v[88:91]
	v_mfma_f32_16x16x32_bf16 v[80:83], v[132:135], v[240:243], v[80:83]
	v_mfma_f32_16x16x32_bf16 v[72:75], v[140:143], v[240:243], v[72:75]
	s_setprio 0
	s_setprio 1
	v_mfma_f32_16x16x32_bf16 v[116:119], v[192:195], v[208:211], 0
	v_mfma_f32_16x16x32_bf16 v[104:107], v[200:203], v[208:211], 0
	v_mfma_f32_16x16x32_bf16 v[100:103], v[192:195], v[216:219], 0
	v_mfma_f32_16x16x32_bf16 v[92:95], v[200:203], v[216:219], 0
	v_mfma_f32_16x16x32_bf16 v[84:87], v[192:195], v[224:227], 0
	v_mfma_f32_16x16x32_bf16 v[76:79], v[200:203], v[224:227], 0
	v_mfma_f32_16x16x32_bf16 v[68:71], v[192:195], v[236:239], 0
	v_mfma_f32_16x16x32_bf16 v[64:67], v[200:203], v[236:239], 0
	v_mfma_f32_16x16x32_bf16 v[116:119], v[196:199], v[212:215], v[116:119]
	v_mfma_f32_16x16x32_bf16 v[104:107], v[204:207], v[212:215], v[104:107]
	v_mfma_f32_16x16x32_bf16 v[100:103], v[196:199], v[220:223], v[100:103]
	v_mfma_f32_16x16x32_bf16 v[92:95], v[204:207], v[220:223], v[92:95]
	v_mfma_f32_16x16x32_bf16 v[84:87], v[196:199], v[232:235], v[84:87]
	v_mfma_f32_16x16x32_bf16 v[76:79], v[204:207], v[232:235], v[76:79]
	v_mfma_f32_16x16x32_bf16 v[68:71], v[196:199], v[240:243], v[68:71]
	v_mfma_f32_16x16x32_bf16 v[64:67], v[204:207], v[240:243], v[64:67]
	s_setprio 0
	s_barrier
	s_add_i32 s30, s33, s86
	v_lshl_add_u64 v[172:173], s[78:79], 0, v[146:147]
	s_mov_b32 m0, s30
	ds_read_b128 v[208:211], v186 offset:16384
	ds_read_b128 v[212:215], v186 offset:17408
	ds_read_b128 v[216:219], v186 offset:18432
	ds_read_b128 v[220:223], v186 offset:19456
	ds_read_b128 v[224:227], v186 offset:20480
	ds_read_b128 v[232:235], v186 offset:21504
	ds_read_b128 v[236:239], v186 offset:22528
	ds_read_b128 v[240:243], v186 offset:23552
	global_load_lds_dwordx4 v[172:173], off
	s_add_i32 m0, s30, 0x2000
	s_add_u32 s30, s78, 0x40000
	v_lshl_add_u64 v[228:229], s[78:79], 0, v[150:151]
	s_addc_u32 s31, s79, 0
	s_add_i32 s53, s16, s86
	global_load_lds_dwordx4 v[228:229], off
	s_mov_b32 m0, s53
	v_lshl_add_u64 v[246:247], s[80:81], 0, v[148:149]
	global_load_lds_dwordx4 v146, s[30:31]
	s_add_i32 m0, s53, 0x2000
	s_nop 0
	global_load_lds_dwordx4 v150, s[30:31]
	v_lshl_add_u64 v[244:245], s[80:81], 0, v[144:145]
	s_mov_b32 m0, s87
	s_nop 0
	global_load_lds_dwordx4 v[244:245], off
	s_mov_b32 m0, s88
	s_nop 0
	global_load_lds_dwordx4 v[246:247], off
	s_waitcnt vmcnt(8)
	s_waitcnt lgkmcnt(0)
	s_barrier
; #define PG8_STAGE(bufoff, gbase, voff) do { _Pragma("unroll") for (int _i = 0; _i < 2; ++_i) \
;         __builtin_amdgcn_global_load_lds((const unsigned*)((const char*)(gbase) + (voff)[_i]), (PG8_LAS unsigned*)(lds + (bufoff) + ldsw + _i * 8192), 16, 0, 0); } while (0)
; #define PG8_LDA(dst, b, h) do { _Pragma("unroll") for (int m = 0; m < 4; ++m) _Pragma("unroll") for (int k = 0; k < 2; ++k) dst[m][k] = *(const PG8_LAS bf16x8*)(lds + PG8_SA(b, h) + aoff + m * 2048 + k * 1024); } while (0)
; #define PG8_LDB(dst, b, h) do { _Pragma("unroll") for (int n = 0; n < 2; ++n) _Pragma("unroll") for (int k = 0; k < 2; ++k) dst[n][k] = *(const PG8_LAS bf16x8*)(lds + PG8_SB(b, h) + boff + n * 2048 + k * 1024); } while (0)
; #define PG8_MMA(ai, bj, At, Bt) do { __builtin_amdgcn_s_setprio(1); _Pragma("unroll") for (int m = 0; m < 4; ++m) _Pragma("unroll") for (int n = 0; n < 2; ++n) _Pragma("unroll") for (int k = 0; k < 2; ++k) \
;         acc[ai][bj][m][n] = __builtin_amdgcn_mfma_f32_16x16x32_bf16(Bt[n][k], At[m][k], acc[ai][bj][m][n], 0, 0, 0); __builtin_amdgcn_s_setprio(0); } while (0)
; #define PG8_WAIT_V(n) asm volatile("s_waitcnt vmcnt(" #n ")" ::: "memory")
; #define PG8_WAIT_L(n) asm volatile("s_waitcnt lgkmcnt(" #n ")" ::: "memory")
; #define PG8_BAR __builtin_amdgcn_s_barrier()
; #define PG8_SCHED __builtin_amdgcn_sched_barrier(0)
; template <class Epi, class Sched, bool ALIGN_EPI = false, bool SP2 = false>
; __device__ __forceinline__ void gemm_phase(PG8_LAS unsigned char* lds, const Gemm g, const Sched& S, const Epi& E) {
;     ...
;             PG8_WAIT_V(8); PG8_WAIT_L(0); PG8_BAR; PG8_MMA(0, 0, At, B0); PG8_MMA(0, 1, At, B1); PG8_BAR; PG8_SCHED;
;             PG8_LDA(At, 0, 1); PG8_STAGE(PG8_SB(0, 0), b2, voffB); PG8_STAGE(PG8_SB(0, 1), b2 + hstep, voffB); PG8_STAGE(PG8_SA(0, 0), a2, voffA);
;             PG8_WAIT_V(8); PG8_WAIT_L(0); PG8_BAR; PG8_MMA(1, 0, At, B0); PG8_MMA(1, 1, At, B1); PG8_BAR; PG8_SCHED;
;             PG8_LDB(B0, 1, 0); PG8_LDB(B1, 1, 1); PG8_SCHED; PG8_LDA(At, 1, 0); PG8_STAGE(PG8_SA(0, 1), a2 + hstep, voffA);
;             PG8_WAIT_V(8); PG8_WAIT_L(0); PG8_BAR; PG8_MMA(0, 0, At, B0); PG8_MMA(0, 1, At, B1); PG8_BAR; PG8_SCHED;
	s_setprio 1
	s_waitcnt lgkmcnt(0)
	v_mfma_f32_16x16x32_bf16 v[60:63], v[128:131], v[208:211], 0
	v_mfma_f32_16x16x32_bf16 v[56:59], v[136:139], v[208:211], 0
	v_mfma_f32_16x16x32_bf16 v[48:51], v[128:131], v[216:219], 0
	v_mfma_f32_16x16x32_bf16 v[44:47], v[136:139], v[216:219], 0
	v_mfma_f32_16x16x32_bf16 v[32:35], v[128:131], v[224:227], 0
	v_mfma_f32_16x16x32_bf16 v[28:31], v[136:139], v[224:227], 0
	v_mfma_f32_16x16x32_bf16 v[16:19], v[128:131], v[236:239], 0
	v_mfma_f32_16x16x32_bf16 v[12:15], v[136:139], v[236:239], 0
	v_mfma_f32_16x16x32_bf16 v[60:63], v[132:135], v[212:215], v[60:63]
	v_mfma_f32_16x16x32_bf16 v[56:59], v[140:143], v[212:215], v[56:59]
	v_mfma_f32_16x16x32_bf16 v[48:51], v[132:135], v[220:223], v[48:51]
	v_mfma_f32_16x16x32_bf16 v[44:47], v[140:143], v[220:223], v[44:47]
	v_mfma_f32_16x16x32_bf16 v[32:35], v[132:135], v[232:235], v[32:35]
	v_mfma_f32_16x16x32_bf16 v[28:31], v[140:143], v[232:235], v[28:31]
	v_mfma_f32_16x16x32_bf16 v[16:19], v[132:135], v[240:243], v[16:19]
	v_mfma_f32_16x16x32_bf16 v[12:15], v[140:143], v[240:243], v[12:15]
	s_setprio 0
	s_setprio 1
	v_mfma_f32_16x16x32_bf16 v[52:55], v[192:195], v[208:211], 0
	v_mfma_f32_16x16x32_bf16 v[40:43], v[200:203], v[208:211], 0
	v_mfma_f32_16x16x32_bf16 v[36:39], v[192:195], v[216:219], 0
	v_mfma_f32_16x16x32_bf16 v[24:27], v[200:203], v[216:219], 0
	v_mfma_f32_16x16x32_bf16 v[20:23], v[192:195], v[224:227], 0
	v_mfma_f32_16x16x32_bf16 v[8:11], v[200:203], v[224:227], 0
	v_mfma_f32_16x16x32_bf16 v[4:7], v[192:195], v[236:239], 0
	v_mfma_f32_16x16x32_bf16 v[0:3], v[200:203], v[236:239], 0
	v_mfma_f32_16x16x32_bf16 v[52:55], v[196:199], v[212:215], v[52:55]
	v_mfma_f32_16x16x32_bf16 v[40:43], v[204:207], v[212:215], v[40:43]
	v_mfma_f32_16x16x32_bf16 v[36:39], v[196:199], v[220:223], v[36:39]
	v_mfma_f32_16x16x32_bf16 v[24:27], v[204:207], v[220:223], v[24:27]
	v_mfma_f32_16x16x32_bf16 v[20:23], v[196:199], v[232:235], v[20:23]
	v_mfma_f32_16x16x32_bf16 v[8:11], v[204:207], v[232:235], v[8:11]
	v_mfma_f32_16x16x32_bf16 v[4:7], v[196:199], v[240:243], v[4:7]
	v_mfma_f32_16x16x32_bf16 v[0:3], v[204:207], v[240:243], v[0:3]
	s_setprio 0
	s_barrier
	s_add_i32 s53, 0, 0x18000
	s_add_i32 s55, 0, 0x1c000
	v_add_u32_e32 v140, s53, v177
	v_add_u32_e32 v163, s55, v177
	ds_read_b128 v[128:131], v140
	ds_read_b128 v[132:135], v140 offset:1024
	ds_read_b128 v[136:139], v140 offset:2048
	ds_read_b128 v[140:143], v140 offset:3072
	ds_read_b128 v[192:195], v163
	ds_read_b128 v[196:199], v163 offset:1024
	ds_read_b128 v[200:203], v163 offset:2048
	ds_read_b128 v[204:207], v163 offset:3072
	s_add_u32 s30, s80, 0x40000
	s_addc_u32 s31, s81, 0
	s_mov_b32 m0, s89
	ds_read_b128 v[208:211], v186 offset:32768
	ds_read_b128 v[212:215], v186 offset:33792
	ds_read_b128 v[216:219], v186 offset:34816
	ds_read_b128 v[220:223], v186 offset:35840
	ds_read_b128 v[224:227], v186 offset:36864
	ds_read_b128 v[232:235], v186 offset:37888
	ds_read_b128 v[236:239], v186 offset:38912
	ds_read_b128 v[240:243], v186 offset:39936
	global_load_lds_dwordx4 v144, s[30:31]
	v_lshl_add_u64 v[248:249], s[30:31], 0, v[148:149]
	s_mov_b32 m0, s90
	s_nop 0
	global_load_lds_dwordx4 v[248:249], off
	s_waitcnt vmcnt(8)
	s_waitcnt lgkmcnt(0)
	s_barrier
	s_setprio 1
	s_waitcnt lgkmcnt(0)
	v_mfma_f32_16x16x32_bf16 v[124:127], v[128:131], v[208:211], v[124:127]
	v_mfma_f32_16x16x32_bf16 v[120:123], v[136:139], v[208:211], v[120:123]
	v_mfma_f32_16x16x32_bf16 v[112:115], v[128:131], v[216:219], v[112:115]
	v_mfma_f32_16x16x32_bf16 v[108:111], v[136:139], v[216:219], v[108:111]
	v_mfma_f32_16x16x32_bf16 v[96:99], v[128:131], v[224:227], v[96:99]
	v_mfma_f32_16x16x32_bf16 v[88:91], v[136:139], v[224:227], v[88:91]
	v_mfma_f32_16x16x32_bf16 v[80:83], v[128:131], v[236:239], v[80:83]
	v_mfma_f32_16x16x32_bf16 v[72:75], v[136:139], v[236:239], v[72:75]
	v_mfma_f32_16x16x32_bf16 v[124:127], v[132:135], v[212:215], v[124:127]
	v_mfma_f32_16x16x32_bf16 v[120:123], v[140:143], v[212:215], v[120:123]
	v_mfma_f32_16x16x32_bf16 v[112:115], v[132:135], v[220:223], v[112:115]
	v_mfma_f32_16x16x32_bf16 v[108:111], v[140:143], v[220:223], v[108:111]
	v_mfma_f32_16x16x32_bf16 v[96:99], v[132:135], v[232:235], v[96:99]
	v_mfma_f32_16x16x32_bf16 v[88:91], v[140:143], v[232:235], v[88:91]
	v_mfma_f32_16x16x32_bf16 v[80:83], v[132:135], v[240:243], v[80:83]
	v_mfma_f32_16x16x32_bf16 v[72:75], v[140:143], v[240:243], v[72:75]
	s_setprio 0
	s_setprio 1
	v_mfma_f32_16x16x32_bf16 v[116:119], v[192:195], v[208:211], v[116:119]
	v_mfma_f32_16x16x32_bf16 v[104:107], v[200:203], v[208:211], v[104:107]
	v_mfma_f32_16x16x32_bf16 v[100:103], v[192:195], v[216:219], v[100:103]
	v_mfma_f32_16x16x32_bf16 v[92:95], v[200:203], v[216:219], v[92:95]
	v_mfma_f32_16x16x32_bf16 v[84:87], v[192:195], v[224:227], v[84:87]
	v_mfma_f32_16x16x32_bf16 v[76:79], v[200:203], v[224:227], v[76:79]
	v_mfma_f32_16x16x32_bf16 v[68:71], v[192:195], v[236:239], v[68:71]
	v_mfma_f32_16x16x32_bf16 v[64:67], v[200:203], v[236:239], v[64:67]
	v_mfma_f32_16x16x32_bf16 v[116:119], v[196:199], v[212:215], v[116:119]
	v_mfma_f32_16x16x32_bf16 v[104:107], v[204:207], v[212:215], v[104:107]
	v_mfma_f32_16x16x32_bf16 v[100:103], v[196:199], v[220:223], v[100:103]
	v_mfma_f32_16x16x32_bf16 v[92:95], v[204:207], v[220:223], v[92:95]
	v_mfma_f32_16x16x32_bf16 v[84:87], v[196:199], v[232:235], v[84:87]
	v_mfma_f32_16x16x32_bf16 v[76:79], v[204:207], v[232:235], v[76:79]
	v_mfma_f32_16x16x32_bf16 v[68:71], v[196:199], v[240:243], v[68:71]
	v_mfma_f32_16x16x32_bf16 v[64:67], v[204:207], v[240:243], v[64:67]
	s_setprio 0
	s_barrier
; #define PG8_STAGE(bufoff, gbase, voff) do { _Pragma("unroll") for (int _i = 0; _i < 2; ++_i) \
;         __builtin_amdgcn_global_load_lds((const unsigned*)((const char*)(gbase) + (voff)[_i]), (PG8_LAS unsigned*)(lds + (bufoff) + ldsw + _i * 8192), 16, 0, 0); } while (0)
; #define PG8_LDA(dst, b, h) do { _Pragma("unroll") for (int m = 0; m < 4; ++m) _Pragma("unroll") for (int k = 0; k < 2; ++k) dst[m][k] = *(const PG8_LAS bf16x8*)(lds + PG8_SA(b, h) + aoff + m * 2048 + k * 1024); } while (0)
; #define PG8_MMA(ai, bj, At, Bt) do { __builtin_amdgcn_s_setprio(1); _Pragma("unroll") for (int m = 0; m < 4; ++m) _Pragma("unroll") for (int n = 0; n < 2; ++n) _Pragma("unroll") for (int k = 0; k < 2; ++k) \
;         acc[ai][bj][m][n] = __builtin_amdgcn_mfma_f32_16x16x32_bf16(Bt[n][k], At[m][k], acc[ai][bj][m][n], 0, 0, 0); __builtin_amdgcn_s_setprio(0); } while (0)
; #define PG8_WAIT_V(n) asm volatile("s_waitcnt vmcnt(" #n ")" ::: "memory")
; #define PG8_WAIT_L(n) asm volatile("s_waitcnt lgkmcnt(" #n ")" ::: "memory")
; #define PG8_BAR __builtin_amdgcn_s_barrier()
; #define PG8_SCHED __builtin_amdgcn_sched_barrier(0)
; template <class Epi, class Sched, bool ALIGN_EPI = false, bool SP2 = false>
; __device__ __forceinline__ void gemm_phase(PG8_LAS unsigned char* lds, const Gemm g, const Sched& S, const Epi& E) {
;     ...
;             PG8_WAIT_V(8); PG8_WAIT_L(0); PG8_BAR; PG8_MMA(0, 0, At, B0); PG8_MMA(0, 1, At, B1); PG8_BAR; PG8_SCHED;
;             PG8_LDA(At, 1, 1); PG8_STAGE(PG8_SB(1, 0), b3, voffB); PG8_STAGE(PG8_SB(1, 1), b3 + hstep, voffB); PG8_STAGE(PG8_SA(1, 0), a3, voffA);
;             PG8_WAIT_V(8); PG8_WAIT_L(0); PG8_BAR; PG8_MMA(1, 0, At, B0); PG8_MMA(1, 1, At, B1); PG8_BAR; PG8_SCHED;
	s_add_i32 s30, s53, s86
	v_lshl_add_u64 v[172:173], v[172:173], 0, s[18:19]
	s_mov_b32 m0, s30
	ds_read_b128 v[208:211], v186 offset:49152
	ds_read_b128 v[212:215], v186 offset:50176
	ds_read_b128 v[216:219], v186 offset:51200
	ds_read_b128 v[220:223], v186 offset:52224
	ds_read_b128 v[224:227], v186 offset:53248
	ds_read_b128 v[232:235], v186 offset:54272
	ds_read_b128 v[236:239], v186 offset:55296
	ds_read_b128 v[240:243], v186 offset:56320
	global_load_lds_dwordx4 v[172:173], off
	s_add_i32 m0, s30, 0x2000
	s_add_u32 s30, s78, 0x40080
	v_lshl_add_u64 v[172:173], v[228:229], 0, s[18:19]
	s_addc_u32 s31, s79, 0
	s_add_i32 s53, s55, s86
	global_load_lds_dwordx4 v[172:173], off
	s_mov_b32 m0, s53
	s_nop 0
	global_load_lds_dwordx4 v146, s[30:31]
	s_add_i32 m0, s53, 0x2000
	s_nop 0
	global_load_lds_dwordx4 v150, s[30:31]
	v_lshl_add_u64 v[172:173], v[244:245], 0, s[18:19]
	s_mov_b32 m0, s93
	s_nop 0
	global_load_lds_dwordx4 v[172:173], off
	v_lshl_add_u64 v[172:173], v[246:247], 0, s[18:19]
	s_mov_b32 m0, s94
	s_nop 0
	global_load_lds_dwordx4 v[172:173], off
	s_waitcnt vmcnt(8)
	s_waitcnt lgkmcnt(0)
	s_barrier
	s_setprio 1
	s_waitcnt lgkmcnt(0)
	v_mfma_f32_16x16x32_bf16 v[60:63], v[128:131], v[208:211], v[60:63]
	v_mfma_f32_16x16x32_bf16 v[56:59], v[136:139], v[208:211], v[56:59]
	v_mfma_f32_16x16x32_bf16 v[48:51], v[128:131], v[216:219], v[48:51]
	v_mfma_f32_16x16x32_bf16 v[44:47], v[136:139], v[216:219], v[44:47]
	v_mfma_f32_16x16x32_bf16 v[32:35], v[128:131], v[224:227], v[32:35]
	v_mfma_f32_16x16x32_bf16 v[28:31], v[136:139], v[224:227], v[28:31]
	v_mfma_f32_16x16x32_bf16 v[16:19], v[128:131], v[236:239], v[16:19]
	v_mfma_f32_16x16x32_bf16 v[12:15], v[136:139], v[236:239], v[12:15]
	v_mfma_f32_16x16x32_bf16 v[60:63], v[132:135], v[212:215], v[60:63]
	v_mfma_f32_16x16x32_bf16 v[56:59], v[140:143], v[212:215], v[56:59]
	v_mfma_f32_16x16x32_bf16 v[48:51], v[132:135], v[220:223], v[48:51]
	v_mfma_f32_16x16x32_bf16 v[44:47], v[140:143], v[220:223], v[44:47]
	v_mfma_f32_16x16x32_bf16 v[32:35], v[132:135], v[232:235], v[32:35]
	v_mfma_f32_16x16x32_bf16 v[28:31], v[140:143], v[232:235], v[28:31]
	v_mfma_f32_16x16x32_bf16 v[16:19], v[132:135], v[240:243], v[16:19]
	v_mfma_f32_16x16x32_bf16 v[12:15], v[140:143], v[240:243], v[12:15]
	s_setprio 0
	s_setprio 1
	v_mfma_f32_16x16x32_bf16 v[52:55], v[192:195], v[208:211], v[52:55]
	v_mfma_f32_16x16x32_bf16 v[40:43], v[200:203], v[208:211], v[40:43]
	v_mfma_f32_16x16x32_bf16 v[36:39], v[192:195], v[216:219], v[36:39]
	v_mfma_f32_16x16x32_bf16 v[24:27], v[200:203], v[216:219], v[24:27]
	v_mfma_f32_16x16x32_bf16 v[20:23], v[192:195], v[224:227], v[20:23]
	v_mfma_f32_16x16x32_bf16 v[8:11], v[200:203], v[224:227], v[8:11]
	v_mfma_f32_16x16x32_bf16 v[4:7], v[192:195], v[236:239], v[4:7]
	v_mfma_f32_16x16x32_bf16 v[0:3], v[200:203], v[236:239], v[0:3]
	v_mfma_f32_16x16x32_bf16 v[52:55], v[196:199], v[212:215], v[52:55]
	v_mfma_f32_16x16x32_bf16 v[40:43], v[204:207], v[212:215], v[40:43]
	v_mfma_f32_16x16x32_bf16 v[36:39], v[196:199], v[220:223], v[36:39]
	v_mfma_f32_16x16x32_bf16 v[24:27], v[204:207], v[220:223], v[24:27]
	v_mfma_f32_16x16x32_bf16 v[20:23], v[196:199], v[232:235], v[20:23]
	v_mfma_f32_16x16x32_bf16 v[8:11], v[204:207], v[232:235], v[8:11]
	v_mfma_f32_16x16x32_bf16 v[4:7], v[196:199], v[240:243], v[4:7]
	v_mfma_f32_16x16x32_bf16 v[0:3], v[204:207], v[240:243], v[0:3]
	s_setprio 0
	s_barrier
	s_add_i32 s29, s29, 2
	s_add_u32 s76, s76, 0x100
	s_addc_u32 s77, s77, 0
	s_add_u32 s27, s27, 0x100
	s_addc_u32 s28, s28, 0
	s_cmp_gt_u32 s29, 13
.LBB0_91:
	ds_read_b128 v[128:131], v183
	ds_read_b128 v[132:135], v183 offset:1024
	ds_read_b128 v[136:139], v183 offset:2048
	ds_read_b128 v[140:143], v183 offset:3072
	ds_read_b128 v[192:195], v185
	ds_read_b128 v[196:199], v185 offset:1024
	ds_read_b128 v[200:203], v185 offset:2048
	ds_read_b128 v[204:207], v185 offset:3072
	s_add_u32 s30, s76, 0xfffc0080
	s_addc_u32 s31, s77, -1
	s_cmp_eq_u32 s29, 12
	s_cselect_b32 s81, s23, s31
	s_cselect_b32 s80, s24, s30
	s_cselect_b32 s79, s25, s28
	s_cselect_b32 s78, s26, s27
	s_add_i32 m0, s87, 0xc000
	ds_read_b128 v[208:211], v186
	ds_read_b128 v[212:215], v186 offset:1024
	ds_read_b128 v[216:219], v186 offset:2048
	ds_read_b128 v[220:223], v186 offset:3072
	ds_read_b128 v[224:227], v186 offset:4096
	ds_read_b128 v[232:235], v186 offset:5120
	ds_read_b128 v[236:239], v186 offset:6144
	ds_read_b128 v[240:243], v186 offset:7168
	global_load_lds_dwordx4 v158, s[76:77]
	s_add_i32 m0, s87, 0xe000
	s_nop 0
	global_load_lds_dwordx4 v160, s[76:77]
	s_waitcnt vmcnt(8)
	s_waitcnt lgkmcnt(0)
	s_barrier
; #define PG8_STAGE(bufoff, gbase, voff) do { _Pragma("unroll") for (int _i = 0; _i < 2; ++_i) \
;         __builtin_amdgcn_global_load_lds((const unsigned*)((const char*)(gbase) + (voff)[_i]), (PG8_LAS unsigned*)(lds + (bufoff) + ldsw + _i * 8192), 16, 0, 0); } while (0)
; #define PG8_LDA(dst, b, h) do { _Pragma("unroll") for (int m = 0; m < 4; ++m) _Pragma("unroll") for (int k = 0; k < 2; ++k) dst[m][k] = *(const PG8_LAS bf16x8*)(lds + PG8_SA(b, h) + aoff + m * 2048 + k * 1024); } while (0)
; #define PG8_LDB(dst, b, h) do { _Pragma("unroll") for (int n = 0; n < 2; ++n) _Pragma("unroll") for (int k = 0; k < 2; ++k) dst[n][k] = *(const PG8_LAS bf16x8*)(lds + PG8_SB(b, h) + boff + n * 2048 + k * 1024); } while (0)
; #define PG8_MMA(ai, bj, At, Bt) do { __builtin_amdgcn_s_setprio(1); _Pragma("unroll") for (int m = 0; m < 4; ++m) _Pragma("unroll") for (int n = 0; n < 2; ++n) _Pragma("unroll") for (int k = 0; k < 2; ++k) \
;         acc[ai][bj][m][n] = __builtin_amdgcn_mfma_f32_16x16x32_bf16(Bt[n][k], At[m][k], acc[ai][bj][m][n], 0, 0, 0); __builtin_amdgcn_s_setprio(0); } while (0)
; #define PG8_WAIT_V(n) asm volatile("s_waitcnt vmcnt(" #n ")" ::: "memory")
; #define PG8_WAIT_L(n) asm volatile("s_waitcnt lgkmcnt(" #n ")" ::: "memory")
; #define PG8_BAR __builtin_amdgcn_s_barrier()
; #define PG8_SCHED __builtin_amdgcn_sched_barrier(0)
; template <class Epi, class Sched, bool ALIGN_EPI = false, bool SP2 = false>
; __device__ __forceinline__ void gemm_phase(PG8_LAS unsigned char* lds, const Gemm g, const Sched& S, const Epi& E) {
;     ...
;             PG8_LDB(B0, 0, 0); PG8_LDB(B1, 0, 1); PG8_SCHED; PG8_LDA(At, 0, 0); PG8_STAGE(PG8_SA(1, 1), a1 + hstep, voffA);
;             PG8_WAIT_V(8); PG8_WAIT_L(0); PG8_BAR; PG8_MMA(0, 0, At, B0); PG8_MMA(0, 1, At, B1); PG8_BAR; PG8_SCHED;
;             PG8_LDA(At, 0, 1); PG8_STAGE(PG8_SB(0, 0), b2, voffB); PG8_STAGE(PG8_SB(0, 1), b2 + hstep, voffB); PG8_STAGE(PG8_SA(0, 0), a2, voffA);
;             PG8_WAIT_V(8); PG8_WAIT_L(0); PG8_BAR; PG8_MMA(1, 0, At, B0); PG8_MMA(1, 1, At, B1); PG8_BAR; PG8_SCHED;
	s_setprio 1
	s_waitcnt lgkmcnt(0)
	v_mfma_f32_16x16x32_bf16 v[124:127], v[128:131], v[208:211], v[124:127]
	v_mfma_f32_16x16x32_bf16 v[120:123], v[136:139], v[208:211], v[120:123]
	v_mfma_f32_16x16x32_bf16 v[112:115], v[128:131], v[216:219], v[112:115]
	v_mfma_f32_16x16x32_bf16 v[108:111], v[136:139], v[216:219], v[108:111]
	v_mfma_f32_16x16x32_bf16 v[96:99], v[128:131], v[224:227], v[96:99]
	v_mfma_f32_16x16x32_bf16 v[88:91], v[136:139], v[224:227], v[88:91]
	v_mfma_f32_16x16x32_bf16 v[80:83], v[128:131], v[236:239], v[80:83]
	v_mfma_f32_16x16x32_bf16 v[72:75], v[136:139], v[236:239], v[72:75]
	v_mfma_f32_16x16x32_bf16 v[124:127], v[132:135], v[212:215], v[124:127]
	v_mfma_f32_16x16x32_bf16 v[120:123], v[140:143], v[212:215], v[120:123]
	v_mfma_f32_16x16x32_bf16 v[112:115], v[132:135], v[220:223], v[112:115]
	v_mfma_f32_16x16x32_bf16 v[108:111], v[140:143], v[220:223], v[108:111]
	v_mfma_f32_16x16x32_bf16 v[96:99], v[132:135], v[232:235], v[96:99]
	v_mfma_f32_16x16x32_bf16 v[88:91], v[140:143], v[232:235], v[88:91]
	v_mfma_f32_16x16x32_bf16 v[80:83], v[132:135], v[240:243], v[80:83]
	v_mfma_f32_16x16x32_bf16 v[72:75], v[140:143], v[240:243], v[72:75]
	s_setprio 0
	s_setprio 1
	v_mfma_f32_16x16x32_bf16 v[116:119], v[192:195], v[208:211], v[116:119]
	v_mfma_f32_16x16x32_bf16 v[104:107], v[200:203], v[208:211], v[104:107]
	v_mfma_f32_16x16x32_bf16 v[100:103], v[192:195], v[216:219], v[100:103]
	v_mfma_f32_16x16x32_bf16 v[92:95], v[200:203], v[216:219], v[92:95]
	v_mfma_f32_16x16x32_bf16 v[84:87], v[192:195], v[224:227], v[84:87]
	v_mfma_f32_16x16x32_bf16 v[76:79], v[200:203], v[224:227], v[76:79]
	v_mfma_f32_16x16x32_bf16 v[68:71], v[192:195], v[236:239], v[68:71]
	v_mfma_f32_16x16x32_bf16 v[64:67], v[200:203], v[236:239], v[64:67]
	v_mfma_f32_16x16x32_bf16 v[116:119], v[196:199], v[212:215], v[116:119]
	v_mfma_f32_16x16x32_bf16 v[104:107], v[204:207], v[212:215], v[104:107]
	v_mfma_f32_16x16x32_bf16 v[100:103], v[196:199], v[220:223], v[100:103]
	v_mfma_f32_16x16x32_bf16 v[92:95], v[204:207], v[220:223], v[92:95]
	v_mfma_f32_16x16x32_bf16 v[84:87], v[196:199], v[232:235], v[84:87]
	v_mfma_f32_16x16x32_bf16 v[76:79], v[204:207], v[232:235], v[76:79]
	v_mfma_f32_16x16x32_bf16 v[68:71], v[196:199], v[240:243], v[68:71]
	v_mfma_f32_16x16x32_bf16 v[64:67], v[204:207], v[240:243], v[64:67]
	s_setprio 0
	s_barrier
	s_add_i32 s30, s33, s86
	v_lshl_add_u64 v[172:173], s[78:79], 0, v[146:147]
	s_mov_b32 m0, s30
	ds_read_b128 v[208:211], v186 offset:16384
	ds_read_b128 v[212:215], v186 offset:17408
	ds_read_b128 v[216:219], v186 offset:18432
	ds_read_b128 v[220:223], v186 offset:19456
	ds_read_b128 v[224:227], v186 offset:20480
	ds_read_b128 v[232:235], v186 offset:21504
	ds_read_b128 v[236:239], v186 offset:22528
	ds_read_b128 v[240:243], v186 offset:23552
	global_load_lds_dwordx4 v[172:173], off
	s_add_i32 m0, s30, 0x2000
	s_add_u32 s30, s78, 0x40000
	v_lshl_add_u64 v[228:229], s[78:79], 0, v[150:151]
	s_addc_u32 s31, s79, 0
	s_add_i32 s53, s16, s86
	global_load_lds_dwordx4 v[228:229], off
	s_mov_b32 m0, s53
	v_lshl_add_u64 v[246:247], s[80:81], 0, v[148:149]
	global_load_lds_dwordx4 v146, s[30:31]
	s_add_i32 m0, s53, 0x2000
	s_nop 0
	global_load_lds_dwordx4 v150, s[30:31]
	v_lshl_add_u64 v[244:245], s[80:81], 0, v[144:145]
	s_mov_b32 m0, s87
	s_nop 0
	global_load_lds_dwordx4 v[244:245], off
	s_mov_b32 m0, s88
	s_nop 0
	global_load_lds_dwordx4 v[246:247], off
	s_waitcnt vmcnt(8)
	s_waitcnt lgkmcnt(0)
	s_barrier
	s_setprio 1
	s_waitcnt lgkmcnt(0)
	v_mfma_f32_16x16x32_bf16 v[60:63], v[128:131], v[208:211], v[60:63]
	v_mfma_f32_16x16x32_bf16 v[56:59], v[136:139], v[208:211], v[56:59]
	v_mfma_f32_16x16x32_bf16 v[48:51], v[128:131], v[216:219], v[48:51]
	v_mfma_f32_16x16x32_bf16 v[44:47], v[136:139], v[216:219], v[44:47]
	v_mfma_f32_16x16x32_bf16 v[32:35], v[128:131], v[224:227], v[32:35]
	v_mfma_f32_16x16x32_bf16 v[28:31], v[136:139], v[224:227], v[28:31]
	v_mfma_f32_16x16x32_bf16 v[16:19], v[128:131], v[236:239], v[16:19]
	v_mfma_f32_16x16x32_bf16 v[12:15], v[136:139], v[236:239], v[12:15]
	v_mfma_f32_16x16x32_bf16 v[60:63], v[132:135], v[212:215], v[60:63]
	v_mfma_f32_16x16x32_bf16 v[56:59], v[140:143], v[212:215], v[56:59]
	v_mfma_f32_16x16x32_bf16 v[48:51], v[132:135], v[220:223], v[48:51]
	v_mfma_f32_16x16x32_bf16 v[44:47], v[140:143], v[220:223], v[44:47]
	v_mfma_f32_16x16x32_bf16 v[32:35], v[132:135], v[232:235], v[32:35]
	v_mfma_f32_16x16x32_bf16 v[28:31], v[140:143], v[232:235], v[28:31]
	v_mfma_f32_16x16x32_bf16 v[16:19], v[132:135], v[240:243], v[16:19]
	v_mfma_f32_16x16x32_bf16 v[12:15], v[140:143], v[240:243], v[12:15]
	s_setprio 0
	s_setprio 1
	v_mfma_f32_16x16x32_bf16 v[52:55], v[192:195], v[208:211], v[52:55]
	v_mfma_f32_16x16x32_bf16 v[40:43], v[200:203], v[208:211], v[40:43]
	v_mfma_f32_16x16x32_bf16 v[36:39], v[192:195], v[216:219], v[36:39]
	v_mfma_f32_16x16x32_bf16 v[24:27], v[200:203], v[216:219], v[24:27]
	v_mfma_f32_16x16x32_bf16 v[20:23], v[192:195], v[224:227], v[20:23]
	v_mfma_f32_16x16x32_bf16 v[8:11], v[200:203], v[224:227], v[8:11]
	v_mfma_f32_16x16x32_bf16 v[4:7], v[192:195], v[236:239], v[4:7]
	v_mfma_f32_16x16x32_bf16 v[0:3], v[200:203], v[236:239], v[0:3]
	v_mfma_f32_16x16x32_bf16 v[52:55], v[196:199], v[212:215], v[52:55]
	v_mfma_f32_16x16x32_bf16 v[40:43], v[204:207], v[212:215], v[40:43]
	v_mfma_f32_16x16x32_bf16 v[36:39], v[196:199], v[220:223], v[36:39]
	v_mfma_f32_16x16x32_bf16 v[24:27], v[204:207], v[220:223], v[24:27]
	v_mfma_f32_16x16x32_bf16 v[20:23], v[196:199], v[232:235], v[20:23]
	v_mfma_f32_16x16x32_bf16 v[8:11], v[204:207], v[232:235], v[8:11]
	v_mfma_f32_16x16x32_bf16 v[4:7], v[196:199], v[240:243], v[4:7]
	v_mfma_f32_16x16x32_bf16 v[0:3], v[204:207], v[240:243], v[0:3]
	s_setprio 0
	s_barrier
; #define PG8_STAGE(bufoff, gbase, voff) do { _Pragma("unroll") for (int _i = 0; _i < 2; ++_i) \
;         __builtin_amdgcn_global_load_lds((const unsigned*)((const char*)(gbase) + (voff)[_i]), (PG8_LAS unsigned*)(lds + (bufoff) + ldsw + _i * 8192), 16, 0, 0); } while (0)
; #define PG8_LDA(dst, b, h) do { _Pragma("unroll") for (int m = 0; m < 4; ++m) _Pragma("unroll") for (int k = 0; k < 2; ++k) dst[m][k] = *(const PG8_LAS bf16x8*)(lds + PG8_SA(b, h) + aoff + m * 2048 + k * 1024); } while (0)
; #define PG8_LDB(dst, b, h) do { _Pragma("unroll") for (int n = 0; n < 2; ++n) _Pragma("unroll") for (int k = 0; k < 2; ++k) dst[n][k] = *(const PG8_LAS bf16x8*)(lds + PG8_SB(b, h) + boff + n * 2048 + k * 1024); } while (0)
; #define PG8_MMA(ai, bj, At, Bt) do { __builtin_amdgcn_s_setprio(1); _Pragma("unroll") for (int m = 0; m < 4; ++m) _Pragma("unroll") for (int n = 0; n < 2; ++n) _Pragma("unroll") for (int k = 0; k < 2; ++k) \
;         acc[ai][bj][m][n] = __builtin_amdgcn_mfma_f32_16x16x32_bf16(Bt[n][k], At[m][k], acc[ai][bj][m][n], 0, 0, 0); __builtin_amdgcn_s_setprio(0); } while (0)
; #define PG8_WAIT_V(n) asm volatile("s_waitcnt vmcnt(" #n ")" ::: "memory")
; #define PG8_WAIT_L(n) asm volatile("s_waitcnt lgkmcnt(" #n ")" ::: "memory")
; #define PG8_BAR __builtin_amdgcn_s_barrier()
; #define PG8_SCHED __builtin_amdgcn_sched_barrier(0)
; template <class Epi, class Sched, bool ALIGN_EPI = false, bool SP2 = false>
; __device__ __forceinline__ void gemm_phase(PG8_LAS unsigned char* lds, const Gemm g, const Sched& S, const Epi& E) {
;     ...
;             PG8_WAIT_V(8); PG8_WAIT_L(0); PG8_BAR; PG8_MMA(1, 0, At, B0); PG8_MMA(1, 1, At, B1); PG8_BAR; PG8_SCHED;
;             PG8_LDB(B0, 1, 0); PG8_LDB(B1, 1, 1); PG8_SCHED; PG8_LDA(At, 1, 0); PG8_STAGE(PG8_SA(0, 1), a2 + hstep, voffA);
;             PG8_WAIT_V(8); PG8_WAIT_L(0); PG8_BAR; PG8_MMA(0, 0, At, B0); PG8_MMA(0, 1, At, B1); PG8_BAR; PG8_SCHED;
	s_add_i32 s53, 0, 0x18000
	s_add_i32 s55, 0, 0x1c000
	v_add_u32_e32 v140, s53, v177
	v_add_u32_e32 v163, s55, v177
	ds_read_b128 v[128:131], v140
	ds_read_b128 v[132:135], v140 offset:1024
	ds_read_b128 v[136:139], v140 offset:2048
	ds_read_b128 v[140:143], v140 offset:3072
	ds_read_b128 v[192:195], v163
	ds_read_b128 v[196:199], v163 offset:1024
	ds_read_b128 v[200:203], v163 offset:2048
	ds_read_b128 v[204:207], v163 offset:3072
	s_add_u32 s30, s80, 0x40000
	s_addc_u32 s31, s81, 0
	s_mov_b32 m0, s89
	ds_read_b128 v[208:211], v186 offset:32768
	ds_read_b128 v[212:215], v186 offset:33792
	ds_read_b128 v[216:219], v186 offset:34816
	ds_read_b128 v[220:223], v186 offset:35840
	ds_read_b128 v[224:227], v186 offset:36864
	ds_read_b128 v[232:235], v186 offset:37888
	ds_read_b128 v[236:239], v186 offset:38912
	ds_read_b128 v[240:243], v186 offset:39936
	global_load_lds_dwordx4 v144, s[30:31]
	v_lshl_add_u64 v[248:249], s[30:31], 0, v[148:149]
	s_mov_b32 m0, s90
	s_nop 0
	global_load_lds_dwordx4 v[248:249], off
	s_waitcnt vmcnt(8)
	s_waitcnt lgkmcnt(0)
	s_barrier
	s_setprio 1
	s_waitcnt lgkmcnt(0)
	v_mfma_f32_16x16x32_bf16 v[124:127], v[128:131], v[208:211], v[124:127]
	v_mfma_f32_16x16x32_bf16 v[120:123], v[136:139], v[208:211], v[120:123]
	v_mfma_f32_16x16x32_bf16 v[112:115], v[128:131], v[216:219], v[112:115]
	v_mfma_f32_16x16x32_bf16 v[108:111], v[136:139], v[216:219], v[108:111]
	v_mfma_f32_16x16x32_bf16 v[96:99], v[128:131], v[224:227], v[96:99]
	v_mfma_f32_16x16x32_bf16 v[88:91], v[136:139], v[224:227], v[88:91]
	v_mfma_f32_16x16x32_bf16 v[80:83], v[128:131], v[236:239], v[80:83]
	v_mfma_f32_16x16x32_bf16 v[72:75], v[136:139], v[236:239], v[72:75]
	v_mfma_f32_16x16x32_bf16 v[124:127], v[132:135], v[212:215], v[124:127]
	v_mfma_f32_16x16x32_bf16 v[120:123], v[140:143], v[212:215], v[120:123]
	v_mfma_f32_16x16x32_bf16 v[112:115], v[132:135], v[220:223], v[112:115]
	v_mfma_f32_16x16x32_bf16 v[108:111], v[140:143], v[220:223], v[108:111]
	v_mfma_f32_16x16x32_bf16 v[96:99], v[132:135], v[232:235], v[96:99]
	v_mfma_f32_16x16x32_bf16 v[88:91], v[140:143], v[232:235], v[88:91]
	v_mfma_f32_16x16x32_bf16 v[80:83], v[132:135], v[240:243], v[80:83]
	v_mfma_f32_16x16x32_bf16 v[72:75], v[140:143], v[240:243], v[72:75]
	s_setprio 0
	s_setprio 1
	v_mfma_f32_16x16x32_bf16 v[116:119], v[192:195], v[208:211], v[116:119]
	v_mfma_f32_16x16x32_bf16 v[104:107], v[200:203], v[208:211], v[104:107]
	v_mfma_f32_16x16x32_bf16 v[100:103], v[192:195], v[216:219], v[100:103]
	v_mfma_f32_16x16x32_bf16 v[92:95], v[200:203], v[216:219], v[92:95]
	v_mfma_f32_16x16x32_bf16 v[84:87], v[192:195], v[224:227], v[84:87]
	v_mfma_f32_16x16x32_bf16 v[76:79], v[200:203], v[224:227], v[76:79]
	v_mfma_f32_16x16x32_bf16 v[68:71], v[192:195], v[236:239], v[68:71]
	v_mfma_f32_16x16x32_bf16 v[64:67], v[200:203], v[236:239], v[64:67]
	v_mfma_f32_16x16x32_bf16 v[116:119], v[196:199], v[212:215], v[116:119]
	v_mfma_f32_16x16x32_bf16 v[104:107], v[204:207], v[212:215], v[104:107]
	v_mfma_f32_16x16x32_bf16 v[100:103], v[196:199], v[220:223], v[100:103]
	v_mfma_f32_16x16x32_bf16 v[92:95], v[204:207], v[220:223], v[92:95]
	v_mfma_f32_16x16x32_bf16 v[84:87], v[196:199], v[232:235], v[84:87]
	v_mfma_f32_16x16x32_bf16 v[76:79], v[204:207], v[232:235], v[76:79]
	v_mfma_f32_16x16x32_bf16 v[68:71], v[196:199], v[240:243], v[68:71]
	v_mfma_f32_16x16x32_bf16 v[64:67], v[204:207], v[240:243], v[64:67]
	s_setprio 0
	s_barrier
; #define PG8_STAGE(bufoff, gbase, voff) do { _Pragma("unroll") for (int _i = 0; _i < 2; ++_i) \
;         __builtin_amdgcn_global_load_lds((const unsigned*)((const char*)(gbase) + (voff)[_i]), (PG8_LAS unsigned*)(lds + (bufoff) + ldsw + _i * 8192), 16, 0, 0); } while (0)
; #define PG8_LDA(dst, b, h) do { _Pragma("unroll") for (int m = 0; m < 4; ++m) _Pragma("unroll") for (int k = 0; k < 2; ++k) dst[m][k] = *(const PG8_LAS bf16x8*)(lds + PG8_SA(b, h) + aoff + m * 2048 + k * 1024); } while (0)
; #define PG8_MMA(ai, bj, At, Bt) do { __builtin_amdgcn_s_setprio(1); _Pragma("unroll") for (int m = 0; m < 4; ++m) _Pragma("unroll") for (int n = 0; n < 2; ++n) _Pragma("unroll") for (int k = 0; k < 2; ++k) \
;         acc[ai][bj][m][n] = __builtin_amdgcn_mfma_f32_16x16x32_bf16(Bt[n][k], At[m][k], acc[ai][bj][m][n], 0, 0, 0); __builtin_amdgcn_s_setprio(0); } while (0)
; #define PG8_WAIT_V(n) asm volatile("s_waitcnt vmcnt(" #n ")" ::: "memory")
; #define PG8_WAIT_L(n) asm volatile("s_waitcnt lgkmcnt(" #n ")" ::: "memory")
; #define PG8_BAR __builtin_amdgcn_s_barrier()
; #define PG8_SCHED __builtin_amdgcn_sched_barrier(0)
; template <class Epi, class Sched, bool ALIGN_EPI = false, bool SP2 = false>
; __device__ __forceinline__ void gemm_phase(PG8_LAS unsigned char* lds, const Gemm g, const Sched& S, const Epi& E) {
;     ...
;             PG8_WAIT_V(8); PG8_WAIT_L(0); PG8_BAR; PG8_MMA(0, 0, At, B0); PG8_MMA(0, 1, At, B1); PG8_BAR; PG8_SCHED;
;             PG8_LDA(At, 1, 1); PG8_STAGE(PG8_SB(1, 0), b3, voffB); PG8_STAGE(PG8_SB(1, 1), b3 + hstep, voffB); PG8_STAGE(PG8_SA(1, 0), a3, voffA);
;             PG8_WAIT_V(8); PG8_WAIT_L(0); PG8_BAR; PG8_MMA(1, 0, At, B0); PG8_MMA(1, 1, At, B1); PG8_BAR; PG8_SCHED;
;     ...
;         if constexpr (ALIGN_EPI) { if (wr == 0) PG8_BAR; }
	s_add_i32 s30, s53, s86
	v_lshl_add_u64 v[172:173], v[172:173], 0, s[18:19]
	s_mov_b32 m0, s30
	ds_read_b128 v[208:211], v186 offset:49152
	ds_read_b128 v[212:215], v186 offset:50176
	ds_read_b128 v[216:219], v186 offset:51200
	ds_read_b128 v[220:223], v186 offset:52224
	ds_read_b128 v[224:227], v186 offset:53248
	ds_read_b128 v[232:235], v186 offset:54272
	ds_read_b128 v[236:239], v186 offset:55296
	ds_read_b128 v[240:243], v186 offset:56320
	global_load_lds_dwordx4 v[172:173], off
	s_add_i32 m0, s30, 0x2000
	s_add_u32 s30, s78, 0x40080
	v_lshl_add_u64 v[172:173], v[228:229], 0, s[18:19]
	s_addc_u32 s31, s79, 0
	s_add_i32 s53, s55, s86
	global_load_lds_dwordx4 v[172:173], off
	s_mov_b32 m0, s53
	s_nop 0
	global_load_lds_dwordx4 v146, s[30:31]
	s_add_i32 m0, s53, 0x2000
	s_nop 0
	global_load_lds_dwordx4 v150, s[30:31]
	v_lshl_add_u64 v[172:173], v[244:245], 0, s[18:19]
	s_mov_b32 m0, s93
	s_nop 0
	global_load_lds_dwordx4 v[172:173], off
	v_lshl_add_u64 v[172:173], v[246:247], 0, s[18:19]
	s_mov_b32 m0, s94
	s_nop 0
	global_load_lds_dwordx4 v[172:173], off
	s_waitcnt vmcnt(8)
	s_waitcnt lgkmcnt(0)
	s_barrier
	s_setprio 1
	s_waitcnt lgkmcnt(0)
	v_mfma_f32_16x16x32_bf16 v[60:63], v[128:131], v[208:211], v[60:63]
	v_mfma_f32_16x16x32_bf16 v[56:59], v[136:139], v[208:211], v[56:59]
	v_mfma_f32_16x16x32_bf16 v[48:51], v[128:131], v[216:219], v[48:51]
	v_mfma_f32_16x16x32_bf16 v[44:47], v[136:139], v[216:219], v[44:47]
	v_mfma_f32_16x16x32_bf16 v[32:35], v[128:131], v[224:227], v[32:35]
	v_mfma_f32_16x16x32_bf16 v[28:31], v[136:139], v[224:227], v[28:31]
	v_mfma_f32_16x16x32_bf16 v[16:19], v[128:131], v[236:239], v[16:19]
	v_mfma_f32_16x16x32_bf16 v[12:15], v[136:139], v[236:239], v[12:15]
	v_mfma_f32_16x16x32_bf16 v[60:63], v[132:135], v[212:215], v[60:63]
	v_mfma_f32_16x16x32_bf16 v[56:59], v[140:143], v[212:215], v[56:59]
	v_mfma_f32_16x16x32_bf16 v[48:51], v[132:135], v[220:223], v[48:51]
	v_mfma_f32_16x16x32_bf16 v[44:47], v[140:143], v[220:223], v[44:47]
	v_mfma_f32_16x16x32_bf16 v[32:35], v[132:135], v[232:235], v[32:35]
	v_mfma_f32_16x16x32_bf16 v[28:31], v[140:143], v[232:235], v[28:31]
	v_mfma_f32_16x16x32_bf16 v[16:19], v[132:135], v[240:243], v[16:19]
	v_mfma_f32_16x16x32_bf16 v[12:15], v[140:143], v[240:243], v[12:15]
	s_setprio 0
	s_setprio 1
	v_mfma_f32_16x16x32_bf16 v[52:55], v[192:195], v[208:211], v[52:55]
	v_mfma_f32_16x16x32_bf16 v[40:43], v[200:203], v[208:211], v[40:43]
	v_mfma_f32_16x16x32_bf16 v[36:39], v[192:195], v[216:219], v[36:39]
	v_mfma_f32_16x16x32_bf16 v[24:27], v[200:203], v[216:219], v[24:27]
	v_mfma_f32_16x16x32_bf16 v[20:23], v[192:195], v[224:227], v[20:23]
	v_mfma_f32_16x16x32_bf16 v[8:11], v[200:203], v[224:227], v[8:11]
	v_mfma_f32_16x16x32_bf16 v[4:7], v[192:195], v[236:239], v[4:7]
	v_mfma_f32_16x16x32_bf16 v[0:3], v[200:203], v[236:239], v[0:3]
	v_mfma_f32_16x16x32_bf16 v[52:55], v[196:199], v[212:215], v[52:55]
	v_mfma_f32_16x16x32_bf16 v[40:43], v[204:207], v[212:215], v[40:43]
	v_mfma_f32_16x16x32_bf16 v[36:39], v[196:199], v[220:223], v[36:39]
	v_mfma_f32_16x16x32_bf16 v[24:27], v[204:207], v[220:223], v[24:27]
	v_mfma_f32_16x16x32_bf16 v[20:23], v[196:199], v[232:235], v[20:23]
	v_mfma_f32_16x16x32_bf16 v[8:11], v[204:207], v[232:235], v[8:11]
	v_mfma_f32_16x16x32_bf16 v[4:7], v[196:199], v[240:243], v[4:7]
	v_mfma_f32_16x16x32_bf16 v[0:3], v[204:207], v[240:243], v[0:3]
	s_setprio 0
	s_barrier
	s_add_i32 s29, s29, 2
	s_add_u32 s76, s76, 0x100
	s_addc_u32 s77, s77, 0
	s_add_u32 s27, s27, 0x100
	s_addc_u32 s28, s28, 0
	s_cmp_gt_u32 s29, 13
	s_cbranch_scc0 .LBB0_91
	s_and_b64 vcc, exec, s[20:21]
	s_cbranch_vccz .LBB0_94
	s_barrier

; #define PG8_STAGE(bufoff, gbase, voff) do { _Pragma("unroll") for (int _i = 0; _i < 2; ++_i) \
;         __builtin_amdgcn_global_load_lds((const unsigned*)((const char*)(gbase) + (voff)[_i]), (PG8_LAS unsigned*)(lds + (bufoff) + ldsw + _i * 8192), 16, 0, 0); } while (0)
; #define PG8_WAIT_V(n) asm volatile("s_waitcnt vmcnt(" #n ")" ::: "memory")
; #define PG8_BAR __builtin_amdgcn_s_barrier()
; template <class Epi, class Sched, bool ALIGN_EPI = false, bool SP2 = false>
; __device__ __forceinline__ void gemm_phase(PG8_LAS unsigned char* lds, const Gemm g, const Sched& S, const Epi& E) {
;     const int tid = threadIdx.x, wid = __builtin_amdgcn_readfirstlane(tid >> 6), lane = tid & 63, wr = wid >> 2, wc = wid & 3, fr = lane & 15, fq = lane >> 4;
;     const int K = g.K, nt = K / BK;
;     unsigned voffA[2], voffB[2];
; #pragma unroll
;     for (int i = 0; i < 2; ++i) { int R, C; stage_rc(tid * 16 + i * 8192, R, C); const int Rb = Epi::PERM ? ((R & ~31) + perm32(R & 31)) : R;
;         voffA[i] = (unsigned)(R * K + C) * 2u; voffB[i] = (unsigned)(Rb * K + C) * 2u; }
;     const size_t kstep = (size_t)(BK * 2);
;     const size_t hstep = (size_t)HALF * K * 2;
;     const size_t tstep = 2 * hstep;
;     const unsigned ldsw = (unsigned)wid * 1024u;
;     const int aoff = lds_byte(wr * 64 + fr, fq * 8), boff = lds_byte(wc * 32 + fr, fq * 8);
;     ...
;         PG8_STAGE(PG8_SB(1, 0), cB + kstep, voffB); PG8_STAGE(PG8_SA(1, 0), cA + kstep, voffA); PG8_STAGE(PG8_SB(1, 1), cB + hstep + kstep, voffB);
;         PG8_WAIT_V(6); PG8_BAR;
.LBB0_382:
	s_mov_b64 s[18:19], 0x80
	s_and_b32 s30, s1, 3
	s_add_i32 m0, s26, 0x18000
	v_lshl_add_u64 v[6:7], v[6:7], 0, s[18:19]
	s_lshl_b32 s1, s0, 13
	s_lshl_b32 s21, s30, 12
	s_waitcnt vmcnt(2)
	s_barrier
	global_load_lds_dwordx4 v[6:7], off
	v_lshl_add_u64 v[4:5], v[4:5], 0, s[18:19]
	s_add_i32 m0, s26, 0x1a000
	s_add_i32 s31, s26, 0x8000
	s_add_i32 s33, s26, 0xa000
	global_load_lds_dwordx4 v[4:5], off
	v_lshl_add_u64 v[0:1], v[0:1], 0, s[18:19]
	s_mov_b32 m0, s31
	s_add_u32 s36, s50, 0x40080
	global_load_lds_dwordx4 v[0:1], off
	v_lshl_add_u64 v[0:1], v[2:3], 0, s[18:19]
	s_mov_b32 m0, s33
	s_addc_u32 s37, s51, 0
	global_load_lds_dwordx4 v[0:1], off
	s_add_i32 m0, s26, 0x1c000
	global_load_lds_dwordx4 v186, s[36:37]
	v_lshl_add_u64 v[0:1], s[36:37], 0, v[190:191]
	s_add_i32 m0, s26, 0x1e000
	v_lshlrev_b32_e32 v4, 2, v230
	global_load_lds_dwordx4 v[0:1], off
	v_bfe_u32 v0, v230, 4, 2
	v_and_b32_e32 v1, 15, v230
	v_lshlrev_b32_e32 v3, 4, v0
	v_lshl_or_b32 v231, s0, 6, v1
	v_lshl_or_b32 v1, v1, 6, v3
	v_and_b32_e32 v4, 32, v4
	v_lshlrev_b32_e32 v5, 6, v230
	s_movk_i32 s0, 0x3c0
	v_lshlrev_b32_e32 v2, 3, v0
	v_bitop3_b32 v1, v1, s1, v4 bitop3:0xde
	v_and_or_b32 v3, v5, s0, v3
	v_cmp_eq_u32_e64 s[0:1], 0, v0
	v_lshlrev_b32_e32 v0, 8, v230
	v_lshl_or_b32 v233, s30, 5, v2
	v_and_b32_e32 v0, 0x38000, v0
	v_lshlrev_b32_e32 v2, 11, v10
	v_or3_b32 v0, v8, v0, v2
	v_add_u32_e32 v192, v0, v9
	v_lshlrev_b32_e32 v0, 4, v11
	v_and_b32_e32 v0, 0x78000, v0
	s_waitcnt vmcnt(6)
	s_cmpk_lt_u32 s20, 0x100
	v_or3_b32 v0, v8, v0, v2
	v_bitop3_b32 v232, s21, v3, v4 bitop3:0xf6
	s_cselect_b64 s[20:21], -1, 0
	v_add_u32_e32 v194, v0, v9
	s_add_i32 s56, 0, 0x10000
	s_add_i32 s57, 0, 0x14000
	v_mbcnt_lo_u32_b32 v0, -1, 0
	s_add_i32 s54, s22, -2
	s_ashr_i32 s55, s2, 31
	v_mov_b32_e32 v193, v187
	v_mov_b32_e32 v195, v187
	v_add_u32_e32 v234, s56, v232
	v_add_u32_e32 v235, s57, v232
	v_add_u32_e32 v236, 0, v1
	v_mbcnt_hi_u32_b32 v237, -1, v0
	v_mov_b64_e32 v[196:197], 0x7ff
	s_mov_b32 s37, 0
	s_barrier
	s_branch .LBB0_385

; #define PG8_STAGE(bufoff, gbase, voff) do { _Pragma("unroll") for (int _i = 0; _i < 2; ++_i) \
;         __builtin_amdgcn_global_load_lds((const unsigned*)((const char*)(gbase) + (voff)[_i]), (PG8_LAS unsigned*)(lds + (bufoff) + ldsw + _i * 8192), 16, 0, 0); } while (0)
; #define PG8_LDA(dst, b, h) do { _Pragma("unroll") for (int m = 0; m < 4; ++m) _Pragma("unroll") for (int k = 0; k < 2; ++k) dst[m][k] = *(const PG8_LAS bf16x8*)(lds + PG8_SA(b, h) + aoff + m * 2048 + k * 1024); } while (0)
; #define PG8_LDB(dst, b, h) do { _Pragma("unroll") for (int n = 0; n < 2; ++n) _Pragma("unroll") for (int k = 0; k < 2; ++k) dst[n][k] = *(const PG8_LAS bf16x8*)(lds + PG8_SB(b, h) + boff + n * 2048 + k * 1024); } while (0)
; #define PG8_MMA(ai, bj, At, Bt) do { __builtin_amdgcn_s_setprio(1); _Pragma("unroll") for (int m = 0; m < 4; ++m) _Pragma("unroll") for (int n = 0; n < 2; ++n) _Pragma("unroll") for (int k = 0; k < 2; ++k) \
;         acc[ai][bj][m][n] = __builtin_amdgcn_mfma_f32_16x16x32_bf16(Bt[n][k], At[m][k], acc[ai][bj][m][n], 0, 0, 0); __builtin_amdgcn_s_setprio(0); } while (0)
; #define PG8_BAR __builtin_amdgcn_s_barrier()
; template <class Epi, class Sched, bool ALIGN_EPI = false, bool SP2 = false>
; __device__ __forceinline__ void gemm_phase(PG8_LAS unsigned char* lds, const Gemm g, const Sched& S, const Epi& E) {
;     ...
;         const bool has_next = S.next(ui + 1, nxt);
;         const char* nA = has_next ? (const char*)g.A + (size_t)nxt.pm * tstep : cA; const char* nB = has_next ? (const char*)g.Bt + (size_t)nxt.pn * tstep : cB;
;         for (int t = 0; t < nt; t += 2) {
;             const bool last = (t == nt - 2);
;             const char* a1 = cA + (size_t)(t + 1) * kstep;
;             const char* a2 = last ? nA : cA + (size_t)(t + 2) * kstep; const char* b2 = last ? nB : cB + (size_t)(t + 2) * kstep;
;             const char* a3 = a2 + kstep; const char* b3 = b2 + kstep;
;             if (last && has_next) S.a_ready(nxt);
;             if constexpr (SP2) {
;             PG8_LDB(B0, 0, 0); PG8_LDB(B1, 0, 1); PG8_SCHED; PG8_LDA(At, 0, 0); PG8_STAGE(PG8_SA(1, 1), a1 + hstep, voffA);
;             PG8_WAIT_V(8); PG8_WAIT_L(0); PG8_BAR; PG8_MMA(0, 0, At, B0); PG8_MMA(0, 1, At, B1); PG8_BAR; PG8_SCHED;
;             PG8_LDA(At, 0, 1); PG8_STAGE(PG8_SB(0, 0), b2, voffB); PG8_STAGE(PG8_SB(0, 1), b2 + hstep, voffB); PG8_STAGE(PG8_SA(0, 0), a2, voffA);
.LBB0_392:
	s_ashr_i32 s39, s38, 31
	s_lshl_b64 s[42:43], s[38:39], 19
	s_add_u32 s42, s68, s42
	s_addc_u32 s43, s69, s43
	s_and_b64 s[44:45], s[40:41], exec
	s_cselect_b32 s39, s43, s49
	s_cselect_b32 s47, s42, s48
	s_ashr_i32 s37, s36, 31
	s_lshl_b64 s[44:45], s[36:37], 19
	s_add_u32 s44, s23, s44
	s_addc_u32 s45, s24, s45
	s_and_b64 s[52:53], s[40:41], exec
	s_cselect_b32 s37, s45, s51
	s_cselect_b32 s59, s44, s50
	s_add_u32 s48, s48, 0x40080
	s_addc_u32 s49, s49, 0
	s_add_u32 s60, s50, 0x100
	s_addc_u32 s61, s51, 0
	s_mov_b32 s62, -2
	s_waitcnt lgkmcnt(0)
	ds_read_b128 v[124:127], v234
	ds_read_b128 v[132:135], v234 offset:1024
	ds_read_b128 v[136:139], v234 offset:2048
	ds_read_b128 v[140:143], v234 offset:3072
	ds_read_b128 v[144:147], v235
	ds_read_b128 v[148:151], v235 offset:1024
	ds_read_b128 v[152:155], v235 offset:2048
	ds_read_b128 v[156:159], v235 offset:3072
	s_add_u32 s50, s48, 0xfffc0080
	s_addc_u32 s51, s49, -1
	s_cmp_eq_u32 s62, 12
	s_cselect_b32 s53, s39, s51
	s_cselect_b32 s52, s47, s50
	s_cselect_b32 s51, s37, s61
	s_cselect_b32 s50, s59, s60
	s_add_i32 m0, s26, 0xc000
	ds_read_b128 v[160:163], v236
	ds_read_b128 v[164:167], v236 offset:1024
	ds_read_b128 v[168:171], v236 offset:2048
	ds_read_b128 v[172:175], v236 offset:3072
	ds_read_b128 v[176:179], v236 offset:4096
	ds_read_b128 v[180:183], v236 offset:5120
	ds_read_b128 v[198:201], v236 offset:6144
	ds_read_b128 v[202:205], v236 offset:7168
	global_load_lds_dwordx4 v192, s[48:49]
	s_add_i32 m0, s26, 0xe000
	s_nop 0
	global_load_lds_dwordx4 v194, s[48:49]
	s_waitcnt vmcnt(8)
	s_waitcnt lgkmcnt(0)
	s_barrier
	s_setprio 1
	s_waitcnt lgkmcnt(0)
	v_mfma_f32_16x16x32_bf16 v[128:131], v[124:127], v[160:163], 0
	v_mfma_f32_16x16x32_bf16 v[120:123], v[136:139], v[160:163], 0
	v_mfma_f32_16x16x32_bf16 v[108:111], v[124:127], v[168:171], 0
	v_mfma_f32_16x16x32_bf16 v[104:107], v[136:139], v[168:171], 0
	v_mfma_f32_16x16x32_bf16 v[92:95], v[124:127], v[176:179], 0
	v_mfma_f32_16x16x32_bf16 v[88:91], v[136:139], v[176:179], 0
	v_mfma_f32_16x16x32_bf16 v[76:79], v[124:127], v[198:201], 0
	v_mfma_f32_16x16x32_bf16 v[72:75], v[136:139], v[198:201], 0
	v_mfma_f32_16x16x32_bf16 v[128:131], v[132:135], v[164:167], v[128:131]
	v_mfma_f32_16x16x32_bf16 v[120:123], v[140:143], v[164:167], v[120:123]
	v_mfma_f32_16x16x32_bf16 v[108:111], v[132:135], v[172:175], v[108:111]
	v_mfma_f32_16x16x32_bf16 v[104:107], v[140:143], v[172:175], v[104:107]
	v_mfma_f32_16x16x32_bf16 v[92:95], v[132:135], v[180:183], v[92:95]
	v_mfma_f32_16x16x32_bf16 v[88:91], v[140:143], v[180:183], v[88:91]
	v_mfma_f32_16x16x32_bf16 v[76:79], v[132:135], v[202:205], v[76:79]
	v_mfma_f32_16x16x32_bf16 v[72:75], v[140:143], v[202:205], v[72:75]
	s_setprio 0
	s_setprio 1
	v_mfma_f32_16x16x32_bf16 v[116:119], v[144:147], v[160:163], 0
	v_mfma_f32_16x16x32_bf16 v[112:115], v[152:155], v[160:163], 0
	v_mfma_f32_16x16x32_bf16 v[100:103], v[144:147], v[168:171], 0
	v_mfma_f32_16x16x32_bf16 v[96:99], v[152:155], v[168:171], 0
	v_mfma_f32_16x16x32_bf16 v[84:87], v[144:147], v[176:179], 0
	v_mfma_f32_16x16x32_bf16 v[80:83], v[152:155], v[176:179], 0
	v_mfma_f32_16x16x32_bf16 v[68:71], v[144:147], v[198:201], 0
	v_mfma_f32_16x16x32_bf16 v[64:67], v[152:155], v[198:201], 0
	v_mfma_f32_16x16x32_bf16 v[116:119], v[148:151], v[164:167], v[116:119]
	v_mfma_f32_16x16x32_bf16 v[112:115], v[156:159], v[164:167], v[112:115]
	v_mfma_f32_16x16x32_bf16 v[100:103], v[148:151], v[172:175], v[100:103]
	v_mfma_f32_16x16x32_bf16 v[96:99], v[156:159], v[172:175], v[96:99]
	v_mfma_f32_16x16x32_bf16 v[84:87], v[148:151], v[180:183], v[84:87]
	v_mfma_f32_16x16x32_bf16 v[80:83], v[156:159], v[180:183], v[80:83]
	v_mfma_f32_16x16x32_bf16 v[68:71], v[148:151], v[202:205], v[68:71]
	v_mfma_f32_16x16x32_bf16 v[64:67], v[156:159], v[202:205], v[64:67]
	s_setprio 0
	s_barrier
	s_add_i32 s63, s56, s25
	v_lshl_add_u64 v[206:207], s[50:51], 0, v[186:187]
	s_mov_b32 m0, s63
	ds_read_b128 v[160:163], v236 offset:16384
	ds_read_b128 v[164:167], v236 offset:17408
	ds_read_b128 v[168:171], v236 offset:18432
	ds_read_b128 v[172:175], v236 offset:19456
	ds_read_b128 v[176:179], v236 offset:20480
	ds_read_b128 v[180:183], v236 offset:21504
	ds_read_b128 v[198:201], v236 offset:22528
	ds_read_b128 v[202:205], v236 offset:23552
	global_load_lds_dwordx4 v[206:207], off
	s_add_i32 m0, s63, 0x2000
	s_add_u32 s64, s50, 0x40000
	v_lshl_add_u64 v[208:209], s[50:51], 0, v[190:191]
	s_addc_u32 s65, s51, 0
	s_add_i32 s63, s57, s25
	global_load_lds_dwordx4 v[208:209], off
	s_mov_b32 m0, s63
	v_lshl_add_u64 v[212:213], s[52:53], 0, v[188:189]
	global_load_lds_dwordx4 v186, s[64:65]
	s_add_i32 m0, s63, 0x2000
	s_nop 0
	global_load_lds_dwordx4 v190, s[64:65]
	v_lshl_add_u64 v[210:211], s[52:53], 0, v[184:185]
	s_mov_b32 m0, s26
	s_nop 0
	global_load_lds_dwordx4 v[210:211], off
	s_mov_b32 m0, s27
	s_nop 0
	global_load_lds_dwordx4 v[212:213], off
	s_waitcnt vmcnt(8)
	s_waitcnt lgkmcnt(0)
	s_barrier
; #define PG8_STAGE(bufoff, gbase, voff) do { _Pragma("unroll") for (int _i = 0; _i < 2; ++_i) \
;         __builtin_amdgcn_global_load_lds((const unsigned*)((const char*)(gbase) + (voff)[_i]), (PG8_LAS unsigned*)(lds + (bufoff) + ldsw + _i * 8192), 16, 0, 0); } while (0)
; #define PG8_LDA(dst, b, h) do { _Pragma("unroll") for (int m = 0; m < 4; ++m) _Pragma("unroll") for (int k = 0; k < 2; ++k) dst[m][k] = *(const PG8_LAS bf16x8*)(lds + PG8_SA(b, h) + aoff + m * 2048 + k * 1024); } while (0)
; #define PG8_LDB(dst, b, h) do { _Pragma("unroll") for (int n = 0; n < 2; ++n) _Pragma("unroll") for (int k = 0; k < 2; ++k) dst[n][k] = *(const PG8_LAS bf16x8*)(lds + PG8_SB(b, h) + boff + n * 2048 + k * 1024); } while (0)
; #define PG8_MMA(ai, bj, At, Bt) do { __builtin_amdgcn_s_setprio(1); _Pragma("unroll") for (int m = 0; m < 4; ++m) _Pragma("unroll") for (int n = 0; n < 2; ++n) _Pragma("unroll") for (int k = 0; k < 2; ++k) \
;         acc[ai][bj][m][n] = __builtin_amdgcn_mfma_f32_16x16x32_bf16(Bt[n][k], At[m][k], acc[ai][bj][m][n], 0, 0, 0); __builtin_amdgcn_s_setprio(0); } while (0)
; #define PG8_WAIT_V(n) asm volatile("s_waitcnt vmcnt(" #n ")" ::: "memory")
; #define PG8_WAIT_L(n) asm volatile("s_waitcnt lgkmcnt(" #n ")" ::: "memory")
; #define PG8_BAR __builtin_amdgcn_s_barrier()
; #define PG8_SCHED __builtin_amdgcn_sched_barrier(0)
; template <class Epi, class Sched, bool ALIGN_EPI = false, bool SP2 = false>
; __device__ __forceinline__ void gemm_phase(PG8_LAS unsigned char* lds, const Gemm g, const Sched& S, const Epi& E) {
;     ...
;             PG8_WAIT_V(8); PG8_WAIT_L(0); PG8_BAR; PG8_MMA(0, 0, At, B0); PG8_MMA(0, 1, At, B1); PG8_BAR; PG8_SCHED;
;             PG8_LDA(At, 0, 1); PG8_STAGE(PG8_SB(0, 0), b2, voffB); PG8_STAGE(PG8_SB(0, 1), b2 + hstep, voffB); PG8_STAGE(PG8_SA(0, 0), a2, voffA);
;             PG8_WAIT_V(8); PG8_WAIT_L(0); PG8_BAR; PG8_MMA(1, 0, At, B0); PG8_MMA(1, 1, At, B1); PG8_BAR; PG8_SCHED;
;             PG8_LDB(B0, 1, 0); PG8_LDB(B1, 1, 1); PG8_SCHED; PG8_LDA(At, 1, 0); PG8_STAGE(PG8_SA(0, 1), a2 + hstep, voffA);
;             PG8_WAIT_V(8); PG8_WAIT_L(0); PG8_BAR; PG8_MMA(0, 0, At, B0); PG8_MMA(0, 1, At, B1); PG8_BAR; PG8_SCHED;
	s_setprio 1
	s_waitcnt lgkmcnt(0)
	v_mfma_f32_16x16x32_bf16 v[60:63], v[124:127], v[160:163], 0
	v_mfma_f32_16x16x32_bf16 v[56:59], v[136:139], v[160:163], 0
	v_mfma_f32_16x16x32_bf16 v[44:47], v[124:127], v[168:171], 0
	v_mfma_f32_16x16x32_bf16 v[40:43], v[136:139], v[168:171], 0
	v_mfma_f32_16x16x32_bf16 v[28:31], v[124:127], v[176:179], 0
	v_mfma_f32_16x16x32_bf16 v[24:27], v[136:139], v[176:179], 0
	v_mfma_f32_16x16x32_bf16 v[12:15], v[124:127], v[198:201], 0
	v_mfma_f32_16x16x32_bf16 v[8:11], v[136:139], v[198:201], 0
	v_mfma_f32_16x16x32_bf16 v[60:63], v[132:135], v[164:167], v[60:63]
	v_mfma_f32_16x16x32_bf16 v[56:59], v[140:143], v[164:167], v[56:59]
	v_mfma_f32_16x16x32_bf16 v[44:47], v[132:135], v[172:175], v[44:47]
	v_mfma_f32_16x16x32_bf16 v[40:43], v[140:143], v[172:175], v[40:43]
	v_mfma_f32_16x16x32_bf16 v[28:31], v[132:135], v[180:183], v[28:31]
	v_mfma_f32_16x16x32_bf16 v[24:27], v[140:143], v[180:183], v[24:27]
	v_mfma_f32_16x16x32_bf16 v[12:15], v[132:135], v[202:205], v[12:15]
	v_mfma_f32_16x16x32_bf16 v[8:11], v[140:143], v[202:205], v[8:11]
	s_setprio 0
	s_setprio 1
	v_mfma_f32_16x16x32_bf16 v[52:55], v[144:147], v[160:163], 0
	v_mfma_f32_16x16x32_bf16 v[48:51], v[152:155], v[160:163], 0
	v_mfma_f32_16x16x32_bf16 v[36:39], v[144:147], v[168:171], 0
	v_mfma_f32_16x16x32_bf16 v[32:35], v[152:155], v[168:171], 0
	v_mfma_f32_16x16x32_bf16 v[20:23], v[144:147], v[176:179], 0
	v_mfma_f32_16x16x32_bf16 v[16:19], v[152:155], v[176:179], 0
	v_mfma_f32_16x16x32_bf16 v[4:7], v[144:147], v[198:201], 0
	v_mfma_f32_16x16x32_bf16 v[0:3], v[152:155], v[198:201], 0
	v_mfma_f32_16x16x32_bf16 v[52:55], v[148:151], v[164:167], v[52:55]
	v_mfma_f32_16x16x32_bf16 v[48:51], v[156:159], v[164:167], v[48:51]
	v_mfma_f32_16x16x32_bf16 v[36:39], v[148:151], v[172:175], v[36:39]
	v_mfma_f32_16x16x32_bf16 v[32:35], v[156:159], v[172:175], v[32:35]
	v_mfma_f32_16x16x32_bf16 v[20:23], v[148:151], v[180:183], v[20:23]
	v_mfma_f32_16x16x32_bf16 v[16:19], v[156:159], v[180:183], v[16:19]
	v_mfma_f32_16x16x32_bf16 v[4:7], v[148:151], v[202:205], v[4:7]
	v_mfma_f32_16x16x32_bf16 v[0:3], v[156:159], v[202:205], v[0:3]
	s_setprio 0
	s_barrier
	s_add_i32 s63, 0, 0x18000
	s_add_i32 s64, 0, 0x1c000
	v_add_u32_e32 v140, s63, v232
	v_add_u32_e32 v156, s64, v232
	ds_read_b128 v[124:127], v140
	ds_read_b128 v[132:135], v140 offset:1024
	ds_read_b128 v[136:139], v140 offset:2048
	ds_read_b128 v[140:143], v140 offset:3072
	ds_read_b128 v[144:147], v156
	ds_read_b128 v[148:151], v156 offset:1024
	ds_read_b128 v[152:155], v156 offset:2048
	ds_read_b128 v[156:159], v156 offset:3072
	s_add_u32 s52, s52, 0x40000
	s_addc_u32 s53, s53, 0
	s_mov_b32 m0, s28
	ds_read_b128 v[160:163], v236 offset:32768
	ds_read_b128 v[164:167], v236 offset:33792
	ds_read_b128 v[168:171], v236 offset:34816
	ds_read_b128 v[172:175], v236 offset:35840
	ds_read_b128 v[176:179], v236 offset:36864
	ds_read_b128 v[180:183], v236 offset:37888
	ds_read_b128 v[198:201], v236 offset:38912
	ds_read_b128 v[202:205], v236 offset:39936
	global_load_lds_dwordx4 v184, s[52:53]
	v_lshl_add_u64 v[214:215], s[52:53], 0, v[188:189]
	s_mov_b32 m0, s29
	s_nop 0
	global_load_lds_dwordx4 v[214:215], off
	s_waitcnt vmcnt(8)
	s_waitcnt lgkmcnt(0)
	s_barrier
	s_setprio 1
	s_waitcnt lgkmcnt(0)
	v_mfma_f32_16x16x32_bf16 v[128:131], v[124:127], v[160:163], v[128:131]
	v_mfma_f32_16x16x32_bf16 v[120:123], v[136:139], v[160:163], v[120:123]
	v_mfma_f32_16x16x32_bf16 v[108:111], v[124:127], v[168:171], v[108:111]
	v_mfma_f32_16x16x32_bf16 v[104:107], v[136:139], v[168:171], v[104:107]
	v_mfma_f32_16x16x32_bf16 v[92:95], v[124:127], v[176:179], v[92:95]
	v_mfma_f32_16x16x32_bf16 v[88:91], v[136:139], v[176:179], v[88:91]
	v_mfma_f32_16x16x32_bf16 v[76:79], v[124:127], v[198:201], v[76:79]
	v_mfma_f32_16x16x32_bf16 v[72:75], v[136:139], v[198:201], v[72:75]
	v_mfma_f32_16x16x32_bf16 v[128:131], v[132:135], v[164:167], v[128:131]
	v_mfma_f32_16x16x32_bf16 v[120:123], v[140:143], v[164:167], v[120:123]
	v_mfma_f32_16x16x32_bf16 v[108:111], v[132:135], v[172:175], v[108:111]
	v_mfma_f32_16x16x32_bf16 v[104:107], v[140:143], v[172:175], v[104:107]
	v_mfma_f32_16x16x32_bf16 v[92:95], v[132:135], v[180:183], v[92:95]
	v_mfma_f32_16x16x32_bf16 v[88:91], v[140:143], v[180:183], v[88:91]
	v_mfma_f32_16x16x32_bf16 v[76:79], v[132:135], v[202:205], v[76:79]
	v_mfma_f32_16x16x32_bf16 v[72:75], v[140:143], v[202:205], v[72:75]
	s_setprio 0
	s_setprio 1
	v_mfma_f32_16x16x32_bf16 v[116:119], v[144:147], v[160:163], v[116:119]
	v_mfma_f32_16x16x32_bf16 v[112:115], v[152:155], v[160:163], v[112:115]
	v_mfma_f32_16x16x32_bf16 v[100:103], v[144:147], v[168:171], v[100:103]
	v_mfma_f32_16x16x32_bf16 v[96:99], v[152:155], v[168:171], v[96:99]
	v_mfma_f32_16x16x32_bf16 v[84:87], v[144:147], v[176:179], v[84:87]
	v_mfma_f32_16x16x32_bf16 v[80:83], v[152:155], v[176:179], v[80:83]
	v_mfma_f32_16x16x32_bf16 v[68:71], v[144:147], v[198:201], v[68:71]
	v_mfma_f32_16x16x32_bf16 v[64:67], v[152:155], v[198:201], v[64:67]
	v_mfma_f32_16x16x32_bf16 v[116:119], v[148:151], v[164:167], v[116:119]
	v_mfma_f32_16x16x32_bf16 v[112:115], v[156:159], v[164:167], v[112:115]
	v_mfma_f32_16x16x32_bf16 v[100:103], v[148:151], v[172:175], v[100:103]
	v_mfma_f32_16x16x32_bf16 v[96:99], v[156:159], v[172:175], v[96:99]
	v_mfma_f32_16x16x32_bf16 v[84:87], v[148:151], v[180:183], v[84:87]
	v_mfma_f32_16x16x32_bf16 v[80:83], v[156:159], v[180:183], v[80:83]
	v_mfma_f32_16x16x32_bf16 v[68:71], v[148:151], v[202:205], v[68:71]
	v_mfma_f32_16x16x32_bf16 v[64:67], v[156:159], v[202:205], v[64:67]
	s_setprio 0
	s_barrier
; #define PG8_STAGE(bufoff, gbase, voff) do { _Pragma("unroll") for (int _i = 0; _i < 2; ++_i) \
;         __builtin_amdgcn_global_load_lds((const unsigned*)((const char*)(gbase) + (voff)[_i]), (PG8_LAS unsigned*)(lds + (bufoff) + ldsw + _i * 8192), 16, 0, 0); } while (0)
; #define PG8_LDA(dst, b, h) do { _Pragma("unroll") for (int m = 0; m < 4; ++m) _Pragma("unroll") for (int k = 0; k < 2; ++k) dst[m][k] = *(const PG8_LAS bf16x8*)(lds + PG8_SA(b, h) + aoff + m * 2048 + k * 1024); } while (0)
; #define PG8_MMA(ai, bj, At, Bt) do { __builtin_amdgcn_s_setprio(1); _Pragma("unroll") for (int m = 0; m < 4; ++m) _Pragma("unroll") for (int n = 0; n < 2; ++n) _Pragma("unroll") for (int k = 0; k < 2; ++k) \
;         acc[ai][bj][m][n] = __builtin_amdgcn_mfma_f32_16x16x32_bf16(Bt[n][k], At[m][k], acc[ai][bj][m][n], 0, 0, 0); __builtin_amdgcn_s_setprio(0); } while (0)
; #define PG8_WAIT_V(n) asm volatile("s_waitcnt vmcnt(" #n ")" ::: "memory")
; #define PG8_WAIT_L(n) asm volatile("s_waitcnt lgkmcnt(" #n ")" ::: "memory")
; #define PG8_BAR __builtin_amdgcn_s_barrier()
; #define PG8_SCHED __builtin_amdgcn_sched_barrier(0)
; template <class Epi, class Sched, bool ALIGN_EPI = false, bool SP2 = false>
; __device__ __forceinline__ void gemm_phase(PG8_LAS unsigned char* lds, const Gemm g, const Sched& S, const Epi& E) {
;     ...
;             PG8_WAIT_V(8); PG8_WAIT_L(0); PG8_BAR; PG8_MMA(0, 0, At, B0); PG8_MMA(0, 1, At, B1); PG8_BAR; PG8_SCHED;
;             PG8_LDA(At, 1, 1); PG8_STAGE(PG8_SB(1, 0), b3, voffB); PG8_STAGE(PG8_SB(1, 1), b3 + hstep, voffB); PG8_STAGE(PG8_SA(1, 0), a3, voffA);
;             PG8_WAIT_V(8); PG8_WAIT_L(0); PG8_BAR; PG8_MMA(1, 0, At, B0); PG8_MMA(1, 1, At, B1); PG8_BAR; PG8_SCHED;
	s_add_i32 s52, s63, s25
	v_lshl_add_u64 v[206:207], v[206:207], 0, s[18:19]
	s_mov_b32 m0, s52
	ds_read_b128 v[160:163], v236 offset:49152
	ds_read_b128 v[164:167], v236 offset:50176
	ds_read_b128 v[168:171], v236 offset:51200
	ds_read_b128 v[172:175], v236 offset:52224
	ds_read_b128 v[176:179], v236 offset:53248
	ds_read_b128 v[180:183], v236 offset:54272
	ds_read_b128 v[198:201], v236 offset:55296
	ds_read_b128 v[202:205], v236 offset:56320
	global_load_lds_dwordx4 v[206:207], off
	s_add_i32 m0, s52, 0x2000
	s_add_u32 s50, s50, 0x40080
	v_lshl_add_u64 v[206:207], v[208:209], 0, s[18:19]
	s_addc_u32 s51, s51, 0
	s_add_i32 s52, s64, s25
	global_load_lds_dwordx4 v[206:207], off
	s_mov_b32 m0, s52
	s_nop 0
	global_load_lds_dwordx4 v186, s[50:51]
	s_add_i32 m0, s52, 0x2000
	s_nop 0
	global_load_lds_dwordx4 v190, s[50:51]
	v_lshl_add_u64 v[206:207], v[210:211], 0, s[18:19]
	s_mov_b32 m0, s31
	s_nop 0
	global_load_lds_dwordx4 v[206:207], off
	v_lshl_add_u64 v[206:207], v[212:213], 0, s[18:19]
	s_mov_b32 m0, s33
	s_nop 0
	global_load_lds_dwordx4 v[206:207], off
	s_waitcnt vmcnt(8)
	s_waitcnt lgkmcnt(0)
	s_barrier
	s_setprio 1
	s_waitcnt lgkmcnt(0)
	v_mfma_f32_16x16x32_bf16 v[60:63], v[124:127], v[160:163], v[60:63]
	v_mfma_f32_16x16x32_bf16 v[56:59], v[136:139], v[160:163], v[56:59]
	v_mfma_f32_16x16x32_bf16 v[44:47], v[124:127], v[168:171], v[44:47]
	v_mfma_f32_16x16x32_bf16 v[40:43], v[136:139], v[168:171], v[40:43]
	v_mfma_f32_16x16x32_bf16 v[28:31], v[124:127], v[176:179], v[28:31]
	v_mfma_f32_16x16x32_bf16 v[24:27], v[136:139], v[176:179], v[24:27]
	v_mfma_f32_16x16x32_bf16 v[12:15], v[124:127], v[198:201], v[12:15]
	v_mfma_f32_16x16x32_bf16 v[8:11], v[136:139], v[198:201], v[8:11]
	v_mfma_f32_16x16x32_bf16 v[60:63], v[132:135], v[164:167], v[60:63]
	v_mfma_f32_16x16x32_bf16 v[56:59], v[140:143], v[164:167], v[56:59]
	v_mfma_f32_16x16x32_bf16 v[44:47], v[132:135], v[172:175], v[44:47]
	v_mfma_f32_16x16x32_bf16 v[40:43], v[140:143], v[172:175], v[40:43]
	v_mfma_f32_16x16x32_bf16 v[28:31], v[132:135], v[180:183], v[28:31]
	v_mfma_f32_16x16x32_bf16 v[24:27], v[140:143], v[180:183], v[24:27]
	v_mfma_f32_16x16x32_bf16 v[12:15], v[132:135], v[202:205], v[12:15]
	v_mfma_f32_16x16x32_bf16 v[8:11], v[140:143], v[202:205], v[8:11]
	s_setprio 0
	s_setprio 1
	v_mfma_f32_16x16x32_bf16 v[52:55], v[144:147], v[160:163], v[52:55]
	v_mfma_f32_16x16x32_bf16 v[48:51], v[152:155], v[160:163], v[48:51]
	v_mfma_f32_16x16x32_bf16 v[36:39], v[144:147], v[168:171], v[36:39]
	v_mfma_f32_16x16x32_bf16 v[32:35], v[152:155], v[168:171], v[32:35]
	v_mfma_f32_16x16x32_bf16 v[20:23], v[144:147], v[176:179], v[20:23]
	v_mfma_f32_16x16x32_bf16 v[16:19], v[152:155], v[176:179], v[16:19]
	v_mfma_f32_16x16x32_bf16 v[4:7], v[144:147], v[198:201], v[4:7]
	v_mfma_f32_16x16x32_bf16 v[0:3], v[152:155], v[198:201], v[0:3]
	v_mfma_f32_16x16x32_bf16 v[52:55], v[148:151], v[164:167], v[52:55]
	v_mfma_f32_16x16x32_bf16 v[48:51], v[156:159], v[164:167], v[48:51]
	v_mfma_f32_16x16x32_bf16 v[36:39], v[148:151], v[172:175], v[36:39]
	v_mfma_f32_16x16x32_bf16 v[32:35], v[156:159], v[172:175], v[32:35]
	v_mfma_f32_16x16x32_bf16 v[20:23], v[148:151], v[180:183], v[20:23]
	v_mfma_f32_16x16x32_bf16 v[16:19], v[156:159], v[180:183], v[16:19]
	v_mfma_f32_16x16x32_bf16 v[4:7], v[148:151], v[202:205], v[4:7]
	v_mfma_f32_16x16x32_bf16 v[0:3], v[156:159], v[202:205], v[0:3]
	s_setprio 0
	s_barrier
	s_add_i32 s62, s62, 2
	s_add_u32 s48, s48, 0x100
	s_addc_u32 s49, s49, 0
	s_add_u32 s60, s60, 0x100
	s_addc_u32 s61, s61, 0
	s_cmp_gt_u32 s62, 13
.LBB0_393:
	ds_read_b128 v[124:127], v234
	ds_read_b128 v[132:135], v234 offset:1024
	ds_read_b128 v[136:139], v234 offset:2048
	ds_read_b128 v[140:143], v234 offset:3072
	ds_read_b128 v[144:147], v235
	ds_read_b128 v[148:151], v235 offset:1024
	ds_read_b128 v[152:155], v235 offset:2048
	ds_read_b128 v[156:159], v235 offset:3072
	s_add_u32 s50, s48, 0xfffc0080
	s_addc_u32 s51, s49, -1
	s_cmp_eq_u32 s62, 12
	s_cselect_b32 s53, s39, s51
	s_cselect_b32 s52, s47, s50
	s_cselect_b32 s51, s37, s61
	s_cselect_b32 s50, s59, s60
	s_add_i32 m0, s26, 0xc000
	ds_read_b128 v[160:163], v236
	ds_read_b128 v[164:167], v236 offset:1024
	ds_read_b128 v[168:171], v236 offset:2048
	ds_read_b128 v[172:175], v236 offset:3072
	ds_read_b128 v[176:179], v236 offset:4096
	ds_read_b128 v[180:183], v236 offset:5120
	ds_read_b128 v[198:201], v236 offset:6144
	ds_read_b128 v[202:205], v236 offset:7168
	global_load_lds_dwordx4 v192, s[48:49]
	s_add_i32 m0, s26, 0xe000
	s_nop 0
	global_load_lds_dwordx4 v194, s[48:49]
	s_waitcnt vmcnt(8)
	s_waitcnt lgkmcnt(0)
	s_barrier
; #define PG8_STAGE(bufoff, gbase, voff) do { _Pragma("unroll") for (int _i = 0; _i < 2; ++_i) \
;         __builtin_amdgcn_global_load_lds((const unsigned*)((const char*)(gbase) + (voff)[_i]), (PG8_LAS unsigned*)(lds + (bufoff) + ldsw + _i * 8192), 16, 0, 0); } while (0)
; #define PG8_LDA(dst, b, h) do { _Pragma("unroll") for (int m = 0; m < 4; ++m) _Pragma("unroll") for (int k = 0; k < 2; ++k) dst[m][k] = *(const PG8_LAS bf16x8*)(lds + PG8_SA(b, h) + aoff + m * 2048 + k * 1024); } while (0)
; #define PG8_LDB(dst, b, h) do { _Pragma("unroll") for (int n = 0; n < 2; ++n) _Pragma("unroll") for (int k = 0; k < 2; ++k) dst[n][k] = *(const PG8_LAS bf16x8*)(lds + PG8_SB(b, h) + boff + n * 2048 + k * 1024); } while (0)
; #define PG8_MMA(ai, bj, At, Bt) do { __builtin_amdgcn_s_setprio(1); _Pragma("unroll") for (int m = 0; m < 4; ++m) _Pragma("unroll") for (int n = 0; n < 2; ++n) _Pragma("unroll") for (int k = 0; k < 2; ++k) \
;         acc[ai][bj][m][n] = __builtin_amdgcn_mfma_f32_16x16x32_bf16(Bt[n][k], At[m][k], acc[ai][bj][m][n], 0, 0, 0); __builtin_amdgcn_s_setprio(0); } while (0)
; #define PG8_WAIT_V(n) asm volatile("s_waitcnt vmcnt(" #n ")" ::: "memory")
; #define PG8_WAIT_L(n) asm volatile("s_waitcnt lgkmcnt(" #n ")" ::: "memory")
; #define PG8_BAR __builtin_amdgcn_s_barrier()
; #define PG8_SCHED __builtin_amdgcn_sched_barrier(0)
; template <class Epi, class Sched, bool ALIGN_EPI = false, bool SP2 = false>
; __device__ __forceinline__ void gemm_phase(PG8_LAS unsigned char* lds, const Gemm g, const Sched& S, const Epi& E) {
;     ...
;             PG8_LDB(B0, 0, 0); PG8_LDB(B1, 0, 1); PG8_SCHED; PG8_LDA(At, 0, 0); PG8_STAGE(PG8_SA(1, 1), a1 + hstep, voffA);
;             PG8_WAIT_V(8); PG8_WAIT_L(0); PG8_BAR; PG8_MMA(0, 0, At, B0); PG8_MMA(0, 1, At, B1); PG8_BAR; PG8_SCHED;
;             PG8_LDA(At, 0, 1); PG8_STAGE(PG8_SB(0, 0), b2, voffB); PG8_STAGE(PG8_SB(0, 1), b2 + hstep, voffB); PG8_STAGE(PG8_SA(0, 0), a2, voffA);
;             PG8_WAIT_V(8); PG8_WAIT_L(0); PG8_BAR; PG8_MMA(1, 0, At, B0); PG8_MMA(1, 1, At, B1); PG8_BAR; PG8_SCHED;
	s_setprio 1
	s_waitcnt lgkmcnt(0)
	v_mfma_f32_16x16x32_bf16 v[128:131], v[124:127], v[160:163], v[128:131]
	v_mfma_f32_16x16x32_bf16 v[120:123], v[136:139], v[160:163], v[120:123]
	v_mfma_f32_16x16x32_bf16 v[108:111], v[124:127], v[168:171], v[108:111]
	v_mfma_f32_16x16x32_bf16 v[104:107], v[136:139], v[168:171], v[104:107]
	v_mfma_f32_16x16x32_bf16 v[92:95], v[124:127], v[176:179], v[92:95]
	v_mfma_f32_16x16x32_bf16 v[88:91], v[136:139], v[176:179], v[88:91]
	v_mfma_f32_16x16x32_bf16 v[76:79], v[124:127], v[198:201], v[76:79]
	v_mfma_f32_16x16x32_bf16 v[72:75], v[136:139], v[198:201], v[72:75]
	v_mfma_f32_16x16x32_bf16 v[128:131], v[132:135], v[164:167], v[128:131]
	v_mfma_f32_16x16x32_bf16 v[120:123], v[140:143], v[164:167], v[120:123]
	v_mfma_f32_16x16x32_bf16 v[108:111], v[132:135], v[172:175], v[108:111]
	v_mfma_f32_16x16x32_bf16 v[104:107], v[140:143], v[172:175], v[104:107]
	v_mfma_f32_16x16x32_bf16 v[92:95], v[132:135], v[180:183], v[92:95]
	v_mfma_f32_16x16x32_bf16 v[88:91], v[140:143], v[180:183], v[88:91]
	v_mfma_f32_16x16x32_bf16 v[76:79], v[132:135], v[202:205], v[76:79]
	v_mfma_f32_16x16x32_bf16 v[72:75], v[140:143], v[202:205], v[72:75]
	s_setprio 0
	s_setprio 1
	v_mfma_f32_16x16x32_bf16 v[116:119], v[144:147], v[160:163], v[116:119]
	v_mfma_f32_16x16x32_bf16 v[112:115], v[152:155], v[160:163], v[112:115]
	v_mfma_f32_16x16x32_bf16 v[100:103], v[144:147], v[168:171], v[100:103]
	v_mfma_f32_16x16x32_bf16 v[96:99], v[152:155], v[168:171], v[96:99]
	v_mfma_f32_16x16x32_bf16 v[84:87], v[144:147], v[176:179], v[84:87]
	v_mfma_f32_16x16x32_bf16 v[80:83], v[152:155], v[176:179], v[80:83]
	v_mfma_f32_16x16x32_bf16 v[68:71], v[144:147], v[198:201], v[68:71]
	v_mfma_f32_16x16x32_bf16 v[64:67], v[152:155], v[198:201], v[64:67]
	v_mfma_f32_16x16x32_bf16 v[116:119], v[148:151], v[164:167], v[116:119]
	v_mfma_f32_16x16x32_bf16 v[112:115], v[156:159], v[164:167], v[112:115]
	v_mfma_f32_16x16x32_bf16 v[100:103], v[148:151], v[172:175], v[100:103]
	v_mfma_f32_16x16x32_bf16 v[96:99], v[156:159], v[172:175], v[96:99]
	v_mfma_f32_16x16x32_bf16 v[84:87], v[148:151], v[180:183], v[84:87]
	v_mfma_f32_16x16x32_bf16 v[80:83], v[156:159], v[180:183], v[80:83]
	v_mfma_f32_16x16x32_bf16 v[68:71], v[148:151], v[202:205], v[68:71]
	v_mfma_f32_16x16x32_bf16 v[64:67], v[156:159], v[202:205], v[64:67]
	s_setprio 0
	s_barrier
	s_add_i32 s63, s56, s25
	v_lshl_add_u64 v[206:207], s[50:51], 0, v[186:187]
	s_mov_b32 m0, s63
	ds_read_b128 v[160:163], v236 offset:16384
	ds_read_b128 v[164:167], v236 offset:17408
	ds_read_b128 v[168:171], v236 offset:18432
	ds_read_b128 v[172:175], v236 offset:19456
	ds_read_b128 v[176:179], v236 offset:20480
	ds_read_b128 v[180:183], v236 offset:21504
	ds_read_b128 v[198:201], v236 offset:22528
	ds_read_b128 v[202:205], v236 offset:23552
	global_load_lds_dwordx4 v[206:207], off
	s_add_i32 m0, s63, 0x2000
	s_add_u32 s64, s50, 0x40000
	v_lshl_add_u64 v[208:209], s[50:51], 0, v[190:191]
	s_addc_u32 s65, s51, 0
	s_add_i32 s63, s57, s25
	global_load_lds_dwordx4 v[208:209], off
	s_mov_b32 m0, s63
	v_lshl_add_u64 v[212:213], s[52:53], 0, v[188:189]
	global_load_lds_dwordx4 v186, s[64:65]
	s_add_i32 m0, s63, 0x2000
	s_nop 0
	global_load_lds_dwordx4 v190, s[64:65]
	v_lshl_add_u64 v[210:211], s[52:53], 0, v[184:185]
	s_mov_b32 m0, s26
	s_nop 0
	global_load_lds_dwordx4 v[210:211], off
	s_mov_b32 m0, s27
	s_nop 0
	global_load_lds_dwordx4 v[212:213], off
	s_waitcnt vmcnt(8)
	s_waitcnt lgkmcnt(0)
	s_barrier
	s_setprio 1
	s_waitcnt lgkmcnt(0)
	v_mfma_f32_16x16x32_bf16 v[60:63], v[124:127], v[160:163], v[60:63]
	v_mfma_f32_16x16x32_bf16 v[56:59], v[136:139], v[160:163], v[56:59]
	v_mfma_f32_16x16x32_bf16 v[44:47], v[124:127], v[168:171], v[44:47]
	v_mfma_f32_16x16x32_bf16 v[40:43], v[136:139], v[168:171], v[40:43]
	v_mfma_f32_16x16x32_bf16 v[28:31], v[124:127], v[176:179], v[28:31]
	v_mfma_f32_16x16x32_bf16 v[24:27], v[136:139], v[176:179], v[24:27]
	v_mfma_f32_16x16x32_bf16 v[12:15], v[124:127], v[198:201], v[12:15]
	v_mfma_f32_16x16x32_bf16 v[8:11], v[136:139], v[198:201], v[8:11]
	v_mfma_f32_16x16x32_bf16 v[60:63], v[132:135], v[164:167], v[60:63]
	v_mfma_f32_16x16x32_bf16 v[56:59], v[140:143], v[164:167], v[56:59]
	v_mfma_f32_16x16x32_bf16 v[44:47], v[132:135], v[172:175], v[44:47]
	v_mfma_f32_16x16x32_bf16 v[40:43], v[140:143], v[172:175], v[40:43]
	v_mfma_f32_16x16x32_bf16 v[28:31], v[132:135], v[180:183], v[28:31]
	v_mfma_f32_16x16x32_bf16 v[24:27], v[140:143], v[180:183], v[24:27]
	v_mfma_f32_16x16x32_bf16 v[12:15], v[132:135], v[202:205], v[12:15]
	v_mfma_f32_16x16x32_bf16 v[8:11], v[140:143], v[202:205], v[8:11]
	s_setprio 0
	s_setprio 1
	v_mfma_f32_16x16x32_bf16 v[52:55], v[144:147], v[160:163], v[52:55]
	v_mfma_f32_16x16x32_bf16 v[48:51], v[152:155], v[160:163], v[48:51]
	v_mfma_f32_16x16x32_bf16 v[36:39], v[144:147], v[168:171], v[36:39]
	v_mfma_f32_16x16x32_bf16 v[32:35], v[152:155], v[168:171], v[32:35]
	v_mfma_f32_16x16x32_bf16 v[20:23], v[144:147], v[176:179], v[20:23]
	v_mfma_f32_16x16x32_bf16 v[16:19], v[152:155], v[176:179], v[16:19]
	v_mfma_f32_16x16x32_bf16 v[4:7], v[144:147], v[198:201], v[4:7]
	v_mfma_f32_16x16x32_bf16 v[0:3], v[152:155], v[198:201], v[0:3]
	v_mfma_f32_16x16x32_bf16 v[52:55], v[148:151], v[164:167], v[52:55]
	v_mfma_f32_16x16x32_bf16 v[48:51], v[156:159], v[164:167], v[48:51]
	v_mfma_f32_16x16x32_bf16 v[36:39], v[148:151], v[172:175], v[36:39]
	v_mfma_f32_16x16x32_bf16 v[32:35], v[156:159], v[172:175], v[32:35]
	v_mfma_f32_16x16x32_bf16 v[20:23], v[148:151], v[180:183], v[20:23]
	v_mfma_f32_16x16x32_bf16 v[16:19], v[156:159], v[180:183], v[16:19]
	v_mfma_f32_16x16x32_bf16 v[4:7], v[148:151], v[202:205], v[4:7]
	v_mfma_f32_16x16x32_bf16 v[0:3], v[156:159], v[202:205], v[0:3]
	s_setprio 0
	s_barrier
; #define PG8_STAGE(bufoff, gbase, voff) do { _Pragma("unroll") for (int _i = 0; _i < 2; ++_i) \
;         __builtin_amdgcn_global_load_lds((const unsigned*)((const char*)(gbase) + (voff)[_i]), (PG8_LAS unsigned*)(lds + (bufoff) + ldsw + _i * 8192), 16, 0, 0); } while (0)
; #define PG8_LDA(dst, b, h) do { _Pragma("unroll") for (int m = 0; m < 4; ++m) _Pragma("unroll") for (int k = 0; k < 2; ++k) dst[m][k] = *(const PG8_LAS bf16x8*)(lds + PG8_SA(b, h) + aoff + m * 2048 + k * 1024); } while (0)
; #define PG8_LDB(dst, b, h) do { _Pragma("unroll") for (int n = 0; n < 2; ++n) _Pragma("unroll") for (int k = 0; k < 2; ++k) dst[n][k] = *(const PG8_LAS bf16x8*)(lds + PG8_SB(b, h) + boff + n * 2048 + k * 1024); } while (0)
; #define PG8_MMA(ai, bj, At, Bt) do { __builtin_amdgcn_s_setprio(1); _Pragma("unroll") for (int m = 0; m < 4; ++m) _Pragma("unroll") for (int n = 0; n < 2; ++n) _Pragma("unroll") for (int k = 0; k < 2; ++k) \
;         acc[ai][bj][m][n] = __builtin_amdgcn_mfma_f32_16x16x32_bf16(Bt[n][k], At[m][k], acc[ai][bj][m][n], 0, 0, 0); __builtin_amdgcn_s_setprio(0); } while (0)
; #define PG8_WAIT_V(n) asm volatile("s_waitcnt vmcnt(" #n ")" ::: "memory")
; #define PG8_WAIT_L(n) asm volatile("s_waitcnt lgkmcnt(" #n ")" ::: "memory")
; #define PG8_BAR __builtin_amdgcn_s_barrier()
; #define PG8_SCHED __builtin_amdgcn_sched_barrier(0)
; template <class Epi, class Sched, bool ALIGN_EPI = false, bool SP2 = false>
; __device__ __forceinline__ void gemm_phase(PG8_LAS unsigned char* lds, const Gemm g, const Sched& S, const Epi& E) {
;     ...
;             PG8_WAIT_V(8); PG8_WAIT_L(0); PG8_BAR; PG8_MMA(1, 0, At, B0); PG8_MMA(1, 1, At, B1); PG8_BAR; PG8_SCHED;
;             PG8_LDB(B0, 1, 0); PG8_LDB(B1, 1, 1); PG8_SCHED; PG8_LDA(At, 1, 0); PG8_STAGE(PG8_SA(0, 1), a2 + hstep, voffA);
;             PG8_WAIT_V(8); PG8_WAIT_L(0); PG8_BAR; PG8_MMA(0, 0, At, B0); PG8_MMA(0, 1, At, B1); PG8_BAR; PG8_SCHED;
	s_add_i32 s63, 0, 0x18000
	s_add_i32 s64, 0, 0x1c000
	v_add_u32_e32 v140, s63, v232
	v_add_u32_e32 v156, s64, v232
	ds_read_b128 v[124:127], v140
	ds_read_b128 v[132:135], v140 offset:1024
	ds_read_b128 v[136:139], v140 offset:2048
	ds_read_b128 v[140:143], v140 offset:3072
	ds_read_b128 v[144:147], v156
	ds_read_b128 v[148:151], v156 offset:1024
	ds_read_b128 v[152:155], v156 offset:2048
	ds_read_b128 v[156:159], v156 offset:3072
	s_add_u32 s52, s52, 0x40000
	s_addc_u32 s53, s53, 0
	s_mov_b32 m0, s28
	ds_read_b128 v[160:163], v236 offset:32768
	ds_read_b128 v[164:167], v236 offset:33792
	ds_read_b128 v[168:171], v236 offset:34816
	ds_read_b128 v[172:175], v236 offset:35840
	ds_read_b128 v[176:179], v236 offset:36864
	ds_read_b128 v[180:183], v236 offset:37888
	ds_read_b128 v[198:201], v236 offset:38912
	ds_read_b128 v[202:205], v236 offset:39936
	global_load_lds_dwordx4 v184, s[52:53]
	v_lshl_add_u64 v[214:215], s[52:53], 0, v[188:189]
	s_mov_b32 m0, s29
	s_nop 0
	global_load_lds_dwordx4 v[214:215], off
	s_waitcnt vmcnt(8)
	s_waitcnt lgkmcnt(0)
	s_barrier
	s_setprio 1
	s_waitcnt lgkmcnt(0)
	v_mfma_f32_16x16x32_bf16 v[128:131], v[124:127], v[160:163], v[128:131]
	v_mfma_f32_16x16x32_bf16 v[120:123], v[136:139], v[160:163], v[120:123]
	v_mfma_f32_16x16x32_bf16 v[108:111], v[124:127], v[168:171], v[108:111]
	v_mfma_f32_16x16x32_bf16 v[104:107], v[136:139], v[168:171], v[104:107]
	v_mfma_f32_16x16x32_bf16 v[92:95], v[124:127], v[176:179], v[92:95]
	v_mfma_f32_16x16x32_bf16 v[88:91], v[136:139], v[176:179], v[88:91]
	v_mfma_f32_16x16x32_bf16 v[76:79], v[124:127], v[198:201], v[76:79]
	v_mfma_f32_16x16x32_bf16 v[72:75], v[136:139], v[198:201], v[72:75]
	v_mfma_f32_16x16x32_bf16 v[128:131], v[132:135], v[164:167], v[128:131]
	v_mfma_f32_16x16x32_bf16 v[120:123], v[140:143], v[164:167], v[120:123]
	v_mfma_f32_16x16x32_bf16 v[108:111], v[132:135], v[172:175], v[108:111]
	v_mfma_f32_16x16x32_bf16 v[104:107], v[140:143], v[172:175], v[104:107]
	v_mfma_f32_16x16x32_bf16 v[92:95], v[132:135], v[180:183], v[92:95]
	v_mfma_f32_16x16x32_bf16 v[88:91], v[140:143], v[180:183], v[88:91]
	v_mfma_f32_16x16x32_bf16 v[76:79], v[132:135], v[202:205], v[76:79]
	v_mfma_f32_16x16x32_bf16 v[72:75], v[140:143], v[202:205], v[72:75]
	s_setprio 0
	s_setprio 1
	v_mfma_f32_16x16x32_bf16 v[116:119], v[144:147], v[160:163], v[116:119]
	v_mfma_f32_16x16x32_bf16 v[112:115], v[152:155], v[160:163], v[112:115]
	v_mfma_f32_16x16x32_bf16 v[100:103], v[144:147], v[168:171], v[100:103]
	v_mfma_f32_16x16x32_bf16 v[96:99], v[152:155], v[168:171], v[96:99]
	v_mfma_f32_16x16x32_bf16 v[84:87], v[144:147], v[176:179], v[84:87]
	v_mfma_f32_16x16x32_bf16 v[80:83], v[152:155], v[176:179], v[80:83]
	v_mfma_f32_16x16x32_bf16 v[68:71], v[144:147], v[198:201], v[68:71]
	v_mfma_f32_16x16x32_bf16 v[64:67], v[152:155], v[198:201], v[64:67]
	v_mfma_f32_16x16x32_bf16 v[116:119], v[148:151], v[164:167], v[116:119]
	v_mfma_f32_16x16x32_bf16 v[112:115], v[156:159], v[164:167], v[112:115]
	v_mfma_f32_16x16x32_bf16 v[100:103], v[148:151], v[172:175], v[100:103]
	v_mfma_f32_16x16x32_bf16 v[96:99], v[156:159], v[172:175], v[96:99]
	v_mfma_f32_16x16x32_bf16 v[84:87], v[148:151], v[180:183], v[84:87]
	v_mfma_f32_16x16x32_bf16 v[80:83], v[156:159], v[180:183], v[80:83]
	v_mfma_f32_16x16x32_bf16 v[68:71], v[148:151], v[202:205], v[68:71]
	v_mfma_f32_16x16x32_bf16 v[64:67], v[156:159], v[202:205], v[64:67]
	s_setprio 0
	s_barrier
; #define PG8_STAGE(bufoff, gbase, voff) do { _Pragma("unroll") for (int _i = 0; _i < 2; ++_i) \
;         __builtin_amdgcn_global_load_lds((const unsigned*)((const char*)(gbase) + (voff)[_i]), (PG8_LAS unsigned*)(lds + (bufoff) + ldsw + _i * 8192), 16, 0, 0); } while (0)
; #define PG8_LDA(dst, b, h) do { _Pragma("unroll") for (int m = 0; m < 4; ++m) _Pragma("unroll") for (int k = 0; k < 2; ++k) dst[m][k] = *(const PG8_LAS bf16x8*)(lds + PG8_SA(b, h) + aoff + m * 2048 + k * 1024); } while (0)
; #define PG8_MMA(ai, bj, At, Bt) do { __builtin_amdgcn_s_setprio(1); _Pragma("unroll") for (int m = 0; m < 4; ++m) _Pragma("unroll") for (int n = 0; n < 2; ++n) _Pragma("unroll") for (int k = 0; k < 2; ++k) \
;         acc[ai][bj][m][n] = __builtin_amdgcn_mfma_f32_16x16x32_bf16(Bt[n][k], At[m][k], acc[ai][bj][m][n], 0, 0, 0); __builtin_amdgcn_s_setprio(0); } while (0)
; #define PG8_WAIT_V(n) asm volatile("s_waitcnt vmcnt(" #n ")" ::: "memory")
; #define PG8_WAIT_L(n) asm volatile("s_waitcnt lgkmcnt(" #n ")" ::: "memory")
; #define PG8_BAR __builtin_amdgcn_s_barrier()
; #define PG8_SCHED __builtin_amdgcn_sched_barrier(0)
; template <class Epi, class Sched, bool ALIGN_EPI = false, bool SP2 = false>
; __device__ __forceinline__ void gemm_phase(PG8_LAS unsigned char* lds, const Gemm g, const Sched& S, const Epi& E) {
;     ...
;             PG8_WAIT_V(8); PG8_WAIT_L(0); PG8_BAR; PG8_MMA(0, 0, At, B0); PG8_MMA(0, 1, At, B1); PG8_BAR; PG8_SCHED;
;             PG8_LDA(At, 1, 1); PG8_STAGE(PG8_SB(1, 0), b3, voffB); PG8_STAGE(PG8_SB(1, 1), b3 + hstep, voffB); PG8_STAGE(PG8_SA(1, 0), a3, voffA);
;             PG8_WAIT_V(8); PG8_WAIT_L(0); PG8_BAR; PG8_MMA(1, 0, At, B0); PG8_MMA(1, 1, At, B1); PG8_BAR; PG8_SCHED;
;     ...
;         if constexpr (ALIGN_EPI) { if (wr == 0) PG8_BAR; }
	s_add_i32 s52, s63, s25
	v_lshl_add_u64 v[206:207], v[206:207], 0, s[18:19]
	s_mov_b32 m0, s52
	ds_read_b128 v[160:163], v236 offset:49152
	ds_read_b128 v[164:167], v236 offset:50176
	ds_read_b128 v[168:171], v236 offset:51200
	ds_read_b128 v[172:175], v236 offset:52224
	ds_read_b128 v[176:179], v236 offset:53248
	ds_read_b128 v[180:183], v236 offset:54272
	ds_read_b128 v[198:201], v236 offset:55296
	ds_read_b128 v[202:205], v236 offset:56320
	global_load_lds_dwordx4 v[206:207], off
	s_add_i32 m0, s52, 0x2000
	s_add_u32 s50, s50, 0x40080
	v_lshl_add_u64 v[206:207], v[208:209], 0, s[18:19]
	s_addc_u32 s51, s51, 0
	s_add_i32 s52, s64, s25
	global_load_lds_dwordx4 v[206:207], off
	s_mov_b32 m0, s52
	s_nop 0
	global_load_lds_dwordx4 v186, s[50:51]
	s_add_i32 m0, s52, 0x2000
	s_nop 0
	global_load_lds_dwordx4 v190, s[50:51]
	v_lshl_add_u64 v[206:207], v[210:211], 0, s[18:19]
	s_mov_b32 m0, s31
	s_nop 0
	global_load_lds_dwordx4 v[206:207], off
	v_lshl_add_u64 v[206:207], v[212:213], 0, s[18:19]
	s_mov_b32 m0, s33
	s_nop 0
	global_load_lds_dwordx4 v[206:207], off
	s_waitcnt vmcnt(8)
	s_waitcnt lgkmcnt(0)
	s_barrier
	s_setprio 1
	s_waitcnt lgkmcnt(0)
	v_mfma_f32_16x16x32_bf16 v[60:63], v[124:127], v[160:163], v[60:63]
	v_mfma_f32_16x16x32_bf16 v[56:59], v[136:139], v[160:163], v[56:59]
	v_mfma_f32_16x16x32_bf16 v[44:47], v[124:127], v[168:171], v[44:47]
	v_mfma_f32_16x16x32_bf16 v[40:43], v[136:139], v[168:171], v[40:43]
	v_mfma_f32_16x16x32_bf16 v[28:31], v[124:127], v[176:179], v[28:31]
	v_mfma_f32_16x16x32_bf16 v[24:27], v[136:139], v[176:179], v[24:27]
	v_mfma_f32_16x16x32_bf16 v[12:15], v[124:127], v[198:201], v[12:15]
	v_mfma_f32_16x16x32_bf16 v[8:11], v[136:139], v[198:201], v[8:11]
	v_mfma_f32_16x16x32_bf16 v[60:63], v[132:135], v[164:167], v[60:63]
	v_mfma_f32_16x16x32_bf16 v[56:59], v[140:143], v[164:167], v[56:59]
	v_mfma_f32_16x16x32_bf16 v[44:47], v[132:135], v[172:175], v[44:47]
	v_mfma_f32_16x16x32_bf16 v[40:43], v[140:143], v[172:175], v[40:43]
	v_mfma_f32_16x16x32_bf16 v[28:31], v[132:135], v[180:183], v[28:31]
	v_mfma_f32_16x16x32_bf16 v[24:27], v[140:143], v[180:183], v[24:27]
	v_mfma_f32_16x16x32_bf16 v[12:15], v[132:135], v[202:205], v[12:15]
	v_mfma_f32_16x16x32_bf16 v[8:11], v[140:143], v[202:205], v[8:11]
	s_setprio 0
	s_setprio 1
	v_mfma_f32_16x16x32_bf16 v[52:55], v[144:147], v[160:163], v[52:55]
	v_mfma_f32_16x16x32_bf16 v[48:51], v[152:155], v[160:163], v[48:51]
	v_mfma_f32_16x16x32_bf16 v[36:39], v[144:147], v[168:171], v[36:39]
	v_mfma_f32_16x16x32_bf16 v[32:35], v[152:155], v[168:171], v[32:35]
	v_mfma_f32_16x16x32_bf16 v[20:23], v[144:147], v[176:179], v[20:23]
	v_mfma_f32_16x16x32_bf16 v[16:19], v[152:155], v[176:179], v[16:19]
	v_mfma_f32_16x16x32_bf16 v[4:7], v[144:147], v[198:201], v[4:7]
	v_mfma_f32_16x16x32_bf16 v[0:3], v[152:155], v[198:201], v[0:3]
	v_mfma_f32_16x16x32_bf16 v[52:55], v[148:151], v[164:167], v[52:55]
	v_mfma_f32_16x16x32_bf16 v[48:51], v[156:159], v[164:167], v[48:51]
	v_mfma_f32_16x16x32_bf16 v[36:39], v[148:151], v[172:175], v[36:39]
	v_mfma_f32_16x16x32_bf16 v[32:35], v[156:159], v[172:175], v[32:35]
	v_mfma_f32_16x16x32_bf16 v[20:23], v[148:151], v[180:183], v[20:23]
	v_mfma_f32_16x16x32_bf16 v[16:19], v[156:159], v[180:183], v[16:19]
	v_mfma_f32_16x16x32_bf16 v[4:7], v[148:151], v[202:205], v[4:7]
	v_mfma_f32_16x16x32_bf16 v[0:3], v[156:159], v[202:205], v[0:3]
	s_setprio 0
	s_barrier
	s_add_i32 s62, s62, 2
	s_add_u32 s48, s48, 0x100
	s_addc_u32 s49, s49, 0
	s_add_u32 s60, s60, 0x100
	s_addc_u32 s61, s61, 0
	s_cmp_gt_u32 s62, 13
	s_cbranch_scc0 .LBB0_393
	s_and_b64 vcc, exec, s[20:21]
	s_cbranch_vccz .LBB0_396
	s_barrier

; #define PG8_STAGE(bufoff, gbase, voff) do { _Pragma("unroll") for (int _i = 0; _i < 2; ++_i) \
;         __builtin_amdgcn_global_load_lds((const unsigned*)((const char*)(gbase) + (voff)[_i]), (PG8_LAS unsigned*)(lds + (bufoff) + ldsw + _i * 8192), 16, 0, 0); } while (0)
; #define PG8_WAIT_V(n) asm volatile("s_waitcnt vmcnt(" #n ")" ::: "memory")
; #define PG8_BAR __builtin_amdgcn_s_barrier()
; template <class Epi, class Sched, bool ALIGN_EPI = false, bool SP2 = false>
; __device__ __forceinline__ void gemm_phase(PG8_LAS unsigned char* lds, const Gemm g, const Sched& S, const Epi& E) {
;     const int tid = threadIdx.x, wid = __builtin_amdgcn_readfirstlane(tid >> 6), lane = tid & 63, wr = wid >> 2, wc = wid & 3, fr = lane & 15, fq = lane >> 4;
;     const int K = g.K, nt = K / BK;
;     unsigned voffA[2], voffB[2];
; #pragma unroll
;     for (int i = 0; i < 2; ++i) { int R, C; stage_rc(tid * 16 + i * 8192, R, C); const int Rb = Epi::PERM ? ((R & ~31) + perm32(R & 31)) : R;
;         voffA[i] = (unsigned)(R * K + C) * 2u; voffB[i] = (unsigned)(Rb * K + C) * 2u; }
;     const size_t kstep = (size_t)(BK * 2);
;     const size_t hstep = (size_t)HALF * K * 2;
;     const size_t tstep = 2 * hstep;
;     const unsigned ldsw = (unsigned)wid * 1024u;
;     const int aoff = lds_byte(wr * 64 + fr, fq * 8), boff = lds_byte(wc * 32 + fr, fq * 8);
;     ...
;         PG8_STAGE(PG8_SB(1, 0), cB + kstep, voffB); PG8_STAGE(PG8_SA(1, 0), cA + kstep, voffA); PG8_STAGE(PG8_SB(1, 1), cB + hstep + kstep, voffB);
;         PG8_WAIT_V(6); PG8_BAR;
.LBB0_475:
	s_lshl_b32 s8, s8, 5
	s_and_b32 s20, s8, 0x60
	s_mov_b64 s[8:9], 0x80
	s_add_i32 m0, s28, 0x18000
	v_lshl_add_u64 v[6:7], v[6:7], 0, s[8:9]
	s_ashr_i32 s41, s74, 31
	s_lshl_b32 s17, s16, 13
	s_lshl_b32 s21, s20, 7
	s_waitcnt vmcnt(2)
	s_barrier
	global_load_lds_dwordx4 v[6:7], off
	v_lshl_add_u64 v[4:5], v[4:5], 0, s[8:9]
	s_add_i32 m0, s28, 0x1a000
	s_add_i32 s48, s28, 0x8000
	s_add_i32 s49, s28, 0xa000
	global_load_lds_dwordx4 v[4:5], off
	v_lshl_add_u64 v[0:1], v[0:1], 0, s[8:9]
	s_mov_b32 m0, s48
	s_add_u32 s18, s44, 0x40080
	global_load_lds_dwordx4 v[0:1], off
	v_lshl_add_u64 v[0:1], v[2:3], 0, s[8:9]
	s_mov_b32 m0, s49
	s_addc_u32 s19, s45, 0
	global_load_lds_dwordx4 v[0:1], off
	s_add_i32 m0, s28, 0x1c000
	global_load_lds_dwordx4 v130, s[18:19]
	v_lshl_add_u64 v[0:1], s[18:19], 0, v[134:135]
	s_add_i32 m0, s28, 0x1e000
	v_bfe_u32 v2, v230, 4, 2
	global_load_lds_dwordx4 v[0:1], off
	v_and_b32_e32 v1, 15, v230
	v_lshlrev_b32_e32 v0, 4, v2
	v_lshlrev_b32_e32 v3, 2, v230
	v_lshl_or_b32 v149, s16, 6, v1
	v_lshl_or_b32 v1, v1, 6, v0
	v_and_b32_e32 v3, 32, v3
	s_sext_i32_i16 s54, s12
	v_bitop3_b32 v4, v1, s17, v3 bitop3:0xde
	v_lshlrev_b32_e32 v1, 6, v230
	s_movk_i32 s12, 0x3c0
	v_and_or_b32 v1, v1, s12, v0
	v_bitop3_b32 v153, s21, v1, v3 bitop3:0xf6
	v_mov_b32_e32 v1, v131
	v_lshl_add_u64 v[136:137], s[34:35], 0, v[0:1]
	v_lshlrev_b32_e32 v0, 8, v230
	v_and_b32_e32 v0, 0x38000, v0
	v_lshlrev_b32_e32 v1, 11, v10
	v_or3_b32 v0, v8, v0, v1
	v_add_u32_e32 v138, v0, v9
	v_lshlrev_b32_e32 v0, 4, v11
	v_and_b32_e32 v0, 0x78000, v0
	s_waitcnt vmcnt(6)
	s_cmpk_lt_u32 s13, 0x100
	v_or3_b32 v0, v8, v0, v1
	s_cselect_b64 s[12:13], -1, 0
	v_add_u32_e32 v140, v0, v9
	s_add_i32 s51, 0, 0x10000
	s_add_i32 s52, 0, 0x14000
	v_mbcnt_lo_u32_b32 v0, -1, 0
	s_mov_b32 s50, s74
	v_lshl_or_b32 v157, v2, 3, s20
	v_mov_b32_e32 v139, v131
	v_mov_b32_e32 v141, v131
	v_add_u32_e32 v161, s51, v153
	v_add_u32_e32 v165, s52, v153
	v_add_u32_e32 v169, 0, v4
	v_mbcnt_hi_u32_b32 v175, -1, v0
	v_mov_b32_e32 v176, 0x358637bd
	s_movk_i32 s53, 0x1600
	v_mov_b64_e32 v[142:143], 0x2bff
	s_barrier
	s_branch .LBB0_478

; #define PG8_STAGE(bufoff, gbase, voff) do { _Pragma("unroll") for (int _i = 0; _i < 2; ++_i) \
;         __builtin_amdgcn_global_load_lds((const unsigned*)((const char*)(gbase) + (voff)[_i]), (PG8_LAS unsigned*)(lds + (bufoff) + ldsw + _i * 8192), 16, 0, 0); } while (0)
; #define PG8_LDA(dst, b, h) do { _Pragma("unroll") for (int m = 0; m < 4; ++m) _Pragma("unroll") for (int k = 0; k < 2; ++k) dst[m][k] = *(const PG8_LAS bf16x8*)(lds + PG8_SA(b, h) + aoff + m * 2048 + k * 1024); } while (0)
; #define PG8_LDB(dst, b, h) do { _Pragma("unroll") for (int n = 0; n < 2; ++n) _Pragma("unroll") for (int k = 0; k < 2; ++k) dst[n][k] = *(const PG8_LAS bf16x8*)(lds + PG8_SB(b, h) + boff + n * 2048 + k * 1024); } while (0)
; #define PG8_MMA(ai, bj, At, Bt) do { __builtin_amdgcn_s_setprio(1); _Pragma("unroll") for (int m = 0; m < 4; ++m) _Pragma("unroll") for (int n = 0; n < 2; ++n) _Pragma("unroll") for (int k = 0; k < 2; ++k) \
;         acc[ai][bj][m][n] = __builtin_amdgcn_mfma_f32_16x16x32_bf16(Bt[n][k], At[m][k], acc[ai][bj][m][n], 0, 0, 0); __builtin_amdgcn_s_setprio(0); } while (0)
; #define PG8_BAR __builtin_amdgcn_s_barrier()
; template <class Epi, class Sched, bool ALIGN_EPI = false, bool SP2 = false>
; __device__ __forceinline__ void gemm_phase(PG8_LAS unsigned char* lds, const Gemm g, const Sched& S, const Epi& E) {
;     ...
;         const bool has_next = S.next(ui + 1, nxt);
;         const char* nA = has_next ? (const char*)g.A + (size_t)nxt.pm * tstep : cA; const char* nB = has_next ? (const char*)g.Bt + (size_t)nxt.pn * tstep : cB;
;         for (int t = 0; t < nt; t += 2) {
;             const bool last = (t == nt - 2);
;             const char* a1 = cA + (size_t)(t + 1) * kstep;
;             const char* a2 = last ? nA : cA + (size_t)(t + 2) * kstep; const char* b2 = last ? nB : cB + (size_t)(t + 2) * kstep;
;             const char* a3 = a2 + kstep; const char* b3 = b2 + kstep;
;             if (last && has_next) S.a_ready(nxt);
;             if constexpr (SP2) {
;             PG8_LDB(B0, 0, 0); PG8_LDB(B1, 0, 1); PG8_SCHED; PG8_LDA(At, 0, 0); PG8_STAGE(PG8_SA(1, 1), a1 + hstep, voffA);
;             PG8_WAIT_V(8); PG8_WAIT_L(0); PG8_BAR; PG8_MMA(0, 0, At, B0); PG8_MMA(0, 1, At, B1); PG8_BAR; PG8_SCHED;
;             PG8_LDA(At, 0, 1); PG8_STAGE(PG8_SB(0, 0), b2, voffB); PG8_STAGE(PG8_SB(0, 1), b2 + hstep, voffB); PG8_STAGE(PG8_SA(0, 0), a2, voffA);
.LBB0_481:
	s_ashr_i32 s19, s18, 31
	s_lshl_b64 s[36:37], s[18:19], 19
	s_add_u32 s36, s70, s36
	s_addc_u32 s37, s71, s37
	s_and_b64 s[38:39], s[20:21], exec
	s_cselect_b32 s19, s37, s43
	s_cselect_b32 s55, s36, s42
	s_ashr_i32 s17, s16, 31
	s_lshl_b64 s[38:39], s[16:17], 19
	s_add_u32 s38, s23, s38
	s_addc_u32 s39, s24, s39
	s_and_b64 s[46:47], s[20:21], exec
	s_cselect_b32 s17, s39, s45
	s_cselect_b32 s56, s38, s44
	s_add_u32 s42, s42, 0x40080
	s_addc_u32 s43, s43, 0
	s_add_u32 s57, s44, 0x100
	s_addc_u32 s58, s45, 0
	s_mov_b32 s59, -2
	ds_read_b128 v[144:147], v161
	ds_read_b128 v[170:173], v161 offset:1024
	ds_read_b128 v[178:181], v161 offset:2048
	ds_read_b128 v[182:185], v161 offset:3072
	ds_read_b128 v[186:189], v165
	ds_read_b128 v[190:193], v165 offset:1024
	ds_read_b128 v[194:197], v165 offset:2048
	ds_read_b128 v[198:201], v165 offset:3072
	s_add_u32 s44, s42, 0xfffc0080
	s_addc_u32 s45, s43, -1
	s_cmp_eq_u32 s59, 12
	s_cselect_b32 s47, s19, s45
	s_cselect_b32 s46, s55, s44
	s_cselect_b32 s45, s17, s58
	s_cselect_b32 s44, s56, s57
	s_add_i32 m0, s28, 0xc000
	ds_read_b128 v[202:205], v169
	ds_read_b128 v[206:209], v169 offset:1024
	ds_read_b128 v[210:213], v169 offset:2048
	ds_read_b128 v[214:217], v169 offset:3072
	ds_read_b128 v[218:221], v169 offset:4096
	ds_read_b128 v[222:225], v169 offset:5120
	ds_read_b128 v[226:229], v169 offset:6144
	ds_read_b128 v[232:235], v169 offset:7168
	global_load_lds_dwordx4 v138, s[42:43]
	s_add_i32 m0, s28, 0xe000
	s_nop 0
	global_load_lds_dwordx4 v140, s[42:43]
	s_waitcnt vmcnt(8)
	s_waitcnt lgkmcnt(0)
	s_barrier
	s_setprio 1
	s_waitcnt lgkmcnt(0)
	v_mfma_f32_16x16x32_bf16 v[124:127], v[144:147], v[202:205], 0
	v_mfma_f32_16x16x32_bf16 v[116:119], v[178:181], v[202:205], 0
	v_mfma_f32_16x16x32_bf16 v[108:111], v[144:147], v[210:213], 0
	v_mfma_f32_16x16x32_bf16 v[100:103], v[178:181], v[210:213], 0
	v_mfma_f32_16x16x32_bf16 v[92:95], v[144:147], v[218:221], 0
	v_mfma_f32_16x16x32_bf16 v[84:87], v[178:181], v[218:221], 0
	v_mfma_f32_16x16x32_bf16 v[76:79], v[144:147], v[226:229], 0
	v_mfma_f32_16x16x32_bf16 v[68:71], v[178:181], v[226:229], 0
	v_mfma_f32_16x16x32_bf16 v[124:127], v[170:173], v[206:209], v[124:127]
	v_mfma_f32_16x16x32_bf16 v[116:119], v[182:185], v[206:209], v[116:119]
	v_mfma_f32_16x16x32_bf16 v[108:111], v[170:173], v[214:217], v[108:111]
	v_mfma_f32_16x16x32_bf16 v[100:103], v[182:185], v[214:217], v[100:103]
	v_mfma_f32_16x16x32_bf16 v[92:95], v[170:173], v[222:225], v[92:95]
	v_mfma_f32_16x16x32_bf16 v[84:87], v[182:185], v[222:225], v[84:87]
	v_mfma_f32_16x16x32_bf16 v[76:79], v[170:173], v[232:235], v[76:79]
	v_mfma_f32_16x16x32_bf16 v[68:71], v[182:185], v[232:235], v[68:71]
	s_setprio 0
	s_setprio 1
	v_mfma_f32_16x16x32_bf16 v[120:123], v[186:189], v[202:205], 0
	v_mfma_f32_16x16x32_bf16 v[112:115], v[194:197], v[202:205], 0
	v_mfma_f32_16x16x32_bf16 v[104:107], v[186:189], v[210:213], 0
	v_mfma_f32_16x16x32_bf16 v[96:99], v[194:197], v[210:213], 0
	v_mfma_f32_16x16x32_bf16 v[88:91], v[186:189], v[218:221], 0
	v_mfma_f32_16x16x32_bf16 v[80:83], v[194:197], v[218:221], 0
	v_mfma_f32_16x16x32_bf16 v[72:75], v[186:189], v[226:229], 0
	v_mfma_f32_16x16x32_bf16 v[64:67], v[194:197], v[226:229], 0
	v_mfma_f32_16x16x32_bf16 v[120:123], v[190:193], v[206:209], v[120:123]
	v_mfma_f32_16x16x32_bf16 v[112:115], v[198:201], v[206:209], v[112:115]
	v_mfma_f32_16x16x32_bf16 v[104:107], v[190:193], v[214:217], v[104:107]
	v_mfma_f32_16x16x32_bf16 v[96:99], v[198:201], v[214:217], v[96:99]
	v_mfma_f32_16x16x32_bf16 v[88:91], v[190:193], v[222:225], v[88:91]
	v_mfma_f32_16x16x32_bf16 v[80:83], v[198:201], v[222:225], v[80:83]
	v_mfma_f32_16x16x32_bf16 v[72:75], v[190:193], v[232:235], v[72:75]
	v_mfma_f32_16x16x32_bf16 v[64:67], v[198:201], v[232:235], v[64:67]
	s_setprio 0
	s_barrier
	s_add_i32 s60, s51, s25
	v_lshl_add_u64 v[150:151], s[44:45], 0, v[130:131]
	s_mov_b32 m0, s60
	ds_read_b128 v[202:205], v169 offset:16384
	ds_read_b128 v[206:209], v169 offset:17408
	ds_read_b128 v[210:213], v169 offset:18432
	ds_read_b128 v[214:217], v169 offset:19456
	ds_read_b128 v[218:221], v169 offset:20480
	ds_read_b128 v[222:225], v169 offset:21504
	ds_read_b128 v[226:229], v169 offset:22528
	ds_read_b128 v[232:235], v169 offset:23552
	global_load_lds_dwordx4 v[150:151], off
	s_add_i32 m0, s60, 0x2000
	s_add_u32 s60, s44, 0x40000
	v_lshl_add_u64 v[154:155], s[44:45], 0, v[134:135]
	s_addc_u32 s61, s45, 0
	s_add_i32 s62, s52, s25
	global_load_lds_dwordx4 v[154:155], off
	s_mov_b32 m0, s62
	v_lshl_add_u64 v[162:163], s[46:47], 0, v[132:133]
	global_load_lds_dwordx4 v130, s[60:61]
	s_add_i32 m0, s62, 0x2000
	s_nop 0
	global_load_lds_dwordx4 v134, s[60:61]
	v_lshl_add_u64 v[158:159], s[46:47], 0, v[128:129]
	s_mov_b32 m0, s28
	s_nop 0
	global_load_lds_dwordx4 v[158:159], off
	s_mov_b32 m0, s29
	s_nop 0
	global_load_lds_dwordx4 v[162:163], off
	s_cmp_lg_i32 s59, -2
	s_cbranch_scc1 .Lrsa_a_pl
	v_lshrrev_b32_e32 v250, 6, v230
	v_lshlrev_b32_e32 v250, 11, v250
	v_and_b32_e32 v251, 63, v230
	v_lshl_or_b32 v250, v251, 4, v250
	v_lshl_add_u32 v250, s40, 14, v250
	v_readfirstlane_b32 s98, v230
	s_lshr_b32 s98, s98, 6
	s_lshl_b32 s98, s98, 11
	s_add_i32 m0, s98, 0x20000
	s_add_u32 s100, s70, 0x3f000000
	s_addc_u32 s101, s71, 0
	global_load_lds_dwordx4 v250, s[100:101]
	global_load_lds_dwordx4 v250, s[100:101] offset:1024
	s_waitcnt vmcnt(10)
	s_branch .Lrsa_b_pl

; #define PG8_STAGE(bufoff, gbase, voff) do { _Pragma("unroll") for (int _i = 0; _i < 2; ++_i) \
;         __builtin_amdgcn_global_load_lds((const unsigned*)((const char*)(gbase) + (voff)[_i]), (PG8_LAS unsigned*)(lds + (bufoff) + ldsw + _i * 8192), 16, 0, 0); } while (0)
; #define PG8_LDA(dst, b, h) do { _Pragma("unroll") for (int m = 0; m < 4; ++m) _Pragma("unroll") for (int k = 0; k < 2; ++k) dst[m][k] = *(const PG8_LAS bf16x8*)(lds + PG8_SA(b, h) + aoff + m * 2048 + k * 1024); } while (0)
; #define PG8_LDB(dst, b, h) do { _Pragma("unroll") for (int n = 0; n < 2; ++n) _Pragma("unroll") for (int k = 0; k < 2; ++k) dst[n][k] = *(const PG8_LAS bf16x8*)(lds + PG8_SB(b, h) + boff + n * 2048 + k * 1024); } while (0)
; #define PG8_MMA(ai, bj, At, Bt) do { __builtin_amdgcn_s_setprio(1); _Pragma("unroll") for (int m = 0; m < 4; ++m) _Pragma("unroll") for (int n = 0; n < 2; ++n) _Pragma("unroll") for (int k = 0; k < 2; ++k) \
;         acc[ai][bj][m][n] = __builtin_amdgcn_mfma_f32_16x16x32_bf16(Bt[n][k], At[m][k], acc[ai][bj][m][n], 0, 0, 0); __builtin_amdgcn_s_setprio(0); } while (0)
; #define PG8_WAIT_V(n) asm volatile("s_waitcnt vmcnt(" #n ")" ::: "memory")
; #define PG8_WAIT_L(n) asm volatile("s_waitcnt lgkmcnt(" #n ")" ::: "memory")
; #define PG8_BAR __builtin_amdgcn_s_barrier()
; #define PG8_SCHED __builtin_amdgcn_sched_barrier(0)
; template <class Epi, class Sched, bool ALIGN_EPI = false, bool SP2 = false>
; __device__ __forceinline__ void gemm_phase(PG8_LAS unsigned char* lds, const Gemm g, const Sched& S, const Epi& E) {
;     ...
;             PG8_WAIT_V(8); PG8_WAIT_L(0); PG8_BAR; PG8_MMA(0, 0, At, B0); PG8_MMA(0, 1, At, B1); PG8_BAR; PG8_SCHED;
;             PG8_LDA(At, 0, 1); PG8_STAGE(PG8_SB(0, 0), b2, voffB); PG8_STAGE(PG8_SB(0, 1), b2 + hstep, voffB); PG8_STAGE(PG8_SA(0, 0), a2, voffA);
;             PG8_WAIT_V(8); PG8_WAIT_L(0); PG8_BAR; PG8_MMA(1, 0, At, B0); PG8_MMA(1, 1, At, B1); PG8_BAR; PG8_SCHED;
;             PG8_LDB(B0, 1, 0); PG8_LDB(B1, 1, 1); PG8_SCHED; PG8_LDA(At, 1, 0); PG8_STAGE(PG8_SA(0, 1), a2 + hstep, voffA);
;             PG8_WAIT_V(8); PG8_WAIT_L(0); PG8_BAR; PG8_MMA(0, 0, At, B0); PG8_MMA(0, 1, At, B1); PG8_BAR; PG8_SCHED;
.Lrsa_b_pl:
	s_waitcnt lgkmcnt(0)
	s_barrier
	s_setprio 1
	s_waitcnt lgkmcnt(0)
	v_mfma_f32_16x16x32_bf16 v[60:63], v[144:147], v[202:205], 0
	v_mfma_f32_16x16x32_bf16 v[52:55], v[178:181], v[202:205], 0
	v_mfma_f32_16x16x32_bf16 v[44:47], v[144:147], v[210:213], 0
	v_mfma_f32_16x16x32_bf16 v[36:39], v[178:181], v[210:213], 0
	v_mfma_f32_16x16x32_bf16 v[28:31], v[144:147], v[218:221], 0
	v_mfma_f32_16x16x32_bf16 v[20:23], v[178:181], v[218:221], 0
	v_mfma_f32_16x16x32_bf16 v[12:15], v[144:147], v[226:229], 0
	v_mfma_f32_16x16x32_bf16 v[4:7], v[178:181], v[226:229], 0
	v_mfma_f32_16x16x32_bf16 v[60:63], v[170:173], v[206:209], v[60:63]
	v_mfma_f32_16x16x32_bf16 v[52:55], v[182:185], v[206:209], v[52:55]
	v_mfma_f32_16x16x32_bf16 v[44:47], v[170:173], v[214:217], v[44:47]
	v_mfma_f32_16x16x32_bf16 v[36:39], v[182:185], v[214:217], v[36:39]
	v_mfma_f32_16x16x32_bf16 v[28:31], v[170:173], v[222:225], v[28:31]
	v_mfma_f32_16x16x32_bf16 v[20:23], v[182:185], v[222:225], v[20:23]
	v_mfma_f32_16x16x32_bf16 v[12:15], v[170:173], v[232:235], v[12:15]
	v_mfma_f32_16x16x32_bf16 v[4:7], v[182:185], v[232:235], v[4:7]
	s_setprio 0
	s_setprio 1
	v_mfma_f32_16x16x32_bf16 v[56:59], v[186:189], v[202:205], 0
	v_mfma_f32_16x16x32_bf16 v[48:51], v[194:197], v[202:205], 0
	v_mfma_f32_16x16x32_bf16 v[40:43], v[186:189], v[210:213], 0
	v_mfma_f32_16x16x32_bf16 v[32:35], v[194:197], v[210:213], 0
	v_mfma_f32_16x16x32_bf16 v[24:27], v[186:189], v[218:221], 0
	v_mfma_f32_16x16x32_bf16 v[16:19], v[194:197], v[218:221], 0
	v_mfma_f32_16x16x32_bf16 v[8:11], v[186:189], v[226:229], 0
	v_mfma_f32_16x16x32_bf16 v[0:3], v[194:197], v[226:229], 0
	v_mfma_f32_16x16x32_bf16 v[56:59], v[190:193], v[206:209], v[56:59]
	v_mfma_f32_16x16x32_bf16 v[48:51], v[198:201], v[206:209], v[48:51]
	v_mfma_f32_16x16x32_bf16 v[40:43], v[190:193], v[214:217], v[40:43]
	v_mfma_f32_16x16x32_bf16 v[32:35], v[198:201], v[214:217], v[32:35]
	v_mfma_f32_16x16x32_bf16 v[24:27], v[190:193], v[222:225], v[24:27]
	v_mfma_f32_16x16x32_bf16 v[16:19], v[198:201], v[222:225], v[16:19]
	v_mfma_f32_16x16x32_bf16 v[8:11], v[190:193], v[232:235], v[8:11]
	v_mfma_f32_16x16x32_bf16 v[0:3], v[198:201], v[232:235], v[0:3]
	s_setprio 0
	s_barrier
	s_add_i32 s60, 0, 0x18000
	v_add_u32_e32 v148, s60, v153
	s_add_i32 s61, 0, 0x1c000
	ds_read_b128 v[144:147], v148
	ds_read_b128 v[170:173], v148 offset:1024
	ds_read_b128 v[178:181], v148 offset:2048
	ds_read_b128 v[182:185], v148 offset:3072
	v_add_u32_e32 v148, s61, v153
	ds_read_b128 v[186:189], v148
	ds_read_b128 v[190:193], v148 offset:1024
	ds_read_b128 v[194:197], v148 offset:2048
	ds_read_b128 v[198:201], v148 offset:3072
	s_add_u32 s46, s46, 0x40000
	s_addc_u32 s47, s47, 0
	s_mov_b32 m0, s30
	ds_read_b128 v[202:205], v169 offset:32768
	ds_read_b128 v[206:209], v169 offset:33792
	ds_read_b128 v[210:213], v169 offset:34816
	ds_read_b128 v[214:217], v169 offset:35840
	ds_read_b128 v[218:221], v169 offset:36864
	ds_read_b128 v[222:225], v169 offset:37888
	ds_read_b128 v[226:229], v169 offset:38912
	ds_read_b128 v[232:235], v169 offset:39936
	global_load_lds_dwordx4 v128, s[46:47]
	v_lshl_add_u64 v[166:167], s[46:47], 0, v[132:133]
	s_mov_b32 m0, s31
	s_nop 0
	global_load_lds_dwordx4 v[166:167], off
	s_cmp_lg_i32 s59, -2
	s_cbranch_scc1 .Lrsa_c_pl
	s_waitcnt vmcnt(10)
	s_branch .Lrsa_d_pl

; #define PG8_STAGE(bufoff, gbase, voff) do { _Pragma("unroll") for (int _i = 0; _i < 2; ++_i) \
;         __builtin_amdgcn_global_load_lds((const unsigned*)((const char*)(gbase) + (voff)[_i]), (PG8_LAS unsigned*)(lds + (bufoff) + ldsw + _i * 8192), 16, 0, 0); } while (0)
; #define PG8_LDA(dst, b, h) do { _Pragma("unroll") for (int m = 0; m < 4; ++m) _Pragma("unroll") for (int k = 0; k < 2; ++k) dst[m][k] = *(const PG8_LAS bf16x8*)(lds + PG8_SA(b, h) + aoff + m * 2048 + k * 1024); } while (0)
; #define PG8_MMA(ai, bj, At, Bt) do { __builtin_amdgcn_s_setprio(1); _Pragma("unroll") for (int m = 0; m < 4; ++m) _Pragma("unroll") for (int n = 0; n < 2; ++n) _Pragma("unroll") for (int k = 0; k < 2; ++k) \
;         acc[ai][bj][m][n] = __builtin_amdgcn_mfma_f32_16x16x32_bf16(Bt[n][k], At[m][k], acc[ai][bj][m][n], 0, 0, 0); __builtin_amdgcn_s_setprio(0); } while (0)
; #define PG8_WAIT_V(n) asm volatile("s_waitcnt vmcnt(" #n ")" ::: "memory")
; #define PG8_WAIT_L(n) asm volatile("s_waitcnt lgkmcnt(" #n ")" ::: "memory")
; #define PG8_BAR __builtin_amdgcn_s_barrier()
; #define PG8_SCHED __builtin_amdgcn_sched_barrier(0)
; template <class Epi, class Sched, bool ALIGN_EPI = false, bool SP2 = false>
; __device__ __forceinline__ void gemm_phase(PG8_LAS unsigned char* lds, const Gemm g, const Sched& S, const Epi& E) {
;     ...
;             PG8_WAIT_V(8); PG8_WAIT_L(0); PG8_BAR; PG8_MMA(0, 0, At, B0); PG8_MMA(0, 1, At, B1); PG8_BAR; PG8_SCHED;
;             PG8_LDA(At, 1, 1); PG8_STAGE(PG8_SB(1, 0), b3, voffB); PG8_STAGE(PG8_SB(1, 1), b3 + hstep, voffB); PG8_STAGE(PG8_SA(1, 0), a3, voffA);
;             PG8_WAIT_V(8); PG8_WAIT_L(0); PG8_BAR; PG8_MMA(1, 0, At, B0); PG8_MMA(1, 1, At, B1); PG8_BAR; PG8_SCHED;
.Lrsa_d_pl:
	s_waitcnt lgkmcnt(0)
	s_barrier
	s_setprio 1
	s_waitcnt lgkmcnt(0)
	v_mfma_f32_16x16x32_bf16 v[124:127], v[144:147], v[202:205], v[124:127]
	v_mfma_f32_16x16x32_bf16 v[116:119], v[178:181], v[202:205], v[116:119]
	v_mfma_f32_16x16x32_bf16 v[108:111], v[144:147], v[210:213], v[108:111]
	v_mfma_f32_16x16x32_bf16 v[100:103], v[178:181], v[210:213], v[100:103]
	v_mfma_f32_16x16x32_bf16 v[92:95], v[144:147], v[218:221], v[92:95]
	v_mfma_f32_16x16x32_bf16 v[84:87], v[178:181], v[218:221], v[84:87]
	v_mfma_f32_16x16x32_bf16 v[76:79], v[144:147], v[226:229], v[76:79]
	v_mfma_f32_16x16x32_bf16 v[68:71], v[178:181], v[226:229], v[68:71]
	v_mfma_f32_16x16x32_bf16 v[124:127], v[170:173], v[206:209], v[124:127]
	v_mfma_f32_16x16x32_bf16 v[116:119], v[182:185], v[206:209], v[116:119]
	v_mfma_f32_16x16x32_bf16 v[108:111], v[170:173], v[214:217], v[108:111]
	v_mfma_f32_16x16x32_bf16 v[100:103], v[182:185], v[214:217], v[100:103]
	v_mfma_f32_16x16x32_bf16 v[92:95], v[170:173], v[222:225], v[92:95]
	v_mfma_f32_16x16x32_bf16 v[84:87], v[182:185], v[222:225], v[84:87]
	v_mfma_f32_16x16x32_bf16 v[76:79], v[170:173], v[232:235], v[76:79]
	v_mfma_f32_16x16x32_bf16 v[68:71], v[182:185], v[232:235], v[68:71]
	s_setprio 0
	s_setprio 1
	v_mfma_f32_16x16x32_bf16 v[120:123], v[186:189], v[202:205], v[120:123]
	v_mfma_f32_16x16x32_bf16 v[112:115], v[194:197], v[202:205], v[112:115]
	v_mfma_f32_16x16x32_bf16 v[104:107], v[186:189], v[210:213], v[104:107]
	v_mfma_f32_16x16x32_bf16 v[96:99], v[194:197], v[210:213], v[96:99]
	v_mfma_f32_16x16x32_bf16 v[88:91], v[186:189], v[218:221], v[88:91]
	v_mfma_f32_16x16x32_bf16 v[80:83], v[194:197], v[218:221], v[80:83]
	v_mfma_f32_16x16x32_bf16 v[72:75], v[186:189], v[226:229], v[72:75]
	v_mfma_f32_16x16x32_bf16 v[64:67], v[194:197], v[226:229], v[64:67]
	v_mfma_f32_16x16x32_bf16 v[120:123], v[190:193], v[206:209], v[120:123]
	v_mfma_f32_16x16x32_bf16 v[112:115], v[198:201], v[206:209], v[112:115]
	v_mfma_f32_16x16x32_bf16 v[104:107], v[190:193], v[214:217], v[104:107]
	v_mfma_f32_16x16x32_bf16 v[96:99], v[198:201], v[214:217], v[96:99]
	v_mfma_f32_16x16x32_bf16 v[88:91], v[190:193], v[222:225], v[88:91]
	v_mfma_f32_16x16x32_bf16 v[80:83], v[198:201], v[222:225], v[80:83]
	v_mfma_f32_16x16x32_bf16 v[72:75], v[190:193], v[232:235], v[72:75]
	v_mfma_f32_16x16x32_bf16 v[64:67], v[198:201], v[232:235], v[64:67]
	s_setprio 0
	s_barrier
	s_add_i32 s46, s60, s25
	v_lshl_add_u64 v[150:151], v[150:151], 0, s[8:9]
	s_mov_b32 m0, s46
	ds_read_b128 v[202:205], v169 offset:49152
	ds_read_b128 v[206:209], v169 offset:50176
	ds_read_b128 v[210:213], v169 offset:51200
	ds_read_b128 v[214:217], v169 offset:52224
	ds_read_b128 v[218:221], v169 offset:53248
	ds_read_b128 v[222:225], v169 offset:54272
	ds_read_b128 v[226:229], v169 offset:55296
	ds_read_b128 v[232:235], v169 offset:56320
	global_load_lds_dwordx4 v[150:151], off
	s_add_i32 m0, s46, 0x2000
	s_add_u32 s44, s44, 0x40080
	v_lshl_add_u64 v[150:151], v[154:155], 0, s[8:9]
	s_addc_u32 s45, s45, 0
	s_add_i32 s46, s61, s25
	global_load_lds_dwordx4 v[150:151], off
	s_mov_b32 m0, s46
	s_nop 0
	global_load_lds_dwordx4 v130, s[44:45]
	s_add_i32 m0, s46, 0x2000
	s_nop 0
	global_load_lds_dwordx4 v134, s[44:45]
	v_lshl_add_u64 v[150:151], v[158:159], 0, s[8:9]
	s_mov_b32 m0, s48
	s_nop 0
	global_load_lds_dwordx4 v[150:151], off
	v_lshl_add_u64 v[150:151], v[162:163], 0, s[8:9]
	s_mov_b32 m0, s49
	s_nop 0
	global_load_lds_dwordx4 v[150:151], off
	s_waitcnt vmcnt(8)
	s_waitcnt lgkmcnt(0)
	s_barrier
	s_setprio 1
	s_waitcnt lgkmcnt(0)
	v_mfma_f32_16x16x32_bf16 v[60:63], v[144:147], v[202:205], v[60:63]
	v_mfma_f32_16x16x32_bf16 v[52:55], v[178:181], v[202:205], v[52:55]
	v_mfma_f32_16x16x32_bf16 v[44:47], v[144:147], v[210:213], v[44:47]
	v_mfma_f32_16x16x32_bf16 v[36:39], v[178:181], v[210:213], v[36:39]
	v_mfma_f32_16x16x32_bf16 v[28:31], v[144:147], v[218:221], v[28:31]
	v_mfma_f32_16x16x32_bf16 v[20:23], v[178:181], v[218:221], v[20:23]
	v_mfma_f32_16x16x32_bf16 v[12:15], v[144:147], v[226:229], v[12:15]
	v_mfma_f32_16x16x32_bf16 v[4:7], v[178:181], v[226:229], v[4:7]
	v_mfma_f32_16x16x32_bf16 v[60:63], v[170:173], v[206:209], v[60:63]
	v_mfma_f32_16x16x32_bf16 v[52:55], v[182:185], v[206:209], v[52:55]
	v_mfma_f32_16x16x32_bf16 v[44:47], v[170:173], v[214:217], v[44:47]
	v_mfma_f32_16x16x32_bf16 v[36:39], v[182:185], v[214:217], v[36:39]
	v_mfma_f32_16x16x32_bf16 v[28:31], v[170:173], v[222:225], v[28:31]
	v_mfma_f32_16x16x32_bf16 v[20:23], v[182:185], v[222:225], v[20:23]
	v_mfma_f32_16x16x32_bf16 v[12:15], v[170:173], v[232:235], v[12:15]
	v_mfma_f32_16x16x32_bf16 v[4:7], v[182:185], v[232:235], v[4:7]
	s_setprio 0
	s_setprio 1
	v_mfma_f32_16x16x32_bf16 v[56:59], v[186:189], v[202:205], v[56:59]
	v_mfma_f32_16x16x32_bf16 v[48:51], v[194:197], v[202:205], v[48:51]
	v_mfma_f32_16x16x32_bf16 v[40:43], v[186:189], v[210:213], v[40:43]
	v_mfma_f32_16x16x32_bf16 v[32:35], v[194:197], v[210:213], v[32:35]
	v_mfma_f32_16x16x32_bf16 v[24:27], v[186:189], v[218:221], v[24:27]
	v_mfma_f32_16x16x32_bf16 v[16:19], v[194:197], v[218:221], v[16:19]
	v_mfma_f32_16x16x32_bf16 v[8:11], v[186:189], v[226:229], v[8:11]
	v_mfma_f32_16x16x32_bf16 v[0:3], v[194:197], v[226:229], v[0:3]
	v_mfma_f32_16x16x32_bf16 v[56:59], v[190:193], v[206:209], v[56:59]
	v_mfma_f32_16x16x32_bf16 v[48:51], v[198:201], v[206:209], v[48:51]
	v_mfma_f32_16x16x32_bf16 v[40:43], v[190:193], v[214:217], v[40:43]
	v_mfma_f32_16x16x32_bf16 v[32:35], v[198:201], v[214:217], v[32:35]
	v_mfma_f32_16x16x32_bf16 v[24:27], v[190:193], v[222:225], v[24:27]
	v_mfma_f32_16x16x32_bf16 v[16:19], v[198:201], v[222:225], v[16:19]
	v_mfma_f32_16x16x32_bf16 v[8:11], v[190:193], v[232:235], v[8:11]
	v_mfma_f32_16x16x32_bf16 v[0:3], v[198:201], v[232:235], v[0:3]
	s_setprio 0
	s_barrier
	s_add_i32 s59, s59, 2
	s_add_u32 s42, s42, 0x100
	s_addc_u32 s43, s43, 0
	s_add_u32 s57, s57, 0x100
	s_addc_u32 s58, s58, 0
	s_cmp_gt_u32 s59, 13
; #define PG8_STAGE(bufoff, gbase, voff) do { _Pragma("unroll") for (int _i = 0; _i < 2; ++_i) \
;         __builtin_amdgcn_global_load_lds((const unsigned*)((const char*)(gbase) + (voff)[_i]), (PG8_LAS unsigned*)(lds + (bufoff) + ldsw + _i * 8192), 16, 0, 0); } while (0)
; #define PG8_LDA(dst, b, h) do { _Pragma("unroll") for (int m = 0; m < 4; ++m) _Pragma("unroll") for (int k = 0; k < 2; ++k) dst[m][k] = *(const PG8_LAS bf16x8*)(lds + PG8_SA(b, h) + aoff + m * 2048 + k * 1024); } while (0)
; #define PG8_LDB(dst, b, h) do { _Pragma("unroll") for (int n = 0; n < 2; ++n) _Pragma("unroll") for (int k = 0; k < 2; ++k) dst[n][k] = *(const PG8_LAS bf16x8*)(lds + PG8_SB(b, h) + boff + n * 2048 + k * 1024); } while (0)
; #define PG8_MMA(ai, bj, At, Bt) do { __builtin_amdgcn_s_setprio(1); _Pragma("unroll") for (int m = 0; m < 4; ++m) _Pragma("unroll") for (int n = 0; n < 2; ++n) _Pragma("unroll") for (int k = 0; k < 2; ++k) \
;         acc[ai][bj][m][n] = __builtin_amdgcn_mfma_f32_16x16x32_bf16(Bt[n][k], At[m][k], acc[ai][bj][m][n], 0, 0, 0); __builtin_amdgcn_s_setprio(0); } while (0)
; #define PG8_WAIT_V(n) asm volatile("s_waitcnt vmcnt(" #n ")" ::: "memory")
; #define PG8_WAIT_L(n) asm volatile("s_waitcnt lgkmcnt(" #n ")" ::: "memory")
; #define PG8_BAR __builtin_amdgcn_s_barrier()
; #define PG8_SCHED __builtin_amdgcn_sched_barrier(0)
; template <class Epi, class Sched, bool ALIGN_EPI = false, bool SP2 = false>
; __device__ __forceinline__ void gemm_phase(PG8_LAS unsigned char* lds, const Gemm g, const Sched& S, const Epi& E) {
;     ...
;             PG8_LDB(B0, 0, 0); PG8_LDB(B1, 0, 1); PG8_SCHED; PG8_LDA(At, 0, 0); PG8_STAGE(PG8_SA(1, 1), a1 + hstep, voffA);
;             PG8_WAIT_V(8); PG8_WAIT_L(0); PG8_BAR; PG8_MMA(0, 0, At, B0); PG8_MMA(0, 1, At, B1); PG8_BAR; PG8_SCHED;
;             PG8_LDA(At, 0, 1); PG8_STAGE(PG8_SB(0, 0), b2, voffB); PG8_STAGE(PG8_SB(0, 1), b2 + hstep, voffB); PG8_STAGE(PG8_SA(0, 0), a2, voffA);
;             PG8_WAIT_V(8); PG8_WAIT_L(0); PG8_BAR; PG8_MMA(1, 0, At, B0); PG8_MMA(1, 1, At, B1); PG8_BAR; PG8_SCHED;
.LBB0_482:
	ds_read_b128 v[144:147], v161
	ds_read_b128 v[170:173], v161 offset:1024
	ds_read_b128 v[178:181], v161 offset:2048
	ds_read_b128 v[182:185], v161 offset:3072
	ds_read_b128 v[186:189], v165
	ds_read_b128 v[190:193], v165 offset:1024
	ds_read_b128 v[194:197], v165 offset:2048
	ds_read_b128 v[198:201], v165 offset:3072
	s_add_u32 s44, s42, 0xfffc0080
	s_addc_u32 s45, s43, -1
	s_cmp_eq_u32 s59, 12
	s_cselect_b32 s47, s19, s45
	s_cselect_b32 s46, s55, s44
	s_cselect_b32 s45, s17, s58
	s_cselect_b32 s44, s56, s57
	s_add_i32 m0, s28, 0xc000
	ds_read_b128 v[202:205], v169
	ds_read_b128 v[206:209], v169 offset:1024
	ds_read_b128 v[210:213], v169 offset:2048
	ds_read_b128 v[214:217], v169 offset:3072
	ds_read_b128 v[218:221], v169 offset:4096
	ds_read_b128 v[222:225], v169 offset:5120
	ds_read_b128 v[226:229], v169 offset:6144
	ds_read_b128 v[232:235], v169 offset:7168
	global_load_lds_dwordx4 v138, s[42:43]
	s_add_i32 m0, s28, 0xe000
	s_nop 0
	global_load_lds_dwordx4 v140, s[42:43]
	s_waitcnt vmcnt(8)
	s_waitcnt lgkmcnt(0)
	s_barrier
	s_setprio 1
	s_waitcnt lgkmcnt(0)
	v_mfma_f32_16x16x32_bf16 v[124:127], v[144:147], v[202:205], v[124:127]
	v_mfma_f32_16x16x32_bf16 v[116:119], v[178:181], v[202:205], v[116:119]
	v_mfma_f32_16x16x32_bf16 v[108:111], v[144:147], v[210:213], v[108:111]
	v_mfma_f32_16x16x32_bf16 v[100:103], v[178:181], v[210:213], v[100:103]
	v_mfma_f32_16x16x32_bf16 v[92:95], v[144:147], v[218:221], v[92:95]
	v_mfma_f32_16x16x32_bf16 v[84:87], v[178:181], v[218:221], v[84:87]
	v_mfma_f32_16x16x32_bf16 v[76:79], v[144:147], v[226:229], v[76:79]
	v_mfma_f32_16x16x32_bf16 v[68:71], v[178:181], v[226:229], v[68:71]
	v_mfma_f32_16x16x32_bf16 v[124:127], v[170:173], v[206:209], v[124:127]
	v_mfma_f32_16x16x32_bf16 v[116:119], v[182:185], v[206:209], v[116:119]
	v_mfma_f32_16x16x32_bf16 v[108:111], v[170:173], v[214:217], v[108:111]
	v_mfma_f32_16x16x32_bf16 v[100:103], v[182:185], v[214:217], v[100:103]
	v_mfma_f32_16x16x32_bf16 v[92:95], v[170:173], v[222:225], v[92:95]
	v_mfma_f32_16x16x32_bf16 v[84:87], v[182:185], v[222:225], v[84:87]
	v_mfma_f32_16x16x32_bf16 v[76:79], v[170:173], v[232:235], v[76:79]
	v_mfma_f32_16x16x32_bf16 v[68:71], v[182:185], v[232:235], v[68:71]
	s_setprio 0
	s_setprio 1
	v_mfma_f32_16x16x32_bf16 v[120:123], v[186:189], v[202:205], v[120:123]
	v_mfma_f32_16x16x32_bf16 v[112:115], v[194:197], v[202:205], v[112:115]
	v_mfma_f32_16x16x32_bf16 v[104:107], v[186:189], v[210:213], v[104:107]
	v_mfma_f32_16x16x32_bf16 v[96:99], v[194:197], v[210:213], v[96:99]
	v_mfma_f32_16x16x32_bf16 v[88:91], v[186:189], v[218:221], v[88:91]
	v_mfma_f32_16x16x32_bf16 v[80:83], v[194:197], v[218:221], v[80:83]
	v_mfma_f32_16x16x32_bf16 v[72:75], v[186:189], v[226:229], v[72:75]
	v_mfma_f32_16x16x32_bf16 v[64:67], v[194:197], v[226:229], v[64:67]
	v_mfma_f32_16x16x32_bf16 v[120:123], v[190:193], v[206:209], v[120:123]
	v_mfma_f32_16x16x32_bf16 v[112:115], v[198:201], v[206:209], v[112:115]
	v_mfma_f32_16x16x32_bf16 v[104:107], v[190:193], v[214:217], v[104:107]
	v_mfma_f32_16x16x32_bf16 v[96:99], v[198:201], v[214:217], v[96:99]
	v_mfma_f32_16x16x32_bf16 v[88:91], v[190:193], v[222:225], v[88:91]
	v_mfma_f32_16x16x32_bf16 v[80:83], v[198:201], v[222:225], v[80:83]
	v_mfma_f32_16x16x32_bf16 v[72:75], v[190:193], v[232:235], v[72:75]
	v_mfma_f32_16x16x32_bf16 v[64:67], v[198:201], v[232:235], v[64:67]
	s_setprio 0
	s_barrier
	s_add_i32 s60, s51, s25
	v_lshl_add_u64 v[150:151], s[44:45], 0, v[130:131]
	s_mov_b32 m0, s60
	ds_read_b128 v[202:205], v169 offset:16384
	ds_read_b128 v[206:209], v169 offset:17408
	ds_read_b128 v[210:213], v169 offset:18432
	ds_read_b128 v[214:217], v169 offset:19456
	ds_read_b128 v[218:221], v169 offset:20480
	ds_read_b128 v[222:225], v169 offset:21504
	ds_read_b128 v[226:229], v169 offset:22528
	ds_read_b128 v[232:235], v169 offset:23552
	global_load_lds_dwordx4 v[150:151], off
	s_add_i32 m0, s60, 0x2000
	s_add_u32 s60, s44, 0x40000
	v_lshl_add_u64 v[154:155], s[44:45], 0, v[134:135]
	s_addc_u32 s61, s45, 0
	s_add_i32 s62, s52, s25
	global_load_lds_dwordx4 v[154:155], off
	s_mov_b32 m0, s62
	v_lshl_add_u64 v[162:163], s[46:47], 0, v[132:133]
	global_load_lds_dwordx4 v130, s[60:61]
	s_add_i32 m0, s62, 0x2000
	s_nop 0
	global_load_lds_dwordx4 v134, s[60:61]
	v_lshl_add_u64 v[158:159], s[46:47], 0, v[128:129]
	s_mov_b32 m0, s28
	s_nop 0
	global_load_lds_dwordx4 v[158:159], off
	s_mov_b32 m0, s29
	s_nop 0
	global_load_lds_dwordx4 v[162:163], off
	s_cmp_lg_i32 s59, -2
	s_cbranch_scc1 .Lrsa_a
	v_lshrrev_b32_e32 v250, 6, v230
	v_lshlrev_b32_e32 v250, 11, v250
	v_and_b32_e32 v251, 63, v230
	v_lshl_or_b32 v250, v251, 4, v250
	v_lshl_add_u32 v250, s40, 14, v250
	v_readfirstlane_b32 s98, v230
	s_lshr_b32 s98, s98, 6
	s_lshl_b32 s98, s98, 11
	s_add_i32 m0, s98, 0x20000
	s_add_u32 s100, s70, 0x3f000000
	s_addc_u32 s101, s71, 0
	global_load_lds_dwordx4 v250, s[100:101]
	global_load_lds_dwordx4 v250, s[100:101] offset:1024
	s_waitcnt vmcnt(10)
	s_branch .Lrsa_b

; #define PG8_STAGE(bufoff, gbase, voff) do { _Pragma("unroll") for (int _i = 0; _i < 2; ++_i) \
;         __builtin_amdgcn_global_load_lds((const unsigned*)((const char*)(gbase) + (voff)[_i]), (PG8_LAS unsigned*)(lds + (bufoff) + ldsw + _i * 8192), 16, 0, 0); } while (0)
; #define PG8_LDA(dst, b, h) do { _Pragma("unroll") for (int m = 0; m < 4; ++m) _Pragma("unroll") for (int k = 0; k < 2; ++k) dst[m][k] = *(const PG8_LAS bf16x8*)(lds + PG8_SA(b, h) + aoff + m * 2048 + k * 1024); } while (0)
; #define PG8_LDB(dst, b, h) do { _Pragma("unroll") for (int n = 0; n < 2; ++n) _Pragma("unroll") for (int k = 0; k < 2; ++k) dst[n][k] = *(const PG8_LAS bf16x8*)(lds + PG8_SB(b, h) + boff + n * 2048 + k * 1024); } while (0)
; #define PG8_MMA(ai, bj, At, Bt) do { __builtin_amdgcn_s_setprio(1); _Pragma("unroll") for (int m = 0; m < 4; ++m) _Pragma("unroll") for (int n = 0; n < 2; ++n) _Pragma("unroll") for (int k = 0; k < 2; ++k) \
;         acc[ai][bj][m][n] = __builtin_amdgcn_mfma_f32_16x16x32_bf16(Bt[n][k], At[m][k], acc[ai][bj][m][n], 0, 0, 0); __builtin_amdgcn_s_setprio(0); } while (0)
; #define PG8_WAIT_V(n) asm volatile("s_waitcnt vmcnt(" #n ")" ::: "memory")
; #define PG8_WAIT_L(n) asm volatile("s_waitcnt lgkmcnt(" #n ")" ::: "memory")
; #define PG8_BAR __builtin_amdgcn_s_barrier()
; #define PG8_SCHED __builtin_amdgcn_sched_barrier(0)
; template <class Epi, class Sched, bool ALIGN_EPI = false, bool SP2 = false>
; __device__ __forceinline__ void gemm_phase(PG8_LAS unsigned char* lds, const Gemm g, const Sched& S, const Epi& E) {
;     ...
;             PG8_WAIT_V(8); PG8_WAIT_L(0); PG8_BAR; PG8_MMA(0, 0, At, B0); PG8_MMA(0, 1, At, B1); PG8_BAR; PG8_SCHED;
;             PG8_LDA(At, 0, 1); PG8_STAGE(PG8_SB(0, 0), b2, voffB); PG8_STAGE(PG8_SB(0, 1), b2 + hstep, voffB); PG8_STAGE(PG8_SA(0, 0), a2, voffA);
;             PG8_WAIT_V(8); PG8_WAIT_L(0); PG8_BAR; PG8_MMA(1, 0, At, B0); PG8_MMA(1, 1, At, B1); PG8_BAR; PG8_SCHED;
;             PG8_LDB(B0, 1, 0); PG8_LDB(B1, 1, 1); PG8_SCHED; PG8_LDA(At, 1, 0); PG8_STAGE(PG8_SA(0, 1), a2 + hstep, voffA);
;             PG8_WAIT_V(8); PG8_WAIT_L(0); PG8_BAR; PG8_MMA(0, 0, At, B0); PG8_MMA(0, 1, At, B1); PG8_BAR; PG8_SCHED;
.Lrsa_b:
	s_waitcnt lgkmcnt(0)
	s_barrier
	s_setprio 1
	s_waitcnt lgkmcnt(0)
	v_mfma_f32_16x16x32_bf16 v[60:63], v[144:147], v[202:205], v[60:63]
	v_mfma_f32_16x16x32_bf16 v[52:55], v[178:181], v[202:205], v[52:55]
	v_mfma_f32_16x16x32_bf16 v[44:47], v[144:147], v[210:213], v[44:47]
	v_mfma_f32_16x16x32_bf16 v[36:39], v[178:181], v[210:213], v[36:39]
	v_mfma_f32_16x16x32_bf16 v[28:31], v[144:147], v[218:221], v[28:31]
	v_mfma_f32_16x16x32_bf16 v[20:23], v[178:181], v[218:221], v[20:23]
	v_mfma_f32_16x16x32_bf16 v[12:15], v[144:147], v[226:229], v[12:15]
	v_mfma_f32_16x16x32_bf16 v[4:7], v[178:181], v[226:229], v[4:7]
	v_mfma_f32_16x16x32_bf16 v[60:63], v[170:173], v[206:209], v[60:63]
	v_mfma_f32_16x16x32_bf16 v[52:55], v[182:185], v[206:209], v[52:55]
	v_mfma_f32_16x16x32_bf16 v[44:47], v[170:173], v[214:217], v[44:47]
	v_mfma_f32_16x16x32_bf16 v[36:39], v[182:185], v[214:217], v[36:39]
	v_mfma_f32_16x16x32_bf16 v[28:31], v[170:173], v[222:225], v[28:31]
	v_mfma_f32_16x16x32_bf16 v[20:23], v[182:185], v[222:225], v[20:23]
	v_mfma_f32_16x16x32_bf16 v[12:15], v[170:173], v[232:235], v[12:15]
	v_mfma_f32_16x16x32_bf16 v[4:7], v[182:185], v[232:235], v[4:7]
	s_setprio 0
	s_setprio 1
	v_mfma_f32_16x16x32_bf16 v[56:59], v[186:189], v[202:205], v[56:59]
	v_mfma_f32_16x16x32_bf16 v[48:51], v[194:197], v[202:205], v[48:51]
	v_mfma_f32_16x16x32_bf16 v[40:43], v[186:189], v[210:213], v[40:43]
	v_mfma_f32_16x16x32_bf16 v[32:35], v[194:197], v[210:213], v[32:35]
	v_mfma_f32_16x16x32_bf16 v[24:27], v[186:189], v[218:221], v[24:27]
	v_mfma_f32_16x16x32_bf16 v[16:19], v[194:197], v[218:221], v[16:19]
	v_mfma_f32_16x16x32_bf16 v[8:11], v[186:189], v[226:229], v[8:11]
	v_mfma_f32_16x16x32_bf16 v[0:3], v[194:197], v[226:229], v[0:3]
	v_mfma_f32_16x16x32_bf16 v[56:59], v[190:193], v[206:209], v[56:59]
	v_mfma_f32_16x16x32_bf16 v[48:51], v[198:201], v[206:209], v[48:51]
	v_mfma_f32_16x16x32_bf16 v[40:43], v[190:193], v[214:217], v[40:43]
	v_mfma_f32_16x16x32_bf16 v[32:35], v[198:201], v[214:217], v[32:35]
	v_mfma_f32_16x16x32_bf16 v[24:27], v[190:193], v[222:225], v[24:27]
	v_mfma_f32_16x16x32_bf16 v[16:19], v[198:201], v[222:225], v[16:19]
	v_mfma_f32_16x16x32_bf16 v[8:11], v[190:193], v[232:235], v[8:11]
	v_mfma_f32_16x16x32_bf16 v[0:3], v[198:201], v[232:235], v[0:3]
	s_setprio 0
	s_barrier
	s_add_i32 s60, 0, 0x18000
	v_add_u32_e32 v148, s60, v153
	s_add_i32 s61, 0, 0x1c000
	ds_read_b128 v[144:147], v148
	ds_read_b128 v[170:173], v148 offset:1024
	ds_read_b128 v[178:181], v148 offset:2048
	ds_read_b128 v[182:185], v148 offset:3072
	v_add_u32_e32 v148, s61, v153
	ds_read_b128 v[186:189], v148
	ds_read_b128 v[190:193], v148 offset:1024
	ds_read_b128 v[194:197], v148 offset:2048
	ds_read_b128 v[198:201], v148 offset:3072
	s_add_u32 s46, s46, 0x40000
	s_addc_u32 s47, s47, 0
	s_mov_b32 m0, s30
	ds_read_b128 v[202:205], v169 offset:32768
	ds_read_b128 v[206:209], v169 offset:33792
	ds_read_b128 v[210:213], v169 offset:34816
	ds_read_b128 v[214:217], v169 offset:35840
	ds_read_b128 v[218:221], v169 offset:36864
	ds_read_b128 v[222:225], v169 offset:37888
	ds_read_b128 v[226:229], v169 offset:38912
	ds_read_b128 v[232:235], v169 offset:39936
	global_load_lds_dwordx4 v128, s[46:47]
	v_lshl_add_u64 v[166:167], s[46:47], 0, v[132:133]
	s_mov_b32 m0, s31
	s_nop 0
	global_load_lds_dwordx4 v[166:167], off
	s_cmp_lg_i32 s59, -2
	s_cbranch_scc1 .Lrsa_c
	s_waitcnt vmcnt(10)
	s_branch .Lrsa_d

; #define PG8_STAGE(bufoff, gbase, voff) do { _Pragma("unroll") for (int _i = 0; _i < 2; ++_i) \
;         __builtin_amdgcn_global_load_lds((const unsigned*)((const char*)(gbase) + (voff)[_i]), (PG8_LAS unsigned*)(lds + (bufoff) + ldsw + _i * 8192), 16, 0, 0); } while (0)
; #define PG8_LDA(dst, b, h) do { _Pragma("unroll") for (int m = 0; m < 4; ++m) _Pragma("unroll") for (int k = 0; k < 2; ++k) dst[m][k] = *(const PG8_LAS bf16x8*)(lds + PG8_SA(b, h) + aoff + m * 2048 + k * 1024); } while (0)
; #define PG8_MMA(ai, bj, At, Bt) do { __builtin_amdgcn_s_setprio(1); _Pragma("unroll") for (int m = 0; m < 4; ++m) _Pragma("unroll") for (int n = 0; n < 2; ++n) _Pragma("unroll") for (int k = 0; k < 2; ++k) \
;         acc[ai][bj][m][n] = __builtin_amdgcn_mfma_f32_16x16x32_bf16(Bt[n][k], At[m][k], acc[ai][bj][m][n], 0, 0, 0); __builtin_amdgcn_s_setprio(0); } while (0)
; #define PG8_WAIT_V(n) asm volatile("s_waitcnt vmcnt(" #n ")" ::: "memory")
; #define PG8_WAIT_L(n) asm volatile("s_waitcnt lgkmcnt(" #n ")" ::: "memory")
; #define PG8_BAR __builtin_amdgcn_s_barrier()
; #define PG8_SCHED __builtin_amdgcn_sched_barrier(0)
; template <class Epi, class Sched, bool ALIGN_EPI = false, bool SP2 = false>
; __device__ __forceinline__ void gemm_phase(PG8_LAS unsigned char* lds, const Gemm g, const Sched& S, const Epi& E) {
;     ...
;             PG8_WAIT_V(8); PG8_WAIT_L(0); PG8_BAR; PG8_MMA(0, 0, At, B0); PG8_MMA(0, 1, At, B1); PG8_BAR; PG8_SCHED;
;             PG8_LDA(At, 1, 1); PG8_STAGE(PG8_SB(1, 0), b3, voffB); PG8_STAGE(PG8_SB(1, 1), b3 + hstep, voffB); PG8_STAGE(PG8_SA(1, 0), a3, voffA);
;             PG8_WAIT_V(8); PG8_WAIT_L(0); PG8_BAR; PG8_MMA(1, 0, At, B0); PG8_MMA(1, 1, At, B1); PG8_BAR; PG8_SCHED;
;     ...
;         if constexpr (ALIGN_EPI) { if (wr == 0) PG8_BAR; }
.Lrsa_d:
	s_waitcnt lgkmcnt(0)
	s_barrier
	s_setprio 1
	s_waitcnt lgkmcnt(0)
	v_mfma_f32_16x16x32_bf16 v[124:127], v[144:147], v[202:205], v[124:127]
	v_mfma_f32_16x16x32_bf16 v[116:119], v[178:181], v[202:205], v[116:119]
	v_mfma_f32_16x16x32_bf16 v[108:111], v[144:147], v[210:213], v[108:111]
	v_mfma_f32_16x16x32_bf16 v[100:103], v[178:181], v[210:213], v[100:103]
	v_mfma_f32_16x16x32_bf16 v[92:95], v[144:147], v[218:221], v[92:95]
	v_mfma_f32_16x16x32_bf16 v[84:87], v[178:181], v[218:221], v[84:87]
	v_mfma_f32_16x16x32_bf16 v[76:79], v[144:147], v[226:229], v[76:79]
	v_mfma_f32_16x16x32_bf16 v[68:71], v[178:181], v[226:229], v[68:71]
	v_mfma_f32_16x16x32_bf16 v[124:127], v[170:173], v[206:209], v[124:127]
	v_mfma_f32_16x16x32_bf16 v[116:119], v[182:185], v[206:209], v[116:119]
	v_mfma_f32_16x16x32_bf16 v[108:111], v[170:173], v[214:217], v[108:111]
	v_mfma_f32_16x16x32_bf16 v[100:103], v[182:185], v[214:217], v[100:103]
	v_mfma_f32_16x16x32_bf16 v[92:95], v[170:173], v[222:225], v[92:95]
	v_mfma_f32_16x16x32_bf16 v[84:87], v[182:185], v[222:225], v[84:87]
	v_mfma_f32_16x16x32_bf16 v[76:79], v[170:173], v[232:235], v[76:79]
	v_mfma_f32_16x16x32_bf16 v[68:71], v[182:185], v[232:235], v[68:71]
	s_setprio 0
	s_setprio 1
	v_mfma_f32_16x16x32_bf16 v[120:123], v[186:189], v[202:205], v[120:123]
	v_mfma_f32_16x16x32_bf16 v[112:115], v[194:197], v[202:205], v[112:115]
	v_mfma_f32_16x16x32_bf16 v[104:107], v[186:189], v[210:213], v[104:107]
	v_mfma_f32_16x16x32_bf16 v[96:99], v[194:197], v[210:213], v[96:99]
	v_mfma_f32_16x16x32_bf16 v[88:91], v[186:189], v[218:221], v[88:91]
	v_mfma_f32_16x16x32_bf16 v[80:83], v[194:197], v[218:221], v[80:83]
	v_mfma_f32_16x16x32_bf16 v[72:75], v[186:189], v[226:229], v[72:75]
	v_mfma_f32_16x16x32_bf16 v[64:67], v[194:197], v[226:229], v[64:67]
	v_mfma_f32_16x16x32_bf16 v[120:123], v[190:193], v[206:209], v[120:123]
	v_mfma_f32_16x16x32_bf16 v[112:115], v[198:201], v[206:209], v[112:115]
	v_mfma_f32_16x16x32_bf16 v[104:107], v[190:193], v[214:217], v[104:107]
	v_mfma_f32_16x16x32_bf16 v[96:99], v[198:201], v[214:217], v[96:99]
	v_mfma_f32_16x16x32_bf16 v[88:91], v[190:193], v[222:225], v[88:91]
	v_mfma_f32_16x16x32_bf16 v[80:83], v[198:201], v[222:225], v[80:83]
	v_mfma_f32_16x16x32_bf16 v[72:75], v[190:193], v[232:235], v[72:75]
	v_mfma_f32_16x16x32_bf16 v[64:67], v[198:201], v[232:235], v[64:67]
	s_setprio 0
	s_barrier
	s_add_i32 s46, s60, s25
	v_lshl_add_u64 v[150:151], v[150:151], 0, s[8:9]
	s_mov_b32 m0, s46
	ds_read_b128 v[202:205], v169 offset:49152
	ds_read_b128 v[206:209], v169 offset:50176
	ds_read_b128 v[210:213], v169 offset:51200
	ds_read_b128 v[214:217], v169 offset:52224
	ds_read_b128 v[218:221], v169 offset:53248
	ds_read_b128 v[222:225], v169 offset:54272
	ds_read_b128 v[226:229], v169 offset:55296
	ds_read_b128 v[232:235], v169 offset:56320
	global_load_lds_dwordx4 v[150:151], off
	s_add_i32 m0, s46, 0x2000
	s_add_u32 s44, s44, 0x40080
	v_lshl_add_u64 v[150:151], v[154:155], 0, s[8:9]
	s_addc_u32 s45, s45, 0
	s_add_i32 s46, s61, s25
	global_load_lds_dwordx4 v[150:151], off
	s_mov_b32 m0, s46
	s_nop 0
	global_load_lds_dwordx4 v130, s[44:45]
	s_add_i32 m0, s46, 0x2000
	s_nop 0
	global_load_lds_dwordx4 v134, s[44:45]
	v_lshl_add_u64 v[150:151], v[158:159], 0, s[8:9]
	s_mov_b32 m0, s48
	s_nop 0
	global_load_lds_dwordx4 v[150:151], off
	v_lshl_add_u64 v[150:151], v[162:163], 0, s[8:9]
	s_mov_b32 m0, s49
	s_nop 0
	global_load_lds_dwordx4 v[150:151], off
	s_waitcnt vmcnt(8)
	s_waitcnt lgkmcnt(0)
	s_barrier
	s_setprio 1
	s_waitcnt lgkmcnt(0)
	v_mfma_f32_16x16x32_bf16 v[60:63], v[144:147], v[202:205], v[60:63]
	v_mfma_f32_16x16x32_bf16 v[52:55], v[178:181], v[202:205], v[52:55]
	v_mfma_f32_16x16x32_bf16 v[44:47], v[144:147], v[210:213], v[44:47]
	v_mfma_f32_16x16x32_bf16 v[36:39], v[178:181], v[210:213], v[36:39]
	v_mfma_f32_16x16x32_bf16 v[28:31], v[144:147], v[218:221], v[28:31]
	v_mfma_f32_16x16x32_bf16 v[20:23], v[178:181], v[218:221], v[20:23]
	v_mfma_f32_16x16x32_bf16 v[12:15], v[144:147], v[226:229], v[12:15]
	v_mfma_f32_16x16x32_bf16 v[4:7], v[178:181], v[226:229], v[4:7]
	v_mfma_f32_16x16x32_bf16 v[60:63], v[170:173], v[206:209], v[60:63]
	v_mfma_f32_16x16x32_bf16 v[52:55], v[182:185], v[206:209], v[52:55]
	v_mfma_f32_16x16x32_bf16 v[44:47], v[170:173], v[214:217], v[44:47]
	v_mfma_f32_16x16x32_bf16 v[36:39], v[182:185], v[214:217], v[36:39]
	v_mfma_f32_16x16x32_bf16 v[28:31], v[170:173], v[222:225], v[28:31]
	v_mfma_f32_16x16x32_bf16 v[20:23], v[182:185], v[222:225], v[20:23]
	v_mfma_f32_16x16x32_bf16 v[12:15], v[170:173], v[232:235], v[12:15]
	v_mfma_f32_16x16x32_bf16 v[4:7], v[182:185], v[232:235], v[4:7]
	s_setprio 0
	s_setprio 1
	v_mfma_f32_16x16x32_bf16 v[56:59], v[186:189], v[202:205], v[56:59]
	v_mfma_f32_16x16x32_bf16 v[48:51], v[194:197], v[202:205], v[48:51]
	v_mfma_f32_16x16x32_bf16 v[40:43], v[186:189], v[210:213], v[40:43]
	v_mfma_f32_16x16x32_bf16 v[32:35], v[194:197], v[210:213], v[32:35]
	v_mfma_f32_16x16x32_bf16 v[24:27], v[186:189], v[218:221], v[24:27]
	v_mfma_f32_16x16x32_bf16 v[16:19], v[194:197], v[218:221], v[16:19]
	v_mfma_f32_16x16x32_bf16 v[8:11], v[186:189], v[226:229], v[8:11]
	v_mfma_f32_16x16x32_bf16 v[0:3], v[194:197], v[226:229], v[0:3]
	v_mfma_f32_16x16x32_bf16 v[56:59], v[190:193], v[206:209], v[56:59]
	v_mfma_f32_16x16x32_bf16 v[48:51], v[198:201], v[206:209], v[48:51]
	v_mfma_f32_16x16x32_bf16 v[40:43], v[190:193], v[214:217], v[40:43]
	v_mfma_f32_16x16x32_bf16 v[32:35], v[198:201], v[214:217], v[32:35]
	v_mfma_f32_16x16x32_bf16 v[24:27], v[190:193], v[222:225], v[24:27]
	v_mfma_f32_16x16x32_bf16 v[16:19], v[198:201], v[222:225], v[16:19]
	v_mfma_f32_16x16x32_bf16 v[8:11], v[190:193], v[232:235], v[8:11]
	v_mfma_f32_16x16x32_bf16 v[0:3], v[198:201], v[232:235], v[0:3]
	s_setprio 0
	s_barrier
	s_add_i32 s59, s59, 2
	s_add_u32 s42, s42, 0x100
	s_addc_u32 s43, s43, 0
	s_add_u32 s57, s57, 0x100
	s_addc_u32 s58, s58, 0
	s_cmp_gt_u32 s59, 13
	s_cbranch_scc0 .LBB0_482
	s_and_b64 vcc, exec, s[12:13]
	s_cbranch_vccz .LBB0_485
	s_barrier

; #define PG8_STAGE(bufoff, gbase, voff) do { _Pragma("unroll") for (int _i = 0; _i < 2; ++_i) \
;         __builtin_amdgcn_global_load_lds((const unsigned*)((const char*)(gbase) + (voff)[_i]), (PG8_LAS unsigned*)(lds + (bufoff) + ldsw + _i * 8192), 16, 0, 0); } while (0)
; #define PG8_WAIT_V(n) asm volatile("s_waitcnt vmcnt(" #n ")" ::: "memory")
; #define PG8_BAR __builtin_amdgcn_s_barrier()
; template <class Epi, class Sched, bool ALIGN_EPI = false, bool SP2 = false>
; __device__ __forceinline__ void gemm_phase(PG8_LAS unsigned char* lds, const Gemm g, const Sched& S, const Epi& E) {
;     const int tid = threadIdx.x, wid = __builtin_amdgcn_readfirstlane(tid >> 6), lane = tid & 63, wr = wid >> 2, wc = wid & 3, fr = lane & 15, fq = lane >> 4;
;     const int K = g.K, nt = K / BK;
;     unsigned voffA[2], voffB[2];
; #pragma unroll
;     for (int i = 0; i < 2; ++i) { int R, C; stage_rc(tid * 16 + i * 8192, R, C); const int Rb = Epi::PERM ? ((R & ~31) + perm32(R & 31)) : R;
;         voffA[i] = (unsigned)(R * K + C) * 2u; voffB[i] = (unsigned)(Rb * K + C) * 2u; }
;     const size_t kstep = (size_t)(BK * 2);
;     const size_t hstep = (size_t)HALF * K * 2;
;     const size_t tstep = 2 * hstep;
;     const unsigned ldsw = (unsigned)wid * 1024u;
;     const int aoff = lds_byte(wr * 64 + fr, fq * 8), boff = lds_byte(wc * 32 + fr, fq * 8);
;     ...
;         PG8_STAGE(PG8_SB(1, 0), cB + kstep, voffB); PG8_STAGE(PG8_SA(1, 0), cA + kstep, voffA); PG8_STAGE(PG8_SB(1, 1), cB + hstep + kstep, voffB);
;         PG8_WAIT_V(6); PG8_BAR;
.LBB0_555:
	s_mov_b64 s[20:21], 0x80
	s_and_b32 s30, s1, 3
	s_add_i32 m0, s26, 0x18000
	v_lshl_add_u64 v[6:7], v[6:7], 0, s[20:21]
	s_lshl_b32 s1, s0, 13
	s_lshl_b32 s5, s30, 12
	s_waitcnt vmcnt(2)
	s_barrier
	global_load_lds_dwordx4 v[6:7], off
	v_lshl_add_u64 v[4:5], v[4:5], 0, s[20:21]
	s_add_i32 m0, s26, 0x1a000
	s_add_i32 s31, s26, 0x8000
	s_add_i32 s33, s26, 0xa000
	global_load_lds_dwordx4 v[4:5], off
	v_lshl_add_u64 v[0:1], v[0:1], 0, s[20:21]
	s_mov_b32 m0, s31
	s_add_u32 s36, s44, 0xb0080
	global_load_lds_dwordx4 v[0:1], off
	v_lshl_add_u64 v[0:1], v[2:3], 0, s[20:21]
	s_mov_b32 m0, s33
	s_addc_u32 s37, s45, 0
	global_load_lds_dwordx4 v[0:1], off
	s_add_i32 m0, s26, 0x1c000
	global_load_lds_dwordx4 v186, s[36:37]
	v_lshl_add_u64 v[0:1], s[36:37], 0, v[190:191]
	s_add_i32 m0, s26, 0x1e000
	v_lshlrev_b32_e32 v4, 2, v230
	global_load_lds_dwordx4 v[0:1], off
	v_bfe_u32 v0, v230, 4, 2
	v_and_b32_e32 v1, 15, v230
	v_lshlrev_b32_e32 v3, 4, v0
	v_lshl_or_b32 v231, s0, 6, v1
	v_lshl_or_b32 v1, v1, 6, v3
	v_and_b32_e32 v4, 32, v4
	v_lshlrev_b32_e32 v5, 6, v230
	s_movk_i32 s0, 0x3c0
	v_lshlrev_b32_e32 v2, 3, v0
	v_bitop3_b32 v1, v1, s1, v4 bitop3:0xde
	v_and_or_b32 v3, v5, s0, v3
	v_cmp_eq_u32_e64 s[0:1], 0, v0
	v_add_u16_e32 v0, v8, v9
	s_waitcnt vmcnt(6)
	s_cmpk_lt_u32 s4, 0x100
	v_lshrrev_b16_e32 v0, 1, v0
	v_bitop3_b32 v232, s5, v3, v4 bitop3:0xf6
	s_cselect_b64 s[36:37], -1, 0
	v_add_lshl_u32 v192, v10, v0, 1
	v_add_lshl_u32 v194, v11, v0, 1
	s_add_i32 s50, 0, 0x10000
	s_add_i32 s51, 0, 0x14000
	v_mbcnt_lo_u32_b32 v0, -1, 0
	v_lshl_or_b32 v233, s30, 5, v2
	s_add_i32 s48, s22, -2
	s_ashr_i32 s49, s2, 31
	v_mov_b32_e32 v193, v187
	v_mov_b32_e32 v195, v187
	v_add_u32_e32 v234, s50, v232
	v_add_u32_e32 v235, s51, v232
	v_add_u32_e32 v236, 0, v1
	v_mbcnt_hi_u32_b32 v237, -1, v0
	v_mov_b64_e32 v[196:197], 0x7ff
	s_mov_b32 s4, 0
	s_barrier
	s_branch .LBB0_558

; #define PG8_STAGE(bufoff, gbase, voff) do { _Pragma("unroll") for (int _i = 0; _i < 2; ++_i) \
;         __builtin_amdgcn_global_load_lds((const unsigned*)((const char*)(gbase) + (voff)[_i]), (PG8_LAS unsigned*)(lds + (bufoff) + ldsw + _i * 8192), 16, 0, 0); } while (0)
; #define PG8_LDA(dst, b, h) do { _Pragma("unroll") for (int m = 0; m < 4; ++m) _Pragma("unroll") for (int k = 0; k < 2; ++k) dst[m][k] = *(const PG8_LAS bf16x8*)(lds + PG8_SA(b, h) + aoff + m * 2048 + k * 1024); } while (0)
; #define PG8_LDB(dst, b, h) do { _Pragma("unroll") for (int n = 0; n < 2; ++n) _Pragma("unroll") for (int k = 0; k < 2; ++k) dst[n][k] = *(const PG8_LAS bf16x8*)(lds + PG8_SB(b, h) + boff + n * 2048 + k * 1024); } while (0)
; #define PG8_WAIT_V(n) asm volatile("s_waitcnt vmcnt(" #n ")" ::: "memory")
; #define PG8_WAIT_L(n) asm volatile("s_waitcnt lgkmcnt(" #n ")" ::: "memory")
; #define PG8_BAR __builtin_amdgcn_s_barrier()
; #define PG8_SCHED __builtin_amdgcn_sched_barrier(0)
; template <class Epi, class Sched, bool ALIGN_EPI = false, bool SP2 = false>
; __device__ __forceinline__ void gemm_phase(PG8_LAS unsigned char* lds, const Gemm g, const Sched& S, const Epi& E) {
;     ...
;         const bool has_next = S.next(ui + 1, nxt);
;         const char* nA = has_next ? (const char*)g.A + (size_t)nxt.pm * tstep : cA; const char* nB = has_next ? (const char*)g.Bt + (size_t)nxt.pn * tstep : cB;
;         for (int t = 0; t < nt; t += 2) {
;             const bool last = (t == nt - 2);
;             const char* a1 = cA + (size_t)(t + 1) * kstep;
;             const char* a2 = last ? nA : cA + (size_t)(t + 2) * kstep; const char* b2 = last ? nB : cB + (size_t)(t + 2) * kstep;
;             const char* a3 = a2 + kstep; const char* b3 = b2 + kstep;
;             if (last && has_next) S.a_ready(nxt);
;             if constexpr (SP2) {
;             PG8_LDB(B0, 0, 0); PG8_LDB(B1, 0, 1); PG8_SCHED; PG8_LDA(At, 0, 0); PG8_STAGE(PG8_SA(1, 1), a1 + hstep, voffA);
;             PG8_WAIT_V(8); PG8_WAIT_L(0); PG8_BAR; PG8_MMA(0, 0, At, B0); PG8_MMA(0, 1, At, B1); PG8_BAR; PG8_SCHED;
;             PG8_LDA(At, 0, 1); PG8_STAGE(PG8_SB(0, 0), b2, voffB); PG8_STAGE(PG8_SB(0, 1), b2 + hstep, voffB); PG8_STAGE(PG8_SA(0, 0), a2, voffA);
;             PG8_WAIT_V(8); PG8_WAIT_L(0); PG8_BAR; PG8_MMA(1, 0, At, B0); PG8_MMA(1, 1, At, B1); PG8_BAR; PG8_SCHED;
.LBB0_569:
	s_add_u32 s42, s42, 0xb0080
	s_addc_u32 s43, s43, 0
	s_add_u32 s56, s44, 0x100
	s_addc_u32 s57, s45, 0
	s_mov_b32 s58, -2
	s_waitcnt lgkmcnt(0)
	ds_read_b128 v[124:127], v234
	ds_read_b128 v[132:135], v234 offset:1024
	ds_read_b128 v[136:139], v234 offset:2048
	ds_read_b128 v[140:143], v234 offset:3072
	ds_read_b128 v[144:147], v235
	ds_read_b128 v[148:151], v235 offset:1024
	ds_read_b128 v[152:155], v235 offset:2048
	ds_read_b128 v[156:159], v235 offset:3072
	s_add_u32 s44, s42, 0xfff50080
	s_addc_u32 s45, s43, -1
	s_cmp_eq_u32 s58, 40
	s_cselect_b32 s47, s39, s45
	s_cselect_b32 s46, s38, s44
	s_cselect_b32 s45, s41, s57
	s_cselect_b32 s44, s40, s56
	s_add_i32 m0, s26, 0xc000
	ds_read_b128 v[160:163], v236
	ds_read_b128 v[164:167], v236 offset:1024
	ds_read_b128 v[168:171], v236 offset:2048
	ds_read_b128 v[172:175], v236 offset:3072
	ds_read_b128 v[176:179], v236 offset:4096
	ds_read_b128 v[180:183], v236 offset:5120
	ds_read_b128 v[198:201], v236 offset:6144
	ds_read_b128 v[202:205], v236 offset:7168
	global_load_lds_dwordx4 v192, s[42:43]
	s_add_i32 m0, s26, 0xe000
	s_nop 0
	global_load_lds_dwordx4 v194, s[42:43]
	s_waitcnt vmcnt(8)
	s_waitcnt lgkmcnt(0)
	s_barrier
	s_setprio 1
	s_waitcnt lgkmcnt(0)
	v_mfma_f32_16x16x32_bf16 v[128:131], v[124:127], v[160:163], 0
	v_mfma_f32_16x16x32_bf16 v[120:123], v[136:139], v[160:163], 0
	v_mfma_f32_16x16x32_bf16 v[108:111], v[124:127], v[168:171], 0
	v_mfma_f32_16x16x32_bf16 v[104:107], v[136:139], v[168:171], 0
	v_mfma_f32_16x16x32_bf16 v[92:95], v[124:127], v[176:179], 0
	v_mfma_f32_16x16x32_bf16 v[88:91], v[136:139], v[176:179], 0
	v_mfma_f32_16x16x32_bf16 v[76:79], v[124:127], v[198:201], 0
	v_mfma_f32_16x16x32_bf16 v[72:75], v[136:139], v[198:201], 0
	v_mfma_f32_16x16x32_bf16 v[128:131], v[132:135], v[164:167], v[128:131]
	v_mfma_f32_16x16x32_bf16 v[120:123], v[140:143], v[164:167], v[120:123]
	v_mfma_f32_16x16x32_bf16 v[108:111], v[132:135], v[172:175], v[108:111]
	v_mfma_f32_16x16x32_bf16 v[104:107], v[140:143], v[172:175], v[104:107]
	v_mfma_f32_16x16x32_bf16 v[92:95], v[132:135], v[180:183], v[92:95]
	v_mfma_f32_16x16x32_bf16 v[88:91], v[140:143], v[180:183], v[88:91]
	v_mfma_f32_16x16x32_bf16 v[76:79], v[132:135], v[202:205], v[76:79]
	v_mfma_f32_16x16x32_bf16 v[72:75], v[140:143], v[202:205], v[72:75]
	s_setprio 0
	s_setprio 1
	v_mfma_f32_16x16x32_bf16 v[116:119], v[144:147], v[160:163], 0
	v_mfma_f32_16x16x32_bf16 v[112:115], v[152:155], v[160:163], 0
	v_mfma_f32_16x16x32_bf16 v[100:103], v[144:147], v[168:171], 0
	v_mfma_f32_16x16x32_bf16 v[96:99], v[152:155], v[168:171], 0
	v_mfma_f32_16x16x32_bf16 v[84:87], v[144:147], v[176:179], 0
	v_mfma_f32_16x16x32_bf16 v[80:83], v[152:155], v[176:179], 0
	v_mfma_f32_16x16x32_bf16 v[68:71], v[144:147], v[198:201], 0
	v_mfma_f32_16x16x32_bf16 v[64:67], v[152:155], v[198:201], 0
	v_mfma_f32_16x16x32_bf16 v[116:119], v[148:151], v[164:167], v[116:119]
	v_mfma_f32_16x16x32_bf16 v[112:115], v[156:159], v[164:167], v[112:115]
	v_mfma_f32_16x16x32_bf16 v[100:103], v[148:151], v[172:175], v[100:103]
	v_mfma_f32_16x16x32_bf16 v[96:99], v[156:159], v[172:175], v[96:99]
	v_mfma_f32_16x16x32_bf16 v[84:87], v[148:151], v[180:183], v[84:87]
	v_mfma_f32_16x16x32_bf16 v[80:83], v[156:159], v[180:183], v[80:83]
	v_mfma_f32_16x16x32_bf16 v[68:71], v[148:151], v[202:205], v[68:71]
	v_mfma_f32_16x16x32_bf16 v[64:67], v[156:159], v[202:205], v[64:67]
	s_setprio 0
	s_barrier
	s_add_i32 s59, s50, s25
	v_lshl_add_u64 v[206:207], s[44:45], 0, v[186:187]
	s_mov_b32 m0, s59
	ds_read_b128 v[160:163], v236 offset:16384
	ds_read_b128 v[164:167], v236 offset:17408
	ds_read_b128 v[168:171], v236 offset:18432
	ds_read_b128 v[172:175], v236 offset:19456
	ds_read_b128 v[176:179], v236 offset:20480
	ds_read_b128 v[180:183], v236 offset:21504
	ds_read_b128 v[198:201], v236 offset:22528
	ds_read_b128 v[202:205], v236 offset:23552
	global_load_lds_dwordx4 v[206:207], off
	s_add_i32 m0, s59, 0x2000
	s_add_u32 s60, s44, 0xb0000
	v_lshl_add_u64 v[208:209], s[44:45], 0, v[190:191]
	s_addc_u32 s61, s45, 0
	s_add_i32 s59, s51, s25
	global_load_lds_dwordx4 v[208:209], off
	s_mov_b32 m0, s59
	v_lshl_add_u64 v[212:213], s[46:47], 0, v[188:189]
	global_load_lds_dwordx4 v186, s[60:61]
	s_add_i32 m0, s59, 0x2000
	s_nop 0
	global_load_lds_dwordx4 v190, s[60:61]
	v_lshl_add_u64 v[210:211], s[46:47], 0, v[184:185]
	s_mov_b32 m0, s26
	s_nop 0
	global_load_lds_dwordx4 v[210:211], off
	s_mov_b32 m0, s27
	s_nop 0
	global_load_lds_dwordx4 v[212:213], off
	s_waitcnt vmcnt(8)
	s_waitcnt lgkmcnt(0)
	s_barrier
	s_setprio 1
	s_waitcnt lgkmcnt(0)
	v_mfma_f32_16x16x32_bf16 v[60:63], v[124:127], v[160:163], 0
	v_mfma_f32_16x16x32_bf16 v[56:59], v[136:139], v[160:163], 0
	v_mfma_f32_16x16x32_bf16 v[44:47], v[124:127], v[168:171], 0
	v_mfma_f32_16x16x32_bf16 v[40:43], v[136:139], v[168:171], 0
	v_mfma_f32_16x16x32_bf16 v[28:31], v[124:127], v[176:179], 0
	v_mfma_f32_16x16x32_bf16 v[24:27], v[136:139], v[176:179], 0
	v_mfma_f32_16x16x32_bf16 v[12:15], v[124:127], v[198:201], 0
	v_mfma_f32_16x16x32_bf16 v[8:11], v[136:139], v[198:201], 0
	v_mfma_f32_16x16x32_bf16 v[60:63], v[132:135], v[164:167], v[60:63]
	v_mfma_f32_16x16x32_bf16 v[56:59], v[140:143], v[164:167], v[56:59]
	v_mfma_f32_16x16x32_bf16 v[44:47], v[132:135], v[172:175], v[44:47]
	v_mfma_f32_16x16x32_bf16 v[40:43], v[140:143], v[172:175], v[40:43]
	v_mfma_f32_16x16x32_bf16 v[28:31], v[132:135], v[180:183], v[28:31]
	v_mfma_f32_16x16x32_bf16 v[24:27], v[140:143], v[180:183], v[24:27]
	v_mfma_f32_16x16x32_bf16 v[12:15], v[132:135], v[202:205], v[12:15]
	v_mfma_f32_16x16x32_bf16 v[8:11], v[140:143], v[202:205], v[8:11]
	s_setprio 0
	s_setprio 1
	v_mfma_f32_16x16x32_bf16 v[52:55], v[144:147], v[160:163], 0
	v_mfma_f32_16x16x32_bf16 v[48:51], v[152:155], v[160:163], 0
	v_mfma_f32_16x16x32_bf16 v[36:39], v[144:147], v[168:171], 0
	v_mfma_f32_16x16x32_bf16 v[32:35], v[152:155], v[168:171], 0
	v_mfma_f32_16x16x32_bf16 v[20:23], v[144:147], v[176:179], 0
	v_mfma_f32_16x16x32_bf16 v[16:19], v[152:155], v[176:179], 0
	v_mfma_f32_16x16x32_bf16 v[4:7], v[144:147], v[198:201], 0
	v_mfma_f32_16x16x32_bf16 v[0:3], v[152:155], v[198:201], 0
	v_mfma_f32_16x16x32_bf16 v[52:55], v[148:151], v[164:167], v[52:55]
	v_mfma_f32_16x16x32_bf16 v[48:51], v[156:159], v[164:167], v[48:51]
	v_mfma_f32_16x16x32_bf16 v[36:39], v[148:151], v[172:175], v[36:39]
	v_mfma_f32_16x16x32_bf16 v[32:35], v[156:159], v[172:175], v[32:35]
	v_mfma_f32_16x16x32_bf16 v[20:23], v[148:151], v[180:183], v[20:23]
	v_mfma_f32_16x16x32_bf16 v[16:19], v[156:159], v[180:183], v[16:19]
	v_mfma_f32_16x16x32_bf16 v[4:7], v[148:151], v[202:205], v[4:7]
	v_mfma_f32_16x16x32_bf16 v[0:3], v[156:159], v[202:205], v[0:3]
	s_setprio 0
	s_barrier
; #define PG8_STAGE(bufoff, gbase, voff) do { _Pragma("unroll") for (int _i = 0; _i < 2; ++_i) \
;         __builtin_amdgcn_global_load_lds((const unsigned*)((const char*)(gbase) + (voff)[_i]), (PG8_LAS unsigned*)(lds + (bufoff) + ldsw + _i * 8192), 16, 0, 0); } while (0)
; #define PG8_LDA(dst, b, h) do { _Pragma("unroll") for (int m = 0; m < 4; ++m) _Pragma("unroll") for (int k = 0; k < 2; ++k) dst[m][k] = *(const PG8_LAS bf16x8*)(lds + PG8_SA(b, h) + aoff + m * 2048 + k * 1024); } while (0)
; #define PG8_LDB(dst, b, h) do { _Pragma("unroll") for (int n = 0; n < 2; ++n) _Pragma("unroll") for (int k = 0; k < 2; ++k) dst[n][k] = *(const PG8_LAS bf16x8*)(lds + PG8_SB(b, h) + boff + n * 2048 + k * 1024); } while (0)
; #define PG8_MMA(ai, bj, At, Bt) do { __builtin_amdgcn_s_setprio(1); _Pragma("unroll") for (int m = 0; m < 4; ++m) _Pragma("unroll") for (int n = 0; n < 2; ++n) _Pragma("unroll") for (int k = 0; k < 2; ++k) \
;         acc[ai][bj][m][n] = __builtin_amdgcn_mfma_f32_16x16x32_bf16(Bt[n][k], At[m][k], acc[ai][bj][m][n], 0, 0, 0); __builtin_amdgcn_s_setprio(0); } while (0)
; #define PG8_WAIT_V(n) asm volatile("s_waitcnt vmcnt(" #n ")" ::: "memory")
; #define PG8_WAIT_L(n) asm volatile("s_waitcnt lgkmcnt(" #n ")" ::: "memory")
; #define PG8_BAR __builtin_amdgcn_s_barrier()
; #define PG8_SCHED __builtin_amdgcn_sched_barrier(0)
; template <class Epi, class Sched, bool ALIGN_EPI = false, bool SP2 = false>
; __device__ __forceinline__ void gemm_phase(PG8_LAS unsigned char* lds, const Gemm g, const Sched& S, const Epi& E) {
;     ...
;             PG8_LDB(B0, 1, 0); PG8_LDB(B1, 1, 1); PG8_SCHED; PG8_LDA(At, 1, 0); PG8_STAGE(PG8_SA(0, 1), a2 + hstep, voffA);
;             PG8_WAIT_V(8); PG8_WAIT_L(0); PG8_BAR; PG8_MMA(0, 0, At, B0); PG8_MMA(0, 1, At, B1); PG8_BAR; PG8_SCHED;
;             PG8_LDA(At, 1, 1); PG8_STAGE(PG8_SB(1, 0), b3, voffB); PG8_STAGE(PG8_SB(1, 1), b3 + hstep, voffB); PG8_STAGE(PG8_SA(1, 0), a3, voffA);
;             PG8_WAIT_V(8); PG8_WAIT_L(0); PG8_BAR; PG8_MMA(1, 0, At, B0); PG8_MMA(1, 1, At, B1); PG8_BAR; PG8_SCHED;
	s_add_i32 s59, 0, 0x18000
	s_add_i32 s60, 0, 0x1c000
	v_add_u32_e32 v140, s59, v232
	v_add_u32_e32 v156, s60, v232
	ds_read_b128 v[124:127], v140
	ds_read_b128 v[132:135], v140 offset:1024
	ds_read_b128 v[136:139], v140 offset:2048
	ds_read_b128 v[140:143], v140 offset:3072
	ds_read_b128 v[144:147], v156
	ds_read_b128 v[148:151], v156 offset:1024
	ds_read_b128 v[152:155], v156 offset:2048
	ds_read_b128 v[156:159], v156 offset:3072
	s_add_u32 s46, s46, 0xb0000
	s_addc_u32 s47, s47, 0
	s_mov_b32 m0, s28
	ds_read_b128 v[160:163], v236 offset:32768
	ds_read_b128 v[164:167], v236 offset:33792
	ds_read_b128 v[168:171], v236 offset:34816
	ds_read_b128 v[172:175], v236 offset:35840
	ds_read_b128 v[176:179], v236 offset:36864
	ds_read_b128 v[180:183], v236 offset:37888
	ds_read_b128 v[198:201], v236 offset:38912
	ds_read_b128 v[202:205], v236 offset:39936
	global_load_lds_dwordx4 v184, s[46:47]
	v_lshl_add_u64 v[214:215], s[46:47], 0, v[188:189]
	s_mov_b32 m0, s29
	s_nop 0
	global_load_lds_dwordx4 v[214:215], off
	s_waitcnt vmcnt(8)
	s_waitcnt lgkmcnt(0)
	s_barrier
	s_setprio 1
	s_waitcnt lgkmcnt(0)
	v_mfma_f32_16x16x32_bf16 v[128:131], v[124:127], v[160:163], v[128:131]
	v_mfma_f32_16x16x32_bf16 v[120:123], v[136:139], v[160:163], v[120:123]
	v_mfma_f32_16x16x32_bf16 v[108:111], v[124:127], v[168:171], v[108:111]
	v_mfma_f32_16x16x32_bf16 v[104:107], v[136:139], v[168:171], v[104:107]
	v_mfma_f32_16x16x32_bf16 v[92:95], v[124:127], v[176:179], v[92:95]
	v_mfma_f32_16x16x32_bf16 v[88:91], v[136:139], v[176:179], v[88:91]
	v_mfma_f32_16x16x32_bf16 v[76:79], v[124:127], v[198:201], v[76:79]
	v_mfma_f32_16x16x32_bf16 v[72:75], v[136:139], v[198:201], v[72:75]
	v_mfma_f32_16x16x32_bf16 v[128:131], v[132:135], v[164:167], v[128:131]
	v_mfma_f32_16x16x32_bf16 v[120:123], v[140:143], v[164:167], v[120:123]
	v_mfma_f32_16x16x32_bf16 v[108:111], v[132:135], v[172:175], v[108:111]
	v_mfma_f32_16x16x32_bf16 v[104:107], v[140:143], v[172:175], v[104:107]
	v_mfma_f32_16x16x32_bf16 v[92:95], v[132:135], v[180:183], v[92:95]
	v_mfma_f32_16x16x32_bf16 v[88:91], v[140:143], v[180:183], v[88:91]
	v_mfma_f32_16x16x32_bf16 v[76:79], v[132:135], v[202:205], v[76:79]
	v_mfma_f32_16x16x32_bf16 v[72:75], v[140:143], v[202:205], v[72:75]
	s_setprio 0
	s_setprio 1
	v_mfma_f32_16x16x32_bf16 v[116:119], v[144:147], v[160:163], v[116:119]
	v_mfma_f32_16x16x32_bf16 v[112:115], v[152:155], v[160:163], v[112:115]
	v_mfma_f32_16x16x32_bf16 v[100:103], v[144:147], v[168:171], v[100:103]
	v_mfma_f32_16x16x32_bf16 v[96:99], v[152:155], v[168:171], v[96:99]
	v_mfma_f32_16x16x32_bf16 v[84:87], v[144:147], v[176:179], v[84:87]
	v_mfma_f32_16x16x32_bf16 v[80:83], v[152:155], v[176:179], v[80:83]
	v_mfma_f32_16x16x32_bf16 v[68:71], v[144:147], v[198:201], v[68:71]
	v_mfma_f32_16x16x32_bf16 v[64:67], v[152:155], v[198:201], v[64:67]
	v_mfma_f32_16x16x32_bf16 v[116:119], v[148:151], v[164:167], v[116:119]
	v_mfma_f32_16x16x32_bf16 v[112:115], v[156:159], v[164:167], v[112:115]
	v_mfma_f32_16x16x32_bf16 v[100:103], v[148:151], v[172:175], v[100:103]
	v_mfma_f32_16x16x32_bf16 v[96:99], v[156:159], v[172:175], v[96:99]
	v_mfma_f32_16x16x32_bf16 v[84:87], v[148:151], v[180:183], v[84:87]
	v_mfma_f32_16x16x32_bf16 v[80:83], v[156:159], v[180:183], v[80:83]
	v_mfma_f32_16x16x32_bf16 v[68:71], v[148:151], v[202:205], v[68:71]
	v_mfma_f32_16x16x32_bf16 v[64:67], v[156:159], v[202:205], v[64:67]
	s_setprio 0
	s_barrier
	s_add_i32 s46, s59, s25
	v_lshl_add_u64 v[206:207], v[206:207], 0, s[20:21]
	s_mov_b32 m0, s46
	ds_read_b128 v[160:163], v236 offset:49152
	ds_read_b128 v[164:167], v236 offset:50176
	ds_read_b128 v[168:171], v236 offset:51200
	ds_read_b128 v[172:175], v236 offset:52224
	ds_read_b128 v[176:179], v236 offset:53248
	ds_read_b128 v[180:183], v236 offset:54272
	ds_read_b128 v[198:201], v236 offset:55296
	ds_read_b128 v[202:205], v236 offset:56320
	global_load_lds_dwordx4 v[206:207], off
	s_add_i32 m0, s46, 0x2000
	s_add_u32 s44, s44, 0xb0080
	v_lshl_add_u64 v[206:207], v[208:209], 0, s[20:21]
	s_addc_u32 s45, s45, 0
	s_add_i32 s46, s60, s25
	global_load_lds_dwordx4 v[206:207], off
	s_mov_b32 m0, s46
	s_nop 0
	global_load_lds_dwordx4 v186, s[44:45]
	s_add_i32 m0, s46, 0x2000
	s_nop 0
	global_load_lds_dwordx4 v190, s[44:45]
	v_lshl_add_u64 v[206:207], v[210:211], 0, s[20:21]
	s_mov_b32 m0, s31
	s_nop 0
	global_load_lds_dwordx4 v[206:207], off
	v_lshl_add_u64 v[206:207], v[212:213], 0, s[20:21]
	s_mov_b32 m0, s33
	s_nop 0
	global_load_lds_dwordx4 v[206:207], off
	s_waitcnt vmcnt(8)
	s_waitcnt lgkmcnt(0)
	s_barrier
	s_setprio 1
	s_waitcnt lgkmcnt(0)
	v_mfma_f32_16x16x32_bf16 v[60:63], v[124:127], v[160:163], v[60:63]
	v_mfma_f32_16x16x32_bf16 v[56:59], v[136:139], v[160:163], v[56:59]
	v_mfma_f32_16x16x32_bf16 v[44:47], v[124:127], v[168:171], v[44:47]
	v_mfma_f32_16x16x32_bf16 v[40:43], v[136:139], v[168:171], v[40:43]
	v_mfma_f32_16x16x32_bf16 v[28:31], v[124:127], v[176:179], v[28:31]
	v_mfma_f32_16x16x32_bf16 v[24:27], v[136:139], v[176:179], v[24:27]
	v_mfma_f32_16x16x32_bf16 v[12:15], v[124:127], v[198:201], v[12:15]
	v_mfma_f32_16x16x32_bf16 v[8:11], v[136:139], v[198:201], v[8:11]
	v_mfma_f32_16x16x32_bf16 v[60:63], v[132:135], v[164:167], v[60:63]
	v_mfma_f32_16x16x32_bf16 v[56:59], v[140:143], v[164:167], v[56:59]
	v_mfma_f32_16x16x32_bf16 v[44:47], v[132:135], v[172:175], v[44:47]
	v_mfma_f32_16x16x32_bf16 v[40:43], v[140:143], v[172:175], v[40:43]
	v_mfma_f32_16x16x32_bf16 v[28:31], v[132:135], v[180:183], v[28:31]
	v_mfma_f32_16x16x32_bf16 v[24:27], v[140:143], v[180:183], v[24:27]
	v_mfma_f32_16x16x32_bf16 v[12:15], v[132:135], v[202:205], v[12:15]
	v_mfma_f32_16x16x32_bf16 v[8:11], v[140:143], v[202:205], v[8:11]
	s_setprio 0
	s_setprio 1
	v_mfma_f32_16x16x32_bf16 v[52:55], v[144:147], v[160:163], v[52:55]
	v_mfma_f32_16x16x32_bf16 v[48:51], v[152:155], v[160:163], v[48:51]
	v_mfma_f32_16x16x32_bf16 v[36:39], v[144:147], v[168:171], v[36:39]
	v_mfma_f32_16x16x32_bf16 v[32:35], v[152:155], v[168:171], v[32:35]
	v_mfma_f32_16x16x32_bf16 v[20:23], v[144:147], v[176:179], v[20:23]
	v_mfma_f32_16x16x32_bf16 v[16:19], v[152:155], v[176:179], v[16:19]
	v_mfma_f32_16x16x32_bf16 v[4:7], v[144:147], v[198:201], v[4:7]
	v_mfma_f32_16x16x32_bf16 v[0:3], v[152:155], v[198:201], v[0:3]
	v_mfma_f32_16x16x32_bf16 v[52:55], v[148:151], v[164:167], v[52:55]
	v_mfma_f32_16x16x32_bf16 v[48:51], v[156:159], v[164:167], v[48:51]
	v_mfma_f32_16x16x32_bf16 v[36:39], v[148:151], v[172:175], v[36:39]
	v_mfma_f32_16x16x32_bf16 v[32:35], v[156:159], v[172:175], v[32:35]
	v_mfma_f32_16x16x32_bf16 v[20:23], v[148:151], v[180:183], v[20:23]
	v_mfma_f32_16x16x32_bf16 v[16:19], v[156:159], v[180:183], v[16:19]
	v_mfma_f32_16x16x32_bf16 v[4:7], v[148:151], v[202:205], v[4:7]
	v_mfma_f32_16x16x32_bf16 v[0:3], v[156:159], v[202:205], v[0:3]
	s_setprio 0
	s_barrier
	s_add_i32 s58, s58, 2
	s_add_u32 s42, s42, 0x100
	s_addc_u32 s43, s43, 0
	s_add_u32 s56, s56, 0x100
	s_addc_u32 s57, s57, 0
	s_cmp_gt_u32 s58, 41
; #define PG8_STAGE(bufoff, gbase, voff) do { _Pragma("unroll") for (int _i = 0; _i < 2; ++_i) \
;         __builtin_amdgcn_global_load_lds((const unsigned*)((const char*)(gbase) + (voff)[_i]), (PG8_LAS unsigned*)(lds + (bufoff) + ldsw + _i * 8192), 16, 0, 0); } while (0)
; #define PG8_LDA(dst, b, h) do { _Pragma("unroll") for (int m = 0; m < 4; ++m) _Pragma("unroll") for (int k = 0; k < 2; ++k) dst[m][k] = *(const PG8_LAS bf16x8*)(lds + PG8_SA(b, h) + aoff + m * 2048 + k * 1024); } while (0)
; #define PG8_LDB(dst, b, h) do { _Pragma("unroll") for (int n = 0; n < 2; ++n) _Pragma("unroll") for (int k = 0; k < 2; ++k) dst[n][k] = *(const PG8_LAS bf16x8*)(lds + PG8_SB(b, h) + boff + n * 2048 + k * 1024); } while (0)
; #define PG8_MMA(ai, bj, At, Bt) do { __builtin_amdgcn_s_setprio(1); _Pragma("unroll") for (int m = 0; m < 4; ++m) _Pragma("unroll") for (int n = 0; n < 2; ++n) _Pragma("unroll") for (int k = 0; k < 2; ++k) \
;         acc[ai][bj][m][n] = __builtin_amdgcn_mfma_f32_16x16x32_bf16(Bt[n][k], At[m][k], acc[ai][bj][m][n], 0, 0, 0); __builtin_amdgcn_s_setprio(0); } while (0)
; #define PG8_WAIT_V(n) asm volatile("s_waitcnt vmcnt(" #n ")" ::: "memory")
; #define PG8_WAIT_L(n) asm volatile("s_waitcnt lgkmcnt(" #n ")" ::: "memory")
; template <class Epi, class Sched, bool ALIGN_EPI = false, bool SP2 = false>
; __device__ __forceinline__ void gemm_phase(PG8_LAS unsigned char* lds, const Gemm g, const Sched& S, const Epi& E) {
;     ...
;             const bool last = (t == nt - 2);
;             const char* a1 = cA + (size_t)(t + 1) * kstep;
;             const char* a2 = last ? nA : cA + (size_t)(t + 2) * kstep; const char* b2 = last ? nB : cB + (size_t)(t + 2) * kstep;
;             const char* a3 = a2 + kstep; const char* b3 = b2 + kstep;
;             if (last && has_next) S.a_ready(nxt);
;             if constexpr (SP2) {
;             PG8_LDB(B0, 0, 0); PG8_LDB(B1, 0, 1); PG8_SCHED; PG8_LDA(At, 0, 0); PG8_STAGE(PG8_SA(1, 1), a1 + hstep, voffA);
;             PG8_WAIT_V(8); PG8_WAIT_L(0); PG8_BAR; PG8_MMA(0, 0, At, B0); PG8_MMA(0, 1, At, B1); PG8_BAR; PG8_SCHED;
;             PG8_LDA(At, 0, 1); PG8_STAGE(PG8_SB(0, 0), b2, voffB); PG8_STAGE(PG8_SB(0, 1), b2 + hstep, voffB); PG8_STAGE(PG8_SA(0, 0), a2, voffA);
;             PG8_WAIT_V(8); PG8_WAIT_L(0); PG8_BAR; PG8_MMA(1, 0, At, B0); PG8_MMA(1, 1, At, B1); PG8_BAR; PG8_SCHED;
.LBB0_570:
	ds_read_b128 v[124:127], v234
	ds_read_b128 v[132:135], v234 offset:1024
	ds_read_b128 v[136:139], v234 offset:2048
	ds_read_b128 v[140:143], v234 offset:3072
	ds_read_b128 v[144:147], v235
	ds_read_b128 v[148:151], v235 offset:1024
	ds_read_b128 v[152:155], v235 offset:2048
	ds_read_b128 v[156:159], v235 offset:3072
	s_add_u32 s44, s42, 0xfff50080
	s_addc_u32 s45, s43, -1
	s_cmp_eq_u32 s58, 40
	s_cselect_b32 s47, s39, s45
	s_cselect_b32 s46, s38, s44
	s_cselect_b32 s45, s41, s57
	s_cselect_b32 s44, s40, s56
	s_add_i32 m0, s26, 0xc000
	ds_read_b128 v[160:163], v236
	ds_read_b128 v[164:167], v236 offset:1024
	ds_read_b128 v[168:171], v236 offset:2048
	ds_read_b128 v[172:175], v236 offset:3072
	ds_read_b128 v[176:179], v236 offset:4096
	ds_read_b128 v[180:183], v236 offset:5120
	ds_read_b128 v[198:201], v236 offset:6144
	ds_read_b128 v[202:205], v236 offset:7168
	global_load_lds_dwordx4 v192, s[42:43]
	s_add_i32 m0, s26, 0xe000
	s_nop 0
	global_load_lds_dwordx4 v194, s[42:43]
	s_waitcnt vmcnt(8)
	s_waitcnt lgkmcnt(0)
	s_barrier
	s_setprio 1
	s_waitcnt lgkmcnt(0)
	v_mfma_f32_16x16x32_bf16 v[128:131], v[124:127], v[160:163], v[128:131]
	v_mfma_f32_16x16x32_bf16 v[120:123], v[136:139], v[160:163], v[120:123]
	v_mfma_f32_16x16x32_bf16 v[108:111], v[124:127], v[168:171], v[108:111]
	v_mfma_f32_16x16x32_bf16 v[104:107], v[136:139], v[168:171], v[104:107]
	v_mfma_f32_16x16x32_bf16 v[92:95], v[124:127], v[176:179], v[92:95]
	v_mfma_f32_16x16x32_bf16 v[88:91], v[136:139], v[176:179], v[88:91]
	v_mfma_f32_16x16x32_bf16 v[76:79], v[124:127], v[198:201], v[76:79]
	v_mfma_f32_16x16x32_bf16 v[72:75], v[136:139], v[198:201], v[72:75]
	v_mfma_f32_16x16x32_bf16 v[128:131], v[132:135], v[164:167], v[128:131]
	v_mfma_f32_16x16x32_bf16 v[120:123], v[140:143], v[164:167], v[120:123]
	v_mfma_f32_16x16x32_bf16 v[108:111], v[132:135], v[172:175], v[108:111]
	v_mfma_f32_16x16x32_bf16 v[104:107], v[140:143], v[172:175], v[104:107]
	v_mfma_f32_16x16x32_bf16 v[92:95], v[132:135], v[180:183], v[92:95]
	v_mfma_f32_16x16x32_bf16 v[88:91], v[140:143], v[180:183], v[88:91]
	v_mfma_f32_16x16x32_bf16 v[76:79], v[132:135], v[202:205], v[76:79]
	v_mfma_f32_16x16x32_bf16 v[72:75], v[140:143], v[202:205], v[72:75]
	s_setprio 0
	s_setprio 1
	v_mfma_f32_16x16x32_bf16 v[116:119], v[144:147], v[160:163], v[116:119]
	v_mfma_f32_16x16x32_bf16 v[112:115], v[152:155], v[160:163], v[112:115]
	v_mfma_f32_16x16x32_bf16 v[100:103], v[144:147], v[168:171], v[100:103]
	v_mfma_f32_16x16x32_bf16 v[96:99], v[152:155], v[168:171], v[96:99]
	v_mfma_f32_16x16x32_bf16 v[84:87], v[144:147], v[176:179], v[84:87]
	v_mfma_f32_16x16x32_bf16 v[80:83], v[152:155], v[176:179], v[80:83]
	v_mfma_f32_16x16x32_bf16 v[68:71], v[144:147], v[198:201], v[68:71]
	v_mfma_f32_16x16x32_bf16 v[64:67], v[152:155], v[198:201], v[64:67]
	v_mfma_f32_16x16x32_bf16 v[116:119], v[148:151], v[164:167], v[116:119]
	v_mfma_f32_16x16x32_bf16 v[112:115], v[156:159], v[164:167], v[112:115]
	v_mfma_f32_16x16x32_bf16 v[100:103], v[148:151], v[172:175], v[100:103]
	v_mfma_f32_16x16x32_bf16 v[96:99], v[156:159], v[172:175], v[96:99]
	v_mfma_f32_16x16x32_bf16 v[84:87], v[148:151], v[180:183], v[84:87]
	v_mfma_f32_16x16x32_bf16 v[80:83], v[156:159], v[180:183], v[80:83]
	v_mfma_f32_16x16x32_bf16 v[68:71], v[148:151], v[202:205], v[68:71]
	v_mfma_f32_16x16x32_bf16 v[64:67], v[156:159], v[202:205], v[64:67]
	s_setprio 0
	s_barrier
	s_add_i32 s59, s50, s25
	v_lshl_add_u64 v[206:207], s[44:45], 0, v[186:187]
	s_mov_b32 m0, s59
	ds_read_b128 v[160:163], v236 offset:16384
	ds_read_b128 v[164:167], v236 offset:17408
	ds_read_b128 v[168:171], v236 offset:18432
	ds_read_b128 v[172:175], v236 offset:19456
	ds_read_b128 v[176:179], v236 offset:20480
	ds_read_b128 v[180:183], v236 offset:21504
	ds_read_b128 v[198:201], v236 offset:22528
	ds_read_b128 v[202:205], v236 offset:23552
	global_load_lds_dwordx4 v[206:207], off
	s_add_i32 m0, s59, 0x2000
	s_add_u32 s60, s44, 0xb0000
	v_lshl_add_u64 v[208:209], s[44:45], 0, v[190:191]
	s_addc_u32 s61, s45, 0
	s_add_i32 s59, s51, s25
	global_load_lds_dwordx4 v[208:209], off
	s_mov_b32 m0, s59
	v_lshl_add_u64 v[212:213], s[46:47], 0, v[188:189]
	global_load_lds_dwordx4 v186, s[60:61]
	s_add_i32 m0, s59, 0x2000
	s_nop 0
	global_load_lds_dwordx4 v190, s[60:61]
	v_lshl_add_u64 v[210:211], s[46:47], 0, v[184:185]
	s_mov_b32 m0, s26
	s_nop 0
	global_load_lds_dwordx4 v[210:211], off
	s_mov_b32 m0, s27
	s_nop 0
	global_load_lds_dwordx4 v[212:213], off
	s_waitcnt vmcnt(8)
	s_waitcnt lgkmcnt(0)
	s_barrier
; #define PG8_STAGE(bufoff, gbase, voff) do { _Pragma("unroll") for (int _i = 0; _i < 2; ++_i) \
;         __builtin_amdgcn_global_load_lds((const unsigned*)((const char*)(gbase) + (voff)[_i]), (PG8_LAS unsigned*)(lds + (bufoff) + ldsw + _i * 8192), 16, 0, 0); } while (0)
; #define PG8_LDA(dst, b, h) do { _Pragma("unroll") for (int m = 0; m < 4; ++m) _Pragma("unroll") for (int k = 0; k < 2; ++k) dst[m][k] = *(const PG8_LAS bf16x8*)(lds + PG8_SA(b, h) + aoff + m * 2048 + k * 1024); } while (0)
; #define PG8_LDB(dst, b, h) do { _Pragma("unroll") for (int n = 0; n < 2; ++n) _Pragma("unroll") for (int k = 0; k < 2; ++k) dst[n][k] = *(const PG8_LAS bf16x8*)(lds + PG8_SB(b, h) + boff + n * 2048 + k * 1024); } while (0)
; #define PG8_MMA(ai, bj, At, Bt) do { __builtin_amdgcn_s_setprio(1); _Pragma("unroll") for (int m = 0; m < 4; ++m) _Pragma("unroll") for (int n = 0; n < 2; ++n) _Pragma("unroll") for (int k = 0; k < 2; ++k) \
;         acc[ai][bj][m][n] = __builtin_amdgcn_mfma_f32_16x16x32_bf16(Bt[n][k], At[m][k], acc[ai][bj][m][n], 0, 0, 0); __builtin_amdgcn_s_setprio(0); } while (0)
; #define PG8_WAIT_V(n) asm volatile("s_waitcnt vmcnt(" #n ")" ::: "memory")
; #define PG8_WAIT_L(n) asm volatile("s_waitcnt lgkmcnt(" #n ")" ::: "memory")
; #define PG8_BAR __builtin_amdgcn_s_barrier()
; #define PG8_SCHED __builtin_amdgcn_sched_barrier(0)
; template <class Epi, class Sched, bool ALIGN_EPI = false, bool SP2 = false>
; __device__ __forceinline__ void gemm_phase(PG8_LAS unsigned char* lds, const Gemm g, const Sched& S, const Epi& E) {
;     ...
;             PG8_WAIT_V(8); PG8_WAIT_L(0); PG8_BAR; PG8_MMA(1, 0, At, B0); PG8_MMA(1, 1, At, B1); PG8_BAR; PG8_SCHED;
;             PG8_LDB(B0, 1, 0); PG8_LDB(B1, 1, 1); PG8_SCHED; PG8_LDA(At, 1, 0); PG8_STAGE(PG8_SA(0, 1), a2 + hstep, voffA);
;             PG8_WAIT_V(8); PG8_WAIT_L(0); PG8_BAR; PG8_MMA(0, 0, At, B0); PG8_MMA(0, 1, At, B1); PG8_BAR; PG8_SCHED;
;             PG8_LDA(At, 1, 1); PG8_STAGE(PG8_SB(1, 0), b3, voffB); PG8_STAGE(PG8_SB(1, 1), b3 + hstep, voffB); PG8_STAGE(PG8_SA(1, 0), a3, voffA);
	s_setprio 1
	s_waitcnt lgkmcnt(0)
	v_mfma_f32_16x16x32_bf16 v[60:63], v[124:127], v[160:163], v[60:63]
	v_mfma_f32_16x16x32_bf16 v[56:59], v[136:139], v[160:163], v[56:59]
	v_mfma_f32_16x16x32_bf16 v[44:47], v[124:127], v[168:171], v[44:47]
	v_mfma_f32_16x16x32_bf16 v[40:43], v[136:139], v[168:171], v[40:43]
	v_mfma_f32_16x16x32_bf16 v[28:31], v[124:127], v[176:179], v[28:31]
	v_mfma_f32_16x16x32_bf16 v[24:27], v[136:139], v[176:179], v[24:27]
	v_mfma_f32_16x16x32_bf16 v[12:15], v[124:127], v[198:201], v[12:15]
	v_mfma_f32_16x16x32_bf16 v[8:11], v[136:139], v[198:201], v[8:11]
	v_mfma_f32_16x16x32_bf16 v[60:63], v[132:135], v[164:167], v[60:63]
	v_mfma_f32_16x16x32_bf16 v[56:59], v[140:143], v[164:167], v[56:59]
	v_mfma_f32_16x16x32_bf16 v[44:47], v[132:135], v[172:175], v[44:47]
	v_mfma_f32_16x16x32_bf16 v[40:43], v[140:143], v[172:175], v[40:43]
	v_mfma_f32_16x16x32_bf16 v[28:31], v[132:135], v[180:183], v[28:31]
	v_mfma_f32_16x16x32_bf16 v[24:27], v[140:143], v[180:183], v[24:27]
	v_mfma_f32_16x16x32_bf16 v[12:15], v[132:135], v[202:205], v[12:15]
	v_mfma_f32_16x16x32_bf16 v[8:11], v[140:143], v[202:205], v[8:11]
	s_setprio 0
	s_setprio 1
	v_mfma_f32_16x16x32_bf16 v[52:55], v[144:147], v[160:163], v[52:55]
	v_mfma_f32_16x16x32_bf16 v[48:51], v[152:155], v[160:163], v[48:51]
	v_mfma_f32_16x16x32_bf16 v[36:39], v[144:147], v[168:171], v[36:39]
	v_mfma_f32_16x16x32_bf16 v[32:35], v[152:155], v[168:171], v[32:35]
	v_mfma_f32_16x16x32_bf16 v[20:23], v[144:147], v[176:179], v[20:23]
	v_mfma_f32_16x16x32_bf16 v[16:19], v[152:155], v[176:179], v[16:19]
	v_mfma_f32_16x16x32_bf16 v[4:7], v[144:147], v[198:201], v[4:7]
	v_mfma_f32_16x16x32_bf16 v[0:3], v[152:155], v[198:201], v[0:3]
	v_mfma_f32_16x16x32_bf16 v[52:55], v[148:151], v[164:167], v[52:55]
	v_mfma_f32_16x16x32_bf16 v[48:51], v[156:159], v[164:167], v[48:51]
	v_mfma_f32_16x16x32_bf16 v[36:39], v[148:151], v[172:175], v[36:39]
	v_mfma_f32_16x16x32_bf16 v[32:35], v[156:159], v[172:175], v[32:35]
	v_mfma_f32_16x16x32_bf16 v[20:23], v[148:151], v[180:183], v[20:23]
	v_mfma_f32_16x16x32_bf16 v[16:19], v[156:159], v[180:183], v[16:19]
	v_mfma_f32_16x16x32_bf16 v[4:7], v[148:151], v[202:205], v[4:7]
	v_mfma_f32_16x16x32_bf16 v[0:3], v[156:159], v[202:205], v[0:3]
	s_setprio 0
	s_barrier
	s_add_i32 s59, 0, 0x18000
	s_add_i32 s60, 0, 0x1c000
	v_add_u32_e32 v140, s59, v232
	v_add_u32_e32 v156, s60, v232
	ds_read_b128 v[124:127], v140
	ds_read_b128 v[132:135], v140 offset:1024
	ds_read_b128 v[136:139], v140 offset:2048
	ds_read_b128 v[140:143], v140 offset:3072
	ds_read_b128 v[144:147], v156
	ds_read_b128 v[148:151], v156 offset:1024
	ds_read_b128 v[152:155], v156 offset:2048
	ds_read_b128 v[156:159], v156 offset:3072
	s_add_u32 s46, s46, 0xb0000
	s_addc_u32 s47, s47, 0
	s_mov_b32 m0, s28
	ds_read_b128 v[160:163], v236 offset:32768
	ds_read_b128 v[164:167], v236 offset:33792
	ds_read_b128 v[168:171], v236 offset:34816
	ds_read_b128 v[172:175], v236 offset:35840
	ds_read_b128 v[176:179], v236 offset:36864
	ds_read_b128 v[180:183], v236 offset:37888
	ds_read_b128 v[198:201], v236 offset:38912
	ds_read_b128 v[202:205], v236 offset:39936
	global_load_lds_dwordx4 v184, s[46:47]
	v_lshl_add_u64 v[214:215], s[46:47], 0, v[188:189]
	s_mov_b32 m0, s29
	s_nop 0
	global_load_lds_dwordx4 v[214:215], off
	s_waitcnt vmcnt(8)
	s_waitcnt lgkmcnt(0)
	s_barrier
	s_setprio 1
	s_waitcnt lgkmcnt(0)
	v_mfma_f32_16x16x32_bf16 v[128:131], v[124:127], v[160:163], v[128:131]
	v_mfma_f32_16x16x32_bf16 v[120:123], v[136:139], v[160:163], v[120:123]
	v_mfma_f32_16x16x32_bf16 v[108:111], v[124:127], v[168:171], v[108:111]
	v_mfma_f32_16x16x32_bf16 v[104:107], v[136:139], v[168:171], v[104:107]
	v_mfma_f32_16x16x32_bf16 v[92:95], v[124:127], v[176:179], v[92:95]
	v_mfma_f32_16x16x32_bf16 v[88:91], v[136:139], v[176:179], v[88:91]
	v_mfma_f32_16x16x32_bf16 v[76:79], v[124:127], v[198:201], v[76:79]
	v_mfma_f32_16x16x32_bf16 v[72:75], v[136:139], v[198:201], v[72:75]
	v_mfma_f32_16x16x32_bf16 v[128:131], v[132:135], v[164:167], v[128:131]
	v_mfma_f32_16x16x32_bf16 v[120:123], v[140:143], v[164:167], v[120:123]
	v_mfma_f32_16x16x32_bf16 v[108:111], v[132:135], v[172:175], v[108:111]
	v_mfma_f32_16x16x32_bf16 v[104:107], v[140:143], v[172:175], v[104:107]
	v_mfma_f32_16x16x32_bf16 v[92:95], v[132:135], v[180:183], v[92:95]
	v_mfma_f32_16x16x32_bf16 v[88:91], v[140:143], v[180:183], v[88:91]
	v_mfma_f32_16x16x32_bf16 v[76:79], v[132:135], v[202:205], v[76:79]
	v_mfma_f32_16x16x32_bf16 v[72:75], v[140:143], v[202:205], v[72:75]
	s_setprio 0
	s_setprio 1
	v_mfma_f32_16x16x32_bf16 v[116:119], v[144:147], v[160:163], v[116:119]
	v_mfma_f32_16x16x32_bf16 v[112:115], v[152:155], v[160:163], v[112:115]
	v_mfma_f32_16x16x32_bf16 v[100:103], v[144:147], v[168:171], v[100:103]
	v_mfma_f32_16x16x32_bf16 v[96:99], v[152:155], v[168:171], v[96:99]
	v_mfma_f32_16x16x32_bf16 v[84:87], v[144:147], v[176:179], v[84:87]
	v_mfma_f32_16x16x32_bf16 v[80:83], v[152:155], v[176:179], v[80:83]
	v_mfma_f32_16x16x32_bf16 v[68:71], v[144:147], v[198:201], v[68:71]
	v_mfma_f32_16x16x32_bf16 v[64:67], v[152:155], v[198:201], v[64:67]
	v_mfma_f32_16x16x32_bf16 v[116:119], v[148:151], v[164:167], v[116:119]
	v_mfma_f32_16x16x32_bf16 v[112:115], v[156:159], v[164:167], v[112:115]
	v_mfma_f32_16x16x32_bf16 v[100:103], v[148:151], v[172:175], v[100:103]
	v_mfma_f32_16x16x32_bf16 v[96:99], v[156:159], v[172:175], v[96:99]
	v_mfma_f32_16x16x32_bf16 v[84:87], v[148:151], v[180:183], v[84:87]
	v_mfma_f32_16x16x32_bf16 v[80:83], v[156:159], v[180:183], v[80:83]
	v_mfma_f32_16x16x32_bf16 v[68:71], v[148:151], v[202:205], v[68:71]
	v_mfma_f32_16x16x32_bf16 v[64:67], v[156:159], v[202:205], v[64:67]
	s_setprio 0
	s_barrier
; #define PG8_STAGE(bufoff, gbase, voff) do { _Pragma("unroll") for (int _i = 0; _i < 2; ++_i) \
;         __builtin_amdgcn_global_load_lds((const unsigned*)((const char*)(gbase) + (voff)[_i]), (PG8_LAS unsigned*)(lds + (bufoff) + ldsw + _i * 8192), 16, 0, 0); } while (0)
; #define PG8_LDA(dst, b, h) do { _Pragma("unroll") for (int m = 0; m < 4; ++m) _Pragma("unroll") for (int k = 0; k < 2; ++k) dst[m][k] = *(const PG8_LAS bf16x8*)(lds + PG8_SA(b, h) + aoff + m * 2048 + k * 1024); } while (0)
; #define PG8_MMA(ai, bj, At, Bt) do { __builtin_amdgcn_s_setprio(1); _Pragma("unroll") for (int m = 0; m < 4; ++m) _Pragma("unroll") for (int n = 0; n < 2; ++n) _Pragma("unroll") for (int k = 0; k < 2; ++k) \
;         acc[ai][bj][m][n] = __builtin_amdgcn_mfma_f32_16x16x32_bf16(Bt[n][k], At[m][k], acc[ai][bj][m][n], 0, 0, 0); __builtin_amdgcn_s_setprio(0); } while (0)
; #define PG8_WAIT_V(n) asm volatile("s_waitcnt vmcnt(" #n ")" ::: "memory")
; #define PG8_WAIT_L(n) asm volatile("s_waitcnt lgkmcnt(" #n ")" ::: "memory")
; #define PG8_BAR __builtin_amdgcn_s_barrier()
; #define PG8_SCHED __builtin_amdgcn_sched_barrier(0)
; template <class Epi, class Sched, bool ALIGN_EPI = false, bool SP2 = false>
; __device__ __forceinline__ void gemm_phase(PG8_LAS unsigned char* lds, const Gemm g, const Sched& S, const Epi& E) {
;     ...
;             PG8_WAIT_V(8); PG8_WAIT_L(0); PG8_BAR; PG8_MMA(0, 0, At, B0); PG8_MMA(0, 1, At, B1); PG8_BAR; PG8_SCHED;
;             PG8_LDA(At, 1, 1); PG8_STAGE(PG8_SB(1, 0), b3, voffB); PG8_STAGE(PG8_SB(1, 1), b3 + hstep, voffB); PG8_STAGE(PG8_SA(1, 0), a3, voffA);
;             PG8_WAIT_V(8); PG8_WAIT_L(0); PG8_BAR; PG8_MMA(1, 0, At, B0); PG8_MMA(1, 1, At, B1); PG8_BAR; PG8_SCHED;
	s_add_i32 s46, s59, s25
	v_lshl_add_u64 v[206:207], v[206:207], 0, s[20:21]
	s_mov_b32 m0, s46
	ds_read_b128 v[160:163], v236 offset:49152
	ds_read_b128 v[164:167], v236 offset:50176
	ds_read_b128 v[168:171], v236 offset:51200
	ds_read_b128 v[172:175], v236 offset:52224
	ds_read_b128 v[176:179], v236 offset:53248
	ds_read_b128 v[180:183], v236 offset:54272
	ds_read_b128 v[198:201], v236 offset:55296
	ds_read_b128 v[202:205], v236 offset:56320
	global_load_lds_dwordx4 v[206:207], off
	s_add_i32 m0, s46, 0x2000
	s_add_u32 s44, s44, 0xb0080
	v_lshl_add_u64 v[206:207], v[208:209], 0, s[20:21]
	s_addc_u32 s45, s45, 0
	s_add_i32 s46, s60, s25
	global_load_lds_dwordx4 v[206:207], off
	s_mov_b32 m0, s46
	s_nop 0
	global_load_lds_dwordx4 v186, s[44:45]
	s_add_i32 m0, s46, 0x2000
	s_nop 0
	global_load_lds_dwordx4 v190, s[44:45]
	v_lshl_add_u64 v[206:207], v[210:211], 0, s[20:21]
	s_mov_b32 m0, s31
	s_nop 0
	global_load_lds_dwordx4 v[206:207], off
	v_lshl_add_u64 v[206:207], v[212:213], 0, s[20:21]
	s_mov_b32 m0, s33
	s_nop 0
	global_load_lds_dwordx4 v[206:207], off
	s_waitcnt vmcnt(8)
	s_waitcnt lgkmcnt(0)
	s_barrier
	s_setprio 1
	s_waitcnt lgkmcnt(0)
	v_mfma_f32_16x16x32_bf16 v[60:63], v[124:127], v[160:163], v[60:63]
	v_mfma_f32_16x16x32_bf16 v[56:59], v[136:139], v[160:163], v[56:59]
	v_mfma_f32_16x16x32_bf16 v[44:47], v[124:127], v[168:171], v[44:47]
	v_mfma_f32_16x16x32_bf16 v[40:43], v[136:139], v[168:171], v[40:43]
	v_mfma_f32_16x16x32_bf16 v[28:31], v[124:127], v[176:179], v[28:31]
	v_mfma_f32_16x16x32_bf16 v[24:27], v[136:139], v[176:179], v[24:27]
	v_mfma_f32_16x16x32_bf16 v[12:15], v[124:127], v[198:201], v[12:15]
	v_mfma_f32_16x16x32_bf16 v[8:11], v[136:139], v[198:201], v[8:11]
	v_mfma_f32_16x16x32_bf16 v[60:63], v[132:135], v[164:167], v[60:63]
	v_mfma_f32_16x16x32_bf16 v[56:59], v[140:143], v[164:167], v[56:59]
	v_mfma_f32_16x16x32_bf16 v[44:47], v[132:135], v[172:175], v[44:47]
	v_mfma_f32_16x16x32_bf16 v[40:43], v[140:143], v[172:175], v[40:43]
	v_mfma_f32_16x16x32_bf16 v[28:31], v[132:135], v[180:183], v[28:31]
	v_mfma_f32_16x16x32_bf16 v[24:27], v[140:143], v[180:183], v[24:27]
	v_mfma_f32_16x16x32_bf16 v[12:15], v[132:135], v[202:205], v[12:15]
	v_mfma_f32_16x16x32_bf16 v[8:11], v[140:143], v[202:205], v[8:11]
	s_setprio 0
	s_setprio 1
	v_mfma_f32_16x16x32_bf16 v[52:55], v[144:147], v[160:163], v[52:55]
	v_mfma_f32_16x16x32_bf16 v[48:51], v[152:155], v[160:163], v[48:51]
	v_mfma_f32_16x16x32_bf16 v[36:39], v[144:147], v[168:171], v[36:39]
	v_mfma_f32_16x16x32_bf16 v[32:35], v[152:155], v[168:171], v[32:35]
	v_mfma_f32_16x16x32_bf16 v[20:23], v[144:147], v[176:179], v[20:23]
	v_mfma_f32_16x16x32_bf16 v[16:19], v[152:155], v[176:179], v[16:19]
	v_mfma_f32_16x16x32_bf16 v[4:7], v[144:147], v[198:201], v[4:7]
	v_mfma_f32_16x16x32_bf16 v[0:3], v[152:155], v[198:201], v[0:3]
	v_mfma_f32_16x16x32_bf16 v[52:55], v[148:151], v[164:167], v[52:55]
	v_mfma_f32_16x16x32_bf16 v[48:51], v[156:159], v[164:167], v[48:51]
	v_mfma_f32_16x16x32_bf16 v[36:39], v[148:151], v[172:175], v[36:39]
	v_mfma_f32_16x16x32_bf16 v[32:35], v[156:159], v[172:175], v[32:35]
	v_mfma_f32_16x16x32_bf16 v[20:23], v[148:151], v[180:183], v[20:23]
	v_mfma_f32_16x16x32_bf16 v[16:19], v[156:159], v[180:183], v[16:19]
	v_mfma_f32_16x16x32_bf16 v[4:7], v[148:151], v[202:205], v[4:7]
	v_mfma_f32_16x16x32_bf16 v[0:3], v[156:159], v[202:205], v[0:3]
	s_setprio 0
	s_barrier
	s_add_i32 s58, s58, 2
	s_add_u32 s42, s42, 0x100
	s_addc_u32 s43, s43, 0
	s_add_u32 s56, s56, 0x100
	s_addc_u32 s57, s57, 0
	s_cmp_gt_u32 s58, 41
	s_cbranch_scc0 .LBB0_570
	s_and_b64 vcc, exec, s[36:37]
	s_cbranch_vccz .LBB0_573
	s_barrier

; #define PG8_STAGE(bufoff, gbase, voff) do { _Pragma("unroll") for (int _i = 0; _i < 2; ++_i) \
;         __builtin_amdgcn_global_load_lds((const unsigned*)((const char*)(gbase) + (voff)[_i]), (PG8_LAS unsigned*)(lds + (bufoff) + ldsw + _i * 8192), 16, 0, 0); } while (0)
; #define PG8_WAIT_V(n) asm volatile("s_waitcnt vmcnt(" #n ")" ::: "memory")
; #define PG8_BAR __builtin_amdgcn_s_barrier()
; template <class Epi, class Sched, bool ALIGN_EPI = false, bool SP2 = false>
; __device__ __forceinline__ void gemm_phase(PG8_LAS unsigned char* lds, const Gemm g, const Sched& S, const Epi& E) {
;     const int tid = threadIdx.x, wid = __builtin_amdgcn_readfirstlane(tid >> 6), lane = tid & 63, wr = wid >> 2, wc = wid & 3, fr = lane & 15, fq = lane >> 4;
;     const int K = g.K, nt = K / BK;
;     unsigned voffA[2], voffB[2];
; #pragma unroll
;     for (int i = 0; i < 2; ++i) { int R, C; stage_rc(tid * 16 + i * 8192, R, C); const int Rb = Epi::PERM ? ((R & ~31) + perm32(R & 31)) : R;
;         voffA[i] = (unsigned)(R * K + C) * 2u; voffB[i] = (unsigned)(Rb * K + C) * 2u; }
;     const size_t kstep = (size_t)(BK * 2);
;     const size_t hstep = (size_t)HALF * K * 2;
;     const size_t tstep = 2 * hstep;
;     const unsigned ldsw = (unsigned)wid * 1024u;
;     const int aoff = lds_byte(wr * 64 + fr, fq * 8), boff = lds_byte(wc * 32 + fr, fq * 8);
;     ...
;         PG8_STAGE(PG8_SB(1, 0), cB + kstep, voffB); PG8_STAGE(PG8_SA(1, 0), cA + kstep, voffA); PG8_STAGE(PG8_SB(1, 1), cB + hstep + kstep, voffB);
;         PG8_WAIT_V(6); PG8_BAR;
.LBB0_653:
	s_lshl_b32 s16, s16, 5
	s_and_b32 s36, s16, 0x60
	s_mov_b64 s[16:17], 0x80
	s_add_i32 m0, s26, 0x18000
	v_lshl_add_u64 v[6:7], v[6:7], 0, s[16:17]
	s_lshl_b32 s5, s19, 13
	s_lshl_b32 s37, s36, 7
	s_waitcnt vmcnt(2)
	s_barrier
	global_load_lds_dwordx4 v[6:7], off
	v_lshl_add_u64 v[4:5], v[4:5], 0, s[16:17]
	s_add_i32 m0, s26, 0x1a000
	s_add_i32 s31, s26, 0x8000
	s_add_i32 s33, s26, 0xa000
	global_load_lds_dwordx4 v[4:5], off
	v_lshl_add_u64 v[0:1], v[0:1], 0, s[16:17]
	s_mov_b32 m0, s31
	s_add_u32 s20, s46, 0x40080
	global_load_lds_dwordx4 v[0:1], off
	v_lshl_add_u64 v[0:1], v[2:3], 0, s[16:17]
	s_mov_b32 m0, s33
	s_addc_u32 s21, s47, 0
	global_load_lds_dwordx4 v[0:1], off
	s_add_i32 m0, s26, 0x1c000
	global_load_lds_dwordx4 v130, s[20:21]
	v_lshl_add_u64 v[0:1], s[20:21], 0, v[134:135]
	s_add_i32 m0, s26, 0x1e000
	v_lshlrev_b32_e32 v2, 2, v230
	global_load_lds_dwordx4 v[0:1], off
	v_and_b32_e32 v1, 15, v230
	v_and_b32_e32 v0, 48, v230
	v_lshl_or_b32 v161, s19, 6, v1
	v_lshl_or_b32 v1, v1, 6, v0
	v_and_b32_e32 v2, 32, v2
	v_bitop3_b32 v3, v1, s5, v2 bitop3:0xde
	v_lshlrev_b32_e32 v1, 6, v230
	s_movk_i32 s5, 0x3c0
	s_cmpk_lt_u32 s18, 0x100
	v_and_or_b32 v1, v1, s5, v0
	s_cselect_b64 s[18:19], -1, 0
	s_lshl_b32 s5, s36, 1
	s_add_u32 s20, s6, s5
	v_bitop3_b32 v164, s37, v1, v2 bitop3:0xf6
	v_mov_b32_e32 v1, v131
	s_addc_u32 s21, s7, 0
	v_lshl_add_u64 v[136:137], s[34:35], 0, v[0:1]
	v_lshl_add_u64 v[138:139], s[20:21], 0, v[0:1]
	v_lshlrev_b32_e32 v0, 8, v230
	v_and_b32_e32 v0, 0x38000, v0
	v_lshlrev_b32_e32 v1, 11, v10
	v_or3_b32 v0, v8, v0, v1
	v_add_u32_e32 v140, v0, v9
	v_lshlrev_b32_e32 v0, 4, v11
	v_and_b32_e32 v0, 0x78000, v0
	s_waitcnt vmcnt(6)
	v_or3_b32 v0, v8, v0, v1
	v_add_u32_e32 v142, v0, v9
	s_add_i32 s56, 0, 0x10000
	s_add_i32 s57, 0, 0x14000
	v_mbcnt_lo_u32_b32 v0, -1, 0
	s_ashr_i32 s52, s74, 31
	s_mov_b32 s53, s74
	s_ashr_i32 s54, s2, 31
	v_mov_b32_e32 v141, v131
	v_mov_b32_e32 v143, v131
	s_movk_i32 s55, 0x281
	v_add_u32_e32 v165, s56, v164
	v_add_u32_e32 v166, s57, v164
	v_add_u32_e32 v167, 0, v3
	v_mbcnt_hi_u32_b32 v168, -1, v0
	v_mov_b32_e32 v169, 0x358637bd
	s_movk_i32 s58, 0xc00
	v_mov_b64_e32 v[144:145], 0x13ff
	s_barrier
	s_branch .LBB0_656

; #define PG8_STAGE(bufoff, gbase, voff) do { _Pragma("unroll") for (int _i = 0; _i < 2; ++_i) \
;         __builtin_amdgcn_global_load_lds((const unsigned*)((const char*)(gbase) + (voff)[_i]), (PG8_LAS unsigned*)(lds + (bufoff) + ldsw + _i * 8192), 16, 0, 0); } while (0)
; #define PG8_LDA(dst, b, h) do { _Pragma("unroll") for (int m = 0; m < 4; ++m) _Pragma("unroll") for (int k = 0; k < 2; ++k) dst[m][k] = *(const PG8_LAS bf16x8*)(lds + PG8_SA(b, h) + aoff + m * 2048 + k * 1024); } while (0)
; #define PG8_LDB(dst, b, h) do { _Pragma("unroll") for (int n = 0; n < 2; ++n) _Pragma("unroll") for (int k = 0; k < 2; ++k) dst[n][k] = *(const PG8_LAS bf16x8*)(lds + PG8_SB(b, h) + boff + n * 2048 + k * 1024); } while (0)
; #define PG8_WAIT_V(n) asm volatile("s_waitcnt vmcnt(" #n ")" ::: "memory")
; #define PG8_WAIT_L(n) asm volatile("s_waitcnt lgkmcnt(" #n ")" ::: "memory")
; #define PG8_BAR __builtin_amdgcn_s_barrier()
; #define PG8_SCHED __builtin_amdgcn_sched_barrier(0)
; template <class Epi, class Sched, bool ALIGN_EPI = false, bool SP2 = false>
; __device__ __forceinline__ void gemm_phase(PG8_LAS unsigned char* lds, const Gemm g, const Sched& S, const Epi& E) {
;     ...
;         const bool has_next = S.next(ui + 1, nxt);
;         const char* nA = has_next ? (const char*)g.A + (size_t)nxt.pm * tstep : cA; const char* nB = has_next ? (const char*)g.Bt + (size_t)nxt.pn * tstep : cB;
;         for (int t = 0; t < nt; t += 2) {
;             const bool last = (t == nt - 2);
;             const char* a1 = cA + (size_t)(t + 1) * kstep;
;             const char* a2 = last ? nA : cA + (size_t)(t + 2) * kstep; const char* b2 = last ? nB : cB + (size_t)(t + 2) * kstep;
;             const char* a3 = a2 + kstep; const char* b3 = b2 + kstep;
;             if (last && has_next) S.a_ready(nxt);
;             if constexpr (SP2) {
;             PG8_LDB(B0, 0, 0); PG8_LDB(B1, 0, 1); PG8_SCHED; PG8_LDA(At, 0, 0); PG8_STAGE(PG8_SA(1, 1), a1 + hstep, voffA);
;             PG8_WAIT_V(8); PG8_WAIT_L(0); PG8_BAR; PG8_MMA(0, 0, At, B0); PG8_MMA(0, 1, At, B1); PG8_BAR; PG8_SCHED;
;             PG8_LDA(At, 0, 1); PG8_STAGE(PG8_SB(0, 0), b2, voffB); PG8_STAGE(PG8_SB(0, 1), b2 + hstep, voffB); PG8_STAGE(PG8_SA(0, 0), a2, voffA);
;             PG8_WAIT_V(8); PG8_WAIT_L(0); PG8_BAR; PG8_MMA(1, 0, At, B0); PG8_MMA(1, 1, At, B1); PG8_BAR; PG8_SCHED;
.LBB0_659:
	s_ashr_i32 s37, s36, 31
	s_lshl_b64 s[40:41], s[36:37], 19
	s_add_u32 s40, s70, s40
	s_addc_u32 s41, s71, s41
	s_and_b64 s[42:43], s[38:39], exec
	s_cselect_b32 s5, s41, s1
	s_cselect_b32 s37, s40, s0
	s_ashr_i32 s21, s20, 31
	s_lshl_b64 s[42:43], s[20:21], 19
	s_add_u32 s42, s23, s42
	s_addc_u32 s43, s24, s43
	s_and_b64 s[48:49], s[38:39], exec
	s_cselect_b32 s21, s43, s47
	s_cselect_b32 s45, s42, s46
	s_add_u32 s0, s0, 0x40080
	s_addc_u32 s1, s1, 0
	s_add_u32 s50, s46, 0x100
	s_addc_u32 s51, s47, 0
	s_mov_b32 s59, -2
	ds_read_b128 v[146:149], v165
	ds_read_b128 v[150:153], v165 offset:1024
	ds_read_b128 v[154:157], v165 offset:2048
	ds_read_b128 v[170:173], v165 offset:3072
	ds_read_b128 v[174:177], v166
	ds_read_b128 v[178:181], v166 offset:1024
	ds_read_b128 v[182:185], v166 offset:2048
	ds_read_b128 v[186:189], v166 offset:3072
	s_add_u32 s46, s0, 0xfffc0080
	s_addc_u32 s47, s1, -1
	s_cmp_eq_u32 s59, 12
	s_cselect_b32 s49, s5, s47
	s_cselect_b32 s48, s37, s46
	s_cselect_b32 s47, s21, s51
	s_cselect_b32 s46, s45, s50
	s_add_i32 m0, s26, 0xc000
	ds_read_b128 v[190:193], v167
	ds_read_b128 v[194:197], v167 offset:1024
	ds_read_b128 v[198:201], v167 offset:2048
	ds_read_b128 v[202:205], v167 offset:3072
	ds_read_b128 v[206:209], v167 offset:4096
	ds_read_b128 v[210:213], v167 offset:5120
	ds_read_b128 v[214:217], v167 offset:6144
	ds_read_b128 v[218:221], v167 offset:7168
	global_load_lds_dwordx4 v140, s[0:1]
	s_add_i32 m0, s26, 0xe000
	s_nop 0
	global_load_lds_dwordx4 v142, s[0:1]
	s_waitcnt vmcnt(8)
	s_waitcnt lgkmcnt(0)
	s_barrier
	s_setprio 1
	s_waitcnt lgkmcnt(0)
	v_mfma_f32_16x16x32_bf16 v[124:127], v[146:149], v[190:193], 0
	v_mfma_f32_16x16x32_bf16 v[120:123], v[154:157], v[190:193], 0
	v_mfma_f32_16x16x32_bf16 v[108:111], v[146:149], v[198:201], 0
	v_mfma_f32_16x16x32_bf16 v[104:107], v[154:157], v[198:201], 0
	v_mfma_f32_16x16x32_bf16 v[92:95], v[146:149], v[206:209], 0
	v_mfma_f32_16x16x32_bf16 v[88:91], v[154:157], v[206:209], 0
	v_mfma_f32_16x16x32_bf16 v[76:79], v[146:149], v[214:217], 0
	v_mfma_f32_16x16x32_bf16 v[72:75], v[154:157], v[214:217], 0
	v_mfma_f32_16x16x32_bf16 v[124:127], v[150:153], v[194:197], v[124:127]
	v_mfma_f32_16x16x32_bf16 v[120:123], v[170:173], v[194:197], v[120:123]
	v_mfma_f32_16x16x32_bf16 v[108:111], v[150:153], v[202:205], v[108:111]
	v_mfma_f32_16x16x32_bf16 v[104:107], v[170:173], v[202:205], v[104:107]
	v_mfma_f32_16x16x32_bf16 v[92:95], v[150:153], v[210:213], v[92:95]
	v_mfma_f32_16x16x32_bf16 v[88:91], v[170:173], v[210:213], v[88:91]
	v_mfma_f32_16x16x32_bf16 v[76:79], v[150:153], v[218:221], v[76:79]
	v_mfma_f32_16x16x32_bf16 v[72:75], v[170:173], v[218:221], v[72:75]
	s_setprio 0
	s_setprio 1
	v_mfma_f32_16x16x32_bf16 v[116:119], v[174:177], v[190:193], 0
	v_mfma_f32_16x16x32_bf16 v[112:115], v[182:185], v[190:193], 0
	v_mfma_f32_16x16x32_bf16 v[100:103], v[174:177], v[198:201], 0
	v_mfma_f32_16x16x32_bf16 v[96:99], v[182:185], v[198:201], 0
	v_mfma_f32_16x16x32_bf16 v[84:87], v[174:177], v[206:209], 0
	v_mfma_f32_16x16x32_bf16 v[80:83], v[182:185], v[206:209], 0
	v_mfma_f32_16x16x32_bf16 v[68:71], v[174:177], v[214:217], 0
	v_mfma_f32_16x16x32_bf16 v[64:67], v[182:185], v[214:217], 0
	v_mfma_f32_16x16x32_bf16 v[116:119], v[178:181], v[194:197], v[116:119]
	v_mfma_f32_16x16x32_bf16 v[112:115], v[186:189], v[194:197], v[112:115]
	v_mfma_f32_16x16x32_bf16 v[100:103], v[178:181], v[202:205], v[100:103]
	v_mfma_f32_16x16x32_bf16 v[96:99], v[186:189], v[202:205], v[96:99]
	v_mfma_f32_16x16x32_bf16 v[84:87], v[178:181], v[210:213], v[84:87]
	v_mfma_f32_16x16x32_bf16 v[80:83], v[186:189], v[210:213], v[80:83]
	v_mfma_f32_16x16x32_bf16 v[68:71], v[178:181], v[218:221], v[68:71]
	v_mfma_f32_16x16x32_bf16 v[64:67], v[186:189], v[218:221], v[64:67]
	s_setprio 0
	s_barrier
	s_add_i32 s60, s56, s25
	v_lshl_add_u64 v[158:159], s[46:47], 0, v[130:131]
	s_mov_b32 m0, s60
	ds_read_b128 v[190:193], v167 offset:16384
	ds_read_b128 v[194:197], v167 offset:17408
	ds_read_b128 v[198:201], v167 offset:18432
	ds_read_b128 v[202:205], v167 offset:19456
	ds_read_b128 v[206:209], v167 offset:20480
	ds_read_b128 v[210:213], v167 offset:21504
	ds_read_b128 v[214:217], v167 offset:22528
	ds_read_b128 v[218:221], v167 offset:23552
	global_load_lds_dwordx4 v[158:159], off
	s_add_i32 m0, s60, 0x2000
	s_add_u32 s60, s46, 0x40000
	v_lshl_add_u64 v[162:163], s[46:47], 0, v[134:135]
	s_addc_u32 s61, s47, 0
	s_add_i32 s62, s57, s25
	global_load_lds_dwordx4 v[162:163], off
	s_mov_b32 m0, s62
	v_lshl_add_u64 v[224:225], s[48:49], 0, v[132:133]
	global_load_lds_dwordx4 v130, s[60:61]
	s_add_i32 m0, s62, 0x2000
	s_nop 0
	global_load_lds_dwordx4 v134, s[60:61]
	v_lshl_add_u64 v[222:223], s[48:49], 0, v[128:129]
	s_mov_b32 m0, s26
	s_nop 0
	global_load_lds_dwordx4 v[222:223], off
	s_mov_b32 m0, s27
	s_nop 0
	global_load_lds_dwordx4 v[224:225], off
	s_cmp_lg_i32 s59, -2
	s_cbranch_scc1 .Lrsc_a_pl
	v_lshrrev_b32_e32 v250, 6, v230
	v_lshlrev_b32_e32 v250, 11, v250
	v_and_b32_e32 v251, 63, v230
	v_lshl_or_b32 v250, v251, 4, v250
	v_lshl_add_u32 v250, s44, 14, v250
	v_readfirstlane_b32 s98, v230
	s_lshr_b32 s98, s98, 6
	s_lshl_b32 s98, s98, 11
	s_add_i32 m0, s98, 0x20000
	s_add_u32 s100, s70, 0x3f000000
	s_addc_u32 s101, s71, 0
	global_load_lds_dwordx4 v250, s[100:101]
	global_load_lds_dwordx4 v250, s[100:101] offset:1024
	s_waitcnt vmcnt(10)
	s_branch .Lrsc_b_pl

; #define PG8_STAGE(bufoff, gbase, voff) do { _Pragma("unroll") for (int _i = 0; _i < 2; ++_i) \
;         __builtin_amdgcn_global_load_lds((const unsigned*)((const char*)(gbase) + (voff)[_i]), (PG8_LAS unsigned*)(lds + (bufoff) + ldsw + _i * 8192), 16, 0, 0); } while (0)
; #define PG8_LDA(dst, b, h) do { _Pragma("unroll") for (int m = 0; m < 4; ++m) _Pragma("unroll") for (int k = 0; k < 2; ++k) dst[m][k] = *(const PG8_LAS bf16x8*)(lds + PG8_SA(b, h) + aoff + m * 2048 + k * 1024); } while (0)
; #define PG8_LDB(dst, b, h) do { _Pragma("unroll") for (int n = 0; n < 2; ++n) _Pragma("unroll") for (int k = 0; k < 2; ++k) dst[n][k] = *(const PG8_LAS bf16x8*)(lds + PG8_SB(b, h) + boff + n * 2048 + k * 1024); } while (0)
; #define PG8_MMA(ai, bj, At, Bt) do { __builtin_amdgcn_s_setprio(1); _Pragma("unroll") for (int m = 0; m < 4; ++m) _Pragma("unroll") for (int n = 0; n < 2; ++n) _Pragma("unroll") for (int k = 0; k < 2; ++k) \
;         acc[ai][bj][m][n] = __builtin_amdgcn_mfma_f32_16x16x32_bf16(Bt[n][k], At[m][k], acc[ai][bj][m][n], 0, 0, 0); __builtin_amdgcn_s_setprio(0); } while (0)
; #define PG8_WAIT_V(n) asm volatile("s_waitcnt vmcnt(" #n ")" ::: "memory")
; #define PG8_WAIT_L(n) asm volatile("s_waitcnt lgkmcnt(" #n ")" ::: "memory")
; #define PG8_BAR __builtin_amdgcn_s_barrier()
; #define PG8_SCHED __builtin_amdgcn_sched_barrier(0)
; template <class Epi, class Sched, bool ALIGN_EPI = false, bool SP2 = false>
; __device__ __forceinline__ void gemm_phase(PG8_LAS unsigned char* lds, const Gemm g, const Sched& S, const Epi& E) {
;     ...
;             PG8_WAIT_V(8); PG8_WAIT_L(0); PG8_BAR; PG8_MMA(1, 0, At, B0); PG8_MMA(1, 1, At, B1); PG8_BAR; PG8_SCHED;
;             PG8_LDB(B0, 1, 0); PG8_LDB(B1, 1, 1); PG8_SCHED; PG8_LDA(At, 1, 0); PG8_STAGE(PG8_SA(0, 1), a2 + hstep, voffA);
;             PG8_WAIT_V(8); PG8_WAIT_L(0); PG8_BAR; PG8_MMA(0, 0, At, B0); PG8_MMA(0, 1, At, B1); PG8_BAR; PG8_SCHED;
.Lrsc_b_pl:
	s_waitcnt lgkmcnt(0)
	s_barrier
	s_setprio 1
	s_waitcnt lgkmcnt(0)
	v_mfma_f32_16x16x32_bf16 v[60:63], v[146:149], v[190:193], 0
	v_mfma_f32_16x16x32_bf16 v[56:59], v[154:157], v[190:193], 0
	v_mfma_f32_16x16x32_bf16 v[44:47], v[146:149], v[198:201], 0
	v_mfma_f32_16x16x32_bf16 v[40:43], v[154:157], v[198:201], 0
	v_mfma_f32_16x16x32_bf16 v[28:31], v[146:149], v[206:209], 0
	v_mfma_f32_16x16x32_bf16 v[24:27], v[154:157], v[206:209], 0
	v_mfma_f32_16x16x32_bf16 v[12:15], v[146:149], v[214:217], 0
	v_mfma_f32_16x16x32_bf16 v[8:11], v[154:157], v[214:217], 0
	v_mfma_f32_16x16x32_bf16 v[60:63], v[150:153], v[194:197], v[60:63]
	v_mfma_f32_16x16x32_bf16 v[56:59], v[170:173], v[194:197], v[56:59]
	v_mfma_f32_16x16x32_bf16 v[44:47], v[150:153], v[202:205], v[44:47]
	v_mfma_f32_16x16x32_bf16 v[40:43], v[170:173], v[202:205], v[40:43]
	v_mfma_f32_16x16x32_bf16 v[28:31], v[150:153], v[210:213], v[28:31]
	v_mfma_f32_16x16x32_bf16 v[24:27], v[170:173], v[210:213], v[24:27]
	v_mfma_f32_16x16x32_bf16 v[12:15], v[150:153], v[218:221], v[12:15]
	v_mfma_f32_16x16x32_bf16 v[8:11], v[170:173], v[218:221], v[8:11]
	s_setprio 0
	s_setprio 1
	v_mfma_f32_16x16x32_bf16 v[52:55], v[174:177], v[190:193], 0
	v_mfma_f32_16x16x32_bf16 v[48:51], v[182:185], v[190:193], 0
	v_mfma_f32_16x16x32_bf16 v[36:39], v[174:177], v[198:201], 0
	v_mfma_f32_16x16x32_bf16 v[32:35], v[182:185], v[198:201], 0
	v_mfma_f32_16x16x32_bf16 v[20:23], v[174:177], v[206:209], 0
	v_mfma_f32_16x16x32_bf16 v[16:19], v[182:185], v[206:209], 0
	v_mfma_f32_16x16x32_bf16 v[4:7], v[174:177], v[214:217], 0
	v_mfma_f32_16x16x32_bf16 v[0:3], v[182:185], v[214:217], 0
	v_mfma_f32_16x16x32_bf16 v[52:55], v[178:181], v[194:197], v[52:55]
	v_mfma_f32_16x16x32_bf16 v[48:51], v[186:189], v[194:197], v[48:51]
	v_mfma_f32_16x16x32_bf16 v[36:39], v[178:181], v[202:205], v[36:39]
	v_mfma_f32_16x16x32_bf16 v[32:35], v[186:189], v[202:205], v[32:35]
	v_mfma_f32_16x16x32_bf16 v[20:23], v[178:181], v[210:213], v[20:23]
	v_mfma_f32_16x16x32_bf16 v[16:19], v[186:189], v[210:213], v[16:19]
	v_mfma_f32_16x16x32_bf16 v[4:7], v[178:181], v[218:221], v[4:7]
	v_mfma_f32_16x16x32_bf16 v[0:3], v[186:189], v[218:221], v[0:3]
	s_setprio 0
	s_barrier
	s_add_i32 s60, 0, 0x18000
	v_add_u32_e32 v160, s60, v164
	s_add_i32 s61, 0, 0x1c000
	ds_read_b128 v[146:149], v160
	ds_read_b128 v[150:153], v160 offset:1024
	ds_read_b128 v[154:157], v160 offset:2048
	ds_read_b128 v[170:173], v160 offset:3072
	v_add_u32_e32 v160, s61, v164
	ds_read_b128 v[174:177], v160
	ds_read_b128 v[178:181], v160 offset:1024
	ds_read_b128 v[182:185], v160 offset:2048
	ds_read_b128 v[186:189], v160 offset:3072
	s_add_u32 s48, s48, 0x40000
	s_addc_u32 s49, s49, 0
	s_mov_b32 m0, s28
	ds_read_b128 v[190:193], v167 offset:32768
	ds_read_b128 v[194:197], v167 offset:33792
	ds_read_b128 v[198:201], v167 offset:34816
	ds_read_b128 v[202:205], v167 offset:35840
	ds_read_b128 v[206:209], v167 offset:36864
	ds_read_b128 v[210:213], v167 offset:37888
	ds_read_b128 v[214:217], v167 offset:38912
	ds_read_b128 v[218:221], v167 offset:39936
	global_load_lds_dwordx4 v128, s[48:49]
	v_lshl_add_u64 v[226:227], s[48:49], 0, v[132:133]
	s_mov_b32 m0, s29
	s_nop 0
	global_load_lds_dwordx4 v[226:227], off
	s_cmp_lg_i32 s59, -2
	s_cbranch_scc1 .Lrsc_c_pl
	s_waitcnt vmcnt(10)
	s_branch .Lrsc_d_pl

; #define PG8_STAGE(bufoff, gbase, voff) do { _Pragma("unroll") for (int _i = 0; _i < 2; ++_i) \
;         __builtin_amdgcn_global_load_lds((const unsigned*)((const char*)(gbase) + (voff)[_i]), (PG8_LAS unsigned*)(lds + (bufoff) + ldsw + _i * 8192), 16, 0, 0); } while (0)
; #define PG8_LDA(dst, b, h) do { _Pragma("unroll") for (int m = 0; m < 4; ++m) _Pragma("unroll") for (int k = 0; k < 2; ++k) dst[m][k] = *(const PG8_LAS bf16x8*)(lds + PG8_SA(b, h) + aoff + m * 2048 + k * 1024); } while (0)
; #define PG8_MMA(ai, bj, At, Bt) do { __builtin_amdgcn_s_setprio(1); _Pragma("unroll") for (int m = 0; m < 4; ++m) _Pragma("unroll") for (int n = 0; n < 2; ++n) _Pragma("unroll") for (int k = 0; k < 2; ++k) \
;         acc[ai][bj][m][n] = __builtin_amdgcn_mfma_f32_16x16x32_bf16(Bt[n][k], At[m][k], acc[ai][bj][m][n], 0, 0, 0); __builtin_amdgcn_s_setprio(0); } while (0)
; #define PG8_WAIT_V(n) asm volatile("s_waitcnt vmcnt(" #n ")" ::: "memory")
; #define PG8_WAIT_L(n) asm volatile("s_waitcnt lgkmcnt(" #n ")" ::: "memory")
; #define PG8_BAR __builtin_amdgcn_s_barrier()
; #define PG8_SCHED __builtin_amdgcn_sched_barrier(0)
; template <class Epi, class Sched, bool ALIGN_EPI = false, bool SP2 = false>
; __device__ __forceinline__ void gemm_phase(PG8_LAS unsigned char* lds, const Gemm g, const Sched& S, const Epi& E) {
;     ...
;             PG8_WAIT_V(8); PG8_WAIT_L(0); PG8_BAR; PG8_MMA(0, 0, At, B0); PG8_MMA(0, 1, At, B1); PG8_BAR; PG8_SCHED;
;             PG8_LDA(At, 1, 1); PG8_STAGE(PG8_SB(1, 0), b3, voffB); PG8_STAGE(PG8_SB(1, 1), b3 + hstep, voffB); PG8_STAGE(PG8_SA(1, 0), a3, voffA);
;             PG8_WAIT_V(8); PG8_WAIT_L(0); PG8_BAR; PG8_MMA(1, 0, At, B0); PG8_MMA(1, 1, At, B1); PG8_BAR; PG8_SCHED;
.Lrsc_d_pl:
	s_waitcnt lgkmcnt(0)
	s_barrier
	s_setprio 1
	s_waitcnt lgkmcnt(0)
	v_mfma_f32_16x16x32_bf16 v[124:127], v[146:149], v[190:193], v[124:127]
	v_mfma_f32_16x16x32_bf16 v[120:123], v[154:157], v[190:193], v[120:123]
	v_mfma_f32_16x16x32_bf16 v[108:111], v[146:149], v[198:201], v[108:111]
	v_mfma_f32_16x16x32_bf16 v[104:107], v[154:157], v[198:201], v[104:107]
	v_mfma_f32_16x16x32_bf16 v[92:95], v[146:149], v[206:209], v[92:95]
	v_mfma_f32_16x16x32_bf16 v[88:91], v[154:157], v[206:209], v[88:91]
	v_mfma_f32_16x16x32_bf16 v[76:79], v[146:149], v[214:217], v[76:79]
	v_mfma_f32_16x16x32_bf16 v[72:75], v[154:157], v[214:217], v[72:75]
	v_mfma_f32_16x16x32_bf16 v[124:127], v[150:153], v[194:197], v[124:127]
	v_mfma_f32_16x16x32_bf16 v[120:123], v[170:173], v[194:197], v[120:123]
	v_mfma_f32_16x16x32_bf16 v[108:111], v[150:153], v[202:205], v[108:111]
	v_mfma_f32_16x16x32_bf16 v[104:107], v[170:173], v[202:205], v[104:107]
	v_mfma_f32_16x16x32_bf16 v[92:95], v[150:153], v[210:213], v[92:95]
	v_mfma_f32_16x16x32_bf16 v[88:91], v[170:173], v[210:213], v[88:91]
	v_mfma_f32_16x16x32_bf16 v[76:79], v[150:153], v[218:221], v[76:79]
	v_mfma_f32_16x16x32_bf16 v[72:75], v[170:173], v[218:221], v[72:75]
	s_setprio 0
	s_setprio 1
	v_mfma_f32_16x16x32_bf16 v[116:119], v[174:177], v[190:193], v[116:119]
	v_mfma_f32_16x16x32_bf16 v[112:115], v[182:185], v[190:193], v[112:115]
	v_mfma_f32_16x16x32_bf16 v[100:103], v[174:177], v[198:201], v[100:103]
	v_mfma_f32_16x16x32_bf16 v[96:99], v[182:185], v[198:201], v[96:99]
	v_mfma_f32_16x16x32_bf16 v[84:87], v[174:177], v[206:209], v[84:87]
	v_mfma_f32_16x16x32_bf16 v[80:83], v[182:185], v[206:209], v[80:83]
	v_mfma_f32_16x16x32_bf16 v[68:71], v[174:177], v[214:217], v[68:71]
	v_mfma_f32_16x16x32_bf16 v[64:67], v[182:185], v[214:217], v[64:67]
	v_mfma_f32_16x16x32_bf16 v[116:119], v[178:181], v[194:197], v[116:119]
	v_mfma_f32_16x16x32_bf16 v[112:115], v[186:189], v[194:197], v[112:115]
	v_mfma_f32_16x16x32_bf16 v[100:103], v[178:181], v[202:205], v[100:103]
	v_mfma_f32_16x16x32_bf16 v[96:99], v[186:189], v[202:205], v[96:99]
	v_mfma_f32_16x16x32_bf16 v[84:87], v[178:181], v[210:213], v[84:87]
	v_mfma_f32_16x16x32_bf16 v[80:83], v[186:189], v[210:213], v[80:83]
	v_mfma_f32_16x16x32_bf16 v[68:71], v[178:181], v[218:221], v[68:71]
	v_mfma_f32_16x16x32_bf16 v[64:67], v[186:189], v[218:221], v[64:67]
	s_setprio 0
	s_barrier
	s_add_i32 s48, s60, s25
	v_lshl_add_u64 v[158:159], v[158:159], 0, s[16:17]
	s_mov_b32 m0, s48
	ds_read_b128 v[190:193], v167 offset:49152
	ds_read_b128 v[194:197], v167 offset:50176
	ds_read_b128 v[198:201], v167 offset:51200
	ds_read_b128 v[202:205], v167 offset:52224
	ds_read_b128 v[206:209], v167 offset:53248
	ds_read_b128 v[210:213], v167 offset:54272
	ds_read_b128 v[214:217], v167 offset:55296
	ds_read_b128 v[218:221], v167 offset:56320
	global_load_lds_dwordx4 v[158:159], off
	s_add_i32 m0, s48, 0x2000
	s_add_u32 s46, s46, 0x40080
	v_lshl_add_u64 v[158:159], v[162:163], 0, s[16:17]
	s_addc_u32 s47, s47, 0
	s_add_i32 s48, s61, s25
	global_load_lds_dwordx4 v[158:159], off
	s_mov_b32 m0, s48
	s_nop 0
	global_load_lds_dwordx4 v130, s[46:47]
	s_add_i32 m0, s48, 0x2000
	s_nop 0
	global_load_lds_dwordx4 v134, s[46:47]
	v_lshl_add_u64 v[158:159], v[222:223], 0, s[16:17]
	s_mov_b32 m0, s31
	s_nop 0
	global_load_lds_dwordx4 v[158:159], off
	v_lshl_add_u64 v[158:159], v[224:225], 0, s[16:17]
	s_mov_b32 m0, s33
	s_nop 0
	global_load_lds_dwordx4 v[158:159], off
	s_waitcnt vmcnt(8)
	s_waitcnt lgkmcnt(0)
	s_barrier
	s_setprio 1
	s_waitcnt lgkmcnt(0)
	v_mfma_f32_16x16x32_bf16 v[60:63], v[146:149], v[190:193], v[60:63]
	v_mfma_f32_16x16x32_bf16 v[56:59], v[154:157], v[190:193], v[56:59]
	v_mfma_f32_16x16x32_bf16 v[44:47], v[146:149], v[198:201], v[44:47]
	v_mfma_f32_16x16x32_bf16 v[40:43], v[154:157], v[198:201], v[40:43]
	v_mfma_f32_16x16x32_bf16 v[28:31], v[146:149], v[206:209], v[28:31]
	v_mfma_f32_16x16x32_bf16 v[24:27], v[154:157], v[206:209], v[24:27]
	v_mfma_f32_16x16x32_bf16 v[12:15], v[146:149], v[214:217], v[12:15]
	v_mfma_f32_16x16x32_bf16 v[8:11], v[154:157], v[214:217], v[8:11]
	v_mfma_f32_16x16x32_bf16 v[60:63], v[150:153], v[194:197], v[60:63]
	v_mfma_f32_16x16x32_bf16 v[56:59], v[170:173], v[194:197], v[56:59]
	v_mfma_f32_16x16x32_bf16 v[44:47], v[150:153], v[202:205], v[44:47]
	v_mfma_f32_16x16x32_bf16 v[40:43], v[170:173], v[202:205], v[40:43]
	v_mfma_f32_16x16x32_bf16 v[28:31], v[150:153], v[210:213], v[28:31]
	v_mfma_f32_16x16x32_bf16 v[24:27], v[170:173], v[210:213], v[24:27]
	v_mfma_f32_16x16x32_bf16 v[12:15], v[150:153], v[218:221], v[12:15]
	v_mfma_f32_16x16x32_bf16 v[8:11], v[170:173], v[218:221], v[8:11]
	s_setprio 0
	s_setprio 1
	v_mfma_f32_16x16x32_bf16 v[52:55], v[174:177], v[190:193], v[52:55]
	v_mfma_f32_16x16x32_bf16 v[48:51], v[182:185], v[190:193], v[48:51]
	v_mfma_f32_16x16x32_bf16 v[36:39], v[174:177], v[198:201], v[36:39]
	v_mfma_f32_16x16x32_bf16 v[32:35], v[182:185], v[198:201], v[32:35]
	v_mfma_f32_16x16x32_bf16 v[20:23], v[174:177], v[206:209], v[20:23]
	v_mfma_f32_16x16x32_bf16 v[16:19], v[182:185], v[206:209], v[16:19]
	v_mfma_f32_16x16x32_bf16 v[4:7], v[174:177], v[214:217], v[4:7]
	v_mfma_f32_16x16x32_bf16 v[0:3], v[182:185], v[214:217], v[0:3]
	v_mfma_f32_16x16x32_bf16 v[52:55], v[178:181], v[194:197], v[52:55]
	v_mfma_f32_16x16x32_bf16 v[48:51], v[186:189], v[194:197], v[48:51]
	v_mfma_f32_16x16x32_bf16 v[36:39], v[178:181], v[202:205], v[36:39]
	v_mfma_f32_16x16x32_bf16 v[32:35], v[186:189], v[202:205], v[32:35]
	v_mfma_f32_16x16x32_bf16 v[20:23], v[178:181], v[210:213], v[20:23]
	v_mfma_f32_16x16x32_bf16 v[16:19], v[186:189], v[210:213], v[16:19]
	v_mfma_f32_16x16x32_bf16 v[4:7], v[178:181], v[218:221], v[4:7]
	v_mfma_f32_16x16x32_bf16 v[0:3], v[186:189], v[218:221], v[0:3]
	s_setprio 0
	s_barrier
	s_add_i32 s59, s59, 2
	s_add_u32 s0, s0, 0x100
	s_addc_u32 s1, s1, 0
	s_add_u32 s50, s50, 0x100
	s_addc_u32 s51, s51, 0
	s_cmp_gt_u32 s59, 13
; #define PG8_STAGE(bufoff, gbase, voff) do { _Pragma("unroll") for (int _i = 0; _i < 2; ++_i) \
;         __builtin_amdgcn_global_load_lds((const unsigned*)((const char*)(gbase) + (voff)[_i]), (PG8_LAS unsigned*)(lds + (bufoff) + ldsw + _i * 8192), 16, 0, 0); } while (0)
; #define PG8_LDA(dst, b, h) do { _Pragma("unroll") for (int m = 0; m < 4; ++m) _Pragma("unroll") for (int k = 0; k < 2; ++k) dst[m][k] = *(const PG8_LAS bf16x8*)(lds + PG8_SA(b, h) + aoff + m * 2048 + k * 1024); } while (0)
; #define PG8_LDB(dst, b, h) do { _Pragma("unroll") for (int n = 0; n < 2; ++n) _Pragma("unroll") for (int k = 0; k < 2; ++k) dst[n][k] = *(const PG8_LAS bf16x8*)(lds + PG8_SB(b, h) + boff + n * 2048 + k * 1024); } while (0)
; #define PG8_MMA(ai, bj, At, Bt) do { __builtin_amdgcn_s_setprio(1); _Pragma("unroll") for (int m = 0; m < 4; ++m) _Pragma("unroll") for (int n = 0; n < 2; ++n) _Pragma("unroll") for (int k = 0; k < 2; ++k) \
;         acc[ai][bj][m][n] = __builtin_amdgcn_mfma_f32_16x16x32_bf16(Bt[n][k], At[m][k], acc[ai][bj][m][n], 0, 0, 0); __builtin_amdgcn_s_setprio(0); } while (0)
; #define PG8_WAIT_V(n) asm volatile("s_waitcnt vmcnt(" #n ")" ::: "memory")
; #define PG8_WAIT_L(n) asm volatile("s_waitcnt lgkmcnt(" #n ")" ::: "memory")
; #define PG8_BAR __builtin_amdgcn_s_barrier()
; #define PG8_SCHED __builtin_amdgcn_sched_barrier(0)
; template <class Epi, class Sched, bool ALIGN_EPI = false, bool SP2 = false>
; __device__ __forceinline__ void gemm_phase(PG8_LAS unsigned char* lds, const Gemm g, const Sched& S, const Epi& E) {
;     ...
;             PG8_LDB(B0, 0, 0); PG8_LDB(B1, 0, 1); PG8_SCHED; PG8_LDA(At, 0, 0); PG8_STAGE(PG8_SA(1, 1), a1 + hstep, voffA);
;             PG8_WAIT_V(8); PG8_WAIT_L(0); PG8_BAR; PG8_MMA(0, 0, At, B0); PG8_MMA(0, 1, At, B1); PG8_BAR; PG8_SCHED;
;             PG8_LDA(At, 0, 1); PG8_STAGE(PG8_SB(0, 0), b2, voffB); PG8_STAGE(PG8_SB(0, 1), b2 + hstep, voffB); PG8_STAGE(PG8_SA(0, 0), a2, voffA);
;             PG8_WAIT_V(8); PG8_WAIT_L(0); PG8_BAR; PG8_MMA(1, 0, At, B0); PG8_MMA(1, 1, At, B1); PG8_BAR; PG8_SCHED;
.LBB0_660:
	ds_read_b128 v[146:149], v165
	ds_read_b128 v[150:153], v165 offset:1024
	ds_read_b128 v[154:157], v165 offset:2048
	ds_read_b128 v[170:173], v165 offset:3072
	ds_read_b128 v[174:177], v166
	ds_read_b128 v[178:181], v166 offset:1024
	ds_read_b128 v[182:185], v166 offset:2048
	ds_read_b128 v[186:189], v166 offset:3072
	s_add_u32 s46, s0, 0xfffc0080
	s_addc_u32 s47, s1, -1
	s_cmp_eq_u32 s59, 12
	s_cselect_b32 s49, s5, s47
	s_cselect_b32 s48, s37, s46
	s_cselect_b32 s47, s21, s51
	s_cselect_b32 s46, s45, s50
	s_add_i32 m0, s26, 0xc000
	ds_read_b128 v[190:193], v167
	ds_read_b128 v[194:197], v167 offset:1024
	ds_read_b128 v[198:201], v167 offset:2048
	ds_read_b128 v[202:205], v167 offset:3072
	ds_read_b128 v[206:209], v167 offset:4096
	ds_read_b128 v[210:213], v167 offset:5120
	ds_read_b128 v[214:217], v167 offset:6144
	ds_read_b128 v[218:221], v167 offset:7168
	global_load_lds_dwordx4 v140, s[0:1]
	s_add_i32 m0, s26, 0xe000
	s_nop 0
	global_load_lds_dwordx4 v142, s[0:1]
	s_waitcnt vmcnt(8)
	s_waitcnt lgkmcnt(0)
	s_barrier
	s_setprio 1
	s_waitcnt lgkmcnt(0)
	v_mfma_f32_16x16x32_bf16 v[124:127], v[146:149], v[190:193], v[124:127]
	v_mfma_f32_16x16x32_bf16 v[120:123], v[154:157], v[190:193], v[120:123]
	v_mfma_f32_16x16x32_bf16 v[108:111], v[146:149], v[198:201], v[108:111]
	v_mfma_f32_16x16x32_bf16 v[104:107], v[154:157], v[198:201], v[104:107]
	v_mfma_f32_16x16x32_bf16 v[92:95], v[146:149], v[206:209], v[92:95]
	v_mfma_f32_16x16x32_bf16 v[88:91], v[154:157], v[206:209], v[88:91]
	v_mfma_f32_16x16x32_bf16 v[76:79], v[146:149], v[214:217], v[76:79]
	v_mfma_f32_16x16x32_bf16 v[72:75], v[154:157], v[214:217], v[72:75]
	v_mfma_f32_16x16x32_bf16 v[124:127], v[150:153], v[194:197], v[124:127]
	v_mfma_f32_16x16x32_bf16 v[120:123], v[170:173], v[194:197], v[120:123]
	v_mfma_f32_16x16x32_bf16 v[108:111], v[150:153], v[202:205], v[108:111]
	v_mfma_f32_16x16x32_bf16 v[104:107], v[170:173], v[202:205], v[104:107]
	v_mfma_f32_16x16x32_bf16 v[92:95], v[150:153], v[210:213], v[92:95]
	v_mfma_f32_16x16x32_bf16 v[88:91], v[170:173], v[210:213], v[88:91]
	v_mfma_f32_16x16x32_bf16 v[76:79], v[150:153], v[218:221], v[76:79]
	v_mfma_f32_16x16x32_bf16 v[72:75], v[170:173], v[218:221], v[72:75]
	s_setprio 0
	s_setprio 1
	v_mfma_f32_16x16x32_bf16 v[116:119], v[174:177], v[190:193], v[116:119]
	v_mfma_f32_16x16x32_bf16 v[112:115], v[182:185], v[190:193], v[112:115]
	v_mfma_f32_16x16x32_bf16 v[100:103], v[174:177], v[198:201], v[100:103]
	v_mfma_f32_16x16x32_bf16 v[96:99], v[182:185], v[198:201], v[96:99]
	v_mfma_f32_16x16x32_bf16 v[84:87], v[174:177], v[206:209], v[84:87]
	v_mfma_f32_16x16x32_bf16 v[80:83], v[182:185], v[206:209], v[80:83]
	v_mfma_f32_16x16x32_bf16 v[68:71], v[174:177], v[214:217], v[68:71]
	v_mfma_f32_16x16x32_bf16 v[64:67], v[182:185], v[214:217], v[64:67]
	v_mfma_f32_16x16x32_bf16 v[116:119], v[178:181], v[194:197], v[116:119]
	v_mfma_f32_16x16x32_bf16 v[112:115], v[186:189], v[194:197], v[112:115]
	v_mfma_f32_16x16x32_bf16 v[100:103], v[178:181], v[202:205], v[100:103]
	v_mfma_f32_16x16x32_bf16 v[96:99], v[186:189], v[202:205], v[96:99]
	v_mfma_f32_16x16x32_bf16 v[84:87], v[178:181], v[210:213], v[84:87]
	v_mfma_f32_16x16x32_bf16 v[80:83], v[186:189], v[210:213], v[80:83]
	v_mfma_f32_16x16x32_bf16 v[68:71], v[178:181], v[218:221], v[68:71]
	v_mfma_f32_16x16x32_bf16 v[64:67], v[186:189], v[218:221], v[64:67]
	s_setprio 0
	s_barrier
	s_add_i32 s60, s56, s25
	v_lshl_add_u64 v[158:159], s[46:47], 0, v[130:131]
	s_mov_b32 m0, s60
	ds_read_b128 v[190:193], v167 offset:16384
	ds_read_b128 v[194:197], v167 offset:17408
	ds_read_b128 v[198:201], v167 offset:18432
	ds_read_b128 v[202:205], v167 offset:19456
	ds_read_b128 v[206:209], v167 offset:20480
	ds_read_b128 v[210:213], v167 offset:21504
	ds_read_b128 v[214:217], v167 offset:22528
	ds_read_b128 v[218:221], v167 offset:23552
	global_load_lds_dwordx4 v[158:159], off
	s_add_i32 m0, s60, 0x2000
	s_add_u32 s60, s46, 0x40000
	v_lshl_add_u64 v[162:163], s[46:47], 0, v[134:135]
	s_addc_u32 s61, s47, 0
	s_add_i32 s62, s57, s25
	global_load_lds_dwordx4 v[162:163], off
	s_mov_b32 m0, s62
	v_lshl_add_u64 v[224:225], s[48:49], 0, v[132:133]
	global_load_lds_dwordx4 v130, s[60:61]
	s_add_i32 m0, s62, 0x2000
	s_nop 0
	global_load_lds_dwordx4 v134, s[60:61]
	v_lshl_add_u64 v[222:223], s[48:49], 0, v[128:129]
	s_mov_b32 m0, s26
	s_nop 0
	global_load_lds_dwordx4 v[222:223], off
	s_mov_b32 m0, s27
	s_nop 0
	global_load_lds_dwordx4 v[224:225], off
	s_cmp_lg_i32 s59, -2
	s_cbranch_scc1 .Lrsc_a
	v_lshrrev_b32_e32 v250, 6, v230
	v_lshlrev_b32_e32 v250, 11, v250
	v_and_b32_e32 v251, 63, v230
	v_lshl_or_b32 v250, v251, 4, v250
	v_lshl_add_u32 v250, s44, 14, v250
	v_readfirstlane_b32 s98, v230
	s_lshr_b32 s98, s98, 6
	s_lshl_b32 s98, s98, 11
	s_add_i32 m0, s98, 0x20000
	s_add_u32 s100, s70, 0x3f000000
	s_addc_u32 s101, s71, 0
	global_load_lds_dwordx4 v250, s[100:101]
	global_load_lds_dwordx4 v250, s[100:101] offset:1024
	s_waitcnt vmcnt(10)
	s_branch .Lrsc_b

; #define PG8_STAGE(bufoff, gbase, voff) do { _Pragma("unroll") for (int _i = 0; _i < 2; ++_i) \
;         __builtin_amdgcn_global_load_lds((const unsigned*)((const char*)(gbase) + (voff)[_i]), (PG8_LAS unsigned*)(lds + (bufoff) + ldsw + _i * 8192), 16, 0, 0); } while (0)
; #define PG8_LDA(dst, b, h) do { _Pragma("unroll") for (int m = 0; m < 4; ++m) _Pragma("unroll") for (int k = 0; k < 2; ++k) dst[m][k] = *(const PG8_LAS bf16x8*)(lds + PG8_SA(b, h) + aoff + m * 2048 + k * 1024); } while (0)
; #define PG8_LDB(dst, b, h) do { _Pragma("unroll") for (int n = 0; n < 2; ++n) _Pragma("unroll") for (int k = 0; k < 2; ++k) dst[n][k] = *(const PG8_LAS bf16x8*)(lds + PG8_SB(b, h) + boff + n * 2048 + k * 1024); } while (0)
; #define PG8_MMA(ai, bj, At, Bt) do { __builtin_amdgcn_s_setprio(1); _Pragma("unroll") for (int m = 0; m < 4; ++m) _Pragma("unroll") for (int n = 0; n < 2; ++n) _Pragma("unroll") for (int k = 0; k < 2; ++k) \
;         acc[ai][bj][m][n] = __builtin_amdgcn_mfma_f32_16x16x32_bf16(Bt[n][k], At[m][k], acc[ai][bj][m][n], 0, 0, 0); __builtin_amdgcn_s_setprio(0); } while (0)
; #define PG8_WAIT_V(n) asm volatile("s_waitcnt vmcnt(" #n ")" ::: "memory")
; #define PG8_WAIT_L(n) asm volatile("s_waitcnt lgkmcnt(" #n ")" ::: "memory")
; #define PG8_BAR __builtin_amdgcn_s_barrier()
; #define PG8_SCHED __builtin_amdgcn_sched_barrier(0)
; template <class Epi, class Sched, bool ALIGN_EPI = false, bool SP2 = false>
; __device__ __forceinline__ void gemm_phase(PG8_LAS unsigned char* lds, const Gemm g, const Sched& S, const Epi& E) {
;     ...
;             PG8_WAIT_V(8); PG8_WAIT_L(0); PG8_BAR; PG8_MMA(1, 0, At, B0); PG8_MMA(1, 1, At, B1); PG8_BAR; PG8_SCHED;
;             PG8_LDB(B0, 1, 0); PG8_LDB(B1, 1, 1); PG8_SCHED; PG8_LDA(At, 1, 0); PG8_STAGE(PG8_SA(0, 1), a2 + hstep, voffA);
;             PG8_WAIT_V(8); PG8_WAIT_L(0); PG8_BAR; PG8_MMA(0, 0, At, B0); PG8_MMA(0, 1, At, B1); PG8_BAR; PG8_SCHED;
.Lrsc_b:
	s_waitcnt lgkmcnt(0)
	s_barrier
	s_setprio 1
	s_waitcnt lgkmcnt(0)
	v_mfma_f32_16x16x32_bf16 v[60:63], v[146:149], v[190:193], v[60:63]
	v_mfma_f32_16x16x32_bf16 v[56:59], v[154:157], v[190:193], v[56:59]
	v_mfma_f32_16x16x32_bf16 v[44:47], v[146:149], v[198:201], v[44:47]
	v_mfma_f32_16x16x32_bf16 v[40:43], v[154:157], v[198:201], v[40:43]
	v_mfma_f32_16x16x32_bf16 v[28:31], v[146:149], v[206:209], v[28:31]
	v_mfma_f32_16x16x32_bf16 v[24:27], v[154:157], v[206:209], v[24:27]
	v_mfma_f32_16x16x32_bf16 v[12:15], v[146:149], v[214:217], v[12:15]
	v_mfma_f32_16x16x32_bf16 v[8:11], v[154:157], v[214:217], v[8:11]
	v_mfma_f32_16x16x32_bf16 v[60:63], v[150:153], v[194:197], v[60:63]
	v_mfma_f32_16x16x32_bf16 v[56:59], v[170:173], v[194:197], v[56:59]
	v_mfma_f32_16x16x32_bf16 v[44:47], v[150:153], v[202:205], v[44:47]
	v_mfma_f32_16x16x32_bf16 v[40:43], v[170:173], v[202:205], v[40:43]
	v_mfma_f32_16x16x32_bf16 v[28:31], v[150:153], v[210:213], v[28:31]
	v_mfma_f32_16x16x32_bf16 v[24:27], v[170:173], v[210:213], v[24:27]
	v_mfma_f32_16x16x32_bf16 v[12:15], v[150:153], v[218:221], v[12:15]
	v_mfma_f32_16x16x32_bf16 v[8:11], v[170:173], v[218:221], v[8:11]
	s_setprio 0
	s_setprio 1
	v_mfma_f32_16x16x32_bf16 v[52:55], v[174:177], v[190:193], v[52:55]
	v_mfma_f32_16x16x32_bf16 v[48:51], v[182:185], v[190:193], v[48:51]
	v_mfma_f32_16x16x32_bf16 v[36:39], v[174:177], v[198:201], v[36:39]
	v_mfma_f32_16x16x32_bf16 v[32:35], v[182:185], v[198:201], v[32:35]
	v_mfma_f32_16x16x32_bf16 v[20:23], v[174:177], v[206:209], v[20:23]
	v_mfma_f32_16x16x32_bf16 v[16:19], v[182:185], v[206:209], v[16:19]
	v_mfma_f32_16x16x32_bf16 v[4:7], v[174:177], v[214:217], v[4:7]
	v_mfma_f32_16x16x32_bf16 v[0:3], v[182:185], v[214:217], v[0:3]
	v_mfma_f32_16x16x32_bf16 v[52:55], v[178:181], v[194:197], v[52:55]
	v_mfma_f32_16x16x32_bf16 v[48:51], v[186:189], v[194:197], v[48:51]
	v_mfma_f32_16x16x32_bf16 v[36:39], v[178:181], v[202:205], v[36:39]
	v_mfma_f32_16x16x32_bf16 v[32:35], v[186:189], v[202:205], v[32:35]
	v_mfma_f32_16x16x32_bf16 v[20:23], v[178:181], v[210:213], v[20:23]
	v_mfma_f32_16x16x32_bf16 v[16:19], v[186:189], v[210:213], v[16:19]
	v_mfma_f32_16x16x32_bf16 v[4:7], v[178:181], v[218:221], v[4:7]
	v_mfma_f32_16x16x32_bf16 v[0:3], v[186:189], v[218:221], v[0:3]
	s_setprio 0
	s_barrier
	s_add_i32 s60, 0, 0x18000
	v_add_u32_e32 v160, s60, v164
	s_add_i32 s61, 0, 0x1c000
	ds_read_b128 v[146:149], v160
	ds_read_b128 v[150:153], v160 offset:1024
	ds_read_b128 v[154:157], v160 offset:2048
	ds_read_b128 v[170:173], v160 offset:3072
	v_add_u32_e32 v160, s61, v164
	ds_read_b128 v[174:177], v160
	ds_read_b128 v[178:181], v160 offset:1024
	ds_read_b128 v[182:185], v160 offset:2048
	ds_read_b128 v[186:189], v160 offset:3072
	s_add_u32 s48, s48, 0x40000
	s_addc_u32 s49, s49, 0
	s_mov_b32 m0, s28
	ds_read_b128 v[190:193], v167 offset:32768
	ds_read_b128 v[194:197], v167 offset:33792
	ds_read_b128 v[198:201], v167 offset:34816
	ds_read_b128 v[202:205], v167 offset:35840
	ds_read_b128 v[206:209], v167 offset:36864
	ds_read_b128 v[210:213], v167 offset:37888
	ds_read_b128 v[214:217], v167 offset:38912
	ds_read_b128 v[218:221], v167 offset:39936
	global_load_lds_dwordx4 v128, s[48:49]
	v_lshl_add_u64 v[226:227], s[48:49], 0, v[132:133]
	s_mov_b32 m0, s29
	s_nop 0
	global_load_lds_dwordx4 v[226:227], off
	s_cmp_lg_i32 s59, -2
	s_cbranch_scc1 .Lrsc_c
	s_waitcnt vmcnt(10)
	s_branch .Lrsc_d

; #define PG8_STAGE(bufoff, gbase, voff) do { _Pragma("unroll") for (int _i = 0; _i < 2; ++_i) \
;         __builtin_amdgcn_global_load_lds((const unsigned*)((const char*)(gbase) + (voff)[_i]), (PG8_LAS unsigned*)(lds + (bufoff) + ldsw + _i * 8192), 16, 0, 0); } while (0)
; #define PG8_LDA(dst, b, h) do { _Pragma("unroll") for (int m = 0; m < 4; ++m) _Pragma("unroll") for (int k = 0; k < 2; ++k) dst[m][k] = *(const PG8_LAS bf16x8*)(lds + PG8_SA(b, h) + aoff + m * 2048 + k * 1024); } while (0)
; #define PG8_MMA(ai, bj, At, Bt) do { __builtin_amdgcn_s_setprio(1); _Pragma("unroll") for (int m = 0; m < 4; ++m) _Pragma("unroll") for (int n = 0; n < 2; ++n) _Pragma("unroll") for (int k = 0; k < 2; ++k) \
;         acc[ai][bj][m][n] = __builtin_amdgcn_mfma_f32_16x16x32_bf16(Bt[n][k], At[m][k], acc[ai][bj][m][n], 0, 0, 0); __builtin_amdgcn_s_setprio(0); } while (0)
; #define PG8_WAIT_V(n) asm volatile("s_waitcnt vmcnt(" #n ")" ::: "memory")
; #define PG8_WAIT_L(n) asm volatile("s_waitcnt lgkmcnt(" #n ")" ::: "memory")
; #define PG8_BAR __builtin_amdgcn_s_barrier()
; #define PG8_SCHED __builtin_amdgcn_sched_barrier(0)
; template <class Epi, class Sched, bool ALIGN_EPI = false, bool SP2 = false>
; __device__ __forceinline__ void gemm_phase(PG8_LAS unsigned char* lds, const Gemm g, const Sched& S, const Epi& E) {
;     ...
;             PG8_WAIT_V(8); PG8_WAIT_L(0); PG8_BAR; PG8_MMA(0, 0, At, B0); PG8_MMA(0, 1, At, B1); PG8_BAR; PG8_SCHED;
;             PG8_LDA(At, 1, 1); PG8_STAGE(PG8_SB(1, 0), b3, voffB); PG8_STAGE(PG8_SB(1, 1), b3 + hstep, voffB); PG8_STAGE(PG8_SA(1, 0), a3, voffA);
;             PG8_WAIT_V(8); PG8_WAIT_L(0); PG8_BAR; PG8_MMA(1, 0, At, B0); PG8_MMA(1, 1, At, B1); PG8_BAR; PG8_SCHED;
.Lrsc_d:
	s_waitcnt lgkmcnt(0)
	s_barrier
	s_setprio 1
	s_waitcnt lgkmcnt(0)
	v_mfma_f32_16x16x32_bf16 v[124:127], v[146:149], v[190:193], v[124:127]
	v_mfma_f32_16x16x32_bf16 v[120:123], v[154:157], v[190:193], v[120:123]
	v_mfma_f32_16x16x32_bf16 v[108:111], v[146:149], v[198:201], v[108:111]
	v_mfma_f32_16x16x32_bf16 v[104:107], v[154:157], v[198:201], v[104:107]
	v_mfma_f32_16x16x32_bf16 v[92:95], v[146:149], v[206:209], v[92:95]
	v_mfma_f32_16x16x32_bf16 v[88:91], v[154:157], v[206:209], v[88:91]
	v_mfma_f32_16x16x32_bf16 v[76:79], v[146:149], v[214:217], v[76:79]
	v_mfma_f32_16x16x32_bf16 v[72:75], v[154:157], v[214:217], v[72:75]
	v_mfma_f32_16x16x32_bf16 v[124:127], v[150:153], v[194:197], v[124:127]
	v_mfma_f32_16x16x32_bf16 v[120:123], v[170:173], v[194:197], v[120:123]
	v_mfma_f32_16x16x32_bf16 v[108:111], v[150:153], v[202:205], v[108:111]
	v_mfma_f32_16x16x32_bf16 v[104:107], v[170:173], v[202:205], v[104:107]
	v_mfma_f32_16x16x32_bf16 v[92:95], v[150:153], v[210:213], v[92:95]
	v_mfma_f32_16x16x32_bf16 v[88:91], v[170:173], v[210:213], v[88:91]
	v_mfma_f32_16x16x32_bf16 v[76:79], v[150:153], v[218:221], v[76:79]
	v_mfma_f32_16x16x32_bf16 v[72:75], v[170:173], v[218:221], v[72:75]
	s_setprio 0
	s_setprio 1
	v_mfma_f32_16x16x32_bf16 v[116:119], v[174:177], v[190:193], v[116:119]
	v_mfma_f32_16x16x32_bf16 v[112:115], v[182:185], v[190:193], v[112:115]
	v_mfma_f32_16x16x32_bf16 v[100:103], v[174:177], v[198:201], v[100:103]
	v_mfma_f32_16x16x32_bf16 v[96:99], v[182:185], v[198:201], v[96:99]
	v_mfma_f32_16x16x32_bf16 v[84:87], v[174:177], v[206:209], v[84:87]
	v_mfma_f32_16x16x32_bf16 v[80:83], v[182:185], v[206:209], v[80:83]
	v_mfma_f32_16x16x32_bf16 v[68:71], v[174:177], v[214:217], v[68:71]
	v_mfma_f32_16x16x32_bf16 v[64:67], v[182:185], v[214:217], v[64:67]
	v_mfma_f32_16x16x32_bf16 v[116:119], v[178:181], v[194:197], v[116:119]
	v_mfma_f32_16x16x32_bf16 v[112:115], v[186:189], v[194:197], v[112:115]
	v_mfma_f32_16x16x32_bf16 v[100:103], v[178:181], v[202:205], v[100:103]
	v_mfma_f32_16x16x32_bf16 v[96:99], v[186:189], v[202:205], v[96:99]
	v_mfma_f32_16x16x32_bf16 v[84:87], v[178:181], v[210:213], v[84:87]
	v_mfma_f32_16x16x32_bf16 v[80:83], v[186:189], v[210:213], v[80:83]
	v_mfma_f32_16x16x32_bf16 v[68:71], v[178:181], v[218:221], v[68:71]
	v_mfma_f32_16x16x32_bf16 v[64:67], v[186:189], v[218:221], v[64:67]
	s_setprio 0
	s_barrier
	s_add_i32 s48, s60, s25
	v_lshl_add_u64 v[158:159], v[158:159], 0, s[16:17]
	s_mov_b32 m0, s48
	ds_read_b128 v[190:193], v167 offset:49152
	ds_read_b128 v[194:197], v167 offset:50176
	ds_read_b128 v[198:201], v167 offset:51200
	ds_read_b128 v[202:205], v167 offset:52224
	ds_read_b128 v[206:209], v167 offset:53248
	ds_read_b128 v[210:213], v167 offset:54272
	ds_read_b128 v[214:217], v167 offset:55296
	ds_read_b128 v[218:221], v167 offset:56320
	global_load_lds_dwordx4 v[158:159], off
	s_add_i32 m0, s48, 0x2000
	s_add_u32 s46, s46, 0x40080
	v_lshl_add_u64 v[158:159], v[162:163], 0, s[16:17]
	s_addc_u32 s47, s47, 0
	s_add_i32 s48, s61, s25
	global_load_lds_dwordx4 v[158:159], off
	s_mov_b32 m0, s48
	s_nop 0
	global_load_lds_dwordx4 v130, s[46:47]
	s_add_i32 m0, s48, 0x2000
	s_nop 0
	global_load_lds_dwordx4 v134, s[46:47]
	v_lshl_add_u64 v[158:159], v[222:223], 0, s[16:17]
	s_mov_b32 m0, s31
	s_nop 0
	global_load_lds_dwordx4 v[158:159], off
	v_lshl_add_u64 v[158:159], v[224:225], 0, s[16:17]
	s_mov_b32 m0, s33
	s_nop 0
	global_load_lds_dwordx4 v[158:159], off
	s_waitcnt vmcnt(8)
	s_waitcnt lgkmcnt(0)
	s_barrier
	s_setprio 1
	s_waitcnt lgkmcnt(0)
	v_mfma_f32_16x16x32_bf16 v[60:63], v[146:149], v[190:193], v[60:63]
	v_mfma_f32_16x16x32_bf16 v[56:59], v[154:157], v[190:193], v[56:59]
	v_mfma_f32_16x16x32_bf16 v[44:47], v[146:149], v[198:201], v[44:47]
	v_mfma_f32_16x16x32_bf16 v[40:43], v[154:157], v[198:201], v[40:43]
	v_mfma_f32_16x16x32_bf16 v[28:31], v[146:149], v[206:209], v[28:31]
	v_mfma_f32_16x16x32_bf16 v[24:27], v[154:157], v[206:209], v[24:27]
	v_mfma_f32_16x16x32_bf16 v[12:15], v[146:149], v[214:217], v[12:15]
	v_mfma_f32_16x16x32_bf16 v[8:11], v[154:157], v[214:217], v[8:11]
	v_mfma_f32_16x16x32_bf16 v[60:63], v[150:153], v[194:197], v[60:63]
	v_mfma_f32_16x16x32_bf16 v[56:59], v[170:173], v[194:197], v[56:59]
	v_mfma_f32_16x16x32_bf16 v[44:47], v[150:153], v[202:205], v[44:47]
	v_mfma_f32_16x16x32_bf16 v[40:43], v[170:173], v[202:205], v[40:43]
	v_mfma_f32_16x16x32_bf16 v[28:31], v[150:153], v[210:213], v[28:31]
	v_mfma_f32_16x16x32_bf16 v[24:27], v[170:173], v[210:213], v[24:27]
	v_mfma_f32_16x16x32_bf16 v[12:15], v[150:153], v[218:221], v[12:15]
	v_mfma_f32_16x16x32_bf16 v[8:11], v[170:173], v[218:221], v[8:11]
	s_setprio 0
	s_setprio 1
	v_mfma_f32_16x16x32_bf16 v[52:55], v[174:177], v[190:193], v[52:55]
	v_mfma_f32_16x16x32_bf16 v[48:51], v[182:185], v[190:193], v[48:51]
	v_mfma_f32_16x16x32_bf16 v[36:39], v[174:177], v[198:201], v[36:39]
	v_mfma_f32_16x16x32_bf16 v[32:35], v[182:185], v[198:201], v[32:35]
	v_mfma_f32_16x16x32_bf16 v[20:23], v[174:177], v[206:209], v[20:23]
	v_mfma_f32_16x16x32_bf16 v[16:19], v[182:185], v[206:209], v[16:19]
	v_mfma_f32_16x16x32_bf16 v[4:7], v[174:177], v[214:217], v[4:7]
	v_mfma_f32_16x16x32_bf16 v[0:3], v[182:185], v[214:217], v[0:3]
	v_mfma_f32_16x16x32_bf16 v[52:55], v[178:181], v[194:197], v[52:55]
	v_mfma_f32_16x16x32_bf16 v[48:51], v[186:189], v[194:197], v[48:51]
	v_mfma_f32_16x16x32_bf16 v[36:39], v[178:181], v[202:205], v[36:39]
	v_mfma_f32_16x16x32_bf16 v[32:35], v[186:189], v[202:205], v[32:35]
	v_mfma_f32_16x16x32_bf16 v[20:23], v[178:181], v[210:213], v[20:23]
	v_mfma_f32_16x16x32_bf16 v[16:19], v[186:189], v[210:213], v[16:19]
	v_mfma_f32_16x16x32_bf16 v[4:7], v[178:181], v[218:221], v[4:7]
	v_mfma_f32_16x16x32_bf16 v[0:3], v[186:189], v[218:221], v[0:3]
	s_setprio 0
	s_barrier
	s_add_i32 s59, s59, 2
	s_add_u32 s0, s0, 0x100
	s_addc_u32 s1, s1, 0
	s_add_u32 s50, s50, 0x100
	s_addc_u32 s51, s51, 0
	s_cmp_gt_u32 s59, 13
	s_cbranch_scc0 .LBB0_660
	s_and_b64 vcc, exec, s[18:19]
	s_cbranch_vccz .LBB0_663
	s_barrier

; #define PG8_STAGE(bufoff, gbase, voff) do { _Pragma("unroll") for (int _i = 0; _i < 2; ++_i) \
;         __builtin_amdgcn_global_load_lds((const unsigned*)((const char*)(gbase) + (voff)[_i]), (PG8_LAS unsigned*)(lds + (bufoff) + ldsw + _i * 8192), 16, 0, 0); } while (0)
; #define PG8_WAIT_V(n) asm volatile("s_waitcnt vmcnt(" #n ")" ::: "memory")
; #define PG8_BAR __builtin_amdgcn_s_barrier()
; template <class Epi, class Sched, bool ALIGN_EPI = false, bool SP2 = false>
; __device__ __forceinline__ void gemm_phase(PG8_LAS unsigned char* lds, const Gemm g, const Sched& S, const Epi& E) {
;     const int tid = threadIdx.x, wid = __builtin_amdgcn_readfirstlane(tid >> 6), lane = tid & 63, wr = wid >> 2, wc = wid & 3, fr = lane & 15, fq = lane >> 4;
;     const int K = g.K, nt = K / BK;
;     unsigned voffA[2], voffB[2];
; #pragma unroll
;     for (int i = 0; i < 2; ++i) { int R, C; stage_rc(tid * 16 + i * 8192, R, C); const int Rb = Epi::PERM ? ((R & ~31) + perm32(R & 31)) : R;
;         voffA[i] = (unsigned)(R * K + C) * 2u; voffB[i] = (unsigned)(Rb * K + C) * 2u; }
;     const size_t kstep = (size_t)(BK * 2);
;     const size_t hstep = (size_t)HALF * K * 2;
;     const size_t tstep = 2 * hstep;
;     const unsigned ldsw = (unsigned)wid * 1024u;
;     const int aoff = lds_byte(wr * 64 + fr, fq * 8), boff = lds_byte(wc * 32 + fr, fq * 8);
;     ...
;         PG8_STAGE(PG8_SB(1, 0), cB + kstep, voffB); PG8_STAGE(PG8_SA(1, 0), cA + kstep, voffA); PG8_STAGE(PG8_SB(1, 1), cB + hstep + kstep, voffB);
;         PG8_WAIT_V(6); PG8_BAR;
.LBB0_877:
	s_mov_b64 s[16:17], 0x80
	s_and_b32 s49, s1, 3
	s_add_i32 m0, s45, 0x18000
	v_lshl_add_u64 v[6:7], v[6:7], 0, s[16:17]
	s_lshl_b32 s1, s0, 13
	s_lshl_b32 s19, s49, 12
	s_waitcnt vmcnt(2)
	s_barrier
	global_load_lds_dwordx4 v[6:7], off
	v_lshl_add_u64 v[4:5], v[4:5], 0, s[16:17]
	s_add_i32 m0, s45, 0x1a000
	s_add_i32 s50, s45, 0x8000
	s_add_i32 s51, s45, 0xa000
	global_load_lds_dwordx4 v[4:5], off
	v_lshl_add_u64 v[0:1], v[0:1], 0, s[16:17]
	s_mov_b32 m0, s50
	s_add_u32 s20, s38, 0x40080
	global_load_lds_dwordx4 v[0:1], off
	v_lshl_add_u64 v[0:1], v[2:3], 0, s[16:17]
	s_mov_b32 m0, s51
	s_addc_u32 s21, s39, 0
	global_load_lds_dwordx4 v[0:1], off
	s_add_i32 m0, s45, 0x1c000
	global_load_lds_dwordx4 v186, s[20:21]
	v_lshl_add_u64 v[0:1], s[20:21], 0, v[190:191]
	s_add_i32 m0, s45, 0x1e000
	v_lshlrev_b32_e32 v4, 2, v230
	global_load_lds_dwordx4 v[0:1], off
	v_bfe_u32 v0, v230, 4, 2
	v_and_b32_e32 v1, 15, v230
	v_lshlrev_b32_e32 v3, 4, v0
	v_lshl_or_b32 v231, s0, 6, v1
	v_lshl_or_b32 v1, v1, 6, v3
	v_and_b32_e32 v4, 32, v4
	v_lshlrev_b32_e32 v5, 6, v230
	s_movk_i32 s0, 0x3c0
	v_lshlrev_b32_e32 v2, 3, v0
	v_bitop3_b32 v1, v1, s1, v4 bitop3:0xde
	v_and_or_b32 v3, v5, s0, v3
	v_cmp_eq_u32_e64 s[0:1], 0, v0
	v_lshlrev_b32_e32 v0, 8, v230
	v_lshl_or_b32 v233, s49, 5, v2
	v_and_b32_e32 v0, 0x38000, v0
	v_lshlrev_b32_e32 v2, 11, v10
	v_or3_b32 v0, v8, v0, v2
	v_add_u32_e32 v192, v0, v9
	v_lshlrev_b32_e32 v0, 4, v11
	v_and_b32_e32 v0, 0x78000, v0
	s_waitcnt vmcnt(6)
	s_cmpk_lt_u32 s18, 0x100
	v_or3_b32 v0, v8, v0, v2
	v_bitop3_b32 v232, s19, v3, v4 bitop3:0xf6
	s_cselect_b64 s[18:19], -1, 0
	v_add_u32_e32 v194, v0, v9
	s_add_i32 s55, 0, 0x10000
	s_add_i32 s56, 0, 0x14000
	v_mbcnt_lo_u32_b32 v0, -1, 0
	s_ashr_i32 s52, s74, 31
	s_mov_b32 s53, s74
	s_ashr_i32 s54, s2, 31
	v_mov_b32_e32 v193, v187
	v_mov_b32_e32 v195, v187
	v_add_u32_e32 v234, s55, v232
	v_add_u32_e32 v235, s56, v232
	v_add_u32_e32 v236, 0, v1
	v_mbcnt_hi_u32_b32 v237, -1, v0
	v_mov_b64_e32 v[196:197], 0x7ff
	s_mov_b32 s57, 0
	s_barrier
	s_branch .LBB0_880

; #define PG8_STAGE(bufoff, gbase, voff) do { _Pragma("unroll") for (int _i = 0; _i < 2; ++_i) \
;         __builtin_amdgcn_global_load_lds((const unsigned*)((const char*)(gbase) + (voff)[_i]), (PG8_LAS unsigned*)(lds + (bufoff) + ldsw + _i * 8192), 16, 0, 0); } while (0)
; #define PG8_LDA(dst, b, h) do { _Pragma("unroll") for (int m = 0; m < 4; ++m) _Pragma("unroll") for (int k = 0; k < 2; ++k) dst[m][k] = *(const PG8_LAS bf16x8*)(lds + PG8_SA(b, h) + aoff + m * 2048 + k * 1024); } while (0)
; #define PG8_LDB(dst, b, h) do { _Pragma("unroll") for (int n = 0; n < 2; ++n) _Pragma("unroll") for (int k = 0; k < 2; ++k) dst[n][k] = *(const PG8_LAS bf16x8*)(lds + PG8_SB(b, h) + boff + n * 2048 + k * 1024); } while (0)
; #define PG8_WAIT_V(n) asm volatile("s_waitcnt vmcnt(" #n ")" ::: "memory")
; #define PG8_WAIT_L(n) asm volatile("s_waitcnt lgkmcnt(" #n ")" ::: "memory")
; #define PG8_BAR __builtin_amdgcn_s_barrier()
; #define PG8_SCHED __builtin_amdgcn_sched_barrier(0)
; template <class Epi, class Sched, bool ALIGN_EPI = false, bool SP2 = false>
; __device__ __forceinline__ void gemm_phase(PG8_LAS unsigned char* lds, const Gemm g, const Sched& S, const Epi& E) {
;     ...
;         const bool has_next = S.next(ui + 1, nxt);
;         const char* nA = has_next ? (const char*)g.A + (size_t)nxt.pm * tstep : cA; const char* nB = has_next ? (const char*)g.Bt + (size_t)nxt.pn * tstep : cB;
;         for (int t = 0; t < nt; t += 2) {
;             const bool last = (t == nt - 2);
;             const char* a1 = cA + (size_t)(t + 1) * kstep;
;             const char* a2 = last ? nA : cA + (size_t)(t + 2) * kstep; const char* b2 = last ? nB : cB + (size_t)(t + 2) * kstep;
;             const char* a3 = a2 + kstep; const char* b3 = b2 + kstep;
;             if (last && has_next) S.a_ready(nxt);
;             if constexpr (SP2) {
;             PG8_LDB(B0, 0, 0); PG8_LDB(B1, 0, 1); PG8_SCHED; PG8_LDA(At, 0, 0); PG8_STAGE(PG8_SA(1, 1), a1 + hstep, voffA);
;             PG8_WAIT_V(8); PG8_WAIT_L(0); PG8_BAR; PG8_MMA(0, 0, At, B0); PG8_MMA(0, 1, At, B1); PG8_BAR; PG8_SCHED;
;             PG8_LDA(At, 0, 1); PG8_STAGE(PG8_SB(0, 0), b2, voffB); PG8_STAGE(PG8_SB(0, 1), b2 + hstep, voffB); PG8_STAGE(PG8_SA(0, 0), a2, voffA);
;             PG8_WAIT_V(8); PG8_WAIT_L(0); PG8_BAR; PG8_MMA(1, 0, At, B0); PG8_MMA(1, 1, At, B1); PG8_BAR; PG8_SCHED;
.LBB0_887:
	s_ashr_i32 s23, s22, 31
	s_lshl_b64 s[26:27], s[22:23], 19
	s_add_u32 s26, s68, s26
	s_addc_u32 s27, s69, s27
	s_and_b64 s[28:29], s[24:25], exec
	s_cselect_b32 s23, s27, s37
	s_cselect_b32 s31, s26, s36
	s_ashr_i32 s21, s20, 31
	s_lshl_b64 s[28:29], s[20:21], 19
	s_add_u32 s28, s42, s28
	s_addc_u32 s29, s43, s29
	s_and_b64 s[40:41], s[24:25], exec
	s_cselect_b32 s21, s29, s39
	s_cselect_b32 s58, s28, s38
	s_add_u32 s36, s36, 0x40080
	s_addc_u32 s37, s37, 0
	s_add_u32 s59, s38, 0x100
	s_addc_u32 s60, s39, 0
	s_mov_b32 s61, -2
	s_waitcnt lgkmcnt(0)
	ds_read_b128 v[124:127], v234
	ds_read_b128 v[132:135], v234 offset:1024
	ds_read_b128 v[136:139], v234 offset:2048
	ds_read_b128 v[140:143], v234 offset:3072
	ds_read_b128 v[144:147], v235
	ds_read_b128 v[148:151], v235 offset:1024
	ds_read_b128 v[152:155], v235 offset:2048
	ds_read_b128 v[156:159], v235 offset:3072
	s_add_u32 s38, s36, 0xfffc0080
	s_addc_u32 s39, s37, -1
	s_cmp_eq_u32 s61, 12
	s_cselect_b32 s41, s23, s39
	s_cselect_b32 s40, s31, s38
	s_cselect_b32 s39, s21, s60
	s_cselect_b32 s38, s58, s59
	s_add_i32 m0, s45, 0xc000
	ds_read_b128 v[160:163], v236
	ds_read_b128 v[164:167], v236 offset:1024
	ds_read_b128 v[168:171], v236 offset:2048
	ds_read_b128 v[172:175], v236 offset:3072
	ds_read_b128 v[176:179], v236 offset:4096
	ds_read_b128 v[180:183], v236 offset:5120
	ds_read_b128 v[198:201], v236 offset:6144
	ds_read_b128 v[202:205], v236 offset:7168
	global_load_lds_dwordx4 v192, s[36:37]
	s_add_i32 m0, s45, 0xe000
	s_nop 0
	global_load_lds_dwordx4 v194, s[36:37]
	s_waitcnt vmcnt(8)
	s_waitcnt lgkmcnt(0)
	s_barrier
	s_setprio 1
	s_waitcnt lgkmcnt(0)
	v_mfma_f32_16x16x32_bf16 v[128:131], v[124:127], v[160:163], 0
	v_mfma_f32_16x16x32_bf16 v[120:123], v[136:139], v[160:163], 0
	v_mfma_f32_16x16x32_bf16 v[108:111], v[124:127], v[168:171], 0
	v_mfma_f32_16x16x32_bf16 v[104:107], v[136:139], v[168:171], 0
	v_mfma_f32_16x16x32_bf16 v[92:95], v[124:127], v[176:179], 0
	v_mfma_f32_16x16x32_bf16 v[88:91], v[136:139], v[176:179], 0
	v_mfma_f32_16x16x32_bf16 v[76:79], v[124:127], v[198:201], 0
	v_mfma_f32_16x16x32_bf16 v[72:75], v[136:139], v[198:201], 0
	v_mfma_f32_16x16x32_bf16 v[128:131], v[132:135], v[164:167], v[128:131]
	v_mfma_f32_16x16x32_bf16 v[120:123], v[140:143], v[164:167], v[120:123]
	v_mfma_f32_16x16x32_bf16 v[108:111], v[132:135], v[172:175], v[108:111]
	v_mfma_f32_16x16x32_bf16 v[104:107], v[140:143], v[172:175], v[104:107]
	v_mfma_f32_16x16x32_bf16 v[92:95], v[132:135], v[180:183], v[92:95]
	v_mfma_f32_16x16x32_bf16 v[88:91], v[140:143], v[180:183], v[88:91]
	v_mfma_f32_16x16x32_bf16 v[76:79], v[132:135], v[202:205], v[76:79]
	v_mfma_f32_16x16x32_bf16 v[72:75], v[140:143], v[202:205], v[72:75]
	s_setprio 0
	s_setprio 1
	v_mfma_f32_16x16x32_bf16 v[116:119], v[144:147], v[160:163], 0
	v_mfma_f32_16x16x32_bf16 v[112:115], v[152:155], v[160:163], 0
	v_mfma_f32_16x16x32_bf16 v[100:103], v[144:147], v[168:171], 0
	v_mfma_f32_16x16x32_bf16 v[96:99], v[152:155], v[168:171], 0
	v_mfma_f32_16x16x32_bf16 v[84:87], v[144:147], v[176:179], 0
	v_mfma_f32_16x16x32_bf16 v[80:83], v[152:155], v[176:179], 0
	v_mfma_f32_16x16x32_bf16 v[68:71], v[144:147], v[198:201], 0
	v_mfma_f32_16x16x32_bf16 v[64:67], v[152:155], v[198:201], 0
	v_mfma_f32_16x16x32_bf16 v[116:119], v[148:151], v[164:167], v[116:119]
	v_mfma_f32_16x16x32_bf16 v[112:115], v[156:159], v[164:167], v[112:115]
	v_mfma_f32_16x16x32_bf16 v[100:103], v[148:151], v[172:175], v[100:103]
	v_mfma_f32_16x16x32_bf16 v[96:99], v[156:159], v[172:175], v[96:99]
	v_mfma_f32_16x16x32_bf16 v[84:87], v[148:151], v[180:183], v[84:87]
	v_mfma_f32_16x16x32_bf16 v[80:83], v[156:159], v[180:183], v[80:83]
	v_mfma_f32_16x16x32_bf16 v[68:71], v[148:151], v[202:205], v[68:71]
	v_mfma_f32_16x16x32_bf16 v[64:67], v[156:159], v[202:205], v[64:67]
	s_setprio 0
	s_barrier
	s_add_i32 s62, s55, s44
	v_lshl_add_u64 v[206:207], s[38:39], 0, v[186:187]
	s_mov_b32 m0, s62
	ds_read_b128 v[160:163], v236 offset:16384
	ds_read_b128 v[164:167], v236 offset:17408
	ds_read_b128 v[168:171], v236 offset:18432
	ds_read_b128 v[172:175], v236 offset:19456
	ds_read_b128 v[176:179], v236 offset:20480
	ds_read_b128 v[180:183], v236 offset:21504
	ds_read_b128 v[198:201], v236 offset:22528
	ds_read_b128 v[202:205], v236 offset:23552
	global_load_lds_dwordx4 v[206:207], off
	s_add_i32 m0, s62, 0x2000
	s_add_u32 s62, s38, 0x40000
	v_lshl_add_u64 v[208:209], s[38:39], 0, v[190:191]
	s_addc_u32 s63, s39, 0
	s_add_i32 s64, s56, s44
	global_load_lds_dwordx4 v[208:209], off
	s_mov_b32 m0, s64
	v_lshl_add_u64 v[212:213], s[40:41], 0, v[188:189]
	global_load_lds_dwordx4 v186, s[62:63]
	s_add_i32 m0, s64, 0x2000
	s_nop 0
	global_load_lds_dwordx4 v190, s[62:63]
	v_lshl_add_u64 v[210:211], s[40:41], 0, v[184:185]
	s_mov_b32 m0, s45
	s_nop 0
	global_load_lds_dwordx4 v[210:211], off
	s_mov_b32 m0, s46
	s_nop 0
	global_load_lds_dwordx4 v[212:213], off
	s_waitcnt vmcnt(8)
	s_waitcnt lgkmcnt(0)
	s_barrier
; #define PG8_STAGE(bufoff, gbase, voff) do { _Pragma("unroll") for (int _i = 0; _i < 2; ++_i) \
;         __builtin_amdgcn_global_load_lds((const unsigned*)((const char*)(gbase) + (voff)[_i]), (PG8_LAS unsigned*)(lds + (bufoff) + ldsw + _i * 8192), 16, 0, 0); } while (0)
; #define PG8_LDA(dst, b, h) do { _Pragma("unroll") for (int m = 0; m < 4; ++m) _Pragma("unroll") for (int k = 0; k < 2; ++k) dst[m][k] = *(const PG8_LAS bf16x8*)(lds + PG8_SA(b, h) + aoff + m * 2048 + k * 1024); } while (0)
; #define PG8_LDB(dst, b, h) do { _Pragma("unroll") for (int n = 0; n < 2; ++n) _Pragma("unroll") for (int k = 0; k < 2; ++k) dst[n][k] = *(const PG8_LAS bf16x8*)(lds + PG8_SB(b, h) + boff + n * 2048 + k * 1024); } while (0)
; #define PG8_MMA(ai, bj, At, Bt) do { __builtin_amdgcn_s_setprio(1); _Pragma("unroll") for (int m = 0; m < 4; ++m) _Pragma("unroll") for (int n = 0; n < 2; ++n) _Pragma("unroll") for (int k = 0; k < 2; ++k) \
;         acc[ai][bj][m][n] = __builtin_amdgcn_mfma_f32_16x16x32_bf16(Bt[n][k], At[m][k], acc[ai][bj][m][n], 0, 0, 0); __builtin_amdgcn_s_setprio(0); } while (0)
; #define PG8_WAIT_V(n) asm volatile("s_waitcnt vmcnt(" #n ")" ::: "memory")
; #define PG8_WAIT_L(n) asm volatile("s_waitcnt lgkmcnt(" #n ")" ::: "memory")
; #define PG8_BAR __builtin_amdgcn_s_barrier()
; #define PG8_SCHED __builtin_amdgcn_sched_barrier(0)
; template <class Epi, class Sched, bool ALIGN_EPI = false, bool SP2 = false>
; __device__ __forceinline__ void gemm_phase(PG8_LAS unsigned char* lds, const Gemm g, const Sched& S, const Epi& E) {
;     ...
;             PG8_WAIT_V(8); PG8_WAIT_L(0); PG8_BAR; PG8_MMA(1, 0, At, B0); PG8_MMA(1, 1, At, B1); PG8_BAR; PG8_SCHED;
;             PG8_LDB(B0, 1, 0); PG8_LDB(B1, 1, 1); PG8_SCHED; PG8_LDA(At, 1, 0); PG8_STAGE(PG8_SA(0, 1), a2 + hstep, voffA);
;             PG8_WAIT_V(8); PG8_WAIT_L(0); PG8_BAR; PG8_MMA(0, 0, At, B0); PG8_MMA(0, 1, At, B1); PG8_BAR; PG8_SCHED;
	s_setprio 1
	s_waitcnt lgkmcnt(0)
	v_mfma_f32_16x16x32_bf16 v[60:63], v[124:127], v[160:163], 0
	v_mfma_f32_16x16x32_bf16 v[56:59], v[136:139], v[160:163], 0
	v_mfma_f32_16x16x32_bf16 v[44:47], v[124:127], v[168:171], 0
	v_mfma_f32_16x16x32_bf16 v[40:43], v[136:139], v[168:171], 0
	v_mfma_f32_16x16x32_bf16 v[28:31], v[124:127], v[176:179], 0
	v_mfma_f32_16x16x32_bf16 v[24:27], v[136:139], v[176:179], 0
	v_mfma_f32_16x16x32_bf16 v[12:15], v[124:127], v[198:201], 0
	v_mfma_f32_16x16x32_bf16 v[8:11], v[136:139], v[198:201], 0
	v_mfma_f32_16x16x32_bf16 v[60:63], v[132:135], v[164:167], v[60:63]
	v_mfma_f32_16x16x32_bf16 v[56:59], v[140:143], v[164:167], v[56:59]
	v_mfma_f32_16x16x32_bf16 v[44:47], v[132:135], v[172:175], v[44:47]
	v_mfma_f32_16x16x32_bf16 v[40:43], v[140:143], v[172:175], v[40:43]
	v_mfma_f32_16x16x32_bf16 v[28:31], v[132:135], v[180:183], v[28:31]
	v_mfma_f32_16x16x32_bf16 v[24:27], v[140:143], v[180:183], v[24:27]
	v_mfma_f32_16x16x32_bf16 v[12:15], v[132:135], v[202:205], v[12:15]
	v_mfma_f32_16x16x32_bf16 v[8:11], v[140:143], v[202:205], v[8:11]
	s_setprio 0
	s_setprio 1
	v_mfma_f32_16x16x32_bf16 v[52:55], v[144:147], v[160:163], 0
	v_mfma_f32_16x16x32_bf16 v[48:51], v[152:155], v[160:163], 0
	v_mfma_f32_16x16x32_bf16 v[36:39], v[144:147], v[168:171], 0
	v_mfma_f32_16x16x32_bf16 v[32:35], v[152:155], v[168:171], 0
	v_mfma_f32_16x16x32_bf16 v[20:23], v[144:147], v[176:179], 0
	v_mfma_f32_16x16x32_bf16 v[16:19], v[152:155], v[176:179], 0
	v_mfma_f32_16x16x32_bf16 v[4:7], v[144:147], v[198:201], 0
	v_mfma_f32_16x16x32_bf16 v[0:3], v[152:155], v[198:201], 0
	v_mfma_f32_16x16x32_bf16 v[52:55], v[148:151], v[164:167], v[52:55]
	v_mfma_f32_16x16x32_bf16 v[48:51], v[156:159], v[164:167], v[48:51]
	v_mfma_f32_16x16x32_bf16 v[36:39], v[148:151], v[172:175], v[36:39]
	v_mfma_f32_16x16x32_bf16 v[32:35], v[156:159], v[172:175], v[32:35]
	v_mfma_f32_16x16x32_bf16 v[20:23], v[148:151], v[180:183], v[20:23]
	v_mfma_f32_16x16x32_bf16 v[16:19], v[156:159], v[180:183], v[16:19]
	v_mfma_f32_16x16x32_bf16 v[4:7], v[148:151], v[202:205], v[4:7]
	v_mfma_f32_16x16x32_bf16 v[0:3], v[156:159], v[202:205], v[0:3]
	s_setprio 0
	s_barrier
	s_add_i32 s62, 0, 0x18000
	s_add_i32 s63, 0, 0x1c000
	v_add_u32_e32 v140, s62, v232
	v_add_u32_e32 v156, s63, v232
	ds_read_b128 v[124:127], v140
	ds_read_b128 v[132:135], v140 offset:1024
	ds_read_b128 v[136:139], v140 offset:2048
	ds_read_b128 v[140:143], v140 offset:3072
	ds_read_b128 v[144:147], v156
	ds_read_b128 v[148:151], v156 offset:1024
	ds_read_b128 v[152:155], v156 offset:2048
	ds_read_b128 v[156:159], v156 offset:3072
	s_add_u32 s40, s40, 0x40000
	s_addc_u32 s41, s41, 0
	s_mov_b32 m0, s47
	ds_read_b128 v[160:163], v236 offset:32768
	ds_read_b128 v[164:167], v236 offset:33792
	ds_read_b128 v[168:171], v236 offset:34816
	ds_read_b128 v[172:175], v236 offset:35840
	ds_read_b128 v[176:179], v236 offset:36864
	ds_read_b128 v[180:183], v236 offset:37888
	ds_read_b128 v[198:201], v236 offset:38912
	ds_read_b128 v[202:205], v236 offset:39936
	global_load_lds_dwordx4 v184, s[40:41]
	v_lshl_add_u64 v[214:215], s[40:41], 0, v[188:189]
	s_mov_b32 m0, s48
	s_nop 0
	global_load_lds_dwordx4 v[214:215], off
	s_waitcnt vmcnt(8)
	s_waitcnt lgkmcnt(0)
	s_barrier
	s_setprio 1
	s_waitcnt lgkmcnt(0)
	v_mfma_f32_16x16x32_bf16 v[128:131], v[124:127], v[160:163], v[128:131]
	v_mfma_f32_16x16x32_bf16 v[120:123], v[136:139], v[160:163], v[120:123]
	v_mfma_f32_16x16x32_bf16 v[108:111], v[124:127], v[168:171], v[108:111]
	v_mfma_f32_16x16x32_bf16 v[104:107], v[136:139], v[168:171], v[104:107]
	v_mfma_f32_16x16x32_bf16 v[92:95], v[124:127], v[176:179], v[92:95]
	v_mfma_f32_16x16x32_bf16 v[88:91], v[136:139], v[176:179], v[88:91]
	v_mfma_f32_16x16x32_bf16 v[76:79], v[124:127], v[198:201], v[76:79]
	v_mfma_f32_16x16x32_bf16 v[72:75], v[136:139], v[198:201], v[72:75]
	v_mfma_f32_16x16x32_bf16 v[128:131], v[132:135], v[164:167], v[128:131]
	v_mfma_f32_16x16x32_bf16 v[120:123], v[140:143], v[164:167], v[120:123]
	v_mfma_f32_16x16x32_bf16 v[108:111], v[132:135], v[172:175], v[108:111]
	v_mfma_f32_16x16x32_bf16 v[104:107], v[140:143], v[172:175], v[104:107]
	v_mfma_f32_16x16x32_bf16 v[92:95], v[132:135], v[180:183], v[92:95]
	v_mfma_f32_16x16x32_bf16 v[88:91], v[140:143], v[180:183], v[88:91]
	v_mfma_f32_16x16x32_bf16 v[76:79], v[132:135], v[202:205], v[76:79]
	v_mfma_f32_16x16x32_bf16 v[72:75], v[140:143], v[202:205], v[72:75]
	s_setprio 0
	s_setprio 1
	v_mfma_f32_16x16x32_bf16 v[116:119], v[144:147], v[160:163], v[116:119]
	v_mfma_f32_16x16x32_bf16 v[112:115], v[152:155], v[160:163], v[112:115]
	v_mfma_f32_16x16x32_bf16 v[100:103], v[144:147], v[168:171], v[100:103]
	v_mfma_f32_16x16x32_bf16 v[96:99], v[152:155], v[168:171], v[96:99]
	v_mfma_f32_16x16x32_bf16 v[84:87], v[144:147], v[176:179], v[84:87]
	v_mfma_f32_16x16x32_bf16 v[80:83], v[152:155], v[176:179], v[80:83]
	v_mfma_f32_16x16x32_bf16 v[68:71], v[144:147], v[198:201], v[68:71]
	v_mfma_f32_16x16x32_bf16 v[64:67], v[152:155], v[198:201], v[64:67]
	v_mfma_f32_16x16x32_bf16 v[116:119], v[148:151], v[164:167], v[116:119]
	v_mfma_f32_16x16x32_bf16 v[112:115], v[156:159], v[164:167], v[112:115]
	v_mfma_f32_16x16x32_bf16 v[100:103], v[148:151], v[172:175], v[100:103]
	v_mfma_f32_16x16x32_bf16 v[96:99], v[156:159], v[172:175], v[96:99]
	v_mfma_f32_16x16x32_bf16 v[84:87], v[148:151], v[180:183], v[84:87]
	v_mfma_f32_16x16x32_bf16 v[80:83], v[156:159], v[180:183], v[80:83]
	v_mfma_f32_16x16x32_bf16 v[68:71], v[148:151], v[202:205], v[68:71]
	v_mfma_f32_16x16x32_bf16 v[64:67], v[156:159], v[202:205], v[64:67]
	s_setprio 0
	s_barrier
; #define PG8_STAGE(bufoff, gbase, voff) do { _Pragma("unroll") for (int _i = 0; _i < 2; ++_i) \
;         __builtin_amdgcn_global_load_lds((const unsigned*)((const char*)(gbase) + (voff)[_i]), (PG8_LAS unsigned*)(lds + (bufoff) + ldsw + _i * 8192), 16, 0, 0); } while (0)
; #define PG8_LDA(dst, b, h) do { _Pragma("unroll") for (int m = 0; m < 4; ++m) _Pragma("unroll") for (int k = 0; k < 2; ++k) dst[m][k] = *(const PG8_LAS bf16x8*)(lds + PG8_SA(b, h) + aoff + m * 2048 + k * 1024); } while (0)
; #define PG8_LDB(dst, b, h) do { _Pragma("unroll") for (int n = 0; n < 2; ++n) _Pragma("unroll") for (int k = 0; k < 2; ++k) dst[n][k] = *(const PG8_LAS bf16x8*)(lds + PG8_SB(b, h) + boff + n * 2048 + k * 1024); } while (0)
; #define PG8_MMA(ai, bj, At, Bt) do { __builtin_amdgcn_s_setprio(1); _Pragma("unroll") for (int m = 0; m < 4; ++m) _Pragma("unroll") for (int n = 0; n < 2; ++n) _Pragma("unroll") for (int k = 0; k < 2; ++k) \
;         acc[ai][bj][m][n] = __builtin_amdgcn_mfma_f32_16x16x32_bf16(Bt[n][k], At[m][k], acc[ai][bj][m][n], 0, 0, 0); __builtin_amdgcn_s_setprio(0); } while (0)
; #define PG8_WAIT_V(n) asm volatile("s_waitcnt vmcnt(" #n ")" ::: "memory")
; #define PG8_WAIT_L(n) asm volatile("s_waitcnt lgkmcnt(" #n ")" ::: "memory")
; #define PG8_BAR __builtin_amdgcn_s_barrier()
; #define PG8_SCHED __builtin_amdgcn_sched_barrier(0)
; template <class Epi, class Sched, bool ALIGN_EPI = false, bool SP2 = false>
; __device__ __forceinline__ void gemm_phase(PG8_LAS unsigned char* lds, const Gemm g, const Sched& S, const Epi& E) {
;     ...
;             PG8_LDB(B0, 0, 0); PG8_LDB(B1, 0, 1); PG8_SCHED; PG8_LDA(At, 0, 0); PG8_STAGE(PG8_SA(1, 1), a1 + hstep, voffA);
;             PG8_WAIT_V(8); PG8_WAIT_L(0); PG8_BAR; PG8_MMA(0, 0, At, B0); PG8_MMA(0, 1, At, B1); PG8_BAR; PG8_SCHED;
;     ...
;             PG8_LDA(At, 1, 1); PG8_STAGE(PG8_SB(1, 0), b3, voffB); PG8_STAGE(PG8_SB(1, 1), b3 + hstep, voffB); PG8_STAGE(PG8_SA(1, 0), a3, voffA);
;             PG8_WAIT_V(8); PG8_WAIT_L(0); PG8_BAR; PG8_MMA(1, 0, At, B0); PG8_MMA(1, 1, At, B1); PG8_BAR; PG8_SCHED;
	s_add_i32 s40, s62, s44
	v_lshl_add_u64 v[206:207], v[206:207], 0, s[16:17]
	s_mov_b32 m0, s40
	ds_read_b128 v[160:163], v236 offset:49152
	ds_read_b128 v[164:167], v236 offset:50176
	ds_read_b128 v[168:171], v236 offset:51200
	ds_read_b128 v[172:175], v236 offset:52224
	ds_read_b128 v[176:179], v236 offset:53248
	ds_read_b128 v[180:183], v236 offset:54272
	ds_read_b128 v[198:201], v236 offset:55296
	ds_read_b128 v[202:205], v236 offset:56320
	global_load_lds_dwordx4 v[206:207], off
	s_add_i32 m0, s40, 0x2000
	s_add_u32 s38, s38, 0x40080
	v_lshl_add_u64 v[206:207], v[208:209], 0, s[16:17]
	s_addc_u32 s39, s39, 0
	s_add_i32 s40, s63, s44
	global_load_lds_dwordx4 v[206:207], off
	s_mov_b32 m0, s40
	s_nop 0
	global_load_lds_dwordx4 v186, s[38:39]
	s_add_i32 m0, s40, 0x2000
	s_nop 0
	global_load_lds_dwordx4 v190, s[38:39]
	v_lshl_add_u64 v[206:207], v[210:211], 0, s[16:17]
	s_mov_b32 m0, s50
	s_nop 0
	global_load_lds_dwordx4 v[206:207], off
	v_lshl_add_u64 v[206:207], v[212:213], 0, s[16:17]
	s_mov_b32 m0, s51
	s_nop 0
	global_load_lds_dwordx4 v[206:207], off
	s_waitcnt vmcnt(8)
	s_waitcnt lgkmcnt(0)
	s_barrier
	s_setprio 1
	s_waitcnt lgkmcnt(0)
	v_mfma_f32_16x16x32_bf16 v[60:63], v[124:127], v[160:163], v[60:63]
	v_mfma_f32_16x16x32_bf16 v[56:59], v[136:139], v[160:163], v[56:59]
	v_mfma_f32_16x16x32_bf16 v[44:47], v[124:127], v[168:171], v[44:47]
	v_mfma_f32_16x16x32_bf16 v[40:43], v[136:139], v[168:171], v[40:43]
	v_mfma_f32_16x16x32_bf16 v[28:31], v[124:127], v[176:179], v[28:31]
	v_mfma_f32_16x16x32_bf16 v[24:27], v[136:139], v[176:179], v[24:27]
	v_mfma_f32_16x16x32_bf16 v[12:15], v[124:127], v[198:201], v[12:15]
	v_mfma_f32_16x16x32_bf16 v[8:11], v[136:139], v[198:201], v[8:11]
	v_mfma_f32_16x16x32_bf16 v[60:63], v[132:135], v[164:167], v[60:63]
	v_mfma_f32_16x16x32_bf16 v[56:59], v[140:143], v[164:167], v[56:59]
	v_mfma_f32_16x16x32_bf16 v[44:47], v[132:135], v[172:175], v[44:47]
	v_mfma_f32_16x16x32_bf16 v[40:43], v[140:143], v[172:175], v[40:43]
	v_mfma_f32_16x16x32_bf16 v[28:31], v[132:135], v[180:183], v[28:31]
	v_mfma_f32_16x16x32_bf16 v[24:27], v[140:143], v[180:183], v[24:27]
	v_mfma_f32_16x16x32_bf16 v[12:15], v[132:135], v[202:205], v[12:15]
	v_mfma_f32_16x16x32_bf16 v[8:11], v[140:143], v[202:205], v[8:11]
	s_setprio 0
	s_setprio 1
	v_mfma_f32_16x16x32_bf16 v[52:55], v[144:147], v[160:163], v[52:55]
	v_mfma_f32_16x16x32_bf16 v[48:51], v[152:155], v[160:163], v[48:51]
	v_mfma_f32_16x16x32_bf16 v[36:39], v[144:147], v[168:171], v[36:39]
	v_mfma_f32_16x16x32_bf16 v[32:35], v[152:155], v[168:171], v[32:35]
	v_mfma_f32_16x16x32_bf16 v[20:23], v[144:147], v[176:179], v[20:23]
	v_mfma_f32_16x16x32_bf16 v[16:19], v[152:155], v[176:179], v[16:19]
	v_mfma_f32_16x16x32_bf16 v[4:7], v[144:147], v[198:201], v[4:7]
	v_mfma_f32_16x16x32_bf16 v[0:3], v[152:155], v[198:201], v[0:3]
	v_mfma_f32_16x16x32_bf16 v[52:55], v[148:151], v[164:167], v[52:55]
	v_mfma_f32_16x16x32_bf16 v[48:51], v[156:159], v[164:167], v[48:51]
	v_mfma_f32_16x16x32_bf16 v[36:39], v[148:151], v[172:175], v[36:39]
	v_mfma_f32_16x16x32_bf16 v[32:35], v[156:159], v[172:175], v[32:35]
	v_mfma_f32_16x16x32_bf16 v[20:23], v[148:151], v[180:183], v[20:23]
	v_mfma_f32_16x16x32_bf16 v[16:19], v[156:159], v[180:183], v[16:19]
	v_mfma_f32_16x16x32_bf16 v[4:7], v[148:151], v[202:205], v[4:7]
	v_mfma_f32_16x16x32_bf16 v[0:3], v[156:159], v[202:205], v[0:3]
	s_setprio 0
	s_barrier
	s_add_i32 s61, s61, 2
	s_add_u32 s36, s36, 0x100
	s_addc_u32 s37, s37, 0
	s_add_u32 s59, s59, 0x100
	s_addc_u32 s60, s60, 0
	s_cmp_gt_u32 s61, 13
.LBB0_888:
	ds_read_b128 v[124:127], v234
	ds_read_b128 v[132:135], v234 offset:1024
	ds_read_b128 v[136:139], v234 offset:2048
	ds_read_b128 v[140:143], v234 offset:3072
	ds_read_b128 v[144:147], v235
	ds_read_b128 v[148:151], v235 offset:1024
	ds_read_b128 v[152:155], v235 offset:2048
	ds_read_b128 v[156:159], v235 offset:3072
	s_add_u32 s38, s36, 0xfffc0080
	s_addc_u32 s39, s37, -1
	s_cmp_eq_u32 s61, 12
	s_cselect_b32 s41, s23, s39
	s_cselect_b32 s40, s31, s38
	s_cselect_b32 s39, s21, s60
	s_cselect_b32 s38, s58, s59
	s_add_i32 m0, s45, 0xc000
	ds_read_b128 v[160:163], v236
	ds_read_b128 v[164:167], v236 offset:1024
	ds_read_b128 v[168:171], v236 offset:2048
	ds_read_b128 v[172:175], v236 offset:3072
	ds_read_b128 v[176:179], v236 offset:4096
	ds_read_b128 v[180:183], v236 offset:5120
	ds_read_b128 v[198:201], v236 offset:6144
	ds_read_b128 v[202:205], v236 offset:7168
	global_load_lds_dwordx4 v192, s[36:37]
	s_add_i32 m0, s45, 0xe000
	s_nop 0
	global_load_lds_dwordx4 v194, s[36:37]
	s_waitcnt vmcnt(8)
	s_waitcnt lgkmcnt(0)
	s_barrier
; #define PG8_STAGE(bufoff, gbase, voff) do { _Pragma("unroll") for (int _i = 0; _i < 2; ++_i) \
;         __builtin_amdgcn_global_load_lds((const unsigned*)((const char*)(gbase) + (voff)[_i]), (PG8_LAS unsigned*)(lds + (bufoff) + ldsw + _i * 8192), 16, 0, 0); } while (0)
; #define PG8_LDA(dst, b, h) do { _Pragma("unroll") for (int m = 0; m < 4; ++m) _Pragma("unroll") for (int k = 0; k < 2; ++k) dst[m][k] = *(const PG8_LAS bf16x8*)(lds + PG8_SA(b, h) + aoff + m * 2048 + k * 1024); } while (0)
; #define PG8_LDB(dst, b, h) do { _Pragma("unroll") for (int n = 0; n < 2; ++n) _Pragma("unroll") for (int k = 0; k < 2; ++k) dst[n][k] = *(const PG8_LAS bf16x8*)(lds + PG8_SB(b, h) + boff + n * 2048 + k * 1024); } while (0)
; #define PG8_MMA(ai, bj, At, Bt) do { __builtin_amdgcn_s_setprio(1); _Pragma("unroll") for (int m = 0; m < 4; ++m) _Pragma("unroll") for (int n = 0; n < 2; ++n) _Pragma("unroll") for (int k = 0; k < 2; ++k) \
;         acc[ai][bj][m][n] = __builtin_amdgcn_mfma_f32_16x16x32_bf16(Bt[n][k], At[m][k], acc[ai][bj][m][n], 0, 0, 0); __builtin_amdgcn_s_setprio(0); } while (0)
; #define PG8_WAIT_V(n) asm volatile("s_waitcnt vmcnt(" #n ")" ::: "memory")
; #define PG8_WAIT_L(n) asm volatile("s_waitcnt lgkmcnt(" #n ")" ::: "memory")
; #define PG8_BAR __builtin_amdgcn_s_barrier()
; #define PG8_SCHED __builtin_amdgcn_sched_barrier(0)
; template <class Epi, class Sched, bool ALIGN_EPI = false, bool SP2 = false>
; __device__ __forceinline__ void gemm_phase(PG8_LAS unsigned char* lds, const Gemm g, const Sched& S, const Epi& E) {
;     ...
;             PG8_WAIT_V(8); PG8_WAIT_L(0); PG8_BAR; PG8_MMA(0, 0, At, B0); PG8_MMA(0, 1, At, B1); PG8_BAR; PG8_SCHED;
;             PG8_LDA(At, 0, 1); PG8_STAGE(PG8_SB(0, 0), b2, voffB); PG8_STAGE(PG8_SB(0, 1), b2 + hstep, voffB); PG8_STAGE(PG8_SA(0, 0), a2, voffA);
;             PG8_WAIT_V(8); PG8_WAIT_L(0); PG8_BAR; PG8_MMA(1, 0, At, B0); PG8_MMA(1, 1, At, B1); PG8_BAR; PG8_SCHED;
;             PG8_LDB(B0, 1, 0); PG8_LDB(B1, 1, 1); PG8_SCHED; PG8_LDA(At, 1, 0); PG8_STAGE(PG8_SA(0, 1), a2 + hstep, voffA);
;             PG8_WAIT_V(8); PG8_WAIT_L(0); PG8_BAR; PG8_MMA(0, 0, At, B0); PG8_MMA(0, 1, At, B1); PG8_BAR; PG8_SCHED;
	s_setprio 1
	s_waitcnt lgkmcnt(0)
	v_mfma_f32_16x16x32_bf16 v[128:131], v[124:127], v[160:163], v[128:131]
	v_mfma_f32_16x16x32_bf16 v[120:123], v[136:139], v[160:163], v[120:123]
	v_mfma_f32_16x16x32_bf16 v[108:111], v[124:127], v[168:171], v[108:111]
	v_mfma_f32_16x16x32_bf16 v[104:107], v[136:139], v[168:171], v[104:107]
	v_mfma_f32_16x16x32_bf16 v[92:95], v[124:127], v[176:179], v[92:95]
	v_mfma_f32_16x16x32_bf16 v[88:91], v[136:139], v[176:179], v[88:91]
	v_mfma_f32_16x16x32_bf16 v[76:79], v[124:127], v[198:201], v[76:79]
	v_mfma_f32_16x16x32_bf16 v[72:75], v[136:139], v[198:201], v[72:75]
	v_mfma_f32_16x16x32_bf16 v[128:131], v[132:135], v[164:167], v[128:131]
	v_mfma_f32_16x16x32_bf16 v[120:123], v[140:143], v[164:167], v[120:123]
	v_mfma_f32_16x16x32_bf16 v[108:111], v[132:135], v[172:175], v[108:111]
	v_mfma_f32_16x16x32_bf16 v[104:107], v[140:143], v[172:175], v[104:107]
	v_mfma_f32_16x16x32_bf16 v[92:95], v[132:135], v[180:183], v[92:95]
	v_mfma_f32_16x16x32_bf16 v[88:91], v[140:143], v[180:183], v[88:91]
	v_mfma_f32_16x16x32_bf16 v[76:79], v[132:135], v[202:205], v[76:79]
	v_mfma_f32_16x16x32_bf16 v[72:75], v[140:143], v[202:205], v[72:75]
	s_setprio 0
	s_setprio 1
	v_mfma_f32_16x16x32_bf16 v[116:119], v[144:147], v[160:163], v[116:119]
	v_mfma_f32_16x16x32_bf16 v[112:115], v[152:155], v[160:163], v[112:115]
	v_mfma_f32_16x16x32_bf16 v[100:103], v[144:147], v[168:171], v[100:103]
	v_mfma_f32_16x16x32_bf16 v[96:99], v[152:155], v[168:171], v[96:99]
	v_mfma_f32_16x16x32_bf16 v[84:87], v[144:147], v[176:179], v[84:87]
	v_mfma_f32_16x16x32_bf16 v[80:83], v[152:155], v[176:179], v[80:83]
	v_mfma_f32_16x16x32_bf16 v[68:71], v[144:147], v[198:201], v[68:71]
	v_mfma_f32_16x16x32_bf16 v[64:67], v[152:155], v[198:201], v[64:67]
	v_mfma_f32_16x16x32_bf16 v[116:119], v[148:151], v[164:167], v[116:119]
	v_mfma_f32_16x16x32_bf16 v[112:115], v[156:159], v[164:167], v[112:115]
	v_mfma_f32_16x16x32_bf16 v[100:103], v[148:151], v[172:175], v[100:103]
	v_mfma_f32_16x16x32_bf16 v[96:99], v[156:159], v[172:175], v[96:99]
	v_mfma_f32_16x16x32_bf16 v[84:87], v[148:151], v[180:183], v[84:87]
	v_mfma_f32_16x16x32_bf16 v[80:83], v[156:159], v[180:183], v[80:83]
	v_mfma_f32_16x16x32_bf16 v[68:71], v[148:151], v[202:205], v[68:71]
	v_mfma_f32_16x16x32_bf16 v[64:67], v[156:159], v[202:205], v[64:67]
	s_setprio 0
	s_barrier
	s_add_i32 s62, s55, s44
	v_lshl_add_u64 v[206:207], s[38:39], 0, v[186:187]
	s_mov_b32 m0, s62
	ds_read_b128 v[160:163], v236 offset:16384
	ds_read_b128 v[164:167], v236 offset:17408
	ds_read_b128 v[168:171], v236 offset:18432
	ds_read_b128 v[172:175], v236 offset:19456
	ds_read_b128 v[176:179], v236 offset:20480
	ds_read_b128 v[180:183], v236 offset:21504
	ds_read_b128 v[198:201], v236 offset:22528
	ds_read_b128 v[202:205], v236 offset:23552
	global_load_lds_dwordx4 v[206:207], off
	s_add_i32 m0, s62, 0x2000
	s_add_u32 s62, s38, 0x40000
	v_lshl_add_u64 v[208:209], s[38:39], 0, v[190:191]
	s_addc_u32 s63, s39, 0
	s_add_i32 s64, s56, s44
	global_load_lds_dwordx4 v[208:209], off
	s_mov_b32 m0, s64
	v_lshl_add_u64 v[212:213], s[40:41], 0, v[188:189]
	global_load_lds_dwordx4 v186, s[62:63]
	s_add_i32 m0, s64, 0x2000
	s_nop 0
	global_load_lds_dwordx4 v190, s[62:63]
	v_lshl_add_u64 v[210:211], s[40:41], 0, v[184:185]
	s_mov_b32 m0, s45
	s_nop 0
	global_load_lds_dwordx4 v[210:211], off
	s_mov_b32 m0, s46
	s_nop 0
	global_load_lds_dwordx4 v[212:213], off
	s_waitcnt vmcnt(8)
	s_waitcnt lgkmcnt(0)
	s_barrier
	s_setprio 1
	s_waitcnt lgkmcnt(0)
	v_mfma_f32_16x16x32_bf16 v[60:63], v[124:127], v[160:163], v[60:63]
	v_mfma_f32_16x16x32_bf16 v[56:59], v[136:139], v[160:163], v[56:59]
	v_mfma_f32_16x16x32_bf16 v[44:47], v[124:127], v[168:171], v[44:47]
	v_mfma_f32_16x16x32_bf16 v[40:43], v[136:139], v[168:171], v[40:43]
	v_mfma_f32_16x16x32_bf16 v[28:31], v[124:127], v[176:179], v[28:31]
	v_mfma_f32_16x16x32_bf16 v[24:27], v[136:139], v[176:179], v[24:27]
	v_mfma_f32_16x16x32_bf16 v[12:15], v[124:127], v[198:201], v[12:15]
	v_mfma_f32_16x16x32_bf16 v[8:11], v[136:139], v[198:201], v[8:11]
	v_mfma_f32_16x16x32_bf16 v[60:63], v[132:135], v[164:167], v[60:63]
	v_mfma_f32_16x16x32_bf16 v[56:59], v[140:143], v[164:167], v[56:59]
	v_mfma_f32_16x16x32_bf16 v[44:47], v[132:135], v[172:175], v[44:47]
	v_mfma_f32_16x16x32_bf16 v[40:43], v[140:143], v[172:175], v[40:43]
	v_mfma_f32_16x16x32_bf16 v[28:31], v[132:135], v[180:183], v[28:31]
	v_mfma_f32_16x16x32_bf16 v[24:27], v[140:143], v[180:183], v[24:27]
	v_mfma_f32_16x16x32_bf16 v[12:15], v[132:135], v[202:205], v[12:15]
	v_mfma_f32_16x16x32_bf16 v[8:11], v[140:143], v[202:205], v[8:11]
	s_setprio 0
	s_setprio 1
	v_mfma_f32_16x16x32_bf16 v[52:55], v[144:147], v[160:163], v[52:55]
	v_mfma_f32_16x16x32_bf16 v[48:51], v[152:155], v[160:163], v[48:51]
	v_mfma_f32_16x16x32_bf16 v[36:39], v[144:147], v[168:171], v[36:39]
	v_mfma_f32_16x16x32_bf16 v[32:35], v[152:155], v[168:171], v[32:35]
	v_mfma_f32_16x16x32_bf16 v[20:23], v[144:147], v[176:179], v[20:23]
	v_mfma_f32_16x16x32_bf16 v[16:19], v[152:155], v[176:179], v[16:19]
	v_mfma_f32_16x16x32_bf16 v[4:7], v[144:147], v[198:201], v[4:7]
	v_mfma_f32_16x16x32_bf16 v[0:3], v[152:155], v[198:201], v[0:3]
	v_mfma_f32_16x16x32_bf16 v[52:55], v[148:151], v[164:167], v[52:55]
	v_mfma_f32_16x16x32_bf16 v[48:51], v[156:159], v[164:167], v[48:51]
	v_mfma_f32_16x16x32_bf16 v[36:39], v[148:151], v[172:175], v[36:39]
	v_mfma_f32_16x16x32_bf16 v[32:35], v[156:159], v[172:175], v[32:35]
	v_mfma_f32_16x16x32_bf16 v[20:23], v[148:151], v[180:183], v[20:23]
	v_mfma_f32_16x16x32_bf16 v[16:19], v[156:159], v[180:183], v[16:19]
	v_mfma_f32_16x16x32_bf16 v[4:7], v[148:151], v[202:205], v[4:7]
	v_mfma_f32_16x16x32_bf16 v[0:3], v[156:159], v[202:205], v[0:3]
	s_setprio 0
	s_barrier
; #define PG8_STAGE(bufoff, gbase, voff) do { _Pragma("unroll") for (int _i = 0; _i < 2; ++_i) \
;         __builtin_amdgcn_global_load_lds((const unsigned*)((const char*)(gbase) + (voff)[_i]), (PG8_LAS unsigned*)(lds + (bufoff) + ldsw + _i * 8192), 16, 0, 0); } while (0)
; #define PG8_LDA(dst, b, h) do { _Pragma("unroll") for (int m = 0; m < 4; ++m) _Pragma("unroll") for (int k = 0; k < 2; ++k) dst[m][k] = *(const PG8_LAS bf16x8*)(lds + PG8_SA(b, h) + aoff + m * 2048 + k * 1024); } while (0)
; #define PG8_LDB(dst, b, h) do { _Pragma("unroll") for (int n = 0; n < 2; ++n) _Pragma("unroll") for (int k = 0; k < 2; ++k) dst[n][k] = *(const PG8_LAS bf16x8*)(lds + PG8_SB(b, h) + boff + n * 2048 + k * 1024); } while (0)
; #define PG8_MMA(ai, bj, At, Bt) do { __builtin_amdgcn_s_setprio(1); _Pragma("unroll") for (int m = 0; m < 4; ++m) _Pragma("unroll") for (int n = 0; n < 2; ++n) _Pragma("unroll") for (int k = 0; k < 2; ++k) \
;         acc[ai][bj][m][n] = __builtin_amdgcn_mfma_f32_16x16x32_bf16(Bt[n][k], At[m][k], acc[ai][bj][m][n], 0, 0, 0); __builtin_amdgcn_s_setprio(0); } while (0)
; #define PG8_WAIT_V(n) asm volatile("s_waitcnt vmcnt(" #n ")" ::: "memory")
; #define PG8_WAIT_L(n) asm volatile("s_waitcnt lgkmcnt(" #n ")" ::: "memory")
; #define PG8_BAR __builtin_amdgcn_s_barrier()
; #define PG8_SCHED __builtin_amdgcn_sched_barrier(0)
; template <class Epi, class Sched, bool ALIGN_EPI = false, bool SP2 = false>
; __device__ __forceinline__ void gemm_phase(PG8_LAS unsigned char* lds, const Gemm g, const Sched& S, const Epi& E) {
;     ...
;             PG8_LDB(B0, 1, 0); PG8_LDB(B1, 1, 1); PG8_SCHED; PG8_LDA(At, 1, 0); PG8_STAGE(PG8_SA(0, 1), a2 + hstep, voffA);
;             PG8_WAIT_V(8); PG8_WAIT_L(0); PG8_BAR; PG8_MMA(0, 0, At, B0); PG8_MMA(0, 1, At, B1); PG8_BAR; PG8_SCHED;
	s_add_i32 s62, 0, 0x18000
	s_add_i32 s63, 0, 0x1c000
	v_add_u32_e32 v140, s62, v232
	v_add_u32_e32 v156, s63, v232
	ds_read_b128 v[124:127], v140
	ds_read_b128 v[132:135], v140 offset:1024
	ds_read_b128 v[136:139], v140 offset:2048
	ds_read_b128 v[140:143], v140 offset:3072
	ds_read_b128 v[144:147], v156
	ds_read_b128 v[148:151], v156 offset:1024
	ds_read_b128 v[152:155], v156 offset:2048
	ds_read_b128 v[156:159], v156 offset:3072
	s_add_u32 s40, s40, 0x40000
	s_addc_u32 s41, s41, 0
	s_mov_b32 m0, s47
	ds_read_b128 v[160:163], v236 offset:32768
	ds_read_b128 v[164:167], v236 offset:33792
	ds_read_b128 v[168:171], v236 offset:34816
	ds_read_b128 v[172:175], v236 offset:35840
	ds_read_b128 v[176:179], v236 offset:36864
	ds_read_b128 v[180:183], v236 offset:37888
	ds_read_b128 v[198:201], v236 offset:38912
	ds_read_b128 v[202:205], v236 offset:39936
	global_load_lds_dwordx4 v184, s[40:41]
	v_lshl_add_u64 v[214:215], s[40:41], 0, v[188:189]
	s_mov_b32 m0, s48
	s_nop 0
	global_load_lds_dwordx4 v[214:215], off
	s_waitcnt vmcnt(8)
	s_waitcnt lgkmcnt(0)
	s_barrier
	s_setprio 1
	s_waitcnt lgkmcnt(0)
	v_mfma_f32_16x16x32_bf16 v[128:131], v[124:127], v[160:163], v[128:131]
	v_mfma_f32_16x16x32_bf16 v[120:123], v[136:139], v[160:163], v[120:123]
	v_mfma_f32_16x16x32_bf16 v[108:111], v[124:127], v[168:171], v[108:111]
	v_mfma_f32_16x16x32_bf16 v[104:107], v[136:139], v[168:171], v[104:107]
	v_mfma_f32_16x16x32_bf16 v[92:95], v[124:127], v[176:179], v[92:95]
	v_mfma_f32_16x16x32_bf16 v[88:91], v[136:139], v[176:179], v[88:91]
	v_mfma_f32_16x16x32_bf16 v[76:79], v[124:127], v[198:201], v[76:79]
	v_mfma_f32_16x16x32_bf16 v[72:75], v[136:139], v[198:201], v[72:75]
	v_mfma_f32_16x16x32_bf16 v[128:131], v[132:135], v[164:167], v[128:131]
	v_mfma_f32_16x16x32_bf16 v[120:123], v[140:143], v[164:167], v[120:123]
	v_mfma_f32_16x16x32_bf16 v[108:111], v[132:135], v[172:175], v[108:111]
	v_mfma_f32_16x16x32_bf16 v[104:107], v[140:143], v[172:175], v[104:107]
	v_mfma_f32_16x16x32_bf16 v[92:95], v[132:135], v[180:183], v[92:95]
	v_mfma_f32_16x16x32_bf16 v[88:91], v[140:143], v[180:183], v[88:91]
	v_mfma_f32_16x16x32_bf16 v[76:79], v[132:135], v[202:205], v[76:79]
	v_mfma_f32_16x16x32_bf16 v[72:75], v[140:143], v[202:205], v[72:75]
	s_setprio 0
	s_setprio 1
	v_mfma_f32_16x16x32_bf16 v[116:119], v[144:147], v[160:163], v[116:119]
	v_mfma_f32_16x16x32_bf16 v[112:115], v[152:155], v[160:163], v[112:115]
	v_mfma_f32_16x16x32_bf16 v[100:103], v[144:147], v[168:171], v[100:103]
	v_mfma_f32_16x16x32_bf16 v[96:99], v[152:155], v[168:171], v[96:99]
	v_mfma_f32_16x16x32_bf16 v[84:87], v[144:147], v[176:179], v[84:87]
	v_mfma_f32_16x16x32_bf16 v[80:83], v[152:155], v[176:179], v[80:83]
	v_mfma_f32_16x16x32_bf16 v[68:71], v[144:147], v[198:201], v[68:71]
	v_mfma_f32_16x16x32_bf16 v[64:67], v[152:155], v[198:201], v[64:67]
	v_mfma_f32_16x16x32_bf16 v[116:119], v[148:151], v[164:167], v[116:119]
	v_mfma_f32_16x16x32_bf16 v[112:115], v[156:159], v[164:167], v[112:115]
	v_mfma_f32_16x16x32_bf16 v[100:103], v[148:151], v[172:175], v[100:103]
	v_mfma_f32_16x16x32_bf16 v[96:99], v[156:159], v[172:175], v[96:99]
	v_mfma_f32_16x16x32_bf16 v[84:87], v[148:151], v[180:183], v[84:87]
	v_mfma_f32_16x16x32_bf16 v[80:83], v[156:159], v[180:183], v[80:83]
	v_mfma_f32_16x16x32_bf16 v[68:71], v[148:151], v[202:205], v[68:71]
	v_mfma_f32_16x16x32_bf16 v[64:67], v[156:159], v[202:205], v[64:67]
	s_setprio 0
	s_barrier
; #define PG8_STAGE(bufoff, gbase, voff) do { _Pragma("unroll") for (int _i = 0; _i < 2; ++_i) \
;         __builtin_amdgcn_global_load_lds((const unsigned*)((const char*)(gbase) + (voff)[_i]), (PG8_LAS unsigned*)(lds + (bufoff) + ldsw + _i * 8192), 16, 0, 0); } while (0)
; #define PG8_LDA(dst, b, h) do { _Pragma("unroll") for (int m = 0; m < 4; ++m) _Pragma("unroll") for (int k = 0; k < 2; ++k) dst[m][k] = *(const PG8_LAS bf16x8*)(lds + PG8_SA(b, h) + aoff + m * 2048 + k * 1024); } while (0)
; #define PG8_MMA(ai, bj, At, Bt) do { __builtin_amdgcn_s_setprio(1); _Pragma("unroll") for (int m = 0; m < 4; ++m) _Pragma("unroll") for (int n = 0; n < 2; ++n) _Pragma("unroll") for (int k = 0; k < 2; ++k) \
;         acc[ai][bj][m][n] = __builtin_amdgcn_mfma_f32_16x16x32_bf16(Bt[n][k], At[m][k], acc[ai][bj][m][n], 0, 0, 0); __builtin_amdgcn_s_setprio(0); } while (0)
; #define PG8_WAIT_V(n) asm volatile("s_waitcnt vmcnt(" #n ")" ::: "memory")
; #define PG8_WAIT_L(n) asm volatile("s_waitcnt lgkmcnt(" #n ")" ::: "memory")
; #define PG8_BAR __builtin_amdgcn_s_barrier()
; #define PG8_SCHED __builtin_amdgcn_sched_barrier(0)
; template <class Epi, class Sched, bool ALIGN_EPI = false, bool SP2 = false>
; __device__ __forceinline__ void gemm_phase(PG8_LAS unsigned char* lds, const Gemm g, const Sched& S, const Epi& E) {
;     ...
;             PG8_LDA(At, 1, 1); PG8_STAGE(PG8_SB(1, 0), b3, voffB); PG8_STAGE(PG8_SB(1, 1), b3 + hstep, voffB); PG8_STAGE(PG8_SA(1, 0), a3, voffA);
;             PG8_WAIT_V(8); PG8_WAIT_L(0); PG8_BAR; PG8_MMA(1, 0, At, B0); PG8_MMA(1, 1, At, B1); PG8_BAR; PG8_SCHED;
	s_add_i32 s40, s62, s44
	v_lshl_add_u64 v[206:207], v[206:207], 0, s[16:17]
	s_mov_b32 m0, s40
	ds_read_b128 v[160:163], v236 offset:49152
	ds_read_b128 v[164:167], v236 offset:50176
	ds_read_b128 v[168:171], v236 offset:51200
	ds_read_b128 v[172:175], v236 offset:52224
	ds_read_b128 v[176:179], v236 offset:53248
	ds_read_b128 v[180:183], v236 offset:54272
	ds_read_b128 v[198:201], v236 offset:55296
	ds_read_b128 v[202:205], v236 offset:56320
	global_load_lds_dwordx4 v[206:207], off
	s_add_i32 m0, s40, 0x2000
	s_add_u32 s38, s38, 0x40080
	v_lshl_add_u64 v[206:207], v[208:209], 0, s[16:17]
	s_addc_u32 s39, s39, 0
	s_add_i32 s40, s63, s44
	global_load_lds_dwordx4 v[206:207], off
	s_mov_b32 m0, s40
	s_nop 0
	global_load_lds_dwordx4 v186, s[38:39]
	s_add_i32 m0, s40, 0x2000
	s_nop 0
	global_load_lds_dwordx4 v190, s[38:39]
	v_lshl_add_u64 v[206:207], v[210:211], 0, s[16:17]
	s_mov_b32 m0, s50
	s_nop 0
	global_load_lds_dwordx4 v[206:207], off
	v_lshl_add_u64 v[206:207], v[212:213], 0, s[16:17]
	s_mov_b32 m0, s51
	s_nop 0
	global_load_lds_dwordx4 v[206:207], off
	s_waitcnt vmcnt(8)
	s_waitcnt lgkmcnt(0)
	s_barrier
	s_setprio 1
	s_waitcnt lgkmcnt(0)
	v_mfma_f32_16x16x32_bf16 v[60:63], v[124:127], v[160:163], v[60:63]
	v_mfma_f32_16x16x32_bf16 v[56:59], v[136:139], v[160:163], v[56:59]
	v_mfma_f32_16x16x32_bf16 v[44:47], v[124:127], v[168:171], v[44:47]
	v_mfma_f32_16x16x32_bf16 v[40:43], v[136:139], v[168:171], v[40:43]
	v_mfma_f32_16x16x32_bf16 v[28:31], v[124:127], v[176:179], v[28:31]
	v_mfma_f32_16x16x32_bf16 v[24:27], v[136:139], v[176:179], v[24:27]
	v_mfma_f32_16x16x32_bf16 v[12:15], v[124:127], v[198:201], v[12:15]
	v_mfma_f32_16x16x32_bf16 v[8:11], v[136:139], v[198:201], v[8:11]
	v_mfma_f32_16x16x32_bf16 v[60:63], v[132:135], v[164:167], v[60:63]
	v_mfma_f32_16x16x32_bf16 v[56:59], v[140:143], v[164:167], v[56:59]
	v_mfma_f32_16x16x32_bf16 v[44:47], v[132:135], v[172:175], v[44:47]
	v_mfma_f32_16x16x32_bf16 v[40:43], v[140:143], v[172:175], v[40:43]
	v_mfma_f32_16x16x32_bf16 v[28:31], v[132:135], v[180:183], v[28:31]
	v_mfma_f32_16x16x32_bf16 v[24:27], v[140:143], v[180:183], v[24:27]
	v_mfma_f32_16x16x32_bf16 v[12:15], v[132:135], v[202:205], v[12:15]
	v_mfma_f32_16x16x32_bf16 v[8:11], v[140:143], v[202:205], v[8:11]
	s_setprio 0
	s_setprio 1
	v_mfma_f32_16x16x32_bf16 v[52:55], v[144:147], v[160:163], v[52:55]
	v_mfma_f32_16x16x32_bf16 v[48:51], v[152:155], v[160:163], v[48:51]
	v_mfma_f32_16x16x32_bf16 v[36:39], v[144:147], v[168:171], v[36:39]
	v_mfma_f32_16x16x32_bf16 v[32:35], v[152:155], v[168:171], v[32:35]
	v_mfma_f32_16x16x32_bf16 v[20:23], v[144:147], v[176:179], v[20:23]
	v_mfma_f32_16x16x32_bf16 v[16:19], v[152:155], v[176:179], v[16:19]
	v_mfma_f32_16x16x32_bf16 v[4:7], v[144:147], v[198:201], v[4:7]
	v_mfma_f32_16x16x32_bf16 v[0:3], v[152:155], v[198:201], v[0:3]
	v_mfma_f32_16x16x32_bf16 v[52:55], v[148:151], v[164:167], v[52:55]
	v_mfma_f32_16x16x32_bf16 v[48:51], v[156:159], v[164:167], v[48:51]
	v_mfma_f32_16x16x32_bf16 v[36:39], v[148:151], v[172:175], v[36:39]
	v_mfma_f32_16x16x32_bf16 v[32:35], v[156:159], v[172:175], v[32:35]
	v_mfma_f32_16x16x32_bf16 v[20:23], v[148:151], v[180:183], v[20:23]
	v_mfma_f32_16x16x32_bf16 v[16:19], v[156:159], v[180:183], v[16:19]
	v_mfma_f32_16x16x32_bf16 v[4:7], v[148:151], v[202:205], v[4:7]
	v_mfma_f32_16x16x32_bf16 v[0:3], v[156:159], v[202:205], v[0:3]
	s_setprio 0
	s_barrier
	s_add_i32 s61, s61, 2
	s_add_u32 s36, s36, 0x100
	s_addc_u32 s37, s37, 0
	s_add_u32 s59, s59, 0x100
	s_addc_u32 s60, s60, 0
	s_cmp_gt_u32 s61, 13
	s_cbranch_scc0 .LBB0_888
	s_and_b64 vcc, exec, s[18:19]
	s_cbranch_vccz .LBB0_891
	s_barrier

; #define PG8_STAGE(bufoff, gbase, voff) do { _Pragma("unroll") for (int _i = 0; _i < 2; ++_i) \
;         __builtin_amdgcn_global_load_lds((const unsigned*)((const char*)(gbase) + (voff)[_i]), (PG8_LAS unsigned*)(lds + (bufoff) + ldsw + _i * 8192), 16, 0, 0); } while (0)
; #define PG8_WAIT_V(n) asm volatile("s_waitcnt vmcnt(" #n ")" ::: "memory")
; #define PG8_BAR __builtin_amdgcn_s_barrier()
; template <class Epi, class Sched, bool ALIGN_EPI = false, bool SP2 = false>
; __device__ __forceinline__ void gemm_phase(PG8_LAS unsigned char* lds, const Gemm g, const Sched& S, const Epi& E) {
;     const int tid = threadIdx.x, wid = __builtin_amdgcn_readfirstlane(tid >> 6), lane = tid & 63, wr = wid >> 2, wc = wid & 3, fr = lane & 15, fq = lane >> 4;
;     const int K = g.K, nt = K / BK;
;     unsigned voffA[2], voffB[2];
; #pragma unroll
;     for (int i = 0; i < 2; ++i) { int R, C; stage_rc(tid * 16 + i * 8192, R, C); const int Rb = Epi::PERM ? ((R & ~31) + perm32(R & 31)) : R;
;         voffA[i] = (unsigned)(R * K + C) * 2u; voffB[i] = (unsigned)(Rb * K + C) * 2u; }
;     const size_t kstep = (size_t)(BK * 2);
;     const size_t hstep = (size_t)HALF * K * 2;
;     const size_t tstep = 2 * hstep;
;     const unsigned ldsw = (unsigned)wid * 1024u;
;     const int aoff = lds_byte(wr * 64 + fr, fq * 8), boff = lds_byte(wc * 32 + fr, fq * 8);
;     ...
;         PG8_STAGE(PG8_SB(1, 0), cB + kstep, voffB); PG8_STAGE(PG8_SA(1, 0), cA + kstep, voffA); PG8_STAGE(PG8_SB(1, 1), cB + hstep + kstep, voffB);
;         PG8_WAIT_V(6); PG8_BAR;
.LBB0_970:
	s_lshl_b32 s12, s12, 5
	s_and_b32 s22, s12, 0x60
	s_mov_b64 s[12:13], 0x80
	s_add_i32 m0, s29, 0x18000
	v_lshl_add_u64 v[6:7], v[6:7], 0, s[12:13]
	s_lshl_b32 s18, s17, 13
	s_lshl_b32 s23, s22, 7
	s_waitcnt vmcnt(2)
	s_barrier
	global_load_lds_dwordx4 v[6:7], off
	v_lshl_add_u64 v[4:5], v[4:5], 0, s[12:13]
	s_add_i32 m0, s29, 0x1a000
	s_add_i32 s47, s29, 0x8000
	s_add_i32 s48, s29, 0xa000
	global_load_lds_dwordx4 v[4:5], off
	v_lshl_add_u64 v[0:1], v[0:1], 0, s[12:13]
	s_mov_b32 m0, s47
	s_add_u32 s20, s36, 0x40080
	global_load_lds_dwordx4 v[0:1], off
	v_lshl_add_u64 v[0:1], v[2:3], 0, s[12:13]
	s_mov_b32 m0, s48
	s_addc_u32 s21, s37, 0
	global_load_lds_dwordx4 v[0:1], off
	s_add_i32 m0, s29, 0x1c000
	global_load_lds_dwordx4 v130, s[20:21]
	v_lshl_add_u64 v[0:1], s[20:21], 0, v[134:135]
	s_add_i32 m0, s29, 0x1e000
	v_bfe_u32 v2, v230, 4, 2
	global_load_lds_dwordx4 v[0:1], off
	v_and_b32_e32 v1, 15, v230
	v_lshlrev_b32_e32 v0, 4, v2
	v_lshlrev_b32_e32 v3, 2, v230
	v_lshl_or_b32 v149, s17, 6, v1
	v_lshl_or_b32 v1, v1, 6, v0
	v_and_b32_e32 v3, 32, v3
	v_bitop3_b32 v4, v1, s18, v3 bitop3:0xde
	v_lshlrev_b32_e32 v1, 6, v230
	s_movk_i32 s17, 0x3c0
	v_and_or_b32 v1, v1, s17, v0
	v_bitop3_b32 v153, s23, v1, v3 bitop3:0xf6
	v_mov_b32_e32 v1, v131
	v_lshl_add_u64 v[136:137], s[34:35], 0, v[0:1]
	v_lshlrev_b32_e32 v0, 8, v230
	v_and_b32_e32 v0, 0x38000, v0
	v_lshlrev_b32_e32 v1, 11, v10
	v_or3_b32 v0, v8, v0, v1
	v_add_u32_e32 v138, v0, v9
	v_lshlrev_b32_e32 v0, 4, v11
	v_and_b32_e32 v0, 0x78000, v0
	s_waitcnt vmcnt(6)
	s_cmpk_lt_u32 s16, 0x100
	v_or3_b32 v0, v8, v0, v1
	s_cselect_b64 s[16:17], -1, 0
	v_add_u32_e32 v140, v0, v9
	s_add_i32 s50, 0, 0x10000
	s_add_i32 s51, 0, 0x14000
	v_mbcnt_lo_u32_b32 v0, -1, 0
	s_add_i32 s49, s33, -2
	v_lshl_or_b32 v157, v2, 3, s22
	v_mov_b32_e32 v139, v131
	v_mov_b32_e32 v141, v131
	v_add_u32_e32 v161, s50, v153
	v_add_u32_e32 v165, s51, v153
	v_add_u32_e32 v169, 0, v4
	v_mbcnt_hi_u32_b32 v175, -1, v0
	v_mov_b32_e32 v176, 0x358637bd
	s_movk_i32 s52, 0x1600
	v_mov_b64_e32 v[142:143], 0x2bff
	s_barrier
	s_branch .LBB0_973

; #define PG8_STAGE(bufoff, gbase, voff) do { _Pragma("unroll") for (int _i = 0; _i < 2; ++_i) \
;         __builtin_amdgcn_global_load_lds((const unsigned*)((const char*)(gbase) + (voff)[_i]), (PG8_LAS unsigned*)(lds + (bufoff) + ldsw + _i * 8192), 16, 0, 0); } while (0)
; #define PG8_LDA(dst, b, h) do { _Pragma("unroll") for (int m = 0; m < 4; ++m) _Pragma("unroll") for (int k = 0; k < 2; ++k) dst[m][k] = *(const PG8_LAS bf16x8*)(lds + PG8_SA(b, h) + aoff + m * 2048 + k * 1024); } while (0)
; #define PG8_LDB(dst, b, h) do { _Pragma("unroll") for (int n = 0; n < 2; ++n) _Pragma("unroll") for (int k = 0; k < 2; ++k) dst[n][k] = *(const PG8_LAS bf16x8*)(lds + PG8_SB(b, h) + boff + n * 2048 + k * 1024); } while (0)
; #define PG8_WAIT_V(n) asm volatile("s_waitcnt vmcnt(" #n ")" ::: "memory")
; #define PG8_WAIT_L(n) asm volatile("s_waitcnt lgkmcnt(" #n ")" ::: "memory")
; #define PG8_BAR __builtin_amdgcn_s_barrier()
; #define PG8_SCHED __builtin_amdgcn_sched_barrier(0)
; template <class Epi, class Sched, bool ALIGN_EPI = false, bool SP2 = false>
; __device__ __forceinline__ void gemm_phase(PG8_LAS unsigned char* lds, const Gemm g, const Sched& S, const Epi& E) {
;     ...
;         const bool has_next = S.next(ui + 1, nxt);
;         const char* nA = has_next ? (const char*)g.A + (size_t)nxt.pm * tstep : cA; const char* nB = has_next ? (const char*)g.Bt + (size_t)nxt.pn * tstep : cB;
;         for (int t = 0; t < nt; t += 2) {
;             const bool last = (t == nt - 2);
;             const char* a1 = cA + (size_t)(t + 1) * kstep;
;             const char* a2 = last ? nA : cA + (size_t)(t + 2) * kstep; const char* b2 = last ? nB : cB + (size_t)(t + 2) * kstep;
;             const char* a3 = a2 + kstep; const char* b3 = b2 + kstep;
;             if (last && has_next) S.a_ready(nxt);
;             if constexpr (SP2) {
;             PG8_LDB(B0, 0, 0); PG8_LDB(B1, 0, 1); PG8_SCHED; PG8_LDA(At, 0, 0); PG8_STAGE(PG8_SA(1, 1), a1 + hstep, voffA);
;             PG8_WAIT_V(8); PG8_WAIT_L(0); PG8_BAR; PG8_MMA(0, 0, At, B0); PG8_MMA(0, 1, At, B1); PG8_BAR; PG8_SCHED;
;             PG8_LDA(At, 0, 1); PG8_STAGE(PG8_SB(0, 0), b2, voffB); PG8_STAGE(PG8_SB(0, 1), b2 + hstep, voffB); PG8_STAGE(PG8_SA(0, 0), a2, voffA);
;             PG8_WAIT_V(8); PG8_WAIT_L(0); PG8_BAR; PG8_MMA(1, 0, At, B0); PG8_MMA(1, 1, At, B1); PG8_BAR; PG8_SCHED;
.LBB0_976:
	s_ashr_i32 s21, s20, 31
	s_lshl_b64 s[24:25], s[20:21], 19
	s_add_u32 s24, s70, s24
	s_addc_u32 s25, s71, s25
	s_and_b64 s[26:27], s[22:23], exec
	s_cselect_b32 s21, s25, s39
	s_cselect_b32 s54, s24, s38
	s_ashr_i32 s19, s18, 31
	s_lshl_b64 s[26:27], s[18:19], 19
	s_add_u32 s26, s41, s26
	s_addc_u32 s27, s42, s27
	s_and_b64 s[34:35], s[22:23], exec
	s_cselect_b32 s19, s27, s37
	s_cselect_b32 s55, s26, s36
	s_add_u32 s34, s38, 0x40080
	s_addc_u32 s35, s39, 0
	s_add_u32 s56, s36, 0x100
	s_addc_u32 s57, s37, 0
	s_mov_b32 s58, -2
	ds_read_b128 v[144:147], v161
	ds_read_b128 v[170:173], v161 offset:1024
	ds_read_b128 v[178:181], v161 offset:2048
	ds_read_b128 v[182:185], v161 offset:3072
	ds_read_b128 v[186:189], v165
	ds_read_b128 v[190:193], v165 offset:1024
	ds_read_b128 v[194:197], v165 offset:2048
	ds_read_b128 v[198:201], v165 offset:3072
	s_add_u32 s36, s34, 0xfffc0080
	s_addc_u32 s37, s35, -1
	s_cmp_eq_u32 s58, 12
	s_cselect_b32 s39, s21, s37
	s_cselect_b32 s38, s54, s36
	s_cselect_b32 s37, s19, s57
	s_cselect_b32 s36, s55, s56
	s_add_i32 m0, s29, 0xc000
	ds_read_b128 v[202:205], v169
	ds_read_b128 v[206:209], v169 offset:1024
	ds_read_b128 v[210:213], v169 offset:2048
	ds_read_b128 v[214:217], v169 offset:3072
	ds_read_b128 v[218:221], v169 offset:4096
	ds_read_b128 v[222:225], v169 offset:5120
	ds_read_b128 v[226:229], v169 offset:6144
	ds_read_b128 v[232:235], v169 offset:7168
	global_load_lds_dwordx4 v138, s[34:35]
	s_add_i32 m0, s29, 0xe000
	s_nop 0
	global_load_lds_dwordx4 v140, s[34:35]
	s_waitcnt vmcnt(8)
	s_waitcnt lgkmcnt(0)
	s_barrier
	s_setprio 1
	s_waitcnt lgkmcnt(0)
	v_mfma_f32_16x16x32_bf16 v[124:127], v[144:147], v[202:205], 0
	v_mfma_f32_16x16x32_bf16 v[116:119], v[178:181], v[202:205], 0
	v_mfma_f32_16x16x32_bf16 v[108:111], v[144:147], v[210:213], 0
	v_mfma_f32_16x16x32_bf16 v[100:103], v[178:181], v[210:213], 0
	v_mfma_f32_16x16x32_bf16 v[92:95], v[144:147], v[218:221], 0
	v_mfma_f32_16x16x32_bf16 v[84:87], v[178:181], v[218:221], 0
	v_mfma_f32_16x16x32_bf16 v[76:79], v[144:147], v[226:229], 0
	v_mfma_f32_16x16x32_bf16 v[68:71], v[178:181], v[226:229], 0
	v_mfma_f32_16x16x32_bf16 v[124:127], v[170:173], v[206:209], v[124:127]
	v_mfma_f32_16x16x32_bf16 v[116:119], v[182:185], v[206:209], v[116:119]
	v_mfma_f32_16x16x32_bf16 v[108:111], v[170:173], v[214:217], v[108:111]
	v_mfma_f32_16x16x32_bf16 v[100:103], v[182:185], v[214:217], v[100:103]
	v_mfma_f32_16x16x32_bf16 v[92:95], v[170:173], v[222:225], v[92:95]
	v_mfma_f32_16x16x32_bf16 v[84:87], v[182:185], v[222:225], v[84:87]
	v_mfma_f32_16x16x32_bf16 v[76:79], v[170:173], v[232:235], v[76:79]
	v_mfma_f32_16x16x32_bf16 v[68:71], v[182:185], v[232:235], v[68:71]
	s_setprio 0
	s_setprio 1
	v_mfma_f32_16x16x32_bf16 v[120:123], v[186:189], v[202:205], 0
	v_mfma_f32_16x16x32_bf16 v[112:115], v[194:197], v[202:205], 0
	v_mfma_f32_16x16x32_bf16 v[104:107], v[186:189], v[210:213], 0
	v_mfma_f32_16x16x32_bf16 v[96:99], v[194:197], v[210:213], 0
	v_mfma_f32_16x16x32_bf16 v[88:91], v[186:189], v[218:221], 0
	v_mfma_f32_16x16x32_bf16 v[80:83], v[194:197], v[218:221], 0
	v_mfma_f32_16x16x32_bf16 v[72:75], v[186:189], v[226:229], 0
	v_mfma_f32_16x16x32_bf16 v[64:67], v[194:197], v[226:229], 0
	v_mfma_f32_16x16x32_bf16 v[120:123], v[190:193], v[206:209], v[120:123]
	v_mfma_f32_16x16x32_bf16 v[112:115], v[198:201], v[206:209], v[112:115]
	v_mfma_f32_16x16x32_bf16 v[104:107], v[190:193], v[214:217], v[104:107]
	v_mfma_f32_16x16x32_bf16 v[96:99], v[198:201], v[214:217], v[96:99]
	v_mfma_f32_16x16x32_bf16 v[88:91], v[190:193], v[222:225], v[88:91]
	v_mfma_f32_16x16x32_bf16 v[80:83], v[198:201], v[222:225], v[80:83]
	v_mfma_f32_16x16x32_bf16 v[72:75], v[190:193], v[232:235], v[72:75]
	v_mfma_f32_16x16x32_bf16 v[64:67], v[198:201], v[232:235], v[64:67]
	s_setprio 0
	s_barrier
	s_add_i32 s59, s50, s43
	v_lshl_add_u64 v[150:151], s[36:37], 0, v[130:131]
	s_mov_b32 m0, s59
	ds_read_b128 v[202:205], v169 offset:16384
	ds_read_b128 v[206:209], v169 offset:17408
	ds_read_b128 v[210:213], v169 offset:18432
	ds_read_b128 v[214:217], v169 offset:19456
	ds_read_b128 v[218:221], v169 offset:20480
	ds_read_b128 v[222:225], v169 offset:21504
	ds_read_b128 v[226:229], v169 offset:22528
	ds_read_b128 v[232:235], v169 offset:23552
	global_load_lds_dwordx4 v[150:151], off
	s_add_i32 m0, s59, 0x2000
	s_add_u32 s60, s36, 0x40000
	v_lshl_add_u64 v[154:155], s[36:37], 0, v[134:135]
	s_addc_u32 s61, s37, 0
	s_add_i32 s59, s51, s43
	global_load_lds_dwordx4 v[154:155], off
	s_mov_b32 m0, s59
	v_lshl_add_u64 v[162:163], s[38:39], 0, v[132:133]
	global_load_lds_dwordx4 v130, s[60:61]
	s_add_i32 m0, s59, 0x2000
	s_nop 0
	global_load_lds_dwordx4 v134, s[60:61]
	v_lshl_add_u64 v[158:159], s[38:39], 0, v[128:129]
	s_mov_b32 m0, s29
	s_nop 0
	global_load_lds_dwordx4 v[158:159], off
	s_mov_b32 m0, s31
	s_nop 0
	global_load_lds_dwordx4 v[162:163], off
	s_cmp_lg_i32 s58, -2
	s_cbranch_scc1 .Lrsb_a_pl
	v_lshrrev_b32_e32 v250, 6, v230
	v_lshlrev_b32_e32 v250, 11, v250
	v_and_b32_e32 v251, 63, v230
	v_lshl_or_b32 v250, v251, 4, v250
	v_lshl_add_u32 v250, s30, 14, v250
	v_readfirstlane_b32 s98, v230
	s_lshr_b32 s98, s98, 6
	s_lshl_b32 s98, s98, 11
	s_add_i32 m0, s98, 0x20000
	s_add_u32 s100, s70, 0x3f000000
	s_addc_u32 s101, s71, 0
	global_load_lds_dwordx4 v250, s[100:101]
	global_load_lds_dwordx4 v250, s[100:101] offset:1024
	s_waitcnt vmcnt(10)
	s_branch .Lrsb_b_pl

; #define PG8_STAGE(bufoff, gbase, voff) do { _Pragma("unroll") for (int _i = 0; _i < 2; ++_i) \
;         __builtin_amdgcn_global_load_lds((const unsigned*)((const char*)(gbase) + (voff)[_i]), (PG8_LAS unsigned*)(lds + (bufoff) + ldsw + _i * 8192), 16, 0, 0); } while (0)
; #define PG8_LDA(dst, b, h) do { _Pragma("unroll") for (int m = 0; m < 4; ++m) _Pragma("unroll") for (int k = 0; k < 2; ++k) dst[m][k] = *(const PG8_LAS bf16x8*)(lds + PG8_SA(b, h) + aoff + m * 2048 + k * 1024); } while (0)
; #define PG8_LDB(dst, b, h) do { _Pragma("unroll") for (int n = 0; n < 2; ++n) _Pragma("unroll") for (int k = 0; k < 2; ++k) dst[n][k] = *(const PG8_LAS bf16x8*)(lds + PG8_SB(b, h) + boff + n * 2048 + k * 1024); } while (0)
; #define PG8_MMA(ai, bj, At, Bt) do { __builtin_amdgcn_s_setprio(1); _Pragma("unroll") for (int m = 0; m < 4; ++m) _Pragma("unroll") for (int n = 0; n < 2; ++n) _Pragma("unroll") for (int k = 0; k < 2; ++k) \
;         acc[ai][bj][m][n] = __builtin_amdgcn_mfma_f32_16x16x32_bf16(Bt[n][k], At[m][k], acc[ai][bj][m][n], 0, 0, 0); __builtin_amdgcn_s_setprio(0); } while (0)
; #define PG8_WAIT_V(n) asm volatile("s_waitcnt vmcnt(" #n ")" ::: "memory")
; #define PG8_WAIT_L(n) asm volatile("s_waitcnt lgkmcnt(" #n ")" ::: "memory")
; #define PG8_BAR __builtin_amdgcn_s_barrier()
; #define PG8_SCHED __builtin_amdgcn_sched_barrier(0)
; template <class Epi, class Sched, bool ALIGN_EPI = false, bool SP2 = false>
; __device__ __forceinline__ void gemm_phase(PG8_LAS unsigned char* lds, const Gemm g, const Sched& S, const Epi& E) {
;     ...
;             PG8_WAIT_V(8); PG8_WAIT_L(0); PG8_BAR; PG8_MMA(1, 0, At, B0); PG8_MMA(1, 1, At, B1); PG8_BAR; PG8_SCHED;
;             PG8_LDB(B0, 1, 0); PG8_LDB(B1, 1, 1); PG8_SCHED; PG8_LDA(At, 1, 0); PG8_STAGE(PG8_SA(0, 1), a2 + hstep, voffA);
;             PG8_WAIT_V(8); PG8_WAIT_L(0); PG8_BAR; PG8_MMA(0, 0, At, B0); PG8_MMA(0, 1, At, B1); PG8_BAR; PG8_SCHED;
.Lrsb_b_pl:
	s_waitcnt lgkmcnt(0)
	s_barrier
	s_setprio 1
	s_waitcnt lgkmcnt(0)
	v_mfma_f32_16x16x32_bf16 v[60:63], v[144:147], v[202:205], 0
	v_mfma_f32_16x16x32_bf16 v[52:55], v[178:181], v[202:205], 0
	v_mfma_f32_16x16x32_bf16 v[44:47], v[144:147], v[210:213], 0
	v_mfma_f32_16x16x32_bf16 v[36:39], v[178:181], v[210:213], 0
	v_mfma_f32_16x16x32_bf16 v[28:31], v[144:147], v[218:221], 0
	v_mfma_f32_16x16x32_bf16 v[20:23], v[178:181], v[218:221], 0
	v_mfma_f32_16x16x32_bf16 v[12:15], v[144:147], v[226:229], 0
	v_mfma_f32_16x16x32_bf16 v[4:7], v[178:181], v[226:229], 0
	v_mfma_f32_16x16x32_bf16 v[60:63], v[170:173], v[206:209], v[60:63]
	v_mfma_f32_16x16x32_bf16 v[52:55], v[182:185], v[206:209], v[52:55]
	v_mfma_f32_16x16x32_bf16 v[44:47], v[170:173], v[214:217], v[44:47]
	v_mfma_f32_16x16x32_bf16 v[36:39], v[182:185], v[214:217], v[36:39]
	v_mfma_f32_16x16x32_bf16 v[28:31], v[170:173], v[222:225], v[28:31]
	v_mfma_f32_16x16x32_bf16 v[20:23], v[182:185], v[222:225], v[20:23]
	v_mfma_f32_16x16x32_bf16 v[12:15], v[170:173], v[232:235], v[12:15]
	v_mfma_f32_16x16x32_bf16 v[4:7], v[182:185], v[232:235], v[4:7]
	s_setprio 0
	s_setprio 1
	v_mfma_f32_16x16x32_bf16 v[56:59], v[186:189], v[202:205], 0
	v_mfma_f32_16x16x32_bf16 v[48:51], v[194:197], v[202:205], 0
	v_mfma_f32_16x16x32_bf16 v[40:43], v[186:189], v[210:213], 0
	v_mfma_f32_16x16x32_bf16 v[32:35], v[194:197], v[210:213], 0
	v_mfma_f32_16x16x32_bf16 v[24:27], v[186:189], v[218:221], 0
	v_mfma_f32_16x16x32_bf16 v[16:19], v[194:197], v[218:221], 0
	v_mfma_f32_16x16x32_bf16 v[8:11], v[186:189], v[226:229], 0
	v_mfma_f32_16x16x32_bf16 v[0:3], v[194:197], v[226:229], 0
	v_mfma_f32_16x16x32_bf16 v[56:59], v[190:193], v[206:209], v[56:59]
	v_mfma_f32_16x16x32_bf16 v[48:51], v[198:201], v[206:209], v[48:51]
	v_mfma_f32_16x16x32_bf16 v[40:43], v[190:193], v[214:217], v[40:43]
	v_mfma_f32_16x16x32_bf16 v[32:35], v[198:201], v[214:217], v[32:35]
	v_mfma_f32_16x16x32_bf16 v[24:27], v[190:193], v[222:225], v[24:27]
	v_mfma_f32_16x16x32_bf16 v[16:19], v[198:201], v[222:225], v[16:19]
	v_mfma_f32_16x16x32_bf16 v[8:11], v[190:193], v[232:235], v[8:11]
	v_mfma_f32_16x16x32_bf16 v[0:3], v[198:201], v[232:235], v[0:3]
	s_setprio 0
	s_barrier
	s_add_i32 s59, 0, 0x18000
	v_add_u32_e32 v148, s59, v153
	s_add_i32 s60, 0, 0x1c000
	ds_read_b128 v[144:147], v148
	ds_read_b128 v[170:173], v148 offset:1024
	ds_read_b128 v[178:181], v148 offset:2048
	ds_read_b128 v[182:185], v148 offset:3072
	v_add_u32_e32 v148, s60, v153
	ds_read_b128 v[186:189], v148
	ds_read_b128 v[190:193], v148 offset:1024
	ds_read_b128 v[194:197], v148 offset:2048
	ds_read_b128 v[198:201], v148 offset:3072
	s_add_u32 s38, s38, 0x40000
	s_addc_u32 s39, s39, 0
	s_mov_b32 m0, s45
	ds_read_b128 v[202:205], v169 offset:32768
	ds_read_b128 v[206:209], v169 offset:33792
	ds_read_b128 v[210:213], v169 offset:34816
	ds_read_b128 v[214:217], v169 offset:35840
	ds_read_b128 v[218:221], v169 offset:36864
	ds_read_b128 v[222:225], v169 offset:37888
	ds_read_b128 v[226:229], v169 offset:38912
	ds_read_b128 v[232:235], v169 offset:39936
	global_load_lds_dwordx4 v128, s[38:39]
	v_lshl_add_u64 v[166:167], s[38:39], 0, v[132:133]
	s_mov_b32 m0, s46
	s_nop 0
	global_load_lds_dwordx4 v[166:167], off
	s_cmp_lg_i32 s58, -2
	s_cbranch_scc1 .Lrsb_c_pl
	s_waitcnt vmcnt(10)
	s_branch .Lrsb_d_pl

; #define PG8_STAGE(bufoff, gbase, voff) do { _Pragma("unroll") for (int _i = 0; _i < 2; ++_i) \
;         __builtin_amdgcn_global_load_lds((const unsigned*)((const char*)(gbase) + (voff)[_i]), (PG8_LAS unsigned*)(lds + (bufoff) + ldsw + _i * 8192), 16, 0, 0); } while (0)
; #define PG8_LDA(dst, b, h) do { _Pragma("unroll") for (int m = 0; m < 4; ++m) _Pragma("unroll") for (int k = 0; k < 2; ++k) dst[m][k] = *(const PG8_LAS bf16x8*)(lds + PG8_SA(b, h) + aoff + m * 2048 + k * 1024); } while (0)
; #define PG8_MMA(ai, bj, At, Bt) do { __builtin_amdgcn_s_setprio(1); _Pragma("unroll") for (int m = 0; m < 4; ++m) _Pragma("unroll") for (int n = 0; n < 2; ++n) _Pragma("unroll") for (int k = 0; k < 2; ++k) \
;         acc[ai][bj][m][n] = __builtin_amdgcn_mfma_f32_16x16x32_bf16(Bt[n][k], At[m][k], acc[ai][bj][m][n], 0, 0, 0); __builtin_amdgcn_s_setprio(0); } while (0)
; #define PG8_WAIT_V(n) asm volatile("s_waitcnt vmcnt(" #n ")" ::: "memory")
; #define PG8_WAIT_L(n) asm volatile("s_waitcnt lgkmcnt(" #n ")" ::: "memory")
; #define PG8_BAR __builtin_amdgcn_s_barrier()
; #define PG8_SCHED __builtin_amdgcn_sched_barrier(0)
; template <class Epi, class Sched, bool ALIGN_EPI = false, bool SP2 = false>
; __device__ __forceinline__ void gemm_phase(PG8_LAS unsigned char* lds, const Gemm g, const Sched& S, const Epi& E) {
;     ...
;             PG8_WAIT_V(8); PG8_WAIT_L(0); PG8_BAR; PG8_MMA(0, 0, At, B0); PG8_MMA(0, 1, At, B1); PG8_BAR; PG8_SCHED;
;             PG8_LDA(At, 1, 1); PG8_STAGE(PG8_SB(1, 0), b3, voffB); PG8_STAGE(PG8_SB(1, 1), b3 + hstep, voffB); PG8_STAGE(PG8_SA(1, 0), a3, voffA);
;             PG8_WAIT_V(8); PG8_WAIT_L(0); PG8_BAR; PG8_MMA(1, 0, At, B0); PG8_MMA(1, 1, At, B1); PG8_BAR; PG8_SCHED;
.Lrsb_d_pl:
	s_waitcnt lgkmcnt(0)
	s_barrier
	s_setprio 1
	s_waitcnt lgkmcnt(0)
	v_mfma_f32_16x16x32_bf16 v[124:127], v[144:147], v[202:205], v[124:127]
	v_mfma_f32_16x16x32_bf16 v[116:119], v[178:181], v[202:205], v[116:119]
	v_mfma_f32_16x16x32_bf16 v[108:111], v[144:147], v[210:213], v[108:111]
	v_mfma_f32_16x16x32_bf16 v[100:103], v[178:181], v[210:213], v[100:103]
	v_mfma_f32_16x16x32_bf16 v[92:95], v[144:147], v[218:221], v[92:95]
	v_mfma_f32_16x16x32_bf16 v[84:87], v[178:181], v[218:221], v[84:87]
	v_mfma_f32_16x16x32_bf16 v[76:79], v[144:147], v[226:229], v[76:79]
	v_mfma_f32_16x16x32_bf16 v[68:71], v[178:181], v[226:229], v[68:71]
	v_mfma_f32_16x16x32_bf16 v[124:127], v[170:173], v[206:209], v[124:127]
	v_mfma_f32_16x16x32_bf16 v[116:119], v[182:185], v[206:209], v[116:119]
	v_mfma_f32_16x16x32_bf16 v[108:111], v[170:173], v[214:217], v[108:111]
	v_mfma_f32_16x16x32_bf16 v[100:103], v[182:185], v[214:217], v[100:103]
	v_mfma_f32_16x16x32_bf16 v[92:95], v[170:173], v[222:225], v[92:95]
	v_mfma_f32_16x16x32_bf16 v[84:87], v[182:185], v[222:225], v[84:87]
	v_mfma_f32_16x16x32_bf16 v[76:79], v[170:173], v[232:235], v[76:79]
	v_mfma_f32_16x16x32_bf16 v[68:71], v[182:185], v[232:235], v[68:71]
	s_setprio 0
	s_setprio 1
	v_mfma_f32_16x16x32_bf16 v[120:123], v[186:189], v[202:205], v[120:123]
	v_mfma_f32_16x16x32_bf16 v[112:115], v[194:197], v[202:205], v[112:115]
	v_mfma_f32_16x16x32_bf16 v[104:107], v[186:189], v[210:213], v[104:107]
	v_mfma_f32_16x16x32_bf16 v[96:99], v[194:197], v[210:213], v[96:99]
	v_mfma_f32_16x16x32_bf16 v[88:91], v[186:189], v[218:221], v[88:91]
	v_mfma_f32_16x16x32_bf16 v[80:83], v[194:197], v[218:221], v[80:83]
	v_mfma_f32_16x16x32_bf16 v[72:75], v[186:189], v[226:229], v[72:75]
	v_mfma_f32_16x16x32_bf16 v[64:67], v[194:197], v[226:229], v[64:67]
	v_mfma_f32_16x16x32_bf16 v[120:123], v[190:193], v[206:209], v[120:123]
	v_mfma_f32_16x16x32_bf16 v[112:115], v[198:201], v[206:209], v[112:115]
	v_mfma_f32_16x16x32_bf16 v[104:107], v[190:193], v[214:217], v[104:107]
	v_mfma_f32_16x16x32_bf16 v[96:99], v[198:201], v[214:217], v[96:99]
	v_mfma_f32_16x16x32_bf16 v[88:91], v[190:193], v[222:225], v[88:91]
	v_mfma_f32_16x16x32_bf16 v[80:83], v[198:201], v[222:225], v[80:83]
	v_mfma_f32_16x16x32_bf16 v[72:75], v[190:193], v[232:235], v[72:75]
	v_mfma_f32_16x16x32_bf16 v[64:67], v[198:201], v[232:235], v[64:67]
	s_setprio 0
	s_barrier
	s_add_i32 s38, s59, s43
	v_lshl_add_u64 v[150:151], v[150:151], 0, s[12:13]
	s_mov_b32 m0, s38
	ds_read_b128 v[202:205], v169 offset:49152
	ds_read_b128 v[206:209], v169 offset:50176
	ds_read_b128 v[210:213], v169 offset:51200
	ds_read_b128 v[214:217], v169 offset:52224
	ds_read_b128 v[218:221], v169 offset:53248
	ds_read_b128 v[222:225], v169 offset:54272
	ds_read_b128 v[226:229], v169 offset:55296
	ds_read_b128 v[232:235], v169 offset:56320
	global_load_lds_dwordx4 v[150:151], off
	s_add_i32 m0, s38, 0x2000
	s_add_u32 s36, s36, 0x40080
	v_lshl_add_u64 v[150:151], v[154:155], 0, s[12:13]
	s_addc_u32 s37, s37, 0
	s_add_i32 s38, s60, s43
	global_load_lds_dwordx4 v[150:151], off
	s_mov_b32 m0, s38
	s_nop 0
	global_load_lds_dwordx4 v130, s[36:37]
	s_add_i32 m0, s38, 0x2000
	s_nop 0
	global_load_lds_dwordx4 v134, s[36:37]
	v_lshl_add_u64 v[150:151], v[158:159], 0, s[12:13]
	s_mov_b32 m0, s47
	s_nop 0
	global_load_lds_dwordx4 v[150:151], off
	v_lshl_add_u64 v[150:151], v[162:163], 0, s[12:13]
	s_mov_b32 m0, s48
	s_nop 0
	global_load_lds_dwordx4 v[150:151], off
	s_waitcnt vmcnt(8)
	s_waitcnt lgkmcnt(0)
	s_barrier
	s_setprio 1
	s_waitcnt lgkmcnt(0)
	v_mfma_f32_16x16x32_bf16 v[60:63], v[144:147], v[202:205], v[60:63]
	v_mfma_f32_16x16x32_bf16 v[52:55], v[178:181], v[202:205], v[52:55]
	v_mfma_f32_16x16x32_bf16 v[44:47], v[144:147], v[210:213], v[44:47]
	v_mfma_f32_16x16x32_bf16 v[36:39], v[178:181], v[210:213], v[36:39]
	v_mfma_f32_16x16x32_bf16 v[28:31], v[144:147], v[218:221], v[28:31]
	v_mfma_f32_16x16x32_bf16 v[20:23], v[178:181], v[218:221], v[20:23]
	v_mfma_f32_16x16x32_bf16 v[12:15], v[144:147], v[226:229], v[12:15]
	v_mfma_f32_16x16x32_bf16 v[4:7], v[178:181], v[226:229], v[4:7]
	v_mfma_f32_16x16x32_bf16 v[60:63], v[170:173], v[206:209], v[60:63]
	v_mfma_f32_16x16x32_bf16 v[52:55], v[182:185], v[206:209], v[52:55]
	v_mfma_f32_16x16x32_bf16 v[44:47], v[170:173], v[214:217], v[44:47]
	v_mfma_f32_16x16x32_bf16 v[36:39], v[182:185], v[214:217], v[36:39]
	v_mfma_f32_16x16x32_bf16 v[28:31], v[170:173], v[222:225], v[28:31]
	v_mfma_f32_16x16x32_bf16 v[20:23], v[182:185], v[222:225], v[20:23]
	v_mfma_f32_16x16x32_bf16 v[12:15], v[170:173], v[232:235], v[12:15]
	v_mfma_f32_16x16x32_bf16 v[4:7], v[182:185], v[232:235], v[4:7]
	s_setprio 0
	s_setprio 1
	v_mfma_f32_16x16x32_bf16 v[56:59], v[186:189], v[202:205], v[56:59]
	v_mfma_f32_16x16x32_bf16 v[48:51], v[194:197], v[202:205], v[48:51]
	v_mfma_f32_16x16x32_bf16 v[40:43], v[186:189], v[210:213], v[40:43]
	v_mfma_f32_16x16x32_bf16 v[32:35], v[194:197], v[210:213], v[32:35]
	v_mfma_f32_16x16x32_bf16 v[24:27], v[186:189], v[218:221], v[24:27]
	v_mfma_f32_16x16x32_bf16 v[16:19], v[194:197], v[218:221], v[16:19]
	v_mfma_f32_16x16x32_bf16 v[8:11], v[186:189], v[226:229], v[8:11]
	v_mfma_f32_16x16x32_bf16 v[0:3], v[194:197], v[226:229], v[0:3]
	v_mfma_f32_16x16x32_bf16 v[56:59], v[190:193], v[206:209], v[56:59]
	v_mfma_f32_16x16x32_bf16 v[48:51], v[198:201], v[206:209], v[48:51]
	v_mfma_f32_16x16x32_bf16 v[40:43], v[190:193], v[214:217], v[40:43]
	v_mfma_f32_16x16x32_bf16 v[32:35], v[198:201], v[214:217], v[32:35]
	v_mfma_f32_16x16x32_bf16 v[24:27], v[190:193], v[222:225], v[24:27]
	v_mfma_f32_16x16x32_bf16 v[16:19], v[198:201], v[222:225], v[16:19]
	v_mfma_f32_16x16x32_bf16 v[8:11], v[190:193], v[232:235], v[8:11]
	v_mfma_f32_16x16x32_bf16 v[0:3], v[198:201], v[232:235], v[0:3]
	s_setprio 0
	s_barrier
	s_add_i32 s58, s58, 2
	s_add_u32 s34, s34, 0x100
	s_addc_u32 s35, s35, 0
	s_add_u32 s56, s56, 0x100
	s_addc_u32 s57, s57, 0
	s_cmp_gt_u32 s58, 13
; #define PG8_STAGE(bufoff, gbase, voff) do { _Pragma("unroll") for (int _i = 0; _i < 2; ++_i) \
;         __builtin_amdgcn_global_load_lds((const unsigned*)((const char*)(gbase) + (voff)[_i]), (PG8_LAS unsigned*)(lds + (bufoff) + ldsw + _i * 8192), 16, 0, 0); } while (0)
; #define PG8_LDA(dst, b, h) do { _Pragma("unroll") for (int m = 0; m < 4; ++m) _Pragma("unroll") for (int k = 0; k < 2; ++k) dst[m][k] = *(const PG8_LAS bf16x8*)(lds + PG8_SA(b, h) + aoff + m * 2048 + k * 1024); } while (0)
; #define PG8_LDB(dst, b, h) do { _Pragma("unroll") for (int n = 0; n < 2; ++n) _Pragma("unroll") for (int k = 0; k < 2; ++k) dst[n][k] = *(const PG8_LAS bf16x8*)(lds + PG8_SB(b, h) + boff + n * 2048 + k * 1024); } while (0)
; #define PG8_MMA(ai, bj, At, Bt) do { __builtin_amdgcn_s_setprio(1); _Pragma("unroll") for (int m = 0; m < 4; ++m) _Pragma("unroll") for (int n = 0; n < 2; ++n) _Pragma("unroll") for (int k = 0; k < 2; ++k) \
;         acc[ai][bj][m][n] = __builtin_amdgcn_mfma_f32_16x16x32_bf16(Bt[n][k], At[m][k], acc[ai][bj][m][n], 0, 0, 0); __builtin_amdgcn_s_setprio(0); } while (0)
; #define PG8_WAIT_V(n) asm volatile("s_waitcnt vmcnt(" #n ")" ::: "memory")
; #define PG8_WAIT_L(n) asm volatile("s_waitcnt lgkmcnt(" #n ")" ::: "memory")
; #define PG8_BAR __builtin_amdgcn_s_barrier()
; #define PG8_SCHED __builtin_amdgcn_sched_barrier(0)
; template <class Epi, class Sched, bool ALIGN_EPI = false, bool SP2 = false>
; __device__ __forceinline__ void gemm_phase(PG8_LAS unsigned char* lds, const Gemm g, const Sched& S, const Epi& E) {
;     ...
;             PG8_LDB(B0, 0, 0); PG8_LDB(B1, 0, 1); PG8_SCHED; PG8_LDA(At, 0, 0); PG8_STAGE(PG8_SA(1, 1), a1 + hstep, voffA);
;             PG8_WAIT_V(8); PG8_WAIT_L(0); PG8_BAR; PG8_MMA(0, 0, At, B0); PG8_MMA(0, 1, At, B1); PG8_BAR; PG8_SCHED;
;             PG8_LDA(At, 0, 1); PG8_STAGE(PG8_SB(0, 0), b2, voffB); PG8_STAGE(PG8_SB(0, 1), b2 + hstep, voffB); PG8_STAGE(PG8_SA(0, 0), a2, voffA);
;             PG8_WAIT_V(8); PG8_WAIT_L(0); PG8_BAR; PG8_MMA(1, 0, At, B0); PG8_MMA(1, 1, At, B1); PG8_BAR; PG8_SCHED;
.LBB0_977:
	ds_read_b128 v[144:147], v161
	ds_read_b128 v[170:173], v161 offset:1024
	ds_read_b128 v[178:181], v161 offset:2048
	ds_read_b128 v[182:185], v161 offset:3072
	ds_read_b128 v[186:189], v165
	ds_read_b128 v[190:193], v165 offset:1024
	ds_read_b128 v[194:197], v165 offset:2048
	ds_read_b128 v[198:201], v165 offset:3072
	s_add_u32 s36, s34, 0xfffc0080
	s_addc_u32 s37, s35, -1
	s_cmp_eq_u32 s58, 12
	s_cselect_b32 s39, s21, s37
	s_cselect_b32 s38, s54, s36
	s_cselect_b32 s37, s19, s57
	s_cselect_b32 s36, s55, s56
	s_add_i32 m0, s29, 0xc000
	ds_read_b128 v[202:205], v169
	ds_read_b128 v[206:209], v169 offset:1024
	ds_read_b128 v[210:213], v169 offset:2048
	ds_read_b128 v[214:217], v169 offset:3072
	ds_read_b128 v[218:221], v169 offset:4096
	ds_read_b128 v[222:225], v169 offset:5120
	ds_read_b128 v[226:229], v169 offset:6144
	ds_read_b128 v[232:235], v169 offset:7168
	global_load_lds_dwordx4 v138, s[34:35]
	s_add_i32 m0, s29, 0xe000
	s_nop 0
	global_load_lds_dwordx4 v140, s[34:35]
	s_waitcnt vmcnt(8)
	s_waitcnt lgkmcnt(0)
	s_barrier
	s_setprio 1
	s_waitcnt lgkmcnt(0)
	v_mfma_f32_16x16x32_bf16 v[124:127], v[144:147], v[202:205], v[124:127]
	v_mfma_f32_16x16x32_bf16 v[116:119], v[178:181], v[202:205], v[116:119]
	v_mfma_f32_16x16x32_bf16 v[108:111], v[144:147], v[210:213], v[108:111]
	v_mfma_f32_16x16x32_bf16 v[100:103], v[178:181], v[210:213], v[100:103]
	v_mfma_f32_16x16x32_bf16 v[92:95], v[144:147], v[218:221], v[92:95]
	v_mfma_f32_16x16x32_bf16 v[84:87], v[178:181], v[218:221], v[84:87]
	v_mfma_f32_16x16x32_bf16 v[76:79], v[144:147], v[226:229], v[76:79]
	v_mfma_f32_16x16x32_bf16 v[68:71], v[178:181], v[226:229], v[68:71]
	v_mfma_f32_16x16x32_bf16 v[124:127], v[170:173], v[206:209], v[124:127]
	v_mfma_f32_16x16x32_bf16 v[116:119], v[182:185], v[206:209], v[116:119]
	v_mfma_f32_16x16x32_bf16 v[108:111], v[170:173], v[214:217], v[108:111]
	v_mfma_f32_16x16x32_bf16 v[100:103], v[182:185], v[214:217], v[100:103]
	v_mfma_f32_16x16x32_bf16 v[92:95], v[170:173], v[222:225], v[92:95]
	v_mfma_f32_16x16x32_bf16 v[84:87], v[182:185], v[222:225], v[84:87]
	v_mfma_f32_16x16x32_bf16 v[76:79], v[170:173], v[232:235], v[76:79]
	v_mfma_f32_16x16x32_bf16 v[68:71], v[182:185], v[232:235], v[68:71]
	s_setprio 0
	s_setprio 1
	v_mfma_f32_16x16x32_bf16 v[120:123], v[186:189], v[202:205], v[120:123]
	v_mfma_f32_16x16x32_bf16 v[112:115], v[194:197], v[202:205], v[112:115]
	v_mfma_f32_16x16x32_bf16 v[104:107], v[186:189], v[210:213], v[104:107]
	v_mfma_f32_16x16x32_bf16 v[96:99], v[194:197], v[210:213], v[96:99]
	v_mfma_f32_16x16x32_bf16 v[88:91], v[186:189], v[218:221], v[88:91]
	v_mfma_f32_16x16x32_bf16 v[80:83], v[194:197], v[218:221], v[80:83]
	v_mfma_f32_16x16x32_bf16 v[72:75], v[186:189], v[226:229], v[72:75]
	v_mfma_f32_16x16x32_bf16 v[64:67], v[194:197], v[226:229], v[64:67]
	v_mfma_f32_16x16x32_bf16 v[120:123], v[190:193], v[206:209], v[120:123]
	v_mfma_f32_16x16x32_bf16 v[112:115], v[198:201], v[206:209], v[112:115]
	v_mfma_f32_16x16x32_bf16 v[104:107], v[190:193], v[214:217], v[104:107]
	v_mfma_f32_16x16x32_bf16 v[96:99], v[198:201], v[214:217], v[96:99]
	v_mfma_f32_16x16x32_bf16 v[88:91], v[190:193], v[222:225], v[88:91]
	v_mfma_f32_16x16x32_bf16 v[80:83], v[198:201], v[222:225], v[80:83]
	v_mfma_f32_16x16x32_bf16 v[72:75], v[190:193], v[232:235], v[72:75]
	v_mfma_f32_16x16x32_bf16 v[64:67], v[198:201], v[232:235], v[64:67]
	s_setprio 0
	s_barrier
	s_add_i32 s59, s50, s43
	v_lshl_add_u64 v[150:151], s[36:37], 0, v[130:131]
	s_mov_b32 m0, s59
	ds_read_b128 v[202:205], v169 offset:16384
	ds_read_b128 v[206:209], v169 offset:17408
	ds_read_b128 v[210:213], v169 offset:18432
	ds_read_b128 v[214:217], v169 offset:19456
	ds_read_b128 v[218:221], v169 offset:20480
	ds_read_b128 v[222:225], v169 offset:21504
	ds_read_b128 v[226:229], v169 offset:22528
	ds_read_b128 v[232:235], v169 offset:23552
	global_load_lds_dwordx4 v[150:151], off
	s_add_i32 m0, s59, 0x2000
	s_add_u32 s60, s36, 0x40000
	v_lshl_add_u64 v[154:155], s[36:37], 0, v[134:135]
	s_addc_u32 s61, s37, 0
	s_add_i32 s59, s51, s43
	global_load_lds_dwordx4 v[154:155], off
	s_mov_b32 m0, s59
	v_lshl_add_u64 v[162:163], s[38:39], 0, v[132:133]
	global_load_lds_dwordx4 v130, s[60:61]
	s_add_i32 m0, s59, 0x2000
	s_nop 0
	global_load_lds_dwordx4 v134, s[60:61]
	v_lshl_add_u64 v[158:159], s[38:39], 0, v[128:129]
	s_mov_b32 m0, s29
	s_nop 0
	global_load_lds_dwordx4 v[158:159], off
	s_mov_b32 m0, s31
	s_nop 0
	global_load_lds_dwordx4 v[162:163], off
	s_cmp_lg_i32 s58, -2
	s_cbranch_scc1 .Lrsb_a
	v_lshrrev_b32_e32 v250, 6, v230
	v_lshlrev_b32_e32 v250, 11, v250
	v_and_b32_e32 v251, 63, v230
	v_lshl_or_b32 v250, v251, 4, v250
	v_lshl_add_u32 v250, s30, 14, v250
	v_readfirstlane_b32 s98, v230
	s_lshr_b32 s98, s98, 6
	s_lshl_b32 s98, s98, 11
	s_add_i32 m0, s98, 0x20000
	s_add_u32 s100, s70, 0x3f000000
	s_addc_u32 s101, s71, 0
	global_load_lds_dwordx4 v250, s[100:101]
	global_load_lds_dwordx4 v250, s[100:101] offset:1024
	s_waitcnt vmcnt(10)
	s_branch .Lrsb_b

; #define PG8_STAGE(bufoff, gbase, voff) do { _Pragma("unroll") for (int _i = 0; _i < 2; ++_i) \
;         __builtin_amdgcn_global_load_lds((const unsigned*)((const char*)(gbase) + (voff)[_i]), (PG8_LAS unsigned*)(lds + (bufoff) + ldsw + _i * 8192), 16, 0, 0); } while (0)
; #define PG8_LDA(dst, b, h) do { _Pragma("unroll") for (int m = 0; m < 4; ++m) _Pragma("unroll") for (int k = 0; k < 2; ++k) dst[m][k] = *(const PG8_LAS bf16x8*)(lds + PG8_SA(b, h) + aoff + m * 2048 + k * 1024); } while (0)
; #define PG8_LDB(dst, b, h) do { _Pragma("unroll") for (int n = 0; n < 2; ++n) _Pragma("unroll") for (int k = 0; k < 2; ++k) dst[n][k] = *(const PG8_LAS bf16x8*)(lds + PG8_SB(b, h) + boff + n * 2048 + k * 1024); } while (0)
; #define PG8_MMA(ai, bj, At, Bt) do { __builtin_amdgcn_s_setprio(1); _Pragma("unroll") for (int m = 0; m < 4; ++m) _Pragma("unroll") for (int n = 0; n < 2; ++n) _Pragma("unroll") for (int k = 0; k < 2; ++k) \
;         acc[ai][bj][m][n] = __builtin_amdgcn_mfma_f32_16x16x32_bf16(Bt[n][k], At[m][k], acc[ai][bj][m][n], 0, 0, 0); __builtin_amdgcn_s_setprio(0); } while (0)
; #define PG8_WAIT_V(n) asm volatile("s_waitcnt vmcnt(" #n ")" ::: "memory")
; #define PG8_WAIT_L(n) asm volatile("s_waitcnt lgkmcnt(" #n ")" ::: "memory")
; #define PG8_BAR __builtin_amdgcn_s_barrier()
; #define PG8_SCHED __builtin_amdgcn_sched_barrier(0)
; template <class Epi, class Sched, bool ALIGN_EPI = false, bool SP2 = false>
; __device__ __forceinline__ void gemm_phase(PG8_LAS unsigned char* lds, const Gemm g, const Sched& S, const Epi& E) {
;     ...
;             PG8_WAIT_V(8); PG8_WAIT_L(0); PG8_BAR; PG8_MMA(1, 0, At, B0); PG8_MMA(1, 1, At, B1); PG8_BAR; PG8_SCHED;
;             PG8_LDB(B0, 1, 0); PG8_LDB(B1, 1, 1); PG8_SCHED; PG8_LDA(At, 1, 0); PG8_STAGE(PG8_SA(0, 1), a2 + hstep, voffA);
;             PG8_WAIT_V(8); PG8_WAIT_L(0); PG8_BAR; PG8_MMA(0, 0, At, B0); PG8_MMA(0, 1, At, B1); PG8_BAR; PG8_SCHED;
.Lrsb_b:
	s_waitcnt lgkmcnt(0)
	s_barrier
	s_setprio 1
	s_waitcnt lgkmcnt(0)
	v_mfma_f32_16x16x32_bf16 v[60:63], v[144:147], v[202:205], v[60:63]
	v_mfma_f32_16x16x32_bf16 v[52:55], v[178:181], v[202:205], v[52:55]
	v_mfma_f32_16x16x32_bf16 v[44:47], v[144:147], v[210:213], v[44:47]
	v_mfma_f32_16x16x32_bf16 v[36:39], v[178:181], v[210:213], v[36:39]
	v_mfma_f32_16x16x32_bf16 v[28:31], v[144:147], v[218:221], v[28:31]
	v_mfma_f32_16x16x32_bf16 v[20:23], v[178:181], v[218:221], v[20:23]
	v_mfma_f32_16x16x32_bf16 v[12:15], v[144:147], v[226:229], v[12:15]
	v_mfma_f32_16x16x32_bf16 v[4:7], v[178:181], v[226:229], v[4:7]
	v_mfma_f32_16x16x32_bf16 v[60:63], v[170:173], v[206:209], v[60:63]
	v_mfma_f32_16x16x32_bf16 v[52:55], v[182:185], v[206:209], v[52:55]
	v_mfma_f32_16x16x32_bf16 v[44:47], v[170:173], v[214:217], v[44:47]
	v_mfma_f32_16x16x32_bf16 v[36:39], v[182:185], v[214:217], v[36:39]
	v_mfma_f32_16x16x32_bf16 v[28:31], v[170:173], v[222:225], v[28:31]
	v_mfma_f32_16x16x32_bf16 v[20:23], v[182:185], v[222:225], v[20:23]
	v_mfma_f32_16x16x32_bf16 v[12:15], v[170:173], v[232:235], v[12:15]
	v_mfma_f32_16x16x32_bf16 v[4:7], v[182:185], v[232:235], v[4:7]
	s_setprio 0
	s_setprio 1
	v_mfma_f32_16x16x32_bf16 v[56:59], v[186:189], v[202:205], v[56:59]
	v_mfma_f32_16x16x32_bf16 v[48:51], v[194:197], v[202:205], v[48:51]
	v_mfma_f32_16x16x32_bf16 v[40:43], v[186:189], v[210:213], v[40:43]
	v_mfma_f32_16x16x32_bf16 v[32:35], v[194:197], v[210:213], v[32:35]
	v_mfma_f32_16x16x32_bf16 v[24:27], v[186:189], v[218:221], v[24:27]
	v_mfma_f32_16x16x32_bf16 v[16:19], v[194:197], v[218:221], v[16:19]
	v_mfma_f32_16x16x32_bf16 v[8:11], v[186:189], v[226:229], v[8:11]
	v_mfma_f32_16x16x32_bf16 v[0:3], v[194:197], v[226:229], v[0:3]
	v_mfma_f32_16x16x32_bf16 v[56:59], v[190:193], v[206:209], v[56:59]
	v_mfma_f32_16x16x32_bf16 v[48:51], v[198:201], v[206:209], v[48:51]
	v_mfma_f32_16x16x32_bf16 v[40:43], v[190:193], v[214:217], v[40:43]
	v_mfma_f32_16x16x32_bf16 v[32:35], v[198:201], v[214:217], v[32:35]
	v_mfma_f32_16x16x32_bf16 v[24:27], v[190:193], v[222:225], v[24:27]
	v_mfma_f32_16x16x32_bf16 v[16:19], v[198:201], v[222:225], v[16:19]
	v_mfma_f32_16x16x32_bf16 v[8:11], v[190:193], v[232:235], v[8:11]
	v_mfma_f32_16x16x32_bf16 v[0:3], v[198:201], v[232:235], v[0:3]
	s_setprio 0
	s_barrier
	s_add_i32 s59, 0, 0x18000
	v_add_u32_e32 v148, s59, v153
	s_add_i32 s60, 0, 0x1c000
	ds_read_b128 v[144:147], v148
	ds_read_b128 v[170:173], v148 offset:1024
	ds_read_b128 v[178:181], v148 offset:2048
	ds_read_b128 v[182:185], v148 offset:3072
	v_add_u32_e32 v148, s60, v153
	ds_read_b128 v[186:189], v148
	ds_read_b128 v[190:193], v148 offset:1024
	ds_read_b128 v[194:197], v148 offset:2048
	ds_read_b128 v[198:201], v148 offset:3072
	s_add_u32 s38, s38, 0x40000
	s_addc_u32 s39, s39, 0
	s_mov_b32 m0, s45
	ds_read_b128 v[202:205], v169 offset:32768
	ds_read_b128 v[206:209], v169 offset:33792
	ds_read_b128 v[210:213], v169 offset:34816
	ds_read_b128 v[214:217], v169 offset:35840
	ds_read_b128 v[218:221], v169 offset:36864
	ds_read_b128 v[222:225], v169 offset:37888
	ds_read_b128 v[226:229], v169 offset:38912
	ds_read_b128 v[232:235], v169 offset:39936
	global_load_lds_dwordx4 v128, s[38:39]
	v_lshl_add_u64 v[166:167], s[38:39], 0, v[132:133]
	s_mov_b32 m0, s46
	s_nop 0
	global_load_lds_dwordx4 v[166:167], off
	s_cmp_lg_i32 s58, -2
	s_cbranch_scc1 .Lrsb_c
	s_waitcnt vmcnt(10)
	s_branch .Lrsb_d

; #define PG8_STAGE(bufoff, gbase, voff) do { _Pragma("unroll") for (int _i = 0; _i < 2; ++_i) \
;         __builtin_amdgcn_global_load_lds((const unsigned*)((const char*)(gbase) + (voff)[_i]), (PG8_LAS unsigned*)(lds + (bufoff) + ldsw + _i * 8192), 16, 0, 0); } while (0)
; #define PG8_LDA(dst, b, h) do { _Pragma("unroll") for (int m = 0; m < 4; ++m) _Pragma("unroll") for (int k = 0; k < 2; ++k) dst[m][k] = *(const PG8_LAS bf16x8*)(lds + PG8_SA(b, h) + aoff + m * 2048 + k * 1024); } while (0)
; #define PG8_MMA(ai, bj, At, Bt) do { __builtin_amdgcn_s_setprio(1); _Pragma("unroll") for (int m = 0; m < 4; ++m) _Pragma("unroll") for (int n = 0; n < 2; ++n) _Pragma("unroll") for (int k = 0; k < 2; ++k) \
;         acc[ai][bj][m][n] = __builtin_amdgcn_mfma_f32_16x16x32_bf16(Bt[n][k], At[m][k], acc[ai][bj][m][n], 0, 0, 0); __builtin_amdgcn_s_setprio(0); } while (0)
; #define PG8_WAIT_V(n) asm volatile("s_waitcnt vmcnt(" #n ")" ::: "memory")
; #define PG8_WAIT_L(n) asm volatile("s_waitcnt lgkmcnt(" #n ")" ::: "memory")
; #define PG8_BAR __builtin_amdgcn_s_barrier()
; #define PG8_SCHED __builtin_amdgcn_sched_barrier(0)
; template <class Epi, class Sched, bool ALIGN_EPI = false, bool SP2 = false>
; __device__ __forceinline__ void gemm_phase(PG8_LAS unsigned char* lds, const Gemm g, const Sched& S, const Epi& E) {
;     ...
;             PG8_WAIT_V(8); PG8_WAIT_L(0); PG8_BAR; PG8_MMA(0, 0, At, B0); PG8_MMA(0, 1, At, B1); PG8_BAR; PG8_SCHED;
;             PG8_LDA(At, 1, 1); PG8_STAGE(PG8_SB(1, 0), b3, voffB); PG8_STAGE(PG8_SB(1, 1), b3 + hstep, voffB); PG8_STAGE(PG8_SA(1, 0), a3, voffA);
;             PG8_WAIT_V(8); PG8_WAIT_L(0); PG8_BAR; PG8_MMA(1, 0, At, B0); PG8_MMA(1, 1, At, B1); PG8_BAR; PG8_SCHED;
.Lrsb_d:
	s_waitcnt lgkmcnt(0)
	s_barrier
	s_setprio 1
	s_waitcnt lgkmcnt(0)
	v_mfma_f32_16x16x32_bf16 v[124:127], v[144:147], v[202:205], v[124:127]
	v_mfma_f32_16x16x32_bf16 v[116:119], v[178:181], v[202:205], v[116:119]
	v_mfma_f32_16x16x32_bf16 v[108:111], v[144:147], v[210:213], v[108:111]
	v_mfma_f32_16x16x32_bf16 v[100:103], v[178:181], v[210:213], v[100:103]
	v_mfma_f32_16x16x32_bf16 v[92:95], v[144:147], v[218:221], v[92:95]
	v_mfma_f32_16x16x32_bf16 v[84:87], v[178:181], v[218:221], v[84:87]
	v_mfma_f32_16x16x32_bf16 v[76:79], v[144:147], v[226:229], v[76:79]
	v_mfma_f32_16x16x32_bf16 v[68:71], v[178:181], v[226:229], v[68:71]
	v_mfma_f32_16x16x32_bf16 v[124:127], v[170:173], v[206:209], v[124:127]
	v_mfma_f32_16x16x32_bf16 v[116:119], v[182:185], v[206:209], v[116:119]
	v_mfma_f32_16x16x32_bf16 v[108:111], v[170:173], v[214:217], v[108:111]
	v_mfma_f32_16x16x32_bf16 v[100:103], v[182:185], v[214:217], v[100:103]
	v_mfma_f32_16x16x32_bf16 v[92:95], v[170:173], v[222:225], v[92:95]
	v_mfma_f32_16x16x32_bf16 v[84:87], v[182:185], v[222:225], v[84:87]
	v_mfma_f32_16x16x32_bf16 v[76:79], v[170:173], v[232:235], v[76:79]
	v_mfma_f32_16x16x32_bf16 v[68:71], v[182:185], v[232:235], v[68:71]
	s_setprio 0
	s_setprio 1
	v_mfma_f32_16x16x32_bf16 v[120:123], v[186:189], v[202:205], v[120:123]
	v_mfma_f32_16x16x32_bf16 v[112:115], v[194:197], v[202:205], v[112:115]
	v_mfma_f32_16x16x32_bf16 v[104:107], v[186:189], v[210:213], v[104:107]
	v_mfma_f32_16x16x32_bf16 v[96:99], v[194:197], v[210:213], v[96:99]
	v_mfma_f32_16x16x32_bf16 v[88:91], v[186:189], v[218:221], v[88:91]
	v_mfma_f32_16x16x32_bf16 v[80:83], v[194:197], v[218:221], v[80:83]
	v_mfma_f32_16x16x32_bf16 v[72:75], v[186:189], v[226:229], v[72:75]
	v_mfma_f32_16x16x32_bf16 v[64:67], v[194:197], v[226:229], v[64:67]
	v_mfma_f32_16x16x32_bf16 v[120:123], v[190:193], v[206:209], v[120:123]
	v_mfma_f32_16x16x32_bf16 v[112:115], v[198:201], v[206:209], v[112:115]
	v_mfma_f32_16x16x32_bf16 v[104:107], v[190:193], v[214:217], v[104:107]
	v_mfma_f32_16x16x32_bf16 v[96:99], v[198:201], v[214:217], v[96:99]
	v_mfma_f32_16x16x32_bf16 v[88:91], v[190:193], v[222:225], v[88:91]
	v_mfma_f32_16x16x32_bf16 v[80:83], v[198:201], v[222:225], v[80:83]
	v_mfma_f32_16x16x32_bf16 v[72:75], v[190:193], v[232:235], v[72:75]
	v_mfma_f32_16x16x32_bf16 v[64:67], v[198:201], v[232:235], v[64:67]
	s_setprio 0
	s_barrier
	s_add_i32 s38, s59, s43
	v_lshl_add_u64 v[150:151], v[150:151], 0, s[12:13]
	s_mov_b32 m0, s38
	ds_read_b128 v[202:205], v169 offset:49152
	ds_read_b128 v[206:209], v169 offset:50176
	ds_read_b128 v[210:213], v169 offset:51200
	ds_read_b128 v[214:217], v169 offset:52224
	ds_read_b128 v[218:221], v169 offset:53248
	ds_read_b128 v[222:225], v169 offset:54272
	ds_read_b128 v[226:229], v169 offset:55296
	ds_read_b128 v[232:235], v169 offset:56320
	global_load_lds_dwordx4 v[150:151], off
	s_add_i32 m0, s38, 0x2000
	s_add_u32 s36, s36, 0x40080
	v_lshl_add_u64 v[150:151], v[154:155], 0, s[12:13]
	s_addc_u32 s37, s37, 0
	s_add_i32 s38, s60, s43
	global_load_lds_dwordx4 v[150:151], off
	s_mov_b32 m0, s38
	s_nop 0
	global_load_lds_dwordx4 v130, s[36:37]
	s_add_i32 m0, s38, 0x2000
	s_nop 0
	global_load_lds_dwordx4 v134, s[36:37]
	v_lshl_add_u64 v[150:151], v[158:159], 0, s[12:13]
	s_mov_b32 m0, s47
	s_nop 0
	global_load_lds_dwordx4 v[150:151], off
	v_lshl_add_u64 v[150:151], v[162:163], 0, s[12:13]
	s_mov_b32 m0, s48
	s_nop 0
	global_load_lds_dwordx4 v[150:151], off
	s_waitcnt vmcnt(8)
	s_waitcnt lgkmcnt(0)
	s_barrier
	s_setprio 1
	s_waitcnt lgkmcnt(0)
	v_mfma_f32_16x16x32_bf16 v[60:63], v[144:147], v[202:205], v[60:63]
	v_mfma_f32_16x16x32_bf16 v[52:55], v[178:181], v[202:205], v[52:55]
	v_mfma_f32_16x16x32_bf16 v[44:47], v[144:147], v[210:213], v[44:47]
	v_mfma_f32_16x16x32_bf16 v[36:39], v[178:181], v[210:213], v[36:39]
	v_mfma_f32_16x16x32_bf16 v[28:31], v[144:147], v[218:221], v[28:31]
	v_mfma_f32_16x16x32_bf16 v[20:23], v[178:181], v[218:221], v[20:23]
	v_mfma_f32_16x16x32_bf16 v[12:15], v[144:147], v[226:229], v[12:15]
	v_mfma_f32_16x16x32_bf16 v[4:7], v[178:181], v[226:229], v[4:7]
	v_mfma_f32_16x16x32_bf16 v[60:63], v[170:173], v[206:209], v[60:63]
	v_mfma_f32_16x16x32_bf16 v[52:55], v[182:185], v[206:209], v[52:55]
	v_mfma_f32_16x16x32_bf16 v[44:47], v[170:173], v[214:217], v[44:47]
	v_mfma_f32_16x16x32_bf16 v[36:39], v[182:185], v[214:217], v[36:39]
	v_mfma_f32_16x16x32_bf16 v[28:31], v[170:173], v[222:225], v[28:31]
	v_mfma_f32_16x16x32_bf16 v[20:23], v[182:185], v[222:225], v[20:23]
	v_mfma_f32_16x16x32_bf16 v[12:15], v[170:173], v[232:235], v[12:15]
	v_mfma_f32_16x16x32_bf16 v[4:7], v[182:185], v[232:235], v[4:7]
	s_setprio 0
	s_setprio 1
	v_mfma_f32_16x16x32_bf16 v[56:59], v[186:189], v[202:205], v[56:59]
	v_mfma_f32_16x16x32_bf16 v[48:51], v[194:197], v[202:205], v[48:51]
	v_mfma_f32_16x16x32_bf16 v[40:43], v[186:189], v[210:213], v[40:43]
	v_mfma_f32_16x16x32_bf16 v[32:35], v[194:197], v[210:213], v[32:35]
	v_mfma_f32_16x16x32_bf16 v[24:27], v[186:189], v[218:221], v[24:27]
	v_mfma_f32_16x16x32_bf16 v[16:19], v[194:197], v[218:221], v[16:19]
	v_mfma_f32_16x16x32_bf16 v[8:11], v[186:189], v[226:229], v[8:11]
	v_mfma_f32_16x16x32_bf16 v[0:3], v[194:197], v[226:229], v[0:3]
	v_mfma_f32_16x16x32_bf16 v[56:59], v[190:193], v[206:209], v[56:59]
	v_mfma_f32_16x16x32_bf16 v[48:51], v[198:201], v[206:209], v[48:51]
	v_mfma_f32_16x16x32_bf16 v[40:43], v[190:193], v[214:217], v[40:43]
	v_mfma_f32_16x16x32_bf16 v[32:35], v[198:201], v[214:217], v[32:35]
	v_mfma_f32_16x16x32_bf16 v[24:27], v[190:193], v[222:225], v[24:27]
	v_mfma_f32_16x16x32_bf16 v[16:19], v[198:201], v[222:225], v[16:19]
	v_mfma_f32_16x16x32_bf16 v[8:11], v[190:193], v[232:235], v[8:11]
	v_mfma_f32_16x16x32_bf16 v[0:3], v[198:201], v[232:235], v[0:3]
	s_setprio 0
	s_barrier
	s_add_i32 s58, s58, 2
	s_add_u32 s34, s34, 0x100
	s_addc_u32 s35, s35, 0
	s_add_u32 s56, s56, 0x100
	s_addc_u32 s57, s57, 0
	s_cmp_gt_u32 s58, 13
	s_cbranch_scc0 .LBB0_977
	s_and_b64 vcc, exec, s[16:17]
	s_cbranch_vccz .LBB0_980
	s_barrier

; #define PG8_STAGE(bufoff, gbase, voff) do { _Pragma("unroll") for (int _i = 0; _i < 2; ++_i) \
;         __builtin_amdgcn_global_load_lds((const unsigned*)((const char*)(gbase) + (voff)[_i]), (PG8_LAS unsigned*)(lds + (bufoff) + ldsw + _i * 8192), 16, 0, 0); } while (0)
; #define PG8_WAIT_V(n) asm volatile("s_waitcnt vmcnt(" #n ")" ::: "memory")
; #define PG8_BAR __builtin_amdgcn_s_barrier()
; template <class Epi, class Sched, bool ALIGN_EPI = false, bool SP2 = false>
; __device__ __forceinline__ void gemm_phase(PG8_LAS unsigned char* lds, const Gemm g, const Sched& S, const Epi& E) {
;     ...
;     const int aoff = lds_byte(wr * 64 + fr, fq * 8), boff = lds_byte(wc * 32 + fr, fq * 8);
;     ...
;         PG8_STAGE(PG8_SB(1, 0), cB + kstep, voffB); PG8_STAGE(PG8_SA(1, 0), cA + kstep, voffA); PG8_STAGE(PG8_SB(1, 1), cB + hstep + kstep, voffB);
;         PG8_WAIT_V(6); PG8_BAR;
.LBB0_1047:
	s_lshl_b32 s1, s1, 5
	s_mov_b64 s[8:9], 0x80
	s_and_b32 s1, s1, 0x60
	s_add_i32 m0, s26, 0x18000
	v_lshl_add_u64 v[6:7], v[6:7], 0, s[8:9]
	s_ashr_i32 s31, s74, 31
	s_lshl_b32 s11, s0, 13
	s_lshl_b32 s14, s1, 7
	s_waitcnt vmcnt(2)
	s_barrier
	global_load_lds_dwordx4 v[6:7], off
	v_lshl_add_u64 v[4:5], v[4:5], 0, s[8:9]
	s_add_i32 m0, s26, 0x1a000
	s_add_i32 s33, s26, 0x8000
	s_add_i32 s34, s26, 0xa000
	global_load_lds_dwordx4 v[4:5], off
	v_lshl_add_u64 v[0:1], v[0:1], 0, s[8:9]
	s_mov_b32 m0, s33
	s_add_u32 s12, s18, 0xb0080
	global_load_lds_dwordx4 v[0:1], off
	v_lshl_add_u64 v[0:1], v[2:3], 0, s[8:9]
	s_mov_b32 m0, s34
	s_addc_u32 s13, s19, 0
	global_load_lds_dwordx4 v[0:1], off
	s_add_i32 m0, s26, 0x1c000
	global_load_lds_dwordx4 v162, s[12:13]
	v_lshl_add_u64 v[0:1], s[12:13], 0, v[166:167]
	s_add_i32 m0, s26, 0x1e000
	v_lshlrev_b32_e32 v2, 2, v230
	global_load_lds_dwordx4 v[0:1], off
	v_and_b32_e32 v0, 15, v230
	v_lshl_or_b32 v186, s0, 6, v0
	v_lshlrev_b32_e32 v1, 1, v10
	v_lshlrev_b32_e32 v3, 6, v230
	s_movk_i32 s0, 0x3c0
	v_lshl_or_b32 v0, v0, 6, v1
	v_and_b32_e32 v2, 32, v2
	v_and_or_b32 v1, v3, s0, v1
	v_bitop3_b32 v187, s14, v1, v2 bitop3:0xf6
	s_waitcnt vmcnt(6)
	s_cmpk_lt_u32 s10, 0x100
	v_add_u16_e32 v1, v8, v9
	v_bitop3_b32 v0, v0, s11, v2 bitop3:0xde
	s_cselect_b64 s[10:11], -1, 0
	v_lshrrev_b16_e32 v1, 1, v1
	s_add_i32 s35, 0, 0x10000
	s_add_i32 s36, 0, 0x14000
	v_or_b32_e32 v188, s1, v10
	v_add_lshl_u32 v168, v11, v1, 1
	v_mov_b32_e32 v169, v163
	v_add_lshl_u32 v170, v12, v1, 1
	v_mov_b32_e32 v171, v163
	v_add_u32_e32 v189, s35, v187
	v_add_u32_e32 v190, s36, v187
	v_add_u32_e32 v191, 0, v0
	v_mov_b64_e32 v[172:173], 0x7ff
	s_barrier
	s_branch .LBB0_1050

; #define PG8_STAGE(bufoff, gbase, voff) do { _Pragma("unroll") for (int _i = 0; _i < 2; ++_i) \
;         __builtin_amdgcn_global_load_lds((const unsigned*)((const char*)(gbase) + (voff)[_i]), (PG8_LAS unsigned*)(lds + (bufoff) + ldsw + _i * 8192), 16, 0, 0); } while (0)
; #define PG8_LDA(dst, b, h) do { _Pragma("unroll") for (int m = 0; m < 4; ++m) _Pragma("unroll") for (int k = 0; k < 2; ++k) dst[m][k] = *(const PG8_LAS bf16x8*)(lds + PG8_SA(b, h) + aoff + m * 2048 + k * 1024); } while (0)
; #define PG8_LDB(dst, b, h) do { _Pragma("unroll") for (int n = 0; n < 2; ++n) _Pragma("unroll") for (int k = 0; k < 2; ++k) dst[n][k] = *(const PG8_LAS bf16x8*)(lds + PG8_SB(b, h) + boff + n * 2048 + k * 1024); } while (0)
; #define PG8_MMA(ai, bj, At, Bt) do { __builtin_amdgcn_s_setprio(1); _Pragma("unroll") for (int m = 0; m < 4; ++m) _Pragma("unroll") for (int n = 0; n < 2; ++n) _Pragma("unroll") for (int k = 0; k < 2; ++k) \
;         acc[ai][bj][m][n] = __builtin_amdgcn_mfma_f32_16x16x32_bf16(Bt[n][k], At[m][k], acc[ai][bj][m][n], 0, 0, 0); __builtin_amdgcn_s_setprio(0); } while (0)
; #define PG8_WAIT_V(n) asm volatile("s_waitcnt vmcnt(" #n ")" ::: "memory")
; #define PG8_WAIT_L(n) asm volatile("s_waitcnt lgkmcnt(" #n ")" ::: "memory")
; #define PG8_BAR __builtin_amdgcn_s_barrier()
; #define PG8_SCHED __builtin_amdgcn_sched_barrier(0)
; template <class Epi, class Sched, bool ALIGN_EPI = false, bool SP2 = false>
; __device__ __forceinline__ void gemm_phase(PG8_LAS unsigned char* lds, const Gemm g, const Sched& S, const Epi& E) {
;     ...
;             PG8_LDB(B0, 0, 0); PG8_LDB(B1, 0, 1); PG8_SCHED; PG8_LDA(At, 0, 0); PG8_STAGE(PG8_SA(1, 1), a1 + hstep, voffA);
;             PG8_WAIT_V(8); PG8_WAIT_L(0); PG8_BAR; PG8_MMA(0, 0, At, B0); PG8_MMA(0, 1, At, B1); PG8_BAR; PG8_SCHED;
;             PG8_LDA(At, 0, 1); PG8_STAGE(PG8_SB(0, 0), b2, voffB); PG8_STAGE(PG8_SB(0, 1), b2 + hstep, voffB); PG8_STAGE(PG8_SA(0, 0), a2, voffA);
;             PG8_WAIT_V(8); PG8_WAIT_L(0); PG8_BAR; PG8_MMA(1, 0, At, B0); PG8_MMA(1, 1, At, B1); PG8_BAR; PG8_SCHED;
.LBB0_1061:
	s_add_u32 s16, s16, 0xb0080
	s_addc_u32 s17, s17, 0
	s_add_u32 s41, s18, 0x100
	s_addc_u32 s42, s19, 0
	s_mov_b32 s43, -2
	ds_read_b128 v[128:131], v189
	ds_read_b128 v[132:135], v189 offset:1024
	ds_read_b128 v[136:139], v189 offset:2048
	ds_read_b128 v[140:143], v189 offset:3072
	ds_read_b128 v[144:147], v190
	ds_read_b128 v[148:151], v190 offset:1024
	ds_read_b128 v[152:155], v190 offset:2048
	ds_read_b128 v[156:159], v190 offset:3072
	s_add_u32 s18, s16, 0xfff50080
	s_addc_u32 s19, s17, -1
	s_cmp_eq_u32 s43, 40
	s_cselect_b32 s21, s13, s19
	s_cselect_b32 s20, s12, s18
	s_cselect_b32 s19, s15, s42
	s_cselect_b32 s18, s14, s41
	s_add_i32 m0, s26, 0xc000
	ds_read_b128 v[174:177], v191
	ds_read_b128 v[178:181], v191 offset:1024
	ds_read_b128 v[182:185], v191 offset:2048
	ds_read_b128 v[192:195], v191 offset:3072
	ds_read_b128 v[196:199], v191 offset:4096
	ds_read_b128 v[200:203], v191 offset:5120
	ds_read_b128 v[204:207], v191 offset:6144
	ds_read_b128 v[208:211], v191 offset:7168
	global_load_lds_dwordx4 v168, s[16:17]
	s_add_i32 m0, s26, 0xe000
	s_nop 0
	global_load_lds_dwordx4 v170, s[16:17]
	s_waitcnt vmcnt(8)
	s_waitcnt lgkmcnt(0)
	s_barrier
	s_setprio 1
	s_waitcnt lgkmcnt(0)
	v_mfma_f32_16x16x32_bf16 v[124:127], v[128:131], v[174:177], 0
	v_mfma_f32_16x16x32_bf16 v[120:123], v[136:139], v[174:177], 0
	v_mfma_f32_16x16x32_bf16 v[116:119], v[128:131], v[182:185], 0
	v_mfma_f32_16x16x32_bf16 v[104:107], v[136:139], v[182:185], 0
	v_mfma_f32_16x16x32_bf16 v[96:99], v[128:131], v[196:199], 0
	v_mfma_f32_16x16x32_bf16 v[88:91], v[136:139], v[196:199], 0
	v_mfma_f32_16x16x32_bf16 v[80:83], v[128:131], v[204:207], 0
	v_mfma_f32_16x16x32_bf16 v[72:75], v[136:139], v[204:207], 0
	v_mfma_f32_16x16x32_bf16 v[124:127], v[132:135], v[178:181], v[124:127]
	v_mfma_f32_16x16x32_bf16 v[120:123], v[140:143], v[178:181], v[120:123]
	v_mfma_f32_16x16x32_bf16 v[116:119], v[132:135], v[192:195], v[116:119]
	v_mfma_f32_16x16x32_bf16 v[104:107], v[140:143], v[192:195], v[104:107]
	v_mfma_f32_16x16x32_bf16 v[96:99], v[132:135], v[200:203], v[96:99]
	v_mfma_f32_16x16x32_bf16 v[88:91], v[140:143], v[200:203], v[88:91]
	v_mfma_f32_16x16x32_bf16 v[80:83], v[132:135], v[208:211], v[80:83]
	v_mfma_f32_16x16x32_bf16 v[72:75], v[140:143], v[208:211], v[72:75]
	s_setprio 0
	s_setprio 1
	v_mfma_f32_16x16x32_bf16 v[112:115], v[144:147], v[174:177], 0
	v_mfma_f32_16x16x32_bf16 v[108:111], v[152:155], v[174:177], 0
	v_mfma_f32_16x16x32_bf16 v[100:103], v[144:147], v[182:185], 0
	v_mfma_f32_16x16x32_bf16 v[92:95], v[152:155], v[182:185], 0
	v_mfma_f32_16x16x32_bf16 v[84:87], v[144:147], v[196:199], 0
	v_mfma_f32_16x16x32_bf16 v[76:79], v[152:155], v[196:199], 0
	v_mfma_f32_16x16x32_bf16 v[68:71], v[144:147], v[204:207], 0
	v_mfma_f32_16x16x32_bf16 v[64:67], v[152:155], v[204:207], 0
	v_mfma_f32_16x16x32_bf16 v[112:115], v[148:151], v[178:181], v[112:115]
	v_mfma_f32_16x16x32_bf16 v[108:111], v[156:159], v[178:181], v[108:111]
	v_mfma_f32_16x16x32_bf16 v[100:103], v[148:151], v[192:195], v[100:103]
	v_mfma_f32_16x16x32_bf16 v[92:95], v[156:159], v[192:195], v[92:95]
	v_mfma_f32_16x16x32_bf16 v[84:87], v[148:151], v[200:203], v[84:87]
	v_mfma_f32_16x16x32_bf16 v[76:79], v[156:159], v[200:203], v[76:79]
	v_mfma_f32_16x16x32_bf16 v[68:71], v[148:151], v[208:211], v[68:71]
	v_mfma_f32_16x16x32_bf16 v[64:67], v[156:159], v[208:211], v[64:67]
	s_setprio 0
	s_barrier
	s_add_i32 s44, s35, s25
	v_lshl_add_u64 v[212:213], s[18:19], 0, v[162:163]
	s_mov_b32 m0, s44
	ds_read_b128 v[174:177], v191 offset:16384
	ds_read_b128 v[178:181], v191 offset:17408
	ds_read_b128 v[182:185], v191 offset:18432
	ds_read_b128 v[192:195], v191 offset:19456
	ds_read_b128 v[196:199], v191 offset:20480
	ds_read_b128 v[200:203], v191 offset:21504
	ds_read_b128 v[204:207], v191 offset:22528
	ds_read_b128 v[208:211], v191 offset:23552
	global_load_lds_dwordx4 v[212:213], off
	s_add_i32 m0, s44, 0x2000
	s_add_u32 s44, s18, 0xb0000
	v_lshl_add_u64 v[214:215], s[18:19], 0, v[166:167]
	s_addc_u32 s45, s19, 0
	s_add_i32 s46, s36, s25
	global_load_lds_dwordx4 v[214:215], off
	s_mov_b32 m0, s46
	v_lshl_add_u64 v[218:219], s[20:21], 0, v[164:165]
	global_load_lds_dwordx4 v162, s[44:45]
	s_add_i32 m0, s46, 0x2000
	s_nop 0
	global_load_lds_dwordx4 v166, s[44:45]
	v_lshl_add_u64 v[216:217], s[20:21], 0, v[160:161]
	s_mov_b32 m0, s26
	s_nop 0
	global_load_lds_dwordx4 v[216:217], off
	s_mov_b32 m0, s27
	s_nop 0
	global_load_lds_dwordx4 v[218:219], off
	s_waitcnt vmcnt(8)
	s_waitcnt lgkmcnt(0)
	s_barrier
	s_setprio 1
	s_waitcnt lgkmcnt(0)
	v_mfma_f32_16x16x32_bf16 v[60:63], v[128:131], v[174:177], 0
	v_mfma_f32_16x16x32_bf16 v[56:59], v[136:139], v[174:177], 0
	v_mfma_f32_16x16x32_bf16 v[48:51], v[128:131], v[182:185], 0
	v_mfma_f32_16x16x32_bf16 v[40:43], v[136:139], v[182:185], 0
	v_mfma_f32_16x16x32_bf16 v[32:35], v[128:131], v[196:199], 0
	v_mfma_f32_16x16x32_bf16 v[24:27], v[136:139], v[196:199], 0
	v_mfma_f32_16x16x32_bf16 v[16:19], v[128:131], v[204:207], 0
	v_mfma_f32_16x16x32_bf16 v[8:11], v[136:139], v[204:207], 0
	v_mfma_f32_16x16x32_bf16 v[60:63], v[132:135], v[178:181], v[60:63]
	v_mfma_f32_16x16x32_bf16 v[56:59], v[140:143], v[178:181], v[56:59]
	v_mfma_f32_16x16x32_bf16 v[48:51], v[132:135], v[192:195], v[48:51]
	v_mfma_f32_16x16x32_bf16 v[40:43], v[140:143], v[192:195], v[40:43]
	v_mfma_f32_16x16x32_bf16 v[32:35], v[132:135], v[200:203], v[32:35]
	v_mfma_f32_16x16x32_bf16 v[24:27], v[140:143], v[200:203], v[24:27]
	v_mfma_f32_16x16x32_bf16 v[16:19], v[132:135], v[208:211], v[16:19]
	v_mfma_f32_16x16x32_bf16 v[8:11], v[140:143], v[208:211], v[8:11]
	s_setprio 0
	s_setprio 1
	v_mfma_f32_16x16x32_bf16 v[52:55], v[144:147], v[174:177], 0
	v_mfma_f32_16x16x32_bf16 v[44:47], v[152:155], v[174:177], 0
	v_mfma_f32_16x16x32_bf16 v[36:39], v[144:147], v[182:185], 0
	v_mfma_f32_16x16x32_bf16 v[28:31], v[152:155], v[182:185], 0
	v_mfma_f32_16x16x32_bf16 v[20:23], v[144:147], v[196:199], 0
	v_mfma_f32_16x16x32_bf16 v[12:15], v[152:155], v[196:199], 0
	v_mfma_f32_16x16x32_bf16 v[4:7], v[144:147], v[204:207], 0
	v_mfma_f32_16x16x32_bf16 v[0:3], v[152:155], v[204:207], 0
	v_mfma_f32_16x16x32_bf16 v[52:55], v[148:151], v[178:181], v[52:55]
	v_mfma_f32_16x16x32_bf16 v[44:47], v[156:159], v[178:181], v[44:47]
	v_mfma_f32_16x16x32_bf16 v[36:39], v[148:151], v[192:195], v[36:39]
	v_mfma_f32_16x16x32_bf16 v[28:31], v[156:159], v[192:195], v[28:31]
	v_mfma_f32_16x16x32_bf16 v[20:23], v[148:151], v[200:203], v[20:23]
	v_mfma_f32_16x16x32_bf16 v[12:15], v[156:159], v[200:203], v[12:15]
	v_mfma_f32_16x16x32_bf16 v[4:7], v[148:151], v[208:211], v[4:7]
	v_mfma_f32_16x16x32_bf16 v[0:3], v[156:159], v[208:211], v[0:3]
	s_setprio 0
	s_barrier
; #define PG8_STAGE(bufoff, gbase, voff) do { _Pragma("unroll") for (int _i = 0; _i < 2; ++_i) \
;         __builtin_amdgcn_global_load_lds((const unsigned*)((const char*)(gbase) + (voff)[_i]), (PG8_LAS unsigned*)(lds + (bufoff) + ldsw + _i * 8192), 16, 0, 0); } while (0)
; #define PG8_LDA(dst, b, h) do { _Pragma("unroll") for (int m = 0; m < 4; ++m) _Pragma("unroll") for (int k = 0; k < 2; ++k) dst[m][k] = *(const PG8_LAS bf16x8*)(lds + PG8_SA(b, h) + aoff + m * 2048 + k * 1024); } while (0)
; #define PG8_LDB(dst, b, h) do { _Pragma("unroll") for (int n = 0; n < 2; ++n) _Pragma("unroll") for (int k = 0; k < 2; ++k) dst[n][k] = *(const PG8_LAS bf16x8*)(lds + PG8_SB(b, h) + boff + n * 2048 + k * 1024); } while (0)
; #define PG8_MMA(ai, bj, At, Bt) do { __builtin_amdgcn_s_setprio(1); _Pragma("unroll") for (int m = 0; m < 4; ++m) _Pragma("unroll") for (int n = 0; n < 2; ++n) _Pragma("unroll") for (int k = 0; k < 2; ++k) \
;         acc[ai][bj][m][n] = __builtin_amdgcn_mfma_f32_16x16x32_bf16(Bt[n][k], At[m][k], acc[ai][bj][m][n], 0, 0, 0); __builtin_amdgcn_s_setprio(0); } while (0)
; #define PG8_WAIT_V(n) asm volatile("s_waitcnt vmcnt(" #n ")" ::: "memory")
; #define PG8_WAIT_L(n) asm volatile("s_waitcnt lgkmcnt(" #n ")" ::: "memory")
; #define PG8_BAR __builtin_amdgcn_s_barrier()
; #define PG8_SCHED __builtin_amdgcn_sched_barrier(0)
; template <class Epi, class Sched, bool ALIGN_EPI = false, bool SP2 = false>
; __device__ __forceinline__ void gemm_phase(PG8_LAS unsigned char* lds, const Gemm g, const Sched& S, const Epi& E) {
;     ...
;             PG8_LDB(B0, 1, 0); PG8_LDB(B1, 1, 1); PG8_SCHED; PG8_LDA(At, 1, 0); PG8_STAGE(PG8_SA(0, 1), a2 + hstep, voffA);
;             PG8_WAIT_V(8); PG8_WAIT_L(0); PG8_BAR; PG8_MMA(0, 0, At, B0); PG8_MMA(0, 1, At, B1); PG8_BAR; PG8_SCHED;
;             PG8_LDA(At, 1, 1); PG8_STAGE(PG8_SB(1, 0), b3, voffB); PG8_STAGE(PG8_SB(1, 1), b3 + hstep, voffB); PG8_STAGE(PG8_SA(1, 0), a3, voffA);
;             PG8_WAIT_V(8); PG8_WAIT_L(0); PG8_BAR; PG8_MMA(1, 0, At, B0); PG8_MMA(1, 1, At, B1); PG8_BAR; PG8_SCHED;
	s_add_i32 s44, 0, 0x18000
	s_add_i32 s45, 0, 0x1c000
	v_add_u32_e32 v140, s44, v187
	v_add_u32_e32 v156, s45, v187
	ds_read_b128 v[128:131], v140
	ds_read_b128 v[132:135], v140 offset:1024
	ds_read_b128 v[136:139], v140 offset:2048
	ds_read_b128 v[140:143], v140 offset:3072
	ds_read_b128 v[144:147], v156
	ds_read_b128 v[148:151], v156 offset:1024
	ds_read_b128 v[152:155], v156 offset:2048
	ds_read_b128 v[156:159], v156 offset:3072
	s_add_u32 s20, s20, 0xb0000
	s_addc_u32 s21, s21, 0
	s_mov_b32 m0, s28
	ds_read_b128 v[174:177], v191 offset:32768
	ds_read_b128 v[178:181], v191 offset:33792
	ds_read_b128 v[182:185], v191 offset:34816
	ds_read_b128 v[192:195], v191 offset:35840
	ds_read_b128 v[196:199], v191 offset:36864
	ds_read_b128 v[200:203], v191 offset:37888
	ds_read_b128 v[204:207], v191 offset:38912
	ds_read_b128 v[208:211], v191 offset:39936
	global_load_lds_dwordx4 v160, s[20:21]
	v_lshl_add_u64 v[220:221], s[20:21], 0, v[164:165]
	s_mov_b32 m0, s29
	s_nop 0
	global_load_lds_dwordx4 v[220:221], off
	s_waitcnt vmcnt(8)
	s_waitcnt lgkmcnt(0)
	s_barrier
	s_setprio 1
	s_waitcnt lgkmcnt(0)
	v_mfma_f32_16x16x32_bf16 v[124:127], v[128:131], v[174:177], v[124:127]
	v_mfma_f32_16x16x32_bf16 v[120:123], v[136:139], v[174:177], v[120:123]
	v_mfma_f32_16x16x32_bf16 v[116:119], v[128:131], v[182:185], v[116:119]
	v_mfma_f32_16x16x32_bf16 v[104:107], v[136:139], v[182:185], v[104:107]
	v_mfma_f32_16x16x32_bf16 v[96:99], v[128:131], v[196:199], v[96:99]
	v_mfma_f32_16x16x32_bf16 v[88:91], v[136:139], v[196:199], v[88:91]
	v_mfma_f32_16x16x32_bf16 v[80:83], v[128:131], v[204:207], v[80:83]
	v_mfma_f32_16x16x32_bf16 v[72:75], v[136:139], v[204:207], v[72:75]
	v_mfma_f32_16x16x32_bf16 v[124:127], v[132:135], v[178:181], v[124:127]
	v_mfma_f32_16x16x32_bf16 v[120:123], v[140:143], v[178:181], v[120:123]
	v_mfma_f32_16x16x32_bf16 v[116:119], v[132:135], v[192:195], v[116:119]
	v_mfma_f32_16x16x32_bf16 v[104:107], v[140:143], v[192:195], v[104:107]
	v_mfma_f32_16x16x32_bf16 v[96:99], v[132:135], v[200:203], v[96:99]
	v_mfma_f32_16x16x32_bf16 v[88:91], v[140:143], v[200:203], v[88:91]
	v_mfma_f32_16x16x32_bf16 v[80:83], v[132:135], v[208:211], v[80:83]
	v_mfma_f32_16x16x32_bf16 v[72:75], v[140:143], v[208:211], v[72:75]
	s_setprio 0
	s_setprio 1
	v_mfma_f32_16x16x32_bf16 v[112:115], v[144:147], v[174:177], v[112:115]
	v_mfma_f32_16x16x32_bf16 v[108:111], v[152:155], v[174:177], v[108:111]
	v_mfma_f32_16x16x32_bf16 v[100:103], v[144:147], v[182:185], v[100:103]
	v_mfma_f32_16x16x32_bf16 v[92:95], v[152:155], v[182:185], v[92:95]
	v_mfma_f32_16x16x32_bf16 v[84:87], v[144:147], v[196:199], v[84:87]
	v_mfma_f32_16x16x32_bf16 v[76:79], v[152:155], v[196:199], v[76:79]
	v_mfma_f32_16x16x32_bf16 v[68:71], v[144:147], v[204:207], v[68:71]
	v_mfma_f32_16x16x32_bf16 v[64:67], v[152:155], v[204:207], v[64:67]
	v_mfma_f32_16x16x32_bf16 v[112:115], v[148:151], v[178:181], v[112:115]
	v_mfma_f32_16x16x32_bf16 v[108:111], v[156:159], v[178:181], v[108:111]
	v_mfma_f32_16x16x32_bf16 v[100:103], v[148:151], v[192:195], v[100:103]
	v_mfma_f32_16x16x32_bf16 v[92:95], v[156:159], v[192:195], v[92:95]
	v_mfma_f32_16x16x32_bf16 v[84:87], v[148:151], v[200:203], v[84:87]
	v_mfma_f32_16x16x32_bf16 v[76:79], v[156:159], v[200:203], v[76:79]
	v_mfma_f32_16x16x32_bf16 v[68:71], v[148:151], v[208:211], v[68:71]
	v_mfma_f32_16x16x32_bf16 v[64:67], v[156:159], v[208:211], v[64:67]
	s_setprio 0
	s_barrier
	s_add_i32 s20, s44, s25
	v_lshl_add_u64 v[212:213], v[212:213], 0, s[8:9]
	s_mov_b32 m0, s20
	ds_read_b128 v[174:177], v191 offset:49152
	ds_read_b128 v[178:181], v191 offset:50176
	ds_read_b128 v[182:185], v191 offset:51200
	ds_read_b128 v[192:195], v191 offset:52224
	ds_read_b128 v[196:199], v191 offset:53248
	ds_read_b128 v[200:203], v191 offset:54272
	ds_read_b128 v[204:207], v191 offset:55296
	ds_read_b128 v[208:211], v191 offset:56320
	global_load_lds_dwordx4 v[212:213], off
	s_add_i32 m0, s20, 0x2000
	s_add_u32 s18, s18, 0xb0080
	v_lshl_add_u64 v[212:213], v[214:215], 0, s[8:9]
	s_addc_u32 s19, s19, 0
	s_add_i32 s20, s45, s25
	global_load_lds_dwordx4 v[212:213], off
	s_mov_b32 m0, s20
	s_nop 0
	global_load_lds_dwordx4 v162, s[18:19]
	s_add_i32 m0, s20, 0x2000
	s_nop 0
	global_load_lds_dwordx4 v166, s[18:19]
	v_lshl_add_u64 v[212:213], v[216:217], 0, s[8:9]
	s_mov_b32 m0, s33
	s_nop 0
	global_load_lds_dwordx4 v[212:213], off
	v_lshl_add_u64 v[212:213], v[218:219], 0, s[8:9]
	s_mov_b32 m0, s34
	s_nop 0
	global_load_lds_dwordx4 v[212:213], off
	s_waitcnt vmcnt(8)
	s_waitcnt lgkmcnt(0)
	s_barrier
	s_setprio 1
	s_waitcnt lgkmcnt(0)
	v_mfma_f32_16x16x32_bf16 v[60:63], v[128:131], v[174:177], v[60:63]
	v_mfma_f32_16x16x32_bf16 v[56:59], v[136:139], v[174:177], v[56:59]
	v_mfma_f32_16x16x32_bf16 v[48:51], v[128:131], v[182:185], v[48:51]
	v_mfma_f32_16x16x32_bf16 v[40:43], v[136:139], v[182:185], v[40:43]
	v_mfma_f32_16x16x32_bf16 v[32:35], v[128:131], v[196:199], v[32:35]
	v_mfma_f32_16x16x32_bf16 v[24:27], v[136:139], v[196:199], v[24:27]
	v_mfma_f32_16x16x32_bf16 v[16:19], v[128:131], v[204:207], v[16:19]
	v_mfma_f32_16x16x32_bf16 v[8:11], v[136:139], v[204:207], v[8:11]
	v_mfma_f32_16x16x32_bf16 v[60:63], v[132:135], v[178:181], v[60:63]
	v_mfma_f32_16x16x32_bf16 v[56:59], v[140:143], v[178:181], v[56:59]
	v_mfma_f32_16x16x32_bf16 v[48:51], v[132:135], v[192:195], v[48:51]
	v_mfma_f32_16x16x32_bf16 v[40:43], v[140:143], v[192:195], v[40:43]
	v_mfma_f32_16x16x32_bf16 v[32:35], v[132:135], v[200:203], v[32:35]
	v_mfma_f32_16x16x32_bf16 v[24:27], v[140:143], v[200:203], v[24:27]
	v_mfma_f32_16x16x32_bf16 v[16:19], v[132:135], v[208:211], v[16:19]
	v_mfma_f32_16x16x32_bf16 v[8:11], v[140:143], v[208:211], v[8:11]
	s_setprio 0
	s_setprio 1
	v_mfma_f32_16x16x32_bf16 v[52:55], v[144:147], v[174:177], v[52:55]
	v_mfma_f32_16x16x32_bf16 v[44:47], v[152:155], v[174:177], v[44:47]
	v_mfma_f32_16x16x32_bf16 v[36:39], v[144:147], v[182:185], v[36:39]
	v_mfma_f32_16x16x32_bf16 v[28:31], v[152:155], v[182:185], v[28:31]
	v_mfma_f32_16x16x32_bf16 v[20:23], v[144:147], v[196:199], v[20:23]
	v_mfma_f32_16x16x32_bf16 v[12:15], v[152:155], v[196:199], v[12:15]
	v_mfma_f32_16x16x32_bf16 v[4:7], v[144:147], v[204:207], v[4:7]
	v_mfma_f32_16x16x32_bf16 v[0:3], v[152:155], v[204:207], v[0:3]
	v_mfma_f32_16x16x32_bf16 v[52:55], v[148:151], v[178:181], v[52:55]
	v_mfma_f32_16x16x32_bf16 v[44:47], v[156:159], v[178:181], v[44:47]
	v_mfma_f32_16x16x32_bf16 v[36:39], v[148:151], v[192:195], v[36:39]
	v_mfma_f32_16x16x32_bf16 v[28:31], v[156:159], v[192:195], v[28:31]
	v_mfma_f32_16x16x32_bf16 v[20:23], v[148:151], v[200:203], v[20:23]
	v_mfma_f32_16x16x32_bf16 v[12:15], v[156:159], v[200:203], v[12:15]
	v_mfma_f32_16x16x32_bf16 v[4:7], v[148:151], v[208:211], v[4:7]
	v_mfma_f32_16x16x32_bf16 v[0:3], v[156:159], v[208:211], v[0:3]
	s_setprio 0
	s_barrier
	s_add_i32 s43, s43, 2
	s_add_u32 s16, s16, 0x100
	s_addc_u32 s17, s17, 0
	s_add_u32 s41, s41, 0x100
	s_addc_u32 s42, s42, 0
	s_cmp_gt_u32 s43, 41
; #define PG8_STAGE(bufoff, gbase, voff) do { _Pragma("unroll") for (int _i = 0; _i < 2; ++_i) \
;         __builtin_amdgcn_global_load_lds((const unsigned*)((const char*)(gbase) + (voff)[_i]), (PG8_LAS unsigned*)(lds + (bufoff) + ldsw + _i * 8192), 16, 0, 0); } while (0)
; #define PG8_LDA(dst, b, h) do { _Pragma("unroll") for (int m = 0; m < 4; ++m) _Pragma("unroll") for (int k = 0; k < 2; ++k) dst[m][k] = *(const PG8_LAS bf16x8*)(lds + PG8_SA(b, h) + aoff + m * 2048 + k * 1024); } while (0)
; #define PG8_LDB(dst, b, h) do { _Pragma("unroll") for (int n = 0; n < 2; ++n) _Pragma("unroll") for (int k = 0; k < 2; ++k) dst[n][k] = *(const PG8_LAS bf16x8*)(lds + PG8_SB(b, h) + boff + n * 2048 + k * 1024); } while (0)
; #define PG8_MMA(ai, bj, At, Bt) do { __builtin_amdgcn_s_setprio(1); _Pragma("unroll") for (int m = 0; m < 4; ++m) _Pragma("unroll") for (int n = 0; n < 2; ++n) _Pragma("unroll") for (int k = 0; k < 2; ++k) \
;         acc[ai][bj][m][n] = __builtin_amdgcn_mfma_f32_16x16x32_bf16(Bt[n][k], At[m][k], acc[ai][bj][m][n], 0, 0, 0); __builtin_amdgcn_s_setprio(0); } while (0)
; #define PG8_WAIT_V(n) asm volatile("s_waitcnt vmcnt(" #n ")" ::: "memory")
; #define PG8_WAIT_L(n) asm volatile("s_waitcnt lgkmcnt(" #n ")" ::: "memory")
; #define PG8_BAR __builtin_amdgcn_s_barrier()
; #define PG8_SCHED __builtin_amdgcn_sched_barrier(0)
; template <class Epi, class Sched, bool ALIGN_EPI = false, bool SP2 = false>
; __device__ __forceinline__ void gemm_phase(PG8_LAS unsigned char* lds, const Gemm g, const Sched& S, const Epi& E) {
;     ...
;             PG8_LDB(B0, 0, 0); PG8_LDB(B1, 0, 1); PG8_SCHED; PG8_LDA(At, 0, 0); PG8_STAGE(PG8_SA(1, 1), a1 + hstep, voffA);
;             PG8_WAIT_V(8); PG8_WAIT_L(0); PG8_BAR; PG8_MMA(0, 0, At, B0); PG8_MMA(0, 1, At, B1); PG8_BAR; PG8_SCHED;
;             PG8_LDA(At, 0, 1); PG8_STAGE(PG8_SB(0, 0), b2, voffB); PG8_STAGE(PG8_SB(0, 1), b2 + hstep, voffB); PG8_STAGE(PG8_SA(0, 0), a2, voffA);
;             PG8_WAIT_V(8); PG8_WAIT_L(0); PG8_BAR; PG8_MMA(1, 0, At, B0); PG8_MMA(1, 1, At, B1); PG8_BAR; PG8_SCHED;
.LBB0_1062:
	ds_read_b128 v[128:131], v189
	ds_read_b128 v[132:135], v189 offset:1024
	ds_read_b128 v[136:139], v189 offset:2048
	ds_read_b128 v[140:143], v189 offset:3072
	ds_read_b128 v[144:147], v190
	ds_read_b128 v[148:151], v190 offset:1024
	ds_read_b128 v[152:155], v190 offset:2048
	ds_read_b128 v[156:159], v190 offset:3072
	s_add_u32 s18, s16, 0xfff50080
	s_addc_u32 s19, s17, -1
	s_cmp_eq_u32 s43, 40
	s_cselect_b32 s21, s13, s19
	s_cselect_b32 s20, s12, s18
	s_cselect_b32 s19, s15, s42
	s_cselect_b32 s18, s14, s41
	s_add_i32 m0, s26, 0xc000
	ds_read_b128 v[174:177], v191
	ds_read_b128 v[178:181], v191 offset:1024
	ds_read_b128 v[182:185], v191 offset:2048
	ds_read_b128 v[192:195], v191 offset:3072
	ds_read_b128 v[196:199], v191 offset:4096
	ds_read_b128 v[200:203], v191 offset:5120
	ds_read_b128 v[204:207], v191 offset:6144
	ds_read_b128 v[208:211], v191 offset:7168
	global_load_lds_dwordx4 v168, s[16:17]
	s_add_i32 m0, s26, 0xe000
	s_nop 0
	global_load_lds_dwordx4 v170, s[16:17]
	s_waitcnt vmcnt(8)
	s_waitcnt lgkmcnt(0)
	s_barrier
	s_setprio 1
	s_waitcnt lgkmcnt(0)
	v_mfma_f32_16x16x32_bf16 v[124:127], v[128:131], v[174:177], v[124:127]
	v_mfma_f32_16x16x32_bf16 v[120:123], v[136:139], v[174:177], v[120:123]
	v_mfma_f32_16x16x32_bf16 v[116:119], v[128:131], v[182:185], v[116:119]
	v_mfma_f32_16x16x32_bf16 v[104:107], v[136:139], v[182:185], v[104:107]
	v_mfma_f32_16x16x32_bf16 v[96:99], v[128:131], v[196:199], v[96:99]
	v_mfma_f32_16x16x32_bf16 v[88:91], v[136:139], v[196:199], v[88:91]
	v_mfma_f32_16x16x32_bf16 v[80:83], v[128:131], v[204:207], v[80:83]
	v_mfma_f32_16x16x32_bf16 v[72:75], v[136:139], v[204:207], v[72:75]
	v_mfma_f32_16x16x32_bf16 v[124:127], v[132:135], v[178:181], v[124:127]
	v_mfma_f32_16x16x32_bf16 v[120:123], v[140:143], v[178:181], v[120:123]
	v_mfma_f32_16x16x32_bf16 v[116:119], v[132:135], v[192:195], v[116:119]
	v_mfma_f32_16x16x32_bf16 v[104:107], v[140:143], v[192:195], v[104:107]
	v_mfma_f32_16x16x32_bf16 v[96:99], v[132:135], v[200:203], v[96:99]
	v_mfma_f32_16x16x32_bf16 v[88:91], v[140:143], v[200:203], v[88:91]
	v_mfma_f32_16x16x32_bf16 v[80:83], v[132:135], v[208:211], v[80:83]
	v_mfma_f32_16x16x32_bf16 v[72:75], v[140:143], v[208:211], v[72:75]
	s_setprio 0
	s_setprio 1
	v_mfma_f32_16x16x32_bf16 v[112:115], v[144:147], v[174:177], v[112:115]
	v_mfma_f32_16x16x32_bf16 v[108:111], v[152:155], v[174:177], v[108:111]
	v_mfma_f32_16x16x32_bf16 v[100:103], v[144:147], v[182:185], v[100:103]
	v_mfma_f32_16x16x32_bf16 v[92:95], v[152:155], v[182:185], v[92:95]
	v_mfma_f32_16x16x32_bf16 v[84:87], v[144:147], v[196:199], v[84:87]
	v_mfma_f32_16x16x32_bf16 v[76:79], v[152:155], v[196:199], v[76:79]
	v_mfma_f32_16x16x32_bf16 v[68:71], v[144:147], v[204:207], v[68:71]
	v_mfma_f32_16x16x32_bf16 v[64:67], v[152:155], v[204:207], v[64:67]
	v_mfma_f32_16x16x32_bf16 v[112:115], v[148:151], v[178:181], v[112:115]
	v_mfma_f32_16x16x32_bf16 v[108:111], v[156:159], v[178:181], v[108:111]
	v_mfma_f32_16x16x32_bf16 v[100:103], v[148:151], v[192:195], v[100:103]
	v_mfma_f32_16x16x32_bf16 v[92:95], v[156:159], v[192:195], v[92:95]
	v_mfma_f32_16x16x32_bf16 v[84:87], v[148:151], v[200:203], v[84:87]
	v_mfma_f32_16x16x32_bf16 v[76:79], v[156:159], v[200:203], v[76:79]
	v_mfma_f32_16x16x32_bf16 v[68:71], v[148:151], v[208:211], v[68:71]
	v_mfma_f32_16x16x32_bf16 v[64:67], v[156:159], v[208:211], v[64:67]
	s_setprio 0
	s_barrier
	s_add_i32 s44, s35, s25
	v_lshl_add_u64 v[212:213], s[18:19], 0, v[162:163]
	s_mov_b32 m0, s44
	ds_read_b128 v[174:177], v191 offset:16384
	ds_read_b128 v[178:181], v191 offset:17408
	ds_read_b128 v[182:185], v191 offset:18432
	ds_read_b128 v[192:195], v191 offset:19456
	ds_read_b128 v[196:199], v191 offset:20480
	ds_read_b128 v[200:203], v191 offset:21504
	ds_read_b128 v[204:207], v191 offset:22528
	ds_read_b128 v[208:211], v191 offset:23552
	global_load_lds_dwordx4 v[212:213], off
	s_add_i32 m0, s44, 0x2000
	s_add_u32 s44, s18, 0xb0000
	v_lshl_add_u64 v[214:215], s[18:19], 0, v[166:167]
	s_addc_u32 s45, s19, 0
	s_add_i32 s46, s36, s25
	global_load_lds_dwordx4 v[214:215], off
	s_mov_b32 m0, s46
	v_lshl_add_u64 v[218:219], s[20:21], 0, v[164:165]
	global_load_lds_dwordx4 v162, s[44:45]
	s_add_i32 m0, s46, 0x2000
	s_nop 0
	global_load_lds_dwordx4 v166, s[44:45]
	v_lshl_add_u64 v[216:217], s[20:21], 0, v[160:161]
	s_mov_b32 m0, s26
	s_nop 0
	global_load_lds_dwordx4 v[216:217], off
	s_mov_b32 m0, s27
	s_nop 0
	global_load_lds_dwordx4 v[218:219], off
	s_waitcnt vmcnt(8)
	s_waitcnt lgkmcnt(0)
	s_barrier
; #define PG8_STAGE(bufoff, gbase, voff) do { _Pragma("unroll") for (int _i = 0; _i < 2; ++_i) \
;         __builtin_amdgcn_global_load_lds((const unsigned*)((const char*)(gbase) + (voff)[_i]), (PG8_LAS unsigned*)(lds + (bufoff) + ldsw + _i * 8192), 16, 0, 0); } while (0)
; #define PG8_LDA(dst, b, h) do { _Pragma("unroll") for (int m = 0; m < 4; ++m) _Pragma("unroll") for (int k = 0; k < 2; ++k) dst[m][k] = *(const PG8_LAS bf16x8*)(lds + PG8_SA(b, h) + aoff + m * 2048 + k * 1024); } while (0)
; #define PG8_LDB(dst, b, h) do { _Pragma("unroll") for (int n = 0; n < 2; ++n) _Pragma("unroll") for (int k = 0; k < 2; ++k) dst[n][k] = *(const PG8_LAS bf16x8*)(lds + PG8_SB(b, h) + boff + n * 2048 + k * 1024); } while (0)
; #define PG8_MMA(ai, bj, At, Bt) do { __builtin_amdgcn_s_setprio(1); _Pragma("unroll") for (int m = 0; m < 4; ++m) _Pragma("unroll") for (int n = 0; n < 2; ++n) _Pragma("unroll") for (int k = 0; k < 2; ++k) \
;         acc[ai][bj][m][n] = __builtin_amdgcn_mfma_f32_16x16x32_bf16(Bt[n][k], At[m][k], acc[ai][bj][m][n], 0, 0, 0); __builtin_amdgcn_s_setprio(0); } while (0)
; #define PG8_WAIT_V(n) asm volatile("s_waitcnt vmcnt(" #n ")" ::: "memory")
; #define PG8_WAIT_L(n) asm volatile("s_waitcnt lgkmcnt(" #n ")" ::: "memory")
; #define PG8_BAR __builtin_amdgcn_s_barrier()
; #define PG8_SCHED __builtin_amdgcn_sched_barrier(0)
; template <class Epi, class Sched, bool ALIGN_EPI = false, bool SP2 = false>
; __device__ __forceinline__ void gemm_phase(PG8_LAS unsigned char* lds, const Gemm g, const Sched& S, const Epi& E) {
;     ...
;             PG8_WAIT_V(8); PG8_WAIT_L(0); PG8_BAR; PG8_MMA(1, 0, At, B0); PG8_MMA(1, 1, At, B1); PG8_BAR; PG8_SCHED;
;             PG8_LDB(B0, 1, 0); PG8_LDB(B1, 1, 1); PG8_SCHED; PG8_LDA(At, 1, 0); PG8_STAGE(PG8_SA(0, 1), a2 + hstep, voffA);
;             PG8_WAIT_V(8); PG8_WAIT_L(0); PG8_BAR; PG8_MMA(0, 0, At, B0); PG8_MMA(0, 1, At, B1); PG8_BAR; PG8_SCHED;
	s_setprio 1
	s_waitcnt lgkmcnt(0)
	v_mfma_f32_16x16x32_bf16 v[60:63], v[128:131], v[174:177], v[60:63]
	v_mfma_f32_16x16x32_bf16 v[56:59], v[136:139], v[174:177], v[56:59]
	v_mfma_f32_16x16x32_bf16 v[48:51], v[128:131], v[182:185], v[48:51]
	v_mfma_f32_16x16x32_bf16 v[40:43], v[136:139], v[182:185], v[40:43]
	v_mfma_f32_16x16x32_bf16 v[32:35], v[128:131], v[196:199], v[32:35]
	v_mfma_f32_16x16x32_bf16 v[24:27], v[136:139], v[196:199], v[24:27]
	v_mfma_f32_16x16x32_bf16 v[16:19], v[128:131], v[204:207], v[16:19]
	v_mfma_f32_16x16x32_bf16 v[8:11], v[136:139], v[204:207], v[8:11]
	v_mfma_f32_16x16x32_bf16 v[60:63], v[132:135], v[178:181], v[60:63]
	v_mfma_f32_16x16x32_bf16 v[56:59], v[140:143], v[178:181], v[56:59]
	v_mfma_f32_16x16x32_bf16 v[48:51], v[132:135], v[192:195], v[48:51]
	v_mfma_f32_16x16x32_bf16 v[40:43], v[140:143], v[192:195], v[40:43]
	v_mfma_f32_16x16x32_bf16 v[32:35], v[132:135], v[200:203], v[32:35]
	v_mfma_f32_16x16x32_bf16 v[24:27], v[140:143], v[200:203], v[24:27]
	v_mfma_f32_16x16x32_bf16 v[16:19], v[132:135], v[208:211], v[16:19]
	v_mfma_f32_16x16x32_bf16 v[8:11], v[140:143], v[208:211], v[8:11]
	s_setprio 0
	s_setprio 1
	v_mfma_f32_16x16x32_bf16 v[52:55], v[144:147], v[174:177], v[52:55]
	v_mfma_f32_16x16x32_bf16 v[44:47], v[152:155], v[174:177], v[44:47]
	v_mfma_f32_16x16x32_bf16 v[36:39], v[144:147], v[182:185], v[36:39]
	v_mfma_f32_16x16x32_bf16 v[28:31], v[152:155], v[182:185], v[28:31]
	v_mfma_f32_16x16x32_bf16 v[20:23], v[144:147], v[196:199], v[20:23]
	v_mfma_f32_16x16x32_bf16 v[12:15], v[152:155], v[196:199], v[12:15]
	v_mfma_f32_16x16x32_bf16 v[4:7], v[144:147], v[204:207], v[4:7]
	v_mfma_f32_16x16x32_bf16 v[0:3], v[152:155], v[204:207], v[0:3]
	v_mfma_f32_16x16x32_bf16 v[52:55], v[148:151], v[178:181], v[52:55]
	v_mfma_f32_16x16x32_bf16 v[44:47], v[156:159], v[178:181], v[44:47]
	v_mfma_f32_16x16x32_bf16 v[36:39], v[148:151], v[192:195], v[36:39]
	v_mfma_f32_16x16x32_bf16 v[28:31], v[156:159], v[192:195], v[28:31]
	v_mfma_f32_16x16x32_bf16 v[20:23], v[148:151], v[200:203], v[20:23]
	v_mfma_f32_16x16x32_bf16 v[12:15], v[156:159], v[200:203], v[12:15]
	v_mfma_f32_16x16x32_bf16 v[4:7], v[148:151], v[208:211], v[4:7]
	v_mfma_f32_16x16x32_bf16 v[0:3], v[156:159], v[208:211], v[0:3]
	s_setprio 0
	s_barrier
	s_add_i32 s44, 0, 0x18000
	s_add_i32 s45, 0, 0x1c000
	v_add_u32_e32 v140, s44, v187
	v_add_u32_e32 v156, s45, v187
	ds_read_b128 v[128:131], v140
	ds_read_b128 v[132:135], v140 offset:1024
	ds_read_b128 v[136:139], v140 offset:2048
	ds_read_b128 v[140:143], v140 offset:3072
	ds_read_b128 v[144:147], v156
	ds_read_b128 v[148:151], v156 offset:1024
	ds_read_b128 v[152:155], v156 offset:2048
	ds_read_b128 v[156:159], v156 offset:3072
	s_add_u32 s20, s20, 0xb0000
	s_addc_u32 s21, s21, 0
	s_mov_b32 m0, s28
	ds_read_b128 v[174:177], v191 offset:32768
	ds_read_b128 v[178:181], v191 offset:33792
	ds_read_b128 v[182:185], v191 offset:34816
	ds_read_b128 v[192:195], v191 offset:35840
	ds_read_b128 v[196:199], v191 offset:36864
	ds_read_b128 v[200:203], v191 offset:37888
	ds_read_b128 v[204:207], v191 offset:38912
	ds_read_b128 v[208:211], v191 offset:39936
	global_load_lds_dwordx4 v160, s[20:21]
	v_lshl_add_u64 v[220:221], s[20:21], 0, v[164:165]
	s_mov_b32 m0, s29
	s_nop 0
	global_load_lds_dwordx4 v[220:221], off
	s_waitcnt vmcnt(8)
	s_waitcnt lgkmcnt(0)
	s_barrier
	s_setprio 1
	s_waitcnt lgkmcnt(0)
	v_mfma_f32_16x16x32_bf16 v[124:127], v[128:131], v[174:177], v[124:127]
	v_mfma_f32_16x16x32_bf16 v[120:123], v[136:139], v[174:177], v[120:123]
	v_mfma_f32_16x16x32_bf16 v[116:119], v[128:131], v[182:185], v[116:119]
	v_mfma_f32_16x16x32_bf16 v[104:107], v[136:139], v[182:185], v[104:107]
	v_mfma_f32_16x16x32_bf16 v[96:99], v[128:131], v[196:199], v[96:99]
	v_mfma_f32_16x16x32_bf16 v[88:91], v[136:139], v[196:199], v[88:91]
	v_mfma_f32_16x16x32_bf16 v[80:83], v[128:131], v[204:207], v[80:83]
	v_mfma_f32_16x16x32_bf16 v[72:75], v[136:139], v[204:207], v[72:75]
	v_mfma_f32_16x16x32_bf16 v[124:127], v[132:135], v[178:181], v[124:127]
	v_mfma_f32_16x16x32_bf16 v[120:123], v[140:143], v[178:181], v[120:123]
	v_mfma_f32_16x16x32_bf16 v[116:119], v[132:135], v[192:195], v[116:119]
	v_mfma_f32_16x16x32_bf16 v[104:107], v[140:143], v[192:195], v[104:107]
	v_mfma_f32_16x16x32_bf16 v[96:99], v[132:135], v[200:203], v[96:99]
	v_mfma_f32_16x16x32_bf16 v[88:91], v[140:143], v[200:203], v[88:91]
	v_mfma_f32_16x16x32_bf16 v[80:83], v[132:135], v[208:211], v[80:83]
	v_mfma_f32_16x16x32_bf16 v[72:75], v[140:143], v[208:211], v[72:75]
	s_setprio 0
	s_setprio 1
	v_mfma_f32_16x16x32_bf16 v[112:115], v[144:147], v[174:177], v[112:115]
	v_mfma_f32_16x16x32_bf16 v[108:111], v[152:155], v[174:177], v[108:111]
	v_mfma_f32_16x16x32_bf16 v[100:103], v[144:147], v[182:185], v[100:103]
	v_mfma_f32_16x16x32_bf16 v[92:95], v[152:155], v[182:185], v[92:95]
	v_mfma_f32_16x16x32_bf16 v[84:87], v[144:147], v[196:199], v[84:87]
	v_mfma_f32_16x16x32_bf16 v[76:79], v[152:155], v[196:199], v[76:79]
	v_mfma_f32_16x16x32_bf16 v[68:71], v[144:147], v[204:207], v[68:71]
	v_mfma_f32_16x16x32_bf16 v[64:67], v[152:155], v[204:207], v[64:67]
	v_mfma_f32_16x16x32_bf16 v[112:115], v[148:151], v[178:181], v[112:115]
	v_mfma_f32_16x16x32_bf16 v[108:111], v[156:159], v[178:181], v[108:111]
	v_mfma_f32_16x16x32_bf16 v[100:103], v[148:151], v[192:195], v[100:103]
	v_mfma_f32_16x16x32_bf16 v[92:95], v[156:159], v[192:195], v[92:95]
	v_mfma_f32_16x16x32_bf16 v[84:87], v[148:151], v[200:203], v[84:87]
	v_mfma_f32_16x16x32_bf16 v[76:79], v[156:159], v[200:203], v[76:79]
	v_mfma_f32_16x16x32_bf16 v[68:71], v[148:151], v[208:211], v[68:71]
	v_mfma_f32_16x16x32_bf16 v[64:67], v[156:159], v[208:211], v[64:67]
	s_setprio 0
	s_barrier
; #define PG8_STAGE(bufoff, gbase, voff) do { _Pragma("unroll") for (int _i = 0; _i < 2; ++_i) \
;         __builtin_amdgcn_global_load_lds((const unsigned*)((const char*)(gbase) + (voff)[_i]), (PG8_LAS unsigned*)(lds + (bufoff) + ldsw + _i * 8192), 16, 0, 0); } while (0)
; #define PG8_LDA(dst, b, h) do { _Pragma("unroll") for (int m = 0; m < 4; ++m) _Pragma("unroll") for (int k = 0; k < 2; ++k) dst[m][k] = *(const PG8_LAS bf16x8*)(lds + PG8_SA(b, h) + aoff + m * 2048 + k * 1024); } while (0)
; #define PG8_MMA(ai, bj, At, Bt) do { __builtin_amdgcn_s_setprio(1); _Pragma("unroll") for (int m = 0; m < 4; ++m) _Pragma("unroll") for (int n = 0; n < 2; ++n) _Pragma("unroll") for (int k = 0; k < 2; ++k) \
;         acc[ai][bj][m][n] = __builtin_amdgcn_mfma_f32_16x16x32_bf16(Bt[n][k], At[m][k], acc[ai][bj][m][n], 0, 0, 0); __builtin_amdgcn_s_setprio(0); } while (0)
; #define PG8_WAIT_V(n) asm volatile("s_waitcnt vmcnt(" #n ")" ::: "memory")
; #define PG8_WAIT_L(n) asm volatile("s_waitcnt lgkmcnt(" #n ")" ::: "memory")
; #define PG8_BAR __builtin_amdgcn_s_barrier()
; #define PG8_SCHED __builtin_amdgcn_sched_barrier(0)
; template <class Epi, class Sched, bool ALIGN_EPI = false, bool SP2 = false>
; __device__ __forceinline__ void gemm_phase(PG8_LAS unsigned char* lds, const Gemm g, const Sched& S, const Epi& E) {
;     ...
;         for (int t = 0; t < nt; t += 2) {
;     ...
;             PG8_LDA(At, 1, 1); PG8_STAGE(PG8_SB(1, 0), b3, voffB); PG8_STAGE(PG8_SB(1, 1), b3 + hstep, voffB); PG8_STAGE(PG8_SA(1, 0), a3, voffA);
;             PG8_WAIT_V(8); PG8_WAIT_L(0); PG8_BAR; PG8_MMA(1, 0, At, B0); PG8_MMA(1, 1, At, B1); PG8_BAR; PG8_SCHED;
	s_add_i32 s20, s44, s25
	v_lshl_add_u64 v[212:213], v[212:213], 0, s[8:9]
	s_mov_b32 m0, s20
	ds_read_b128 v[174:177], v191 offset:49152
	ds_read_b128 v[178:181], v191 offset:50176
	ds_read_b128 v[182:185], v191 offset:51200
	ds_read_b128 v[192:195], v191 offset:52224
	ds_read_b128 v[196:199], v191 offset:53248
	ds_read_b128 v[200:203], v191 offset:54272
	ds_read_b128 v[204:207], v191 offset:55296
	ds_read_b128 v[208:211], v191 offset:56320
	global_load_lds_dwordx4 v[212:213], off
	s_add_i32 m0, s20, 0x2000
	s_add_u32 s18, s18, 0xb0080
	v_lshl_add_u64 v[212:213], v[214:215], 0, s[8:9]
	s_addc_u32 s19, s19, 0
	s_add_i32 s20, s45, s25
	global_load_lds_dwordx4 v[212:213], off
	s_mov_b32 m0, s20
	s_nop 0
	global_load_lds_dwordx4 v162, s[18:19]
	s_add_i32 m0, s20, 0x2000
	s_nop 0
	global_load_lds_dwordx4 v166, s[18:19]
	v_lshl_add_u64 v[212:213], v[216:217], 0, s[8:9]
	s_mov_b32 m0, s33
	s_nop 0
	global_load_lds_dwordx4 v[212:213], off
	v_lshl_add_u64 v[212:213], v[218:219], 0, s[8:9]
	s_mov_b32 m0, s34
	s_nop 0
	global_load_lds_dwordx4 v[212:213], off
	s_waitcnt vmcnt(8)
	s_waitcnt lgkmcnt(0)
	s_barrier
	s_setprio 1
	s_waitcnt lgkmcnt(0)
	v_mfma_f32_16x16x32_bf16 v[60:63], v[128:131], v[174:177], v[60:63]
	v_mfma_f32_16x16x32_bf16 v[56:59], v[136:139], v[174:177], v[56:59]
	v_mfma_f32_16x16x32_bf16 v[48:51], v[128:131], v[182:185], v[48:51]
	v_mfma_f32_16x16x32_bf16 v[40:43], v[136:139], v[182:185], v[40:43]
	v_mfma_f32_16x16x32_bf16 v[32:35], v[128:131], v[196:199], v[32:35]
	v_mfma_f32_16x16x32_bf16 v[24:27], v[136:139], v[196:199], v[24:27]
	v_mfma_f32_16x16x32_bf16 v[16:19], v[128:131], v[204:207], v[16:19]
	v_mfma_f32_16x16x32_bf16 v[8:11], v[136:139], v[204:207], v[8:11]
	v_mfma_f32_16x16x32_bf16 v[60:63], v[132:135], v[178:181], v[60:63]
	v_mfma_f32_16x16x32_bf16 v[56:59], v[140:143], v[178:181], v[56:59]
	v_mfma_f32_16x16x32_bf16 v[48:51], v[132:135], v[192:195], v[48:51]
	v_mfma_f32_16x16x32_bf16 v[40:43], v[140:143], v[192:195], v[40:43]
	v_mfma_f32_16x16x32_bf16 v[32:35], v[132:135], v[200:203], v[32:35]
	v_mfma_f32_16x16x32_bf16 v[24:27], v[140:143], v[200:203], v[24:27]
	v_mfma_f32_16x16x32_bf16 v[16:19], v[132:135], v[208:211], v[16:19]
	v_mfma_f32_16x16x32_bf16 v[8:11], v[140:143], v[208:211], v[8:11]
	s_setprio 0
	s_setprio 1
	v_mfma_f32_16x16x32_bf16 v[52:55], v[144:147], v[174:177], v[52:55]
	v_mfma_f32_16x16x32_bf16 v[44:47], v[152:155], v[174:177], v[44:47]
	v_mfma_f32_16x16x32_bf16 v[36:39], v[144:147], v[182:185], v[36:39]
	v_mfma_f32_16x16x32_bf16 v[28:31], v[152:155], v[182:185], v[28:31]
	v_mfma_f32_16x16x32_bf16 v[20:23], v[144:147], v[196:199], v[20:23]
	v_mfma_f32_16x16x32_bf16 v[12:15], v[152:155], v[196:199], v[12:15]
	v_mfma_f32_16x16x32_bf16 v[4:7], v[144:147], v[204:207], v[4:7]
	v_mfma_f32_16x16x32_bf16 v[0:3], v[152:155], v[204:207], v[0:3]
	v_mfma_f32_16x16x32_bf16 v[52:55], v[148:151], v[178:181], v[52:55]
	v_mfma_f32_16x16x32_bf16 v[44:47], v[156:159], v[178:181], v[44:47]
	v_mfma_f32_16x16x32_bf16 v[36:39], v[148:151], v[192:195], v[36:39]
	v_mfma_f32_16x16x32_bf16 v[28:31], v[156:159], v[192:195], v[28:31]
	v_mfma_f32_16x16x32_bf16 v[20:23], v[148:151], v[200:203], v[20:23]
	v_mfma_f32_16x16x32_bf16 v[12:15], v[156:159], v[200:203], v[12:15]
	v_mfma_f32_16x16x32_bf16 v[4:7], v[148:151], v[208:211], v[4:7]
	v_mfma_f32_16x16x32_bf16 v[0:3], v[156:159], v[208:211], v[0:3]
	s_setprio 0
	s_barrier
	s_add_i32 s43, s43, 2
	s_add_u32 s16, s16, 0x100
	s_addc_u32 s17, s17, 0
	s_add_u32 s41, s41, 0x100
	s_addc_u32 s42, s42, 0
	s_cmp_gt_u32 s43, 41
	s_cbranch_scc0 .LBB0_1062
	s_and_b64 vcc, exec, s[10:11]
	s_cbranch_vccz .LBB0_1065
	s_barrier
